# GEMM K-loops: one M0 write per A/B piece group (instruction offset steps LDS+global, global side compensated before the loop); stage offsets toggled by s_xor instead of rebuilt each iteration
# baseline (speedup 1.0000x reference)
.LBB0_258:
	s_mul_hi_i32 s4, s44, 0x2aaaaaab
	s_lshr_b32 s5, s4, 31
	s_ashr_i32 s4, s4, 1
	s_add_i32 s4, s4, s5
	s_mul_i32 s5, s4, -12
	s_add_i32 s5, s5, s44
	s_lshl_b32 s6, s5, 7
	v_add_u32_e32 v0, s6, v112
	v_ashrrev_i32_e32 v1, 31, v0
	v_add_u32_e32 v2, 0x4000, v113
	v_lshlrev_b64 v[0:1], 11, v[0:1]
	v_readfirstlane_b32 s5, v2
	s_lshl_b32 s30, s4, 7
	v_lshl_add_u64 v[0:1], v[66:67], 0, v[0:1]
	s_mov_b32 m0, s5
	v_readfirstlane_b32 s5, v113
	global_load_lds_dwordx4 v[0:1], off
	v_add_u32_e32 v0, s30, v112
	v_ashrrev_i32_e32 v1, 31, v0
	v_lshlrev_b64 v[0:1], 11, v[0:1]
	v_lshl_add_u64 v[2:3], v[72:73], 0, v[0:1]
	s_mov_b32 m0, s5
	v_readfirstlane_b32 s5, v137
	global_load_lds_dwordx4 v[2:3], off
	v_add_u32_e32 v2, s6, v114
	v_ashrrev_i32_e32 v3, 31, v2
	v_lshlrev_b64 v[2:3], 11, v[2:3]
	v_lshl_add_u64 v[2:3], v[68:69], 0, v[2:3]
	s_mov_b32 m0, s5
	v_add_u32_e32 v4, 0x400, v113
	global_load_lds_dwordx4 v[2:3], off
	v_add_u32_e32 v2, s30, v114
	v_ashrrev_i32_e32 v3, 31, v2
	v_lshlrev_b64 v[2:3], 11, v[2:3]
	v_readfirstlane_b32 s5, v4
	v_lshl_add_u64 v[2:3], v[74:75], 0, v[2:3]
	s_mov_b32 m0, s5
	v_readfirstlane_b32 s5, v138
	global_load_lds_dwordx4 v[2:3], off
	v_add_u32_e32 v2, s6, v116
	v_ashrrev_i32_e32 v3, 31, v2
	v_lshlrev_b64 v[2:3], 11, v[2:3]
	v_lshl_add_u64 v[2:3], v[66:67], 0, v[2:3]
	s_mov_b32 m0, s5
	v_add_u32_e32 v4, 0x800, v113
	global_load_lds_dwordx4 v[2:3], off
	v_add_u32_e32 v2, s30, v116
	v_ashrrev_i32_e32 v3, 31, v2
	v_lshlrev_b64 v[2:3], 11, v[2:3]
	v_readfirstlane_b32 s5, v4
	v_lshl_add_u64 v[2:3], v[72:73], 0, v[2:3]
	s_mov_b32 m0, s5
	v_readfirstlane_b32 s5, v139
	global_load_lds_dwordx4 v[2:3], off
	v_add_u32_e32 v2, s6, v118
	v_ashrrev_i32_e32 v3, 31, v2
	v_lshlrev_b64 v[2:3], 11, v[2:3]
	v_lshl_add_u64 v[2:3], v[70:71], 0, v[2:3]
	s_mov_b32 m0, s5
	v_add_u32_e32 v4, 0xc00, v113
	global_load_lds_dwordx4 v[2:3], off
	v_add_u32_e32 v2, s30, v118
	v_ashrrev_i32_e32 v3, 31, v2
	v_lshlrev_b64 v[2:3], 11, v[2:3]
	v_readfirstlane_b32 s5, v4
	v_lshl_add_u64 v[2:3], v[76:77], 0, v[2:3]
	s_mov_b32 m0, s5
	s_mulk_i32 s4, 0x600
	global_load_lds_dwordx4 v[2:3], off
	v_lshl_add_u64 v[98:99], v[84:85], 0, v[0:1]
	v_subrev_u32_e32 v0, s4, v129
	v_ashrrev_i32_e32 v1, 31, v0
	v_lshlrev_b64 v[0:1], 11, v[0:1]
	v_lshl_add_u64 v[100:101], v[86:87], 0, v[0:1]
	v_add_u32_e32 v0, s30, v130
	v_ashrrev_i32_e32 v1, 31, v0
	v_lshlrev_b64 v[0:1], 11, v[0:1]
	v_lshl_add_u64 v[102:103], v[88:89], 0, v[0:1]
	v_subrev_u32_e32 v0, s4, v131
	v_ashrrev_i32_e32 v1, 31, v0
	v_lshlrev_b64 v[0:1], 11, v[0:1]
	v_lshl_add_u64 v[104:105], v[82:83], 0, v[0:1]
	v_add_u32_e32 v0, s30, v132
	v_ashrrev_i32_e32 v1, 31, v0
	v_lshlrev_b64 v[0:1], 11, v[0:1]
	v_lshl_add_u64 v[106:107], v[84:85], 0, v[0:1]
	v_subrev_u32_e32 v0, s4, v133
	v_ashrrev_i32_e32 v1, 31, v0
	v_lshlrev_b64 v[0:1], 11, v[0:1]
	v_subrev_u32_e32 v2, s4, v128
	v_lshl_add_u64 v[108:109], v[90:91], 0, v[0:1]
	v_add_u32_e32 v0, s30, v134
	v_ashrrev_i32_e32 v3, 31, v2
	v_ashrrev_i32_e32 v1, 31, v0
	v_lshlrev_b64 v[2:3], 11, v[2:3]
	v_lshlrev_b64 v[0:1], 11, v[0:1]
	v_lshl_add_u64 v[96:97], v[82:83], 0, v[2:3]
	v_lshl_add_u64 v[110:111], v[92:93], 0, v[0:1]
	s_mov_b64 s[4:5], 0
	s_mov_b32 s7, 0
	v_mov_b32_e32 v0, v65
	v_mov_b32_e32 v1, v65
	v_mov_b32_e32 v2, v65
	v_mov_b32_e32 v3, v65
	v_mov_b32_e32 v4, v65
	v_mov_b32_e32 v5, v65
	v_mov_b32_e32 v6, v65
	v_mov_b32_e32 v7, v65
	v_mov_b32_e32 v8, v65
	v_mov_b32_e32 v9, v65
	v_mov_b32_e32 v10, v65
	v_mov_b32_e32 v11, v65
	v_mov_b32_e32 v12, v65
	v_mov_b32_e32 v13, v65
	v_mov_b32_e32 v14, v65
	v_mov_b32_e32 v15, v65
	v_mov_b32_e32 v16, v65
	v_mov_b32_e32 v17, v65
	v_mov_b32_e32 v18, v65
	v_mov_b32_e32 v19, v65
	v_mov_b32_e32 v20, v65
	v_mov_b32_e32 v21, v65
	v_mov_b32_e32 v22, v65
	v_mov_b32_e32 v23, v65
	v_mov_b32_e32 v24, v65
	v_mov_b32_e32 v25, v65
	v_mov_b32_e32 v26, v65
	v_mov_b32_e32 v27, v65
	v_mov_b32_e32 v28, v65
	v_mov_b32_e32 v29, v65
	v_mov_b32_e32 v30, v65
	v_mov_b32_e32 v31, v65
	v_mov_b32_e32 v32, v65
	v_mov_b32_e32 v33, v65
	v_mov_b32_e32 v34, v65
	v_mov_b32_e32 v35, v65
	v_mov_b32_e32 v36, v65
	v_mov_b32_e32 v37, v65
	v_mov_b32_e32 v38, v65
	v_mov_b32_e32 v39, v65
	v_mov_b32_e32 v40, v65
	v_mov_b32_e32 v41, v65
	v_mov_b32_e32 v42, v65
	v_mov_b32_e32 v43, v65
	v_mov_b32_e32 v44, v65
	v_mov_b32_e32 v45, v65
	v_mov_b32_e32 v46, v65
	v_mov_b32_e32 v47, v65
	v_mov_b32_e32 v48, v65
	v_mov_b32_e32 v49, v65
	v_mov_b32_e32 v50, v65
	v_mov_b32_e32 v51, v65
	v_mov_b32_e32 v52, v65
	v_mov_b32_e32 v53, v65
	v_mov_b32_e32 v54, v65
	v_mov_b32_e32 v55, v65
	v_mov_b32_e32 v56, v65
	v_mov_b32_e32 v57, v65
	v_mov_b32_e32 v58, v65
	v_mov_b32_e32 v59, v65
	v_mov_b32_e32 v60, v65
	v_mov_b32_e32 v61, v65
	v_mov_b32_e32 v62, v65
	v_mov_b32_e32 v63, v65
	s_waitcnt vmcnt(0) lgkmcnt(0)
	s_barrier
	v_add3_u32 v182, 0, v140, v141
	v_add_u32_e32 v183, 0x4000, v182
	s_nop 0
	v_readfirstlane_b32 s82, v183
	v_lshl_add_u32 v183, v115, 1, 0
	s_nop 0
	v_readfirstlane_b32 s83, v182
	v_add3_u32 v183, v183, v141, s37
	s_nop 0
	v_readfirstlane_b32 s84, v183
	v_add_u32_e32 v183, 0x400, v182
	s_nop 0
	v_readfirstlane_b32 s85, v183
	v_lshl_add_u32 v183, v117, 1, 0
	v_add3_u32 v183, v183, v141, s37
	s_nop 0
	v_readfirstlane_b32 s86, v183
	v_add_u32_e32 v183, 0x800, v182
	s_nop 0
	v_readfirstlane_b32 s87, v183
	v_lshl_add_u32 v183, v119, 1, 0
	v_add3_u32 v183, v183, v141, s37
	s_nop 0
	v_readfirstlane_b32 s88, v183
	v_add_u32_e32 v182, 0xc00, v182
	s_nop 0
	v_readfirstlane_b32 s89, v182
	v_subrev_u32_e32 v184, s52, v96
	v_subrev_u32_e32 v185, s52, v98
	v_subrev_u32_e32 v186, s52, v100
	v_subrev_u32_e32 v187, s52, v102
	v_subrev_u32_e32 v188, s52, v104
	v_subrev_u32_e32 v189, s52, v106
	v_subrev_u32_e32 v190, s52, v108
	v_subrev_u32_e32 v191, s52, v110
	v_subrev_u32_e32 v187, 0x400, v187
	v_subrev_u32_e32 v186, 0x400, v186
	v_subrev_u32_e32 v189, 0x800, v189
	v_subrev_u32_e32 v188, 0x800, v188
	v_subrev_u32_e32 v191, 0xc00, v191
	v_subrev_u32_e32 v190, 0xc00, v190
	s_and_b32 s9, s7, 0x4000
	s_xor_b32 s8, s9, 0x4000
	s_lshl_b32 s8, s8, 1
	s_add_i32 s8, s8, 32
	s_lshl_b32 s9, s9, 1
	s_add_i32 s9, s9, 32
.LBB0_259:
	s_xor_b32 s8, s8, 0x8000
	s_xor_b32 s9, s9, 0x8000
	s_add_u32 s90, s52, s4
	s_addc_u32 s91, s53, s5
	s_add_i32 m0, s9, s83
	v_lshl_add_u32 v64, v120, 1, s8
	global_load_lds_dwordx4 v185, s[90:91]
	global_load_lds_dwordx4 v187, s[90:91] offset:1024
	global_load_lds_dwordx4 v189, s[90:91] offset:2048
	global_load_lds_dwordx4 v191, s[90:91] offset:3072
	s_add_i32 m0, s9, s82
	v_lshl_add_u32 v95, v121, 1, s8
	global_load_lds_dwordx4 v184, s[90:91]
	global_load_lds_dwordx4 v186, s[90:91] offset:1024
	global_load_lds_dwordx4 v188, s[90:91] offset:2048
	global_load_lds_dwordx4 v190, s[90:91] offset:3072
	v_add_u32_e32 v166, v64, v142
	v_add_u32_e32 v174, v95, v142
	s_addk_i32 s7, 0x4000
	s_add_u32 s4, s4, 0x80
	s_addc_u32 s5, s5, 0
	ds_read_b128 v[146:149], v166
	ds_read_b128 v[154:157], v174 offset:16384
	ds_read_b128 v[158:161], v174 offset:18432
	ds_read_b128 v[170:173], v174 offset:20480
	ds_read_b128 v[174:177], v174 offset:22528
	ds_read_b128 v[150:153], v166 offset:2048
	ds_read_b128 v[162:165], v166 offset:4096
	ds_read_b128 v[166:169], v166 offset:6144
	v_add_u32_e32 v64, v64, v143
	v_add_u32_e32 v95, v95, v143
	ds_read_b128 v[204:207], v64
	ds_read_b128 v[208:211], v95 offset:16384
	ds_read_b128 v[212:215], v95 offset:18432
	ds_read_b128 v[216:219], v95 offset:20480
	ds_read_b128 v[220:223], v95 offset:22528
	ds_read_b128 v[224:227], v64 offset:2048
	ds_read_b128 v[228:231], v64 offset:4096
	ds_read_b128 v[232:235], v64 offset:6144
	s_setprio 1
	s_waitcnt lgkmcnt(11)
	v_mfma_f32_16x16x32_bf16 v[60:63], v[146:149], v[154:157], v[60:63]
	v_mfma_f32_16x16x32_bf16 v[56:59], v[146:149], v[158:161], v[56:59]
	v_mfma_f32_16x16x32_bf16 v[52:55], v[146:149], v[170:173], v[52:55]
	v_mfma_f32_16x16x32_bf16 v[48:51], v[146:149], v[174:177], v[48:51]
	s_waitcnt lgkmcnt(10)
	v_mfma_f32_16x16x32_bf16 v[44:47], v[150:153], v[154:157], v[44:47]
	v_mfma_f32_16x16x32_bf16 v[40:43], v[150:153], v[158:161], v[40:43]
	v_mfma_f32_16x16x32_bf16 v[36:39], v[150:153], v[170:173], v[36:39]
	v_mfma_f32_16x16x32_bf16 v[32:35], v[150:153], v[174:177], v[32:35]
	s_waitcnt lgkmcnt(9)
	v_mfma_f32_16x16x32_bf16 v[28:31], v[162:165], v[154:157], v[28:31]
	v_mfma_f32_16x16x32_bf16 v[24:27], v[162:165], v[158:161], v[24:27]
	v_mfma_f32_16x16x32_bf16 v[20:23], v[162:165], v[170:173], v[20:23]
	v_mfma_f32_16x16x32_bf16 v[16:19], v[162:165], v[174:177], v[16:19]
	s_waitcnt lgkmcnt(8)
	v_mfma_f32_16x16x32_bf16 v[12:15], v[166:169], v[154:157], v[12:15]
	v_mfma_f32_16x16x32_bf16 v[8:11], v[166:169], v[158:161], v[8:11]
	v_mfma_f32_16x16x32_bf16 v[4:7], v[166:169], v[170:173], v[4:7]
	v_mfma_f32_16x16x32_bf16 v[0:3], v[166:169], v[174:177], v[0:3]
	s_waitcnt lgkmcnt(3)
	v_mfma_f32_16x16x32_bf16 v[60:63], v[204:207], v[208:211], v[60:63]
	v_mfma_f32_16x16x32_bf16 v[56:59], v[204:207], v[212:215], v[56:59]
	v_mfma_f32_16x16x32_bf16 v[52:55], v[204:207], v[216:219], v[52:55]
	v_mfma_f32_16x16x32_bf16 v[48:51], v[204:207], v[220:223], v[48:51]
	s_waitcnt lgkmcnt(2)
	v_mfma_f32_16x16x32_bf16 v[44:47], v[224:227], v[208:211], v[44:47]
	v_mfma_f32_16x16x32_bf16 v[40:43], v[224:227], v[212:215], v[40:43]
	v_mfma_f32_16x16x32_bf16 v[36:39], v[224:227], v[216:219], v[36:39]
	v_mfma_f32_16x16x32_bf16 v[32:35], v[224:227], v[220:223], v[32:35]
	s_waitcnt lgkmcnt(1)
	v_mfma_f32_16x16x32_bf16 v[28:31], v[228:231], v[208:211], v[28:31]
	v_mfma_f32_16x16x32_bf16 v[24:27], v[228:231], v[212:215], v[24:27]
	v_mfma_f32_16x16x32_bf16 v[20:23], v[228:231], v[216:219], v[20:23]
	v_mfma_f32_16x16x32_bf16 v[16:19], v[228:231], v[220:223], v[16:19]
	s_waitcnt lgkmcnt(0)
	v_mfma_f32_16x16x32_bf16 v[12:15], v[232:235], v[208:211], v[12:15]
	v_mfma_f32_16x16x32_bf16 v[8:11], v[232:235], v[212:215], v[8:11]
	v_mfma_f32_16x16x32_bf16 v[4:7], v[232:235], v[216:219], v[4:7]
	v_mfma_f32_16x16x32_bf16 v[0:3], v[232:235], v[220:223], v[0:3]
	s_setprio 0
	s_cmpk_eq_i32 s4, 0x780
	s_waitcnt vmcnt(0)
	s_barrier
	s_cbranch_scc0 .LBB0_259
	ds_read_b128 v[96:99], v122 offset:55296
	ds_read_b128 v[100:103], v122 offset:53248
	ds_read_b128 v[104:107], v123 offset:38912
	ds_read_b128 v[108:111], v123 offset:36864
	ds_read_b128 v[146:149], v122 offset:51200
	ds_read_b128 v[150:153], v122 offset:49152
	ds_read_b128 v[154:157], v123 offset:34816
	ds_read_b128 v[158:161], v123 offset:32768
	ds_read_b128 v[204:207], v124 offset:32768
	ds_read_b128 v[208:211], v124 offset:34816
	ds_read_b128 v[212:215], v125 offset:49152
	ds_read_b128 v[216:219], v125 offset:51200
	ds_read_b128 v[220:223], v124 offset:36864
	ds_read_b128 v[224:227], v124 offset:38912
	ds_read_b128 v[228:231], v125 offset:53248
	ds_read_b128 v[232:235], v125 offset:55296
	s_setprio 1
	s_waitcnt lgkmcnt(11)
	v_mfma_f32_16x16x32_bf16 v[24:27], v[108:111], v[146:149], v[24:27]
	v_mfma_f32_16x16x32_bf16 v[20:23], v[108:111], v[100:103], v[20:23]
	v_mfma_f32_16x16x32_bf16 v[16:19], v[108:111], v[96:99], v[16:19]
	s_waitcnt lgkmcnt(8)
	v_mfma_f32_16x16x32_bf16 v[60:63], v[158:161], v[150:153], v[60:63]
	v_mfma_f32_16x16x32_bf16 v[56:59], v[158:161], v[146:149], v[56:59]
	v_mfma_f32_16x16x32_bf16 v[52:55], v[158:161], v[100:103], v[52:55]
	v_mfma_f32_16x16x32_bf16 v[48:51], v[158:161], v[96:99], v[48:51]
	v_mfma_f32_16x16x32_bf16 v[44:47], v[154:157], v[150:153], v[44:47]
	v_mfma_f32_16x16x32_bf16 v[40:43], v[154:157], v[146:149], v[40:43]
	v_mfma_f32_16x16x32_bf16 v[36:39], v[154:157], v[100:103], v[36:39]
	v_mfma_f32_16x16x32_bf16 v[32:35], v[154:157], v[96:99], v[32:35]
	v_mfma_f32_16x16x32_bf16 v[28:31], v[108:111], v[150:153], v[28:31]
	v_mfma_f32_16x16x32_bf16 v[12:15], v[104:107], v[150:153], v[12:15]
	v_mfma_f32_16x16x32_bf16 v[8:11], v[104:107], v[146:149], v[8:11]
	v_mfma_f32_16x16x32_bf16 v[4:7], v[104:107], v[100:103], v[4:7]
	v_mfma_f32_16x16x32_bf16 v[0:3], v[104:107], v[96:99], v[0:3]
	s_waitcnt lgkmcnt(3)
	v_mfma_f32_16x16x32_bf16 v[24:27], v[220:223], v[216:219], v[24:27]
	s_waitcnt lgkmcnt(1)
	v_mfma_f32_16x16x32_bf16 v[20:23], v[220:223], v[228:231], v[20:23]
	s_waitcnt lgkmcnt(0)
	v_mfma_f32_16x16x32_bf16 v[16:19], v[220:223], v[232:235], v[16:19]
	v_mfma_f32_16x16x32_bf16 v[60:63], v[204:207], v[212:215], v[60:63]
	v_mfma_f32_16x16x32_bf16 v[56:59], v[204:207], v[216:219], v[56:59]
	v_mfma_f32_16x16x32_bf16 v[52:55], v[204:207], v[228:231], v[52:55]
	v_mfma_f32_16x16x32_bf16 v[48:51], v[204:207], v[232:235], v[48:51]
	v_mfma_f32_16x16x32_bf16 v[44:47], v[208:211], v[212:215], v[44:47]
	v_mfma_f32_16x16x32_bf16 v[40:43], v[208:211], v[216:219], v[40:43]
	v_mfma_f32_16x16x32_bf16 v[36:39], v[208:211], v[228:231], v[36:39]
	v_mfma_f32_16x16x32_bf16 v[32:35], v[208:211], v[232:235], v[32:35]
	v_mfma_f32_16x16x32_bf16 v[28:31], v[220:223], v[212:215], v[28:31]
	v_mfma_f32_16x16x32_bf16 v[12:15], v[224:227], v[212:215], v[12:15]
	v_mfma_f32_16x16x32_bf16 v[8:11], v[224:227], v[216:219], v[8:11]
	v_mfma_f32_16x16x32_bf16 v[4:7], v[224:227], v[228:231], v[4:7]
	v_mfma_f32_16x16x32_bf16 v[0:3], v[224:227], v[232:235], v[0:3]
	s_setprio 0
	s_barrier
	ds_write2_b32 v126, v60, v56 offset1:16
	ds_write2_b32 v126, v61, v57 offset0:132 offset1:148
	v_add_u32_e32 v56, 0x400, v126
	ds_write2_b32 v56, v62, v58 offset0:8 offset1:24
	ds_write2_b32 v56, v63, v59 offset0:140 offset1:156
	ds_write2_b32 v126, v52, v48 offset0:32 offset1:48
	ds_write2_b32 v126, v53, v49 offset0:164 offset1:180
	ds_write2_b32 v56, v54, v50 offset0:40 offset1:56
	ds_write2_b32 v56, v55, v51 offset0:172 offset1:188
	v_add_u32_e32 v48, 0x2000, v126
	ds_write2_b32 v48, v44, v40 offset0:64 offset1:80
	ds_write2_b32 v48, v45, v41 offset0:196 offset1:212
	v_add_u32_e32 v40, 0x2400, v126
	ds_write2_b32 v40, v46, v42 offset0:72 offset1:88
	ds_write2_b32 v40, v47, v43 offset0:204 offset1:220
	ds_write2_b32 v48, v36, v32 offset0:96 offset1:112
	ds_write2_b32 v48, v37, v33 offset0:228 offset1:244
	ds_write2_b32 v40, v38, v34 offset0:104 offset1:120
	ds_write2_b32 v40, v39, v35 offset0:236 offset1:252
	v_add_u32_e32 v32, 0x4000, v126
	ds_write2_b32 v32, v28, v24 offset0:128 offset1:144
	v_add_u32_e32 v24, 0x4400, v126
	ds_write2_b32 v24, v29, v25 offset0:4 offset1:20
	ds_write2_b32 v24, v30, v26 offset0:136 offset1:152
	v_add_u32_e32 v25, 0x4800, v126
	ds_write2_b32 v25, v31, v27 offset0:12 offset1:28
	ds_write2_b32 v32, v20, v16 offset0:160 offset1:176
	ds_write2_b32 v24, v21, v17 offset0:36 offset1:52
	ds_write2_b32 v24, v22, v18 offset0:168 offset1:184
	ds_write2_b32 v25, v23, v19 offset0:44 offset1:60
	v_add_u32_e32 v16, 0x6000, v126
	ds_write2_b32 v16, v12, v8 offset0:192 offset1:208
	v_add_u32_e32 v8, 0x6400, v126
	ds_write2_b32 v8, v13, v9 offset0:68 offset1:84
	ds_write2_b32 v8, v14, v10 offset0:200 offset1:216
	v_add_u32_e32 v9, 0x6800, v126
	v_or_b32_e32 v64, s6, v127
	ds_write2_b32 v9, v15, v11 offset0:76 offset1:92
	ds_write2_b32 v16, v4, v0 offset0:224 offset1:240
	ds_write2_b32 v8, v5, v1 offset0:100 offset1:116
	ds_write2_b32 v8, v6, v2 offset0:232 offset1:248
	ds_write2_b32 v9, v7, v3 offset0:108 offset1:124
	v_ashrrev_i32_e32 v1, 31, v64
	v_mov_b32_e32 v0, v64
	v_lshlrev_b64 v[2:3], 1, v[64:65]
	v_lshl_add_u64 v[20:21], v[0:1], 1, s[10:11]
	v_mov_b32_e32 v0, s15
	v_mov_b32_e32 v1, s13
	v_cmp_gt_i32_e64 s[8:9], s38, v64
	v_lshl_add_u64 v[16:17], s[18:19], 0, v[2:3]
	v_lshl_add_u64 v[18:19], s[16:17], 0, v[2:3]
	v_cndmask_b32_e64 v1, v0, v1, s[8:9]
	v_mov_b32_e32 v0, s14
	v_mov_b32_e32 v2, s12
	v_cndmask_b32_e64 v0, v0, v2, s[8:9]
	v_mov_b32_e32 v95, v65
	v_cmp_lt_i32_e64 s[4:5], s39, v64
	v_cmp_lt_i32_e64 s[6:7], s40, v64
	v_lshl_add_u64 v[22:23], v[0:1], 0, v[94:95]
	v_add_u32_e32 v24, s30, v135
	s_mov_b32 s45, 0
	s_waitcnt lgkmcnt(0)
	s_barrier
	s_branch .LBB0_263

.LBB0_277:
	s_add_i32 s4, s30, 0xffffff70
	s_cmpk_lt_i32 s30, 0x90
	s_cselect_b32 s5, 8, 4
	v_cvt_f32_ubyte0_e32 v0, s5
	v_rcp_iflag_f32_e32 v0, v0
	s_cselect_b32 s7, 0, 0x400
	s_cselect_b32 s4, s30, s4
	s_cselect_b32 s6, 3, 2
	v_mul_f32_e32 v0, 0x4f7ffffe, v0
	v_cvt_u32_f32_e32 v0, v0
	s_sub_i32 s20, 0, s5
	s_abs_i32 s9, s4
	s_ashr_i32 s8, s4, 31
	v_readfirstlane_b32 s21, v0
	s_mul_i32 s20, s20, s21
	s_mul_hi_u32 s20, s21, s20
	s_add_i32 s21, s21, s20
	s_mul_hi_u32 s20, s9, s21
	s_mul_i32 s21, s20, s5
	s_sub_i32 s9, s9, s21
	s_add_i32 s21, s20, 1
	s_sub_i32 s22, s9, s5
	s_cmp_ge_u32 s9, s5
	s_cselect_b32 s20, s21, s20
	s_cselect_b32 s9, s22, s9
	s_add_i32 s21, s20, 1
	s_cmp_ge_u32 s9, s5
	s_cselect_b32 s5, s21, s20
	s_xor_b32 s5, s5, s8
	s_sub_i32 s5, s5, s8
	s_lshl_b32 s8, s5, s6
	s_sub_i32 s6, s4, s8
	s_lshl_b32 s6, s6, 7
	v_add_u32_e32 v0, s5, v112
	s_add_i32 s6, s6, s7
	v_lshlrev_b32_e32 v143, 7, v0
	v_add_u32_e32 v0, s6, v113
	v_ashrrev_i32_e32 v1, 31, v0
	v_add_u32_e32 v2, 0x4000, v114
	v_lshlrev_b64 v[0:1], 11, v[0:1]
	v_readfirstlane_b32 s5, v2
	v_lshl_add_u64 v[0:1], v[66:67], 0, v[0:1]
	s_mov_b32 m0, s5
	v_readfirstlane_b32 s5, v114
	global_load_lds_dwordx4 v[0:1], off
	v_add_u32_e32 v0, v143, v113
	v_ashrrev_i32_e32 v1, 31, v0
	v_lshlrev_b64 v[0:1], 11, v[0:1]
	v_lshl_add_u64 v[2:3], v[72:73], 0, v[0:1]
	s_mov_b32 m0, s5
	v_readfirstlane_b32 s5, v134
	global_load_lds_dwordx4 v[2:3], off
	v_add_u32_e32 v2, s6, v115
	v_ashrrev_i32_e32 v3, 31, v2
	v_lshlrev_b64 v[2:3], 11, v[2:3]
	v_lshl_add_u64 v[2:3], v[68:69], 0, v[2:3]
	s_mov_b32 m0, s5
	v_add_u32_e32 v4, 0x400, v114
	global_load_lds_dwordx4 v[2:3], off
	v_add_u32_e32 v2, v143, v115
	v_ashrrev_i32_e32 v3, 31, v2
	v_lshlrev_b64 v[2:3], 11, v[2:3]
	v_readfirstlane_b32 s5, v4
	v_lshl_add_u64 v[2:3], v[74:75], 0, v[2:3]
	s_mov_b32 m0, s5
	v_readfirstlane_b32 s5, v135
	global_load_lds_dwordx4 v[2:3], off
	v_add_u32_e32 v2, s6, v117
	v_ashrrev_i32_e32 v3, 31, v2
	v_lshlrev_b64 v[2:3], 11, v[2:3]
	v_lshl_add_u64 v[2:3], v[66:67], 0, v[2:3]
	s_mov_b32 m0, s5
	v_add_u32_e32 v4, 0x800, v114
	global_load_lds_dwordx4 v[2:3], off
	v_add_u32_e32 v2, v143, v117
	v_ashrrev_i32_e32 v3, 31, v2
	v_lshlrev_b64 v[2:3], 11, v[2:3]
	v_readfirstlane_b32 s5, v4
	v_lshl_add_u64 v[2:3], v[72:73], 0, v[2:3]
	s_mov_b32 m0, s5
	v_readfirstlane_b32 s5, v136
	global_load_lds_dwordx4 v[2:3], off
	v_add_u32_e32 v2, s6, v119
	v_ashrrev_i32_e32 v3, 31, v2
	v_lshlrev_b64 v[2:3], 11, v[2:3]
	v_lshl_add_u64 v[2:3], v[70:71], 0, v[2:3]
	s_mov_b32 m0, s5
	v_add_u32_e32 v4, 0xc00, v114
	global_load_lds_dwordx4 v[2:3], off
	v_add_u32_e32 v2, v143, v119
	v_ashrrev_i32_e32 v3, 31, v2
	v_lshlrev_b64 v[2:3], 11, v[2:3]
	v_readfirstlane_b32 s5, v4
	v_lshl_add_u64 v[2:3], v[76:77], 0, v[2:3]
	s_mov_b32 m0, s5
	s_lshl_b32 s4, s4, 7
	global_load_lds_dwordx4 v[2:3], off
	s_add_i32 s4, s4, s7
	s_lshl_b32 s5, s8, 7
	v_lshl_add_u64 v[98:99], v[84:85], 0, v[0:1]
	v_add_u32_e32 v0, s4, v129
	v_subrev_u32_e32 v0, s5, v0
	v_ashrrev_i32_e32 v1, 31, v0
	v_lshlrev_b64 v[0:1], 11, v[0:1]
	v_lshl_add_u64 v[100:101], v[86:87], 0, v[0:1]
	v_add_u32_e32 v0, v129, v143
	v_ashrrev_i32_e32 v1, 31, v0
	v_lshlrev_b64 v[0:1], 11, v[0:1]
	v_lshl_add_u64 v[102:103], v[88:89], 0, v[0:1]
	v_add_u32_e32 v0, s4, v130
	v_subrev_u32_e32 v0, s5, v0
	v_ashrrev_i32_e32 v1, 31, v0
	v_lshlrev_b64 v[0:1], 11, v[0:1]
	v_lshl_add_u64 v[104:105], v[82:83], 0, v[0:1]
	v_add_u32_e32 v0, v130, v143
	v_ashrrev_i32_e32 v1, 31, v0
	v_lshlrev_b64 v[0:1], 11, v[0:1]
	v_lshl_add_u64 v[106:107], v[84:85], 0, v[0:1]
	v_add_u32_e32 v0, s4, v131
	v_subrev_u32_e32 v0, s5, v0
	v_ashrrev_i32_e32 v1, 31, v0
	v_lshlrev_b64 v[0:1], 11, v[0:1]
	v_add_u32_e32 v2, s4, v113
	v_lshl_add_u64 v[108:109], v[90:91], 0, v[0:1]
	v_add_u32_e32 v0, v131, v143
	v_subrev_u32_e32 v2, s5, v2
	v_ashrrev_i32_e32 v1, 31, v0
	v_ashrrev_i32_e32 v3, 31, v2
	v_lshlrev_b64 v[0:1], 11, v[0:1]
	v_lshlrev_b64 v[2:3], 11, v[2:3]
	v_lshl_add_u64 v[110:111], v[92:93], 0, v[0:1]
	v_mov_b32_e32 v0, 0
	v_lshl_add_u64 v[96:97], v[82:83], 0, v[2:3]
	s_mov_b64 s[4:5], 0
	s_mov_b32 s7, 0
	v_mov_b32_e32 v1, v0
	v_mov_b32_e32 v2, v0
	v_mov_b32_e32 v3, v0
	v_mov_b32_e32 v4, v0
	v_mov_b32_e32 v5, v0
	v_mov_b32_e32 v6, v0
	v_mov_b32_e32 v7, v0
	v_mov_b32_e32 v8, v0
	v_mov_b32_e32 v9, v0
	v_mov_b32_e32 v10, v0
	v_mov_b32_e32 v11, v0
	v_mov_b32_e32 v12, v0
	v_mov_b32_e32 v13, v0
	v_mov_b32_e32 v14, v0
	v_mov_b32_e32 v15, v0
	v_mov_b32_e32 v16, v0
	v_mov_b32_e32 v17, v0
	v_mov_b32_e32 v18, v0
	v_mov_b32_e32 v19, v0
	v_mov_b32_e32 v20, v0
	v_mov_b32_e32 v21, v0
	v_mov_b32_e32 v22, v0
	v_mov_b32_e32 v23, v0
	v_mov_b32_e32 v24, v0
	v_mov_b32_e32 v25, v0
	v_mov_b32_e32 v26, v0
	v_mov_b32_e32 v27, v0
	v_mov_b32_e32 v28, v0
	v_mov_b32_e32 v29, v0
	v_mov_b32_e32 v30, v0
	v_mov_b32_e32 v31, v0
	v_mov_b32_e32 v32, v0
	v_mov_b32_e32 v33, v0
	v_mov_b32_e32 v34, v0
	v_mov_b32_e32 v35, v0
	v_mov_b32_e32 v36, v0
	v_mov_b32_e32 v37, v0
	v_mov_b32_e32 v38, v0
	v_mov_b32_e32 v39, v0
	v_mov_b32_e32 v40, v0
	v_mov_b32_e32 v41, v0
	v_mov_b32_e32 v42, v0
	v_mov_b32_e32 v43, v0
	v_mov_b32_e32 v44, v0
	v_mov_b32_e32 v45, v0
	v_mov_b32_e32 v46, v0
	v_mov_b32_e32 v47, v0
	v_mov_b32_e32 v48, v0
	v_mov_b32_e32 v49, v0
	v_mov_b32_e32 v50, v0
	v_mov_b32_e32 v51, v0
	v_mov_b32_e32 v52, v0
	v_mov_b32_e32 v53, v0
	v_mov_b32_e32 v54, v0
	v_mov_b32_e32 v55, v0
	v_mov_b32_e32 v56, v0
	v_mov_b32_e32 v57, v0
	v_mov_b32_e32 v58, v0
	v_mov_b32_e32 v59, v0
	v_mov_b32_e32 v60, v0
	v_mov_b32_e32 v61, v0
	v_mov_b32_e32 v62, v0
	v_mov_b32_e32 v63, v0
	s_waitcnt vmcnt(0) lgkmcnt(0)
	s_barrier
	v_add3_u32 v182, 0, v137, v138
	v_add_u32_e32 v183, 0x4000, v182
	s_nop 0
	v_readfirstlane_b32 s82, v183
	v_lshl_add_u32 v183, v116, 1, 0
	s_nop 0
	v_readfirstlane_b32 s83, v182
	v_add3_u32 v183, v183, v138, s25
	s_nop 0
	v_readfirstlane_b32 s84, v183
	v_add_u32_e32 v183, 0x400, v182
	s_nop 0
	v_readfirstlane_b32 s85, v183
	v_lshl_add_u32 v183, v118, 1, 0
	v_add3_u32 v183, v183, v138, s25
	s_nop 0
	v_readfirstlane_b32 s86, v183
	v_add_u32_e32 v183, 0x800, v182
	s_nop 0
	v_readfirstlane_b32 s87, v183
	v_lshl_add_u32 v183, v120, 1, 0
	v_add3_u32 v183, v183, v138, s25
	s_nop 0
	v_readfirstlane_b32 s88, v183
	v_add_u32_e32 v182, 0xc00, v182
	s_nop 0
	v_readfirstlane_b32 s89, v182
	v_subrev_u32_e32 v184, s52, v96
	v_subrev_u32_e32 v185, s52, v98
	v_subrev_u32_e32 v186, s52, v100
	v_subrev_u32_e32 v187, s52, v102
	v_subrev_u32_e32 v188, s52, v104
	v_subrev_u32_e32 v189, s52, v106
	v_subrev_u32_e32 v190, s52, v108
	v_subrev_u32_e32 v191, s52, v110
	v_subrev_u32_e32 v187, 0x400, v187
	v_subrev_u32_e32 v186, 0x400, v186
	v_subrev_u32_e32 v189, 0x800, v189
	v_subrev_u32_e32 v188, 0x800, v188
	v_subrev_u32_e32 v191, 0xc00, v191
	v_subrev_u32_e32 v190, 0xc00, v190
	s_and_b32 s9, s7, 0x4000
	s_xor_b32 s8, s9, 0x4000
	s_lshl_b32 s8, s8, 1
	s_add_i32 s8, s8, 32
	s_lshl_b32 s9, s9, 1
	s_add_i32 s9, s9, 32
.LBB0_278:
	s_xor_b32 s8, s8, 0x8000
	s_xor_b32 s9, s9, 0x8000
	s_add_u32 s90, s52, s4
	s_addc_u32 s91, s53, s5
	s_add_i32 m0, s9, s83
	v_lshl_add_u32 v64, v121, 1, s8
	global_load_lds_dwordx4 v185, s[90:91]
	global_load_lds_dwordx4 v187, s[90:91] offset:1024
	global_load_lds_dwordx4 v189, s[90:91] offset:2048
	global_load_lds_dwordx4 v191, s[90:91] offset:3072
	s_add_i32 m0, s9, s82
	v_lshl_add_u32 v95, v122, 1, s8
	global_load_lds_dwordx4 v184, s[90:91]
	global_load_lds_dwordx4 v186, s[90:91] offset:1024
	global_load_lds_dwordx4 v188, s[90:91] offset:2048
	global_load_lds_dwordx4 v190, s[90:91] offset:3072
	v_add_u32_e32 v164, v64, v139
	v_add_u32_e32 v172, v95, v139
	s_addk_i32 s7, 0x4000
	s_add_u32 s4, s4, 0x80
	s_addc_u32 s5, s5, 0
	ds_read_b128 v[144:147], v164
	ds_read_b128 v[152:155], v172 offset:16384
	ds_read_b128 v[156:159], v172 offset:18432
	ds_read_b128 v[168:171], v172 offset:20480
	ds_read_b128 v[172:175], v172 offset:22528
	ds_read_b128 v[148:151], v164 offset:2048
	ds_read_b128 v[160:163], v164 offset:4096
	ds_read_b128 v[164:167], v164 offset:6144
	v_add_u32_e32 v64, v64, v140
	v_add_u32_e32 v95, v95, v140
	ds_read_b128 v[204:207], v64
	ds_read_b128 v[208:211], v95 offset:16384
	ds_read_b128 v[212:215], v95 offset:18432
	ds_read_b128 v[216:219], v95 offset:20480
	ds_read_b128 v[220:223], v95 offset:22528
	ds_read_b128 v[224:227], v64 offset:2048
	ds_read_b128 v[228:231], v64 offset:4096
	ds_read_b128 v[232:235], v64 offset:6144
	s_setprio 1
	s_waitcnt lgkmcnt(11)
	v_mfma_f32_16x16x32_bf16 v[60:63], v[144:147], v[152:155], v[60:63]
	v_mfma_f32_16x16x32_bf16 v[56:59], v[144:147], v[156:159], v[56:59]
	v_mfma_f32_16x16x32_bf16 v[52:55], v[144:147], v[168:171], v[52:55]
	v_mfma_f32_16x16x32_bf16 v[48:51], v[144:147], v[172:175], v[48:51]
	s_waitcnt lgkmcnt(10)
	v_mfma_f32_16x16x32_bf16 v[44:47], v[148:151], v[152:155], v[44:47]
	v_mfma_f32_16x16x32_bf16 v[40:43], v[148:151], v[156:159], v[40:43]
	v_mfma_f32_16x16x32_bf16 v[36:39], v[148:151], v[168:171], v[36:39]
	v_mfma_f32_16x16x32_bf16 v[32:35], v[148:151], v[172:175], v[32:35]
	s_waitcnt lgkmcnt(9)
	v_mfma_f32_16x16x32_bf16 v[28:31], v[160:163], v[152:155], v[28:31]
	v_mfma_f32_16x16x32_bf16 v[24:27], v[160:163], v[156:159], v[24:27]
	v_mfma_f32_16x16x32_bf16 v[20:23], v[160:163], v[168:171], v[20:23]
	v_mfma_f32_16x16x32_bf16 v[16:19], v[160:163], v[172:175], v[16:19]
	s_waitcnt lgkmcnt(8)
	v_mfma_f32_16x16x32_bf16 v[12:15], v[164:167], v[152:155], v[12:15]
	v_mfma_f32_16x16x32_bf16 v[8:11], v[164:167], v[156:159], v[8:11]
	v_mfma_f32_16x16x32_bf16 v[4:7], v[164:167], v[168:171], v[4:7]
	v_mfma_f32_16x16x32_bf16 v[0:3], v[164:167], v[172:175], v[0:3]
	s_waitcnt lgkmcnt(3)
	v_mfma_f32_16x16x32_bf16 v[60:63], v[204:207], v[208:211], v[60:63]
	v_mfma_f32_16x16x32_bf16 v[56:59], v[204:207], v[212:215], v[56:59]
	v_mfma_f32_16x16x32_bf16 v[52:55], v[204:207], v[216:219], v[52:55]
	v_mfma_f32_16x16x32_bf16 v[48:51], v[204:207], v[220:223], v[48:51]
	s_waitcnt lgkmcnt(2)
	v_mfma_f32_16x16x32_bf16 v[44:47], v[224:227], v[208:211], v[44:47]
	v_mfma_f32_16x16x32_bf16 v[40:43], v[224:227], v[212:215], v[40:43]
	v_mfma_f32_16x16x32_bf16 v[36:39], v[224:227], v[216:219], v[36:39]
	v_mfma_f32_16x16x32_bf16 v[32:35], v[224:227], v[220:223], v[32:35]
	s_waitcnt lgkmcnt(1)
	v_mfma_f32_16x16x32_bf16 v[28:31], v[228:231], v[208:211], v[28:31]
	v_mfma_f32_16x16x32_bf16 v[24:27], v[228:231], v[212:215], v[24:27]
	v_mfma_f32_16x16x32_bf16 v[20:23], v[228:231], v[216:219], v[20:23]
	v_mfma_f32_16x16x32_bf16 v[16:19], v[228:231], v[220:223], v[16:19]
	s_waitcnt lgkmcnt(0)
	v_mfma_f32_16x16x32_bf16 v[12:15], v[232:235], v[208:211], v[12:15]
	v_mfma_f32_16x16x32_bf16 v[8:11], v[232:235], v[212:215], v[8:11]
	v_mfma_f32_16x16x32_bf16 v[4:7], v[232:235], v[216:219], v[4:7]
	v_mfma_f32_16x16x32_bf16 v[0:3], v[232:235], v[220:223], v[0:3]
	s_setprio 0
	s_cmpk_eq_i32 s4, 0x780
	s_waitcnt vmcnt(0)
	s_barrier
	s_cbranch_scc0 .LBB0_278
	ds_read_b128 v[96:99], v123 offset:55296
	ds_read_b128 v[100:103], v123 offset:53248
	ds_read_b128 v[104:107], v124 offset:38912
	ds_read_b128 v[108:111], v124 offset:36864
	ds_read_b128 v[144:147], v123 offset:51200
	ds_read_b128 v[148:151], v123 offset:49152
	ds_read_b128 v[152:155], v124 offset:34816
	ds_read_b128 v[156:159], v124 offset:32768
	ds_read_b128 v[204:207], v125 offset:32768
	ds_read_b128 v[208:211], v125 offset:34816
	ds_read_b128 v[212:215], v126 offset:49152
	ds_read_b128 v[216:219], v126 offset:51200
	ds_read_b128 v[220:223], v125 offset:36864
	ds_read_b128 v[224:227], v125 offset:38912
	ds_read_b128 v[228:231], v126 offset:53248
	ds_read_b128 v[232:235], v126 offset:55296
	s_setprio 1
	s_waitcnt lgkmcnt(11)
	v_mfma_f32_16x16x32_bf16 v[24:27], v[108:111], v[144:147], v[24:27]
	v_mfma_f32_16x16x32_bf16 v[20:23], v[108:111], v[100:103], v[20:23]
	v_mfma_f32_16x16x32_bf16 v[16:19], v[108:111], v[96:99], v[16:19]
	s_waitcnt lgkmcnt(8)
	v_mfma_f32_16x16x32_bf16 v[60:63], v[156:159], v[148:151], v[60:63]
	v_mfma_f32_16x16x32_bf16 v[56:59], v[156:159], v[144:147], v[56:59]
	v_mfma_f32_16x16x32_bf16 v[52:55], v[156:159], v[100:103], v[52:55]
	v_mfma_f32_16x16x32_bf16 v[48:51], v[156:159], v[96:99], v[48:51]
	v_mfma_f32_16x16x32_bf16 v[44:47], v[152:155], v[148:151], v[44:47]
	v_mfma_f32_16x16x32_bf16 v[40:43], v[152:155], v[144:147], v[40:43]
	v_mfma_f32_16x16x32_bf16 v[36:39], v[152:155], v[100:103], v[36:39]
	v_mfma_f32_16x16x32_bf16 v[32:35], v[152:155], v[96:99], v[32:35]
	v_mfma_f32_16x16x32_bf16 v[28:31], v[108:111], v[148:151], v[28:31]
	v_mfma_f32_16x16x32_bf16 v[12:15], v[104:107], v[148:151], v[12:15]
	v_mfma_f32_16x16x32_bf16 v[8:11], v[104:107], v[144:147], v[8:11]
	v_mfma_f32_16x16x32_bf16 v[4:7], v[104:107], v[100:103], v[4:7]
	v_mfma_f32_16x16x32_bf16 v[0:3], v[104:107], v[96:99], v[0:3]
	s_waitcnt lgkmcnt(3)
	v_mfma_f32_16x16x32_bf16 v[24:27], v[220:223], v[216:219], v[24:27]
	s_waitcnt lgkmcnt(1)
	v_mfma_f32_16x16x32_bf16 v[20:23], v[220:223], v[228:231], v[20:23]
	s_waitcnt lgkmcnt(0)
	v_mfma_f32_16x16x32_bf16 v[16:19], v[220:223], v[232:235], v[16:19]
	v_mfma_f32_16x16x32_bf16 v[60:63], v[204:207], v[212:215], v[60:63]
	v_mfma_f32_16x16x32_bf16 v[56:59], v[204:207], v[216:219], v[56:59]
	v_mfma_f32_16x16x32_bf16 v[52:55], v[204:207], v[228:231], v[52:55]
	v_mfma_f32_16x16x32_bf16 v[48:51], v[204:207], v[232:235], v[48:51]
	v_mfma_f32_16x16x32_bf16 v[44:47], v[208:211], v[212:215], v[44:47]
	v_mfma_f32_16x16x32_bf16 v[40:43], v[208:211], v[216:219], v[40:43]
	v_mfma_f32_16x16x32_bf16 v[36:39], v[208:211], v[228:231], v[36:39]
	v_mfma_f32_16x16x32_bf16 v[32:35], v[208:211], v[232:235], v[32:35]
	v_mfma_f32_16x16x32_bf16 v[28:31], v[220:223], v[212:215], v[28:31]
	v_mfma_f32_16x16x32_bf16 v[12:15], v[224:227], v[212:215], v[12:15]
	v_mfma_f32_16x16x32_bf16 v[8:11], v[224:227], v[216:219], v[8:11]
	v_mfma_f32_16x16x32_bf16 v[4:7], v[224:227], v[228:231], v[4:7]
	v_mfma_f32_16x16x32_bf16 v[0:3], v[224:227], v[232:235], v[0:3]
	s_setprio 0
	s_barrier
	ds_write2_b32 v127, v60, v56 offset1:16
	ds_write2_b32 v127, v61, v57 offset0:132 offset1:148
	v_add_u32_e32 v56, 0x400, v127
	ds_write2_b32 v56, v62, v58 offset0:8 offset1:24
	ds_write2_b32 v56, v63, v59 offset0:140 offset1:156
	ds_write2_b32 v127, v52, v48 offset0:32 offset1:48
	ds_write2_b32 v127, v53, v49 offset0:164 offset1:180
	ds_write2_b32 v56, v54, v50 offset0:40 offset1:56
	ds_write2_b32 v56, v55, v51 offset0:172 offset1:188
	v_add_u32_e32 v48, 0x2000, v127
	ds_write2_b32 v48, v44, v40 offset0:64 offset1:80
	ds_write2_b32 v48, v45, v41 offset0:196 offset1:212
	v_add_u32_e32 v40, 0x2400, v127
	ds_write2_b32 v40, v46, v42 offset0:72 offset1:88
	ds_write2_b32 v40, v47, v43 offset0:204 offset1:220
	ds_write2_b32 v48, v36, v32 offset0:96 offset1:112
	ds_write2_b32 v48, v37, v33 offset0:228 offset1:244
	ds_write2_b32 v40, v38, v34 offset0:104 offset1:120
	ds_write2_b32 v40, v39, v35 offset0:236 offset1:252
	v_add_u32_e32 v32, 0x4000, v127
	ds_write2_b32 v32, v28, v24 offset0:128 offset1:144
	v_add_u32_e32 v24, 0x4400, v127
	ds_write2_b32 v24, v29, v25 offset0:4 offset1:20
	ds_write2_b32 v24, v30, v26 offset0:136 offset1:152
	v_add_u32_e32 v25, 0x4800, v127
	ds_write2_b32 v25, v31, v27 offset0:12 offset1:28
	ds_write2_b32 v32, v20, v16 offset0:160 offset1:176
	ds_write2_b32 v24, v21, v17 offset0:36 offset1:52
	ds_write2_b32 v24, v22, v18 offset0:168 offset1:184
	ds_write2_b32 v25, v23, v19 offset0:44 offset1:60
	v_add_u32_e32 v16, 0x6000, v127
	ds_write2_b32 v16, v12, v8 offset0:192 offset1:208
	v_add_u32_e32 v8, 0x6400, v127
	ds_write2_b32 v8, v13, v9 offset0:68 offset1:84
	ds_write2_b32 v8, v14, v10 offset0:200 offset1:216
	v_add_u32_e32 v9, 0x6800, v127
	v_or_b32_e32 v64, s6, v128
	ds_write2_b32 v9, v15, v11 offset0:76 offset1:92
	ds_write2_b32 v16, v4, v0 offset0:224 offset1:240
	ds_write2_b32 v8, v5, v1 offset0:100 offset1:116
	ds_write2_b32 v8, v6, v2 offset0:232 offset1:248
	ds_write2_b32 v9, v7, v3 offset0:108 offset1:124
	v_ashrrev_i32_e32 v1, 31, v64
	v_mov_b32_e32 v0, v64
	v_lshlrev_b64 v[2:3], 1, v[64:65]
	v_lshl_add_u64 v[20:21], v[0:1], 1, s[10:11]
	v_mov_b32_e32 v0, s15
	v_mov_b32_e32 v1, s13
	v_cmp_gt_i32_e64 s[8:9], s24, v64
	v_lshl_add_u64 v[16:17], s[18:19], 0, v[2:3]
	v_lshl_add_u64 v[18:19], s[16:17], 0, v[2:3]
	v_cndmask_b32_e64 v1, v0, v1, s[8:9]
	v_mov_b32_e32 v0, s14
	v_mov_b32_e32 v2, s12
	v_cndmask_b32_e64 v0, v0, v2, s[8:9]
	v_mov_b32_e32 v95, v65
	v_cmp_lt_i32_e64 s[4:5], s26, v64
	v_cmp_lt_i32_e64 s[6:7], s27, v64
	v_lshl_add_u64 v[22:23], v[0:1], 0, v[94:95]
	v_add_u32_e32 v24, v132, v143
	s_mov_b32 s35, 0
	s_waitcnt lgkmcnt(0)
	s_barrier
	s_branch .LBB0_282

.LBB0_422:
	s_ashr_i32 s14, s21, 31
	s_lshr_b32 s14, s14, 29
	s_add_i32 s14, s21, s14
	s_ashr_i32 s14, s14, 3
	s_lshl_b32 s22, s14, 7
	s_lshl_b32 s14, s14, 10
	s_lshl_b32 s15, s21, 7
	s_sub_i32 s23, s15, s14
	v_add_u32_e32 v0, s23, v106
	v_ashrrev_i32_e32 v1, 31, v0
	v_add_u32_e32 v2, 0x4000, v107
	v_lshlrev_b64 v[0:1], 11, v[0:1]
	v_readfirstlane_b32 s15, v2
	v_lshl_add_u64 v[0:1], v[66:67], 0, v[0:1]
	s_mov_b32 m0, s15
	v_readfirstlane_b32 s15, v107
	global_load_lds_dwordx4 v[0:1], off
	v_add_u32_e32 v0, s22, v106
	v_ashrrev_i32_e32 v1, 31, v0
	v_lshlrev_b64 v[0:1], 11, v[0:1]
	v_lshl_add_u64 v[2:3], v[72:73], 0, v[0:1]
	s_mov_b32 m0, s15
	v_readfirstlane_b32 s15, v130
	global_load_lds_dwordx4 v[2:3], off
	v_add_u32_e32 v2, s23, v108
	v_ashrrev_i32_e32 v3, 31, v2
	v_lshlrev_b64 v[2:3], 11, v[2:3]
	v_lshl_add_u64 v[2:3], v[68:69], 0, v[2:3]
	s_mov_b32 m0, s15
	v_add_u32_e32 v4, 0x400, v107
	global_load_lds_dwordx4 v[2:3], off
	v_add_u32_e32 v2, s22, v108
	v_ashrrev_i32_e32 v3, 31, v2
	v_lshlrev_b64 v[2:3], 11, v[2:3]
	v_readfirstlane_b32 s15, v4
	v_lshl_add_u64 v[2:3], v[74:75], 0, v[2:3]
	s_mov_b32 m0, s15
	v_readfirstlane_b32 s15, v131
	global_load_lds_dwordx4 v[2:3], off
	v_add_u32_e32 v2, s23, v110
	v_ashrrev_i32_e32 v3, 31, v2
	v_lshlrev_b64 v[2:3], 11, v[2:3]
	v_lshl_add_u64 v[2:3], v[66:67], 0, v[2:3]
	s_mov_b32 m0, s15
	v_add_u32_e32 v4, 0x800, v107
	global_load_lds_dwordx4 v[2:3], off
	v_add_u32_e32 v2, s22, v110
	v_ashrrev_i32_e32 v3, 31, v2
	v_lshlrev_b64 v[2:3], 11, v[2:3]
	v_readfirstlane_b32 s15, v4
	v_lshl_add_u64 v[2:3], v[72:73], 0, v[2:3]
	s_mov_b32 m0, s15
	v_readfirstlane_b32 s15, v132
	global_load_lds_dwordx4 v[2:3], off
	v_add_u32_e32 v2, s23, v112
	v_ashrrev_i32_e32 v3, 31, v2
	v_lshlrev_b64 v[2:3], 11, v[2:3]
	v_lshl_add_u64 v[2:3], v[70:71], 0, v[2:3]
	s_mov_b32 m0, s15
	v_add_u32_e32 v4, 0xc00, v107
	global_load_lds_dwordx4 v[2:3], off
	v_add_u32_e32 v2, s22, v112
	v_ashrrev_i32_e32 v3, 31, v2
	v_lshlrev_b64 v[2:3], 11, v[2:3]
	v_readfirstlane_b32 s15, v4
	v_lshl_add_u64 v[2:3], v[76:77], 0, v[2:3]
	s_mov_b32 m0, s15
	v_lshl_add_u64 v[92:93], v[80:81], 0, v[0:1]
	global_load_lds_dwordx4 v[2:3], off
	v_subrev_u32_e32 v0, s14, v123
	v_ashrrev_i32_e32 v1, 31, v0
	v_lshlrev_b64 v[0:1], 11, v[0:1]
	v_lshl_add_u64 v[94:95], v[82:83], 0, v[0:1]
	v_add_u32_e32 v0, s22, v124
	v_ashrrev_i32_e32 v1, 31, v0
	v_lshlrev_b64 v[0:1], 11, v[0:1]
	v_lshl_add_u64 v[96:97], v[84:85], 0, v[0:1]
	v_subrev_u32_e32 v0, s14, v125
	v_ashrrev_i32_e32 v1, 31, v0
	v_lshlrev_b64 v[0:1], 11, v[0:1]
	v_lshl_add_u64 v[98:99], v[78:79], 0, v[0:1]
	v_add_u32_e32 v0, s22, v126
	v_ashrrev_i32_e32 v1, 31, v0
	v_lshlrev_b64 v[0:1], 11, v[0:1]
	v_lshl_add_u64 v[100:101], v[80:81], 0, v[0:1]
	v_subrev_u32_e32 v0, s14, v64
	v_ashrrev_i32_e32 v1, 31, v0
	v_lshlrev_b64 v[0:1], 11, v[0:1]
	v_subrev_u32_e32 v2, s14, v122
	v_lshl_add_u64 v[102:103], v[86:87], 0, v[0:1]
	v_add_u32_e32 v0, s22, v127
	v_ashrrev_i32_e32 v3, 31, v2
	v_ashrrev_i32_e32 v1, 31, v0
	v_lshlrev_b64 v[2:3], 11, v[2:3]
	v_lshlrev_b64 v[0:1], 11, v[0:1]
	v_lshl_add_u64 v[90:91], v[78:79], 0, v[2:3]
	v_lshl_add_u64 v[104:105], v[88:89], 0, v[0:1]
	s_mov_b32 s24, 0
	s_mov_b64 s[14:15], 0
	v_mov_b32_e32 v0, 0
	v_mov_b32_e32 v1, v65
	v_mov_b32_e32 v2, v65
	v_mov_b32_e32 v3, v65
	v_mov_b32_e32 v4, 0
	v_mov_b32_e32 v5, v65
	v_mov_b32_e32 v6, v65
	v_mov_b32_e32 v7, v65
	v_mov_b32_e32 v8, 0
	v_mov_b32_e32 v9, v65
	v_mov_b32_e32 v10, v65
	v_mov_b32_e32 v11, v65
	v_mov_b32_e32 v12, 0
	v_mov_b32_e32 v13, v65
	v_mov_b32_e32 v14, v65
	v_mov_b32_e32 v15, v65
	v_mov_b32_e32 v16, 0
	v_mov_b32_e32 v17, v65
	v_mov_b32_e32 v18, v65
	v_mov_b32_e32 v19, v65
	v_mov_b32_e32 v20, 0
	v_mov_b32_e32 v21, v65
	v_mov_b32_e32 v22, v65
	v_mov_b32_e32 v23, v65
	v_mov_b32_e32 v24, 0
	v_mov_b32_e32 v25, v65
	v_mov_b32_e32 v26, v65
	v_mov_b32_e32 v27, v65
	v_mov_b32_e32 v28, 0
	v_mov_b32_e32 v29, v65
	v_mov_b32_e32 v30, v65
	v_mov_b32_e32 v31, v65
	v_mov_b32_e32 v32, 0
	v_mov_b32_e32 v33, v65
	v_mov_b32_e32 v34, v65
	v_mov_b32_e32 v35, v65
	v_mov_b32_e32 v36, 0
	v_mov_b32_e32 v37, v65
	v_mov_b32_e32 v38, v65
	v_mov_b32_e32 v39, v65
	v_mov_b32_e32 v40, 0
	v_mov_b32_e32 v41, v65
	v_mov_b32_e32 v42, v65
	v_mov_b32_e32 v43, v65
	v_mov_b32_e32 v44, 0
	v_mov_b32_e32 v45, v65
	v_mov_b32_e32 v46, v65
	v_mov_b32_e32 v47, v65
	v_mov_b32_e32 v48, 0
	v_mov_b32_e32 v49, v65
	v_mov_b32_e32 v50, v65
	v_mov_b32_e32 v51, v65
	v_mov_b32_e32 v52, 0
	v_mov_b32_e32 v53, v65
	v_mov_b32_e32 v54, v65
	v_mov_b32_e32 v55, v65
	v_mov_b32_e32 v56, 0
	v_mov_b32_e32 v57, v65
	v_mov_b32_e32 v58, v65
	v_mov_b32_e32 v59, v65
	v_mov_b32_e32 v60, 0
	v_mov_b32_e32 v61, v65
	v_mov_b32_e32 v62, v65
	v_mov_b32_e32 v63, v65
	s_waitcnt vmcnt(0) lgkmcnt(0)
	s_barrier
	v_add3_u32 v186, 0, v133, v134
	v_add_u32_e32 v187, 0x4000, v186
	s_nop 0
	v_readfirstlane_b32 s82, v187
	v_lshl_add_u32 v187, v109, 1, 0
	s_nop 0
	v_readfirstlane_b32 s83, v186
	v_add3_u32 v187, v187, v134, s17
	s_nop 0
	v_readfirstlane_b32 s84, v187
	v_add_u32_e32 v187, 0x400, v186
	s_nop 0
	v_readfirstlane_b32 s85, v187
	v_lshl_add_u32 v187, v111, 1, 0
	v_add3_u32 v187, v187, v134, s17
	s_nop 0
	v_readfirstlane_b32 s86, v187
	v_add_u32_e32 v187, 0x800, v186
	s_nop 0
	v_readfirstlane_b32 s87, v187
	v_lshl_add_u32 v187, v113, 1, 0
	v_add3_u32 v187, v187, v134, s17
	s_nop 0
	v_readfirstlane_b32 s88, v187
	v_add_u32_e32 v186, 0xc00, v186
	s_nop 0
	v_readfirstlane_b32 s89, v186
	v_subrev_u32_e32 v188, s52, v90
	v_subrev_u32_e32 v189, s52, v92
	v_subrev_u32_e32 v190, s52, v94
	v_subrev_u32_e32 v191, s52, v96
	v_subrev_u32_e32 v192, s52, v98
	v_subrev_u32_e32 v193, s52, v100
	v_subrev_u32_e32 v194, s52, v102
	v_subrev_u32_e32 v195, s52, v104
	v_subrev_u32_e32 v191, 0x400, v191
	v_subrev_u32_e32 v190, 0x400, v190
	v_subrev_u32_e32 v193, 0x800, v193
	v_subrev_u32_e32 v192, 0x800, v192
	v_subrev_u32_e32 v195, 0xc00, v195
	v_subrev_u32_e32 v194, 0xc00, v194
	s_and_b32 s26, s24, 0x4000
	s_xor_b32 s25, s26, 0x4000
	s_lshl_b32 s25, s25, 1
	s_add_i32 s25, s25, 32
	s_lshl_b32 s26, s26, 1
	s_add_i32 s26, s26, 32
.LBB0_423:
	s_xor_b32 s25, s25, 0x8000
	s_xor_b32 s26, s26, 0x8000
	s_add_u32 s90, s52, s14
	s_addc_u32 s91, s53, s15
	s_add_i32 m0, s26, s83
	v_add3_u32 v170, s25, v114, v135
	global_load_lds_dwordx4 v189, s[90:91]
	global_load_lds_dwordx4 v191, s[90:91] offset:1024
	global_load_lds_dwordx4 v193, s[90:91] offset:2048
	global_load_lds_dwordx4 v195, s[90:91] offset:3072
	s_add_i32 m0, s26, s82
	v_add3_u32 v171, s25, v115, v135
	global_load_lds_dwordx4 v188, s[90:91]
	global_load_lds_dwordx4 v190, s[90:91] offset:1024
	global_load_lds_dwordx4 v192, s[90:91] offset:2048
	global_load_lds_dwordx4 v194, s[90:91] offset:3072
	v_add_u32_e32 v158, v170, v136
	v_add_u32_e32 v166, v171, v136
	s_addk_i32 s24, 0x4000
	s_add_u32 s14, s14, 0x80
	s_addc_u32 s15, s15, 0
	ds_read_b128 v[138:141], v158
	ds_read_b128 v[146:149], v166 offset:16384
	ds_read_b128 v[150:153], v166 offset:18432
	ds_read_b128 v[162:165], v166 offset:20480
	ds_read_b128 v[166:169], v166 offset:22528
	ds_read_b128 v[142:145], v158 offset:2048
	ds_read_b128 v[154:157], v158 offset:4096
	ds_read_b128 v[158:161], v158 offset:6144
	v_add_u32_e32 v236, v170, v137
	v_add_u32_e32 v237, v171, v137
	ds_read_b128 v[204:207], v236
	ds_read_b128 v[208:211], v237 offset:16384
	ds_read_b128 v[212:215], v237 offset:18432
	ds_read_b128 v[216:219], v237 offset:20480
	ds_read_b128 v[220:223], v237 offset:22528
	ds_read_b128 v[224:227], v236 offset:2048
	ds_read_b128 v[228:231], v236 offset:4096
	ds_read_b128 v[232:235], v236 offset:6144
	s_setprio 1
	s_waitcnt lgkmcnt(11)
	v_mfma_f32_16x16x32_bf16 v[60:63], v[138:141], v[146:149], v[60:63]
	v_mfma_f32_16x16x32_bf16 v[56:59], v[138:141], v[150:153], v[56:59]
	v_mfma_f32_16x16x32_bf16 v[52:55], v[138:141], v[162:165], v[52:55]
	v_mfma_f32_16x16x32_bf16 v[48:51], v[138:141], v[166:169], v[48:51]
	s_waitcnt lgkmcnt(10)
	v_mfma_f32_16x16x32_bf16 v[44:47], v[142:145], v[146:149], v[44:47]
	v_mfma_f32_16x16x32_bf16 v[40:43], v[142:145], v[150:153], v[40:43]
	v_mfma_f32_16x16x32_bf16 v[36:39], v[142:145], v[162:165], v[36:39]
	v_mfma_f32_16x16x32_bf16 v[32:35], v[142:145], v[166:169], v[32:35]
	s_waitcnt lgkmcnt(9)
	v_mfma_f32_16x16x32_bf16 v[28:31], v[154:157], v[146:149], v[28:31]
	v_mfma_f32_16x16x32_bf16 v[24:27], v[154:157], v[150:153], v[24:27]
	v_mfma_f32_16x16x32_bf16 v[20:23], v[154:157], v[162:165], v[20:23]
	v_mfma_f32_16x16x32_bf16 v[16:19], v[154:157], v[166:169], v[16:19]
	s_waitcnt lgkmcnt(8)
	v_mfma_f32_16x16x32_bf16 v[12:15], v[158:161], v[146:149], v[12:15]
	v_mfma_f32_16x16x32_bf16 v[8:11], v[158:161], v[150:153], v[8:11]
	v_mfma_f32_16x16x32_bf16 v[4:7], v[158:161], v[162:165], v[4:7]
	v_mfma_f32_16x16x32_bf16 v[0:3], v[158:161], v[166:169], v[0:3]
	s_waitcnt lgkmcnt(3)
	v_mfma_f32_16x16x32_bf16 v[60:63], v[204:207], v[208:211], v[60:63]
	v_mfma_f32_16x16x32_bf16 v[56:59], v[204:207], v[212:215], v[56:59]
	v_mfma_f32_16x16x32_bf16 v[52:55], v[204:207], v[216:219], v[52:55]
	v_mfma_f32_16x16x32_bf16 v[48:51], v[204:207], v[220:223], v[48:51]
	s_waitcnt lgkmcnt(2)
	v_mfma_f32_16x16x32_bf16 v[44:47], v[224:227], v[208:211], v[44:47]
	v_mfma_f32_16x16x32_bf16 v[40:43], v[224:227], v[212:215], v[40:43]
	v_mfma_f32_16x16x32_bf16 v[36:39], v[224:227], v[216:219], v[36:39]
	v_mfma_f32_16x16x32_bf16 v[32:35], v[224:227], v[220:223], v[32:35]
	s_waitcnt lgkmcnt(1)
	v_mfma_f32_16x16x32_bf16 v[28:31], v[228:231], v[208:211], v[28:31]
	v_mfma_f32_16x16x32_bf16 v[24:27], v[228:231], v[212:215], v[24:27]
	v_mfma_f32_16x16x32_bf16 v[20:23], v[228:231], v[216:219], v[20:23]
	v_mfma_f32_16x16x32_bf16 v[16:19], v[228:231], v[220:223], v[16:19]
	s_waitcnt lgkmcnt(0)
	v_mfma_f32_16x16x32_bf16 v[12:15], v[232:235], v[208:211], v[12:15]
	v_mfma_f32_16x16x32_bf16 v[8:11], v[232:235], v[212:215], v[8:11]
	v_mfma_f32_16x16x32_bf16 v[4:7], v[232:235], v[216:219], v[4:7]
	v_mfma_f32_16x16x32_bf16 v[0:3], v[232:235], v[220:223], v[0:3]
	s_setprio 0
	s_cmpk_eq_i32 s14, 0x780
	s_waitcnt vmcnt(0)
	s_barrier
	s_cbranch_scc0 .LBB0_423
	ds_read_b128 v[90:93], v118 offset:55296
	ds_read_b128 v[94:97], v118 offset:53248
	ds_read_b128 v[98:101], v119 offset:38912
	ds_read_b128 v[102:105], v119 offset:36864
	ds_read_b128 v[138:141], v118 offset:51200
	ds_read_b128 v[142:145], v118 offset:49152
	ds_read_b128 v[146:149], v119 offset:34816
	ds_read_b128 v[150:153], v119 offset:32768
	ds_read_b128 v[204:207], v120 offset:32768
	ds_read_b128 v[208:211], v120 offset:34816
	ds_read_b128 v[212:215], v121 offset:49152
	ds_read_b128 v[216:219], v121 offset:51200
	ds_read_b128 v[220:223], v120 offset:36864
	ds_read_b128 v[224:227], v120 offset:38912
	ds_read_b128 v[228:231], v121 offset:53248
	ds_read_b128 v[232:235], v121 offset:55296
	s_setprio 1
	s_waitcnt lgkmcnt(13)
	v_mfma_f32_16x16x32_bf16 v[4:7], v[98:101], v[94:97], v[4:7]
	v_mfma_f32_16x16x32_bf16 v[0:3], v[98:101], v[90:93], v[0:3]
	s_waitcnt lgkmcnt(8)
	v_mfma_f32_16x16x32_bf16 v[60:63], v[150:153], v[142:145], v[60:63]
	v_mfma_f32_16x16x32_bf16 v[56:59], v[150:153], v[138:141], v[56:59]
	v_mfma_f32_16x16x32_bf16 v[52:55], v[150:153], v[94:97], v[52:55]
	v_mfma_f32_16x16x32_bf16 v[48:51], v[150:153], v[90:93], v[48:51]
	v_mfma_f32_16x16x32_bf16 v[44:47], v[146:149], v[142:145], v[44:47]
	v_mfma_f32_16x16x32_bf16 v[40:43], v[146:149], v[138:141], v[40:43]
	v_mfma_f32_16x16x32_bf16 v[36:39], v[146:149], v[94:97], v[36:39]
	v_mfma_f32_16x16x32_bf16 v[32:35], v[146:149], v[90:93], v[32:35]
	v_mfma_f32_16x16x32_bf16 v[28:31], v[102:105], v[142:145], v[28:31]
	v_mfma_f32_16x16x32_bf16 v[24:27], v[102:105], v[138:141], v[24:27]
	v_mfma_f32_16x16x32_bf16 v[20:23], v[102:105], v[94:97], v[20:23]
	v_mfma_f32_16x16x32_bf16 v[16:19], v[102:105], v[90:93], v[16:19]
	v_mfma_f32_16x16x32_bf16 v[12:15], v[98:101], v[142:145], v[12:15]
	v_mfma_f32_16x16x32_bf16 v[8:11], v[98:101], v[138:141], v[8:11]
	s_waitcnt lgkmcnt(1)
	v_mfma_f32_16x16x32_bf16 v[4:7], v[224:227], v[228:231], v[4:7]
	s_waitcnt lgkmcnt(0)
	v_mfma_f32_16x16x32_bf16 v[0:3], v[224:227], v[232:235], v[0:3]
	v_mfma_f32_16x16x32_bf16 v[60:63], v[204:207], v[212:215], v[60:63]
	v_mfma_f32_16x16x32_bf16 v[56:59], v[204:207], v[216:219], v[56:59]
	v_mfma_f32_16x16x32_bf16 v[52:55], v[204:207], v[228:231], v[52:55]
	v_mfma_f32_16x16x32_bf16 v[48:51], v[204:207], v[232:235], v[48:51]
	v_mfma_f32_16x16x32_bf16 v[44:47], v[208:211], v[212:215], v[44:47]
	v_mfma_f32_16x16x32_bf16 v[40:43], v[208:211], v[216:219], v[40:43]
	v_mfma_f32_16x16x32_bf16 v[36:39], v[208:211], v[228:231], v[36:39]
	v_mfma_f32_16x16x32_bf16 v[32:35], v[208:211], v[232:235], v[32:35]
	v_mfma_f32_16x16x32_bf16 v[28:31], v[220:223], v[212:215], v[28:31]
	v_mfma_f32_16x16x32_bf16 v[24:27], v[220:223], v[216:219], v[24:27]
	v_mfma_f32_16x16x32_bf16 v[20:23], v[220:223], v[228:231], v[20:23]
	v_mfma_f32_16x16x32_bf16 v[16:19], v[220:223], v[232:235], v[16:19]
	v_mfma_f32_16x16x32_bf16 v[12:15], v[224:227], v[212:215], v[12:15]
	v_mfma_f32_16x16x32_bf16 v[8:11], v[224:227], v[216:219], v[8:11]
	s_setprio 0
	s_barrier
	ds_write2_b32 v116, v60, v56 offset1:16
	ds_write2_b32 v116, v61, v57 offset0:132 offset1:148
	v_add_u32_e32 v56, 0x400, v116
	ds_write2_b32 v56, v62, v58 offset0:8 offset1:24
	ds_write2_b32 v56, v63, v59 offset0:140 offset1:156
	ds_write2_b32 v116, v52, v48 offset0:32 offset1:48
	ds_write2_b32 v116, v53, v49 offset0:164 offset1:180
	ds_write2_b32 v56, v54, v50 offset0:40 offset1:56
	ds_write2_b32 v56, v55, v51 offset0:172 offset1:188
	v_add_u32_e32 v48, 0x2000, v116
	ds_write2_b32 v48, v44, v40 offset0:64 offset1:80
	ds_write2_b32 v48, v45, v41 offset0:196 offset1:212
	v_add_u32_e32 v40, 0x2400, v116
	ds_write2_b32 v40, v46, v42 offset0:72 offset1:88
	ds_write2_b32 v40, v47, v43 offset0:204 offset1:220
	ds_write2_b32 v48, v36, v32 offset0:96 offset1:112
	ds_write2_b32 v48, v37, v33 offset0:228 offset1:244
	ds_write2_b32 v40, v38, v34 offset0:104 offset1:120
	ds_write2_b32 v40, v39, v35 offset0:236 offset1:252
	v_add_u32_e32 v32, 0x4000, v116
	ds_write2_b32 v32, v28, v24 offset0:128 offset1:144
	v_add_u32_e32 v24, 0x4400, v116
	ds_write2_b32 v24, v29, v25 offset0:4 offset1:20
	ds_write2_b32 v24, v30, v26 offset0:136 offset1:152
	v_add_u32_e32 v25, 0x4800, v116
	ds_write2_b32 v25, v31, v27 offset0:12 offset1:28
	ds_write2_b32 v32, v20, v16 offset0:160 offset1:176
	ds_write2_b32 v24, v21, v17 offset0:36 offset1:52
	ds_write2_b32 v24, v22, v18 offset0:168 offset1:184
	ds_write2_b32 v25, v23, v19 offset0:44 offset1:60
	v_add_u32_e32 v16, 0x6000, v116
	ds_write2_b32 v16, v12, v8 offset0:192 offset1:208
	v_add_u32_e32 v8, 0x6400, v116
	ds_write2_b32 v8, v13, v9 offset0:68 offset1:84
	ds_write2_b32 v8, v14, v10 offset0:200 offset1:216
	v_add_u32_e32 v9, 0x6800, v116
	ds_write2_b32 v9, v15, v11 offset0:76 offset1:92
	ds_write2_b32 v16, v4, v0 offset0:224 offset1:240
	ds_write2_b32 v8, v5, v1 offset0:100 offset1:116
	ds_write2_b32 v8, v6, v2 offset0:232 offset1:248
	ds_write2_b32 v9, v7, v3 offset0:108 offset1:124
	v_or_b32_e32 v0, s23, v117
	v_ashrrev_i32_e32 v1, 31, v0
	v_lshlrev_b64 v[2:3], 2, v[0:1]
	v_lshl_add_u64 v[0:1], s[12:13], 0, v[2:3]
	v_lshl_add_u64 v[2:3], s[8:9], 0, v[2:3]
	v_add_u32_e32 v4, s22, v128
	s_mov_b32 s14, 0
	s_waitcnt lgkmcnt(0)
	s_barrier

.LBB0_431:
	s_ashr_i32 s14, s16, 31
	s_lshr_b32 s14, s14, 29
	s_add_i32 s14, s16, s14
	s_ashr_i32 s14, s14, 3
	s_lshl_b32 s15, s14, 10
	s_lshl_b32 s23, s16, 7
	v_add_u32_e32 v0, s14, v104
	s_sub_i32 s23, s23, s15
	v_lshlrev_b32_e32 v2, 7, v0
	v_add_u32_e32 v0, s23, v105
	v_ashrrev_i32_e32 v1, 31, v0
	v_add_u32_e32 v3, 0x4000, v106
	v_lshlrev_b64 v[0:1], 11, v[0:1]
	v_readfirstlane_b32 s24, v3
	v_lshl_add_u64 v[0:1], v[64:65], 0, v[0:1]
	s_mov_b32 m0, s24
	v_readfirstlane_b32 s24, v106
	global_load_lds_dwordx4 v[0:1], off
	v_add_u32_e32 v0, v2, v105
	v_ashrrev_i32_e32 v1, 31, v0
	v_lshlrev_b64 v[0:1], 11, v[0:1]
	v_lshl_add_u64 v[0:1], v[70:71], 0, v[0:1]
	s_mov_b32 m0, s24
	v_readfirstlane_b32 s24, v131
	global_load_lds_dwordx4 v[0:1], off
	v_add_u32_e32 v0, s23, v107
	v_ashrrev_i32_e32 v1, 31, v0
	v_lshlrev_b64 v[0:1], 11, v[0:1]
	v_lshl_add_u64 v[0:1], v[66:67], 0, v[0:1]
	s_mov_b32 m0, s24
	v_add_u32_e32 v3, 0x400, v106
	global_load_lds_dwordx4 v[0:1], off
	v_add_u32_e32 v0, v2, v107
	v_ashrrev_i32_e32 v1, 31, v0
	v_lshlrev_b64 v[0:1], 11, v[0:1]
	v_readfirstlane_b32 s24, v3
	v_lshl_add_u64 v[0:1], v[72:73], 0, v[0:1]
	s_mov_b32 m0, s24
	v_readfirstlane_b32 s24, v132
	global_load_lds_dwordx4 v[0:1], off
	v_add_u32_e32 v0, s23, v109
	v_ashrrev_i32_e32 v1, 31, v0
	v_lshlrev_b64 v[0:1], 11, v[0:1]
	v_lshl_add_u64 v[0:1], v[64:65], 0, v[0:1]
	s_mov_b32 m0, s24
	v_add_u32_e32 v3, 0x800, v106
	global_load_lds_dwordx4 v[0:1], off
	v_add_u32_e32 v0, v2, v109
	v_ashrrev_i32_e32 v1, 31, v0
	v_lshlrev_b64 v[0:1], 11, v[0:1]
	v_readfirstlane_b32 s24, v3
	v_lshl_add_u64 v[0:1], v[70:71], 0, v[0:1]
	s_mov_b32 m0, s24
	v_readfirstlane_b32 s24, v133
	global_load_lds_dwordx4 v[0:1], off
	v_add_u32_e32 v0, s23, v111
	v_ashrrev_i32_e32 v1, 31, v0
	v_lshlrev_b64 v[0:1], 11, v[0:1]
	v_lshl_add_u64 v[0:1], v[68:69], 0, v[0:1]
	s_mov_b32 m0, s24
	s_mov_b32 s25, 0
	global_load_lds_dwordx4 v[0:1], off
	v_add_u32_e32 v0, v2, v111
	v_ashrrev_i32_e32 v1, 31, v0
	v_add_u32_e32 v2, 0xc00, v106
	v_lshlrev_b64 v[0:1], 11, v[0:1]
	v_readfirstlane_b32 s24, v2
	v_lshl_add_u64 v[0:1], v[74:75], 0, v[0:1]
	s_mov_b32 m0, s24
	s_lshl_b32 s24, s14, 7
	global_load_lds_dwordx4 v[0:1], off
	v_subrev_u32_e32 v0, s15, v121
	v_ashrrev_i32_e32 v1, 31, v0
	v_lshlrev_b64 v[0:1], 11, v[0:1]
	v_lshl_add_u64 v[88:89], v[76:77], 0, v[0:1]
	v_add_u32_e32 v0, s24, v122
	v_ashrrev_i32_e32 v1, 31, v0
	v_lshlrev_b64 v[0:1], 11, v[0:1]
	v_lshl_add_u64 v[90:91], v[78:79], 0, v[0:1]
	v_subrev_u32_e32 v0, s15, v123
	v_ashrrev_i32_e32 v1, 31, v0
	v_lshlrev_b64 v[0:1], 11, v[0:1]
	v_lshl_add_u64 v[92:93], v[80:81], 0, v[0:1]
	v_add_u32_e32 v0, s24, v124
	v_ashrrev_i32_e32 v1, 31, v0
	v_lshlrev_b64 v[0:1], 11, v[0:1]
	v_lshl_add_u64 v[94:95], v[82:83], 0, v[0:1]
	v_subrev_u32_e32 v0, s15, v125
	v_ashrrev_i32_e32 v1, 31, v0
	v_lshlrev_b64 v[0:1], 11, v[0:1]
	v_lshl_add_u64 v[96:97], v[76:77], 0, v[0:1]
	v_add_u32_e32 v0, s24, v126
	v_ashrrev_i32_e32 v1, 31, v0
	v_lshlrev_b64 v[0:1], 11, v[0:1]
	v_lshl_add_u64 v[98:99], v[78:79], 0, v[0:1]
	v_subrev_u32_e32 v0, s15, v127
	v_ashrrev_i32_e32 v1, 31, v0
	v_lshlrev_b64 v[0:1], 11, v[0:1]
	v_lshl_add_u64 v[100:101], v[84:85], 0, v[0:1]
	v_add_u32_e32 v0, s24, v128
	v_ashrrev_i32_e32 v1, 31, v0
	v_lshlrev_b64 v[0:1], 11, v[0:1]
	v_lshl_add_u64 v[102:103], v[86:87], 0, v[0:1]
	v_mov_b32_e32 v0, 0
	s_mov_b64 s[14:15], 0
	v_mov_b32_e32 v1, v0
	v_mov_b32_e32 v2, v0
	v_mov_b32_e32 v3, v0
	v_mov_b32_e32 v4, v0
	v_mov_b32_e32 v5, v0
	v_mov_b32_e32 v6, v0
	v_mov_b32_e32 v7, v0
	v_mov_b32_e32 v8, v0
	v_mov_b32_e32 v9, v0
	v_mov_b32_e32 v10, v0
	v_mov_b32_e32 v11, v0
	v_mov_b32_e32 v12, v0
	v_mov_b32_e32 v13, v0
	v_mov_b32_e32 v14, v0
	v_mov_b32_e32 v15, v0
	v_mov_b32_e32 v16, v0
	v_mov_b32_e32 v17, v0
	v_mov_b32_e32 v18, v0
	v_mov_b32_e32 v19, v0
	v_mov_b32_e32 v20, v0
	v_mov_b32_e32 v21, v0
	v_mov_b32_e32 v22, v0
	v_mov_b32_e32 v23, v0
	v_mov_b32_e32 v24, v0
	v_mov_b32_e32 v25, v0
	v_mov_b32_e32 v26, v0
	v_mov_b32_e32 v27, v0
	v_mov_b32_e32 v28, v0
	v_mov_b32_e32 v29, v0
	v_mov_b32_e32 v30, v0
	v_mov_b32_e32 v31, v0
	v_mov_b32_e32 v32, v0
	v_mov_b32_e32 v33, v0
	v_mov_b32_e32 v34, v0
	v_mov_b32_e32 v35, v0
	v_mov_b32_e32 v36, v0
	v_mov_b32_e32 v37, v0
	v_mov_b32_e32 v38, v0
	v_mov_b32_e32 v39, v0
	v_mov_b32_e32 v40, v0
	v_mov_b32_e32 v41, v0
	v_mov_b32_e32 v42, v0
	v_mov_b32_e32 v43, v0
	v_mov_b32_e32 v44, v0
	v_mov_b32_e32 v45, v0
	v_mov_b32_e32 v46, v0
	v_mov_b32_e32 v47, v0
	v_mov_b32_e32 v48, v0
	v_mov_b32_e32 v49, v0
	v_mov_b32_e32 v50, v0
	v_mov_b32_e32 v51, v0
	v_mov_b32_e32 v52, v0
	v_mov_b32_e32 v53, v0
	v_mov_b32_e32 v54, v0
	v_mov_b32_e32 v55, v0
	v_mov_b32_e32 v56, v0
	v_mov_b32_e32 v57, v0
	v_mov_b32_e32 v58, v0
	v_mov_b32_e32 v59, v0
	v_mov_b32_e32 v60, v0
	v_mov_b32_e32 v61, v0
	v_mov_b32_e32 v62, v0
	v_mov_b32_e32 v63, v0
	s_waitcnt vmcnt(0) lgkmcnt(0)
	s_barrier
	v_add3_u32 v186, 0, v134, v135
	v_add_u32_e32 v187, 0x4000, v186
	s_nop 0
	v_readfirstlane_b32 s82, v187
	v_lshl_add_u32 v187, v108, 1, 0
	s_nop 0
	v_readfirstlane_b32 s83, v186
	v_add3_u32 v187, v187, v135, s19
	s_nop 0
	v_readfirstlane_b32 s84, v187
	v_add_u32_e32 v187, 0x400, v186
	s_nop 0
	v_readfirstlane_b32 s85, v187
	v_lshl_add_u32 v187, v110, 1, 0
	v_add3_u32 v187, v187, v135, s19
	s_nop 0
	v_readfirstlane_b32 s86, v187
	v_add_u32_e32 v187, 0x800, v186
	s_nop 0
	v_readfirstlane_b32 s87, v187
	v_lshl_add_u32 v187, v112, 1, 0
	v_add3_u32 v187, v187, v135, s19
	s_nop 0
	v_readfirstlane_b32 s88, v187
	v_add_u32_e32 v186, 0xc00, v186
	s_nop 0
	v_readfirstlane_b32 s89, v186
	v_subrev_u32_e32 v188, s52, v88
	v_subrev_u32_e32 v189, s52, v90
	v_subrev_u32_e32 v190, s52, v92
	v_subrev_u32_e32 v191, s52, v94
	v_subrev_u32_e32 v192, s52, v96
	v_subrev_u32_e32 v193, s52, v98
	v_subrev_u32_e32 v194, s52, v100
	v_subrev_u32_e32 v195, s52, v102
	v_subrev_u32_e32 v191, 0x400, v191
	v_subrev_u32_e32 v190, 0x400, v190
	v_subrev_u32_e32 v193, 0x800, v193
	v_subrev_u32_e32 v192, 0x800, v192
	v_subrev_u32_e32 v195, 0xc00, v195
	v_subrev_u32_e32 v194, 0xc00, v194
	s_and_b32 s27, s25, 0x4000
	s_xor_b32 s26, s27, 0x4000
	s_lshl_b32 s26, s26, 1
	s_add_i32 s26, s26, 32
	s_lshl_b32 s27, s27, 1
	s_add_i32 s27, s27, 32
.LBB0_432:
	s_xor_b32 s26, s26, 0x8000
	s_xor_b32 s27, s27, 0x8000
	s_add_u32 s90, s52, s14
	s_addc_u32 s91, s53, s15
	s_add_i32 m0, s27, s83
	v_add3_u32 v139, s26, v113, v136
	global_load_lds_dwordx4 v189, s[90:91]
	global_load_lds_dwordx4 v191, s[90:91] offset:1024
	global_load_lds_dwordx4 v193, s[90:91] offset:2048
	global_load_lds_dwordx4 v195, s[90:91] offset:3072
	s_add_i32 m0, s27, s82
	v_add3_u32 v172, s26, v114, v136
	global_load_lds_dwordx4 v188, s[90:91]
	global_load_lds_dwordx4 v190, s[90:91] offset:1024
	global_load_lds_dwordx4 v192, s[90:91] offset:2048
	global_load_lds_dwordx4 v194, s[90:91] offset:3072
	v_add_u32_e32 v160, v139, v137
	v_add_u32_e32 v168, v172, v137
	s_add_u32 s14, s14, 0x80
	s_addc_u32 s15, s15, 0
	ds_read_b128 v[140:143], v160
	ds_read_b128 v[148:151], v168 offset:16384
	ds_read_b128 v[152:155], v168 offset:18432
	ds_read_b128 v[164:167], v168 offset:20480
	ds_read_b128 v[168:171], v168 offset:22528
	ds_read_b128 v[144:147], v160 offset:2048
	ds_read_b128 v[156:159], v160 offset:4096
	ds_read_b128 v[160:163], v160 offset:6144
	v_add_u32_e32 v139, v139, v138
	v_add_u32_e32 v236, v172, v138
	ds_read_b128 v[204:207], v139
	ds_read_b128 v[208:211], v236 offset:16384
	ds_read_b128 v[212:215], v236 offset:18432
	ds_read_b128 v[216:219], v236 offset:20480
	ds_read_b128 v[220:223], v236 offset:22528
	ds_read_b128 v[224:227], v139 offset:2048
	ds_read_b128 v[228:231], v139 offset:4096
	ds_read_b128 v[232:235], v139 offset:6144
	s_setprio 1
	s_waitcnt lgkmcnt(11)
	v_mfma_f32_16x16x32_bf16 v[60:63], v[140:143], v[148:151], v[60:63]
	v_mfma_f32_16x16x32_bf16 v[56:59], v[140:143], v[152:155], v[56:59]
	v_mfma_f32_16x16x32_bf16 v[52:55], v[140:143], v[164:167], v[52:55]
	v_mfma_f32_16x16x32_bf16 v[48:51], v[140:143], v[168:171], v[48:51]
	s_waitcnt lgkmcnt(10)
	v_mfma_f32_16x16x32_bf16 v[44:47], v[144:147], v[148:151], v[44:47]
	v_mfma_f32_16x16x32_bf16 v[40:43], v[144:147], v[152:155], v[40:43]
	v_mfma_f32_16x16x32_bf16 v[36:39], v[144:147], v[164:167], v[36:39]
	v_mfma_f32_16x16x32_bf16 v[32:35], v[144:147], v[168:171], v[32:35]
	s_waitcnt lgkmcnt(9)
	v_mfma_f32_16x16x32_bf16 v[28:31], v[156:159], v[148:151], v[28:31]
	v_mfma_f32_16x16x32_bf16 v[24:27], v[156:159], v[152:155], v[24:27]
	v_mfma_f32_16x16x32_bf16 v[20:23], v[156:159], v[164:167], v[20:23]
	v_mfma_f32_16x16x32_bf16 v[16:19], v[156:159], v[168:171], v[16:19]
	s_waitcnt lgkmcnt(8)
	v_mfma_f32_16x16x32_bf16 v[12:15], v[160:163], v[148:151], v[12:15]
	v_mfma_f32_16x16x32_bf16 v[8:11], v[160:163], v[152:155], v[8:11]
	v_mfma_f32_16x16x32_bf16 v[4:7], v[160:163], v[164:167], v[4:7]
	v_mfma_f32_16x16x32_bf16 v[0:3], v[160:163], v[168:171], v[0:3]
	s_waitcnt lgkmcnt(3)
	v_mfma_f32_16x16x32_bf16 v[60:63], v[204:207], v[208:211], v[60:63]
	v_mfma_f32_16x16x32_bf16 v[56:59], v[204:207], v[212:215], v[56:59]
	v_mfma_f32_16x16x32_bf16 v[52:55], v[204:207], v[216:219], v[52:55]
	v_mfma_f32_16x16x32_bf16 v[48:51], v[204:207], v[220:223], v[48:51]
	s_waitcnt lgkmcnt(2)
	v_mfma_f32_16x16x32_bf16 v[44:47], v[224:227], v[208:211], v[44:47]
	v_mfma_f32_16x16x32_bf16 v[40:43], v[224:227], v[212:215], v[40:43]
	v_mfma_f32_16x16x32_bf16 v[36:39], v[224:227], v[216:219], v[36:39]
	v_mfma_f32_16x16x32_bf16 v[32:35], v[224:227], v[220:223], v[32:35]
	s_waitcnt lgkmcnt(1)
	v_mfma_f32_16x16x32_bf16 v[28:31], v[228:231], v[208:211], v[28:31]
	v_mfma_f32_16x16x32_bf16 v[24:27], v[228:231], v[212:215], v[24:27]
	v_mfma_f32_16x16x32_bf16 v[20:23], v[228:231], v[216:219], v[20:23]
	v_mfma_f32_16x16x32_bf16 v[16:19], v[228:231], v[220:223], v[16:19]
	s_waitcnt lgkmcnt(0)
	v_mfma_f32_16x16x32_bf16 v[12:15], v[232:235], v[208:211], v[12:15]
	v_mfma_f32_16x16x32_bf16 v[8:11], v[232:235], v[212:215], v[8:11]
	v_mfma_f32_16x16x32_bf16 v[4:7], v[232:235], v[216:219], v[4:7]
	v_mfma_f32_16x16x32_bf16 v[0:3], v[232:235], v[220:223], v[0:3]
	s_setprio 0
	s_cmpk_eq_i32 s14, 0x780
	s_waitcnt vmcnt(0)
	s_barrier
	s_cbranch_scc0 .LBB0_432
	ds_read_b128 v[88:91], v117 offset:55296
	ds_read_b128 v[92:95], v117 offset:53248
	ds_read_b128 v[96:99], v118 offset:38912
	ds_read_b128 v[100:103], v118 offset:36864
	ds_read_b128 v[140:143], v117 offset:51200
	ds_read_b128 v[144:147], v117 offset:49152
	ds_read_b128 v[148:151], v118 offset:34816
	ds_read_b128 v[152:155], v118 offset:32768
	ds_read_b128 v[204:207], v119 offset:32768
	ds_read_b128 v[208:211], v119 offset:34816
	ds_read_b128 v[212:215], v120 offset:49152
	ds_read_b128 v[216:219], v120 offset:51200
	ds_read_b128 v[220:223], v119 offset:36864
	ds_read_b128 v[224:227], v119 offset:38912
	ds_read_b128 v[228:231], v120 offset:53248
	ds_read_b128 v[232:235], v120 offset:55296
	s_setprio 1
	s_waitcnt lgkmcnt(13)
	v_mfma_f32_16x16x32_bf16 v[4:7], v[96:99], v[92:95], v[4:7]
	v_mfma_f32_16x16x32_bf16 v[0:3], v[96:99], v[88:91], v[0:3]
	s_waitcnt lgkmcnt(8)
	v_mfma_f32_16x16x32_bf16 v[60:63], v[152:155], v[144:147], v[60:63]
	v_mfma_f32_16x16x32_bf16 v[56:59], v[152:155], v[140:143], v[56:59]
	v_mfma_f32_16x16x32_bf16 v[52:55], v[152:155], v[92:95], v[52:55]
	v_mfma_f32_16x16x32_bf16 v[48:51], v[152:155], v[88:91], v[48:51]
	v_mfma_f32_16x16x32_bf16 v[44:47], v[148:151], v[144:147], v[44:47]
	v_mfma_f32_16x16x32_bf16 v[40:43], v[148:151], v[140:143], v[40:43]
	v_mfma_f32_16x16x32_bf16 v[36:39], v[148:151], v[92:95], v[36:39]
	v_mfma_f32_16x16x32_bf16 v[32:35], v[148:151], v[88:91], v[32:35]
	v_mfma_f32_16x16x32_bf16 v[28:31], v[100:103], v[144:147], v[28:31]
	v_mfma_f32_16x16x32_bf16 v[24:27], v[100:103], v[140:143], v[24:27]
	v_mfma_f32_16x16x32_bf16 v[20:23], v[100:103], v[92:95], v[20:23]
	v_mfma_f32_16x16x32_bf16 v[16:19], v[100:103], v[88:91], v[16:19]
	v_mfma_f32_16x16x32_bf16 v[12:15], v[96:99], v[144:147], v[12:15]
	v_mfma_f32_16x16x32_bf16 v[8:11], v[96:99], v[140:143], v[8:11]
	s_waitcnt lgkmcnt(1)
	v_mfma_f32_16x16x32_bf16 v[4:7], v[224:227], v[228:231], v[4:7]
	s_waitcnt lgkmcnt(0)
	v_mfma_f32_16x16x32_bf16 v[0:3], v[224:227], v[232:235], v[0:3]
	v_mfma_f32_16x16x32_bf16 v[60:63], v[204:207], v[212:215], v[60:63]
	v_mfma_f32_16x16x32_bf16 v[56:59], v[204:207], v[216:219], v[56:59]
	v_mfma_f32_16x16x32_bf16 v[52:55], v[204:207], v[228:231], v[52:55]
	v_mfma_f32_16x16x32_bf16 v[48:51], v[204:207], v[232:235], v[48:51]
	v_mfma_f32_16x16x32_bf16 v[44:47], v[208:211], v[212:215], v[44:47]
	v_mfma_f32_16x16x32_bf16 v[40:43], v[208:211], v[216:219], v[40:43]
	v_mfma_f32_16x16x32_bf16 v[36:39], v[208:211], v[228:231], v[36:39]
	v_mfma_f32_16x16x32_bf16 v[32:35], v[208:211], v[232:235], v[32:35]
	v_mfma_f32_16x16x32_bf16 v[28:31], v[220:223], v[212:215], v[28:31]
	v_mfma_f32_16x16x32_bf16 v[24:27], v[220:223], v[216:219], v[24:27]
	v_mfma_f32_16x16x32_bf16 v[20:23], v[220:223], v[228:231], v[20:23]
	v_mfma_f32_16x16x32_bf16 v[16:19], v[220:223], v[232:235], v[16:19]
	v_mfma_f32_16x16x32_bf16 v[12:15], v[224:227], v[212:215], v[12:15]
	v_mfma_f32_16x16x32_bf16 v[8:11], v[224:227], v[216:219], v[8:11]
	s_setprio 0
	s_barrier
	ds_write2_b32 v115, v60, v56 offset1:16
	ds_write2_b32 v115, v61, v57 offset0:132 offset1:148
	v_add_u32_e32 v56, 0x400, v115
	ds_write2_b32 v56, v62, v58 offset0:8 offset1:24
	ds_write2_b32 v56, v63, v59 offset0:140 offset1:156
	ds_write2_b32 v115, v52, v48 offset0:32 offset1:48
	ds_write2_b32 v115, v53, v49 offset0:164 offset1:180
	ds_write2_b32 v56, v54, v50 offset0:40 offset1:56
	ds_write2_b32 v56, v55, v51 offset0:172 offset1:188
	v_add_u32_e32 v48, 0x2000, v115
	ds_write2_b32 v48, v44, v40 offset0:64 offset1:80
	ds_write2_b32 v48, v45, v41 offset0:196 offset1:212
	v_add_u32_e32 v40, 0x2400, v115
	ds_write2_b32 v40, v46, v42 offset0:72 offset1:88
	ds_write2_b32 v40, v47, v43 offset0:204 offset1:220
	ds_write2_b32 v48, v36, v32 offset0:96 offset1:112
	ds_write2_b32 v48, v37, v33 offset0:228 offset1:244
	ds_write2_b32 v40, v38, v34 offset0:104 offset1:120
	ds_write2_b32 v40, v39, v35 offset0:236 offset1:252
	v_add_u32_e32 v32, 0x4000, v115
	ds_write2_b32 v32, v28, v24 offset0:128 offset1:144
	v_add_u32_e32 v24, 0x4400, v115
	ds_write2_b32 v24, v29, v25 offset0:4 offset1:20
	ds_write2_b32 v24, v30, v26 offset0:136 offset1:152
	v_add_u32_e32 v25, 0x4800, v115
	ds_write2_b32 v25, v31, v27 offset0:12 offset1:28
	ds_write2_b32 v32, v20, v16 offset0:160 offset1:176
	ds_write2_b32 v24, v21, v17 offset0:36 offset1:52
	ds_write2_b32 v24, v22, v18 offset0:168 offset1:184
	ds_write2_b32 v25, v23, v19 offset0:44 offset1:60
	v_add_u32_e32 v16, 0x6000, v115
	ds_write2_b32 v16, v12, v8 offset0:192 offset1:208
	v_add_u32_e32 v8, 0x6400, v115
	ds_write2_b32 v8, v13, v9 offset0:68 offset1:84
	ds_write2_b32 v8, v14, v10 offset0:200 offset1:216
	v_add_u32_e32 v9, 0x6800, v115
	ds_write2_b32 v9, v15, v11 offset0:76 offset1:92
	ds_write2_b32 v16, v4, v0 offset0:224 offset1:240
	ds_write2_b32 v8, v5, v1 offset0:100 offset1:116
	ds_write2_b32 v8, v6, v2 offset0:232 offset1:248
	ds_write2_b32 v9, v7, v3 offset0:108 offset1:124
	v_or_b32_e32 v0, s23, v116
	v_ashrrev_i32_e32 v1, 31, v0
	v_lshlrev_b64 v[2:3], 2, v[0:1]
	v_lshl_add_u64 v[0:1], s[12:13], 0, v[2:3]
	v_lshl_add_u64 v[2:3], s[8:9], 0, v[2:3]
	v_add_u32_e32 v4, s24, v129
	s_mov_b32 s14, 0
	s_waitcnt lgkmcnt(0)
	s_barrier

.LBB0_442:
	s_and_b32 s10, s16, 0x380
	v_add_lshl_u32 v70, v138, s10, 11
	v_lshl_add_u64 v[96:97], v[84:85], 0, v[70:71]
	v_add_lshl_u32 v70, v140, s10, 11
	v_lshl_add_u64 v[98:99], v[88:89], 0, v[70:71]
	v_add_lshl_u32 v70, v142, s10, 11
	s_lshl_b32 s22, s21, 7
	v_lshl_add_u64 v[100:101], v[84:85], 0, v[70:71]
	v_add_lshl_u32 v70, v144, s10, 11
	s_ashr_i32 s10, s21, 3
	s_and_b32 s22, s22, 0x380
	v_add_u32_e32 v2, 0x4000, v133
	v_lshl_add_u64 v[102:103], v[92:93], 0, v[70:71]
	s_add_i32 s11, s10, s15
	v_add_lshl_u32 v70, s22, v132, 11
	v_readfirstlane_b32 s23, v2
	s_lshl_b32 s11, s11, 7
	v_lshl_add_u64 v[0:1], v[72:73], 0, v[70:71]
	s_mov_b32 m0, s23
	v_readfirstlane_b32 s23, v133
	global_load_lds_dwordx4 v[0:1], off
	v_add_u32_e32 v0, s11, v132
	v_ashrrev_i32_e32 v1, 31, v0
	v_lshlrev_b64 v[0:1], 11, v[0:1]
	v_lshl_add_u64 v[0:1], v[78:79], 0, v[0:1]
	s_mov_b32 m0, s23
	v_add_lshl_u32 v70, s22, v119, 11
	v_readfirstlane_b32 s23, v148
	global_load_lds_dwordx4 v[0:1], off
	v_lshl_add_u64 v[0:1], v[74:75], 0, v[70:71]
	s_mov_b32 m0, s23
	v_add_u32_e32 v2, 0x400, v133
	global_load_lds_dwordx4 v[0:1], off
	v_add_u32_e32 v0, s11, v119
	v_ashrrev_i32_e32 v1, 31, v0
	v_lshlrev_b64 v[0:1], 11, v[0:1]
	v_readfirstlane_b32 s23, v2
	v_lshl_add_u64 v[0:1], v[80:81], 0, v[0:1]
	s_mov_b32 m0, s23
	v_add_lshl_u32 v70, s22, v120, 11
	v_readfirstlane_b32 s23, v149
	global_load_lds_dwordx4 v[0:1], off
	v_lshl_add_u64 v[0:1], v[72:73], 0, v[70:71]
	s_mov_b32 m0, s23
	v_add_u32_e32 v2, 0x800, v133
	global_load_lds_dwordx4 v[0:1], off
	v_add_u32_e32 v0, s11, v120
	v_ashrrev_i32_e32 v1, 31, v0
	v_lshlrev_b64 v[0:1], 11, v[0:1]
	v_readfirstlane_b32 s23, v2
	v_lshl_add_u64 v[0:1], v[78:79], 0, v[0:1]
	s_mov_b32 m0, s23
	v_add_lshl_u32 v70, s22, v118, 11
	v_readfirstlane_b32 s23, v150
	global_load_lds_dwordx4 v[0:1], off
	v_lshl_add_u64 v[0:1], v[76:77], 0, v[70:71]
	s_mov_b32 m0, s23
	v_add_u32_e32 v2, 0xc00, v133
	global_load_lds_dwordx4 v[0:1], off
	v_add_u32_e32 v0, s11, v118
	v_ashrrev_i32_e32 v1, 31, v0
	v_lshlrev_b64 v[0:1], 11, v[0:1]
	v_readfirstlane_b32 s11, v2
	v_lshl_add_u64 v[0:1], v[82:83], 0, v[0:1]
	s_mov_b32 m0, s11
	s_lshl_b32 s23, s10, 7
	global_load_lds_dwordx4 v[0:1], off
	v_add_u32_e32 v0, s23, v139
	v_ashrrev_i32_e32 v1, 31, v0
	v_lshlrev_b64 v[0:1], 11, v[0:1]
	v_lshl_add_u64 v[104:105], v[86:87], 0, v[0:1]
	v_add_u32_e32 v0, s23, v141
	v_ashrrev_i32_e32 v1, 31, v0
	v_lshlrev_b64 v[0:1], 11, v[0:1]
	v_lshl_add_u64 v[106:107], v[90:91], 0, v[0:1]
	v_add_u32_e32 v0, s23, v143
	v_ashrrev_i32_e32 v1, 31, v0
	v_lshlrev_b64 v[0:1], 11, v[0:1]
	v_lshl_add_u64 v[108:109], v[86:87], 0, v[0:1]
	v_add_u32_e32 v0, s23, v145
	v_ashrrev_i32_e32 v1, 31, v0
	v_lshlrev_b64 v[0:1], 11, v[0:1]
	v_lshl_add_u64 v[110:111], v[94:95], 0, v[0:1]
	s_mov_b64 s[10:11], 0
	s_mov_b32 s24, 0
	v_mov_b32_e32 v0, 0
	v_mov_b32_e32 v1, v71
	v_mov_b32_e32 v2, v71
	v_mov_b32_e32 v3, v71
	v_mov_b32_e32 v4, 0
	v_mov_b32_e32 v5, v71
	v_mov_b32_e32 v6, v71
	v_mov_b32_e32 v7, v71
	v_mov_b32_e32 v8, 0
	v_mov_b32_e32 v9, v71
	v_mov_b32_e32 v10, v71
	v_mov_b32_e32 v11, v71
	v_mov_b32_e32 v12, 0
	v_mov_b32_e32 v13, v71
	v_mov_b32_e32 v14, v71
	v_mov_b32_e32 v15, v71
	v_mov_b32_e32 v16, 0
	v_mov_b32_e32 v17, v71
	v_mov_b32_e32 v18, v71
	v_mov_b32_e32 v19, v71
	v_mov_b32_e32 v20, 0
	v_mov_b32_e32 v21, v71
	v_mov_b32_e32 v22, v71
	v_mov_b32_e32 v23, v71
	v_mov_b32_e32 v24, 0
	v_mov_b32_e32 v25, v71
	v_mov_b32_e32 v26, v71
	v_mov_b32_e32 v27, v71
	v_mov_b32_e32 v28, 0
	v_mov_b32_e32 v29, v71
	v_mov_b32_e32 v30, v71
	v_mov_b32_e32 v31, v71
	v_mov_b32_e32 v32, 0
	v_mov_b32_e32 v33, v71
	v_mov_b32_e32 v34, v71
	v_mov_b32_e32 v35, v71
	v_mov_b32_e32 v36, 0
	v_mov_b32_e32 v37, v71
	v_mov_b32_e32 v38, v71
	v_mov_b32_e32 v39, v71
	v_mov_b32_e32 v40, 0
	v_mov_b32_e32 v41, v71
	v_mov_b32_e32 v42, v71
	v_mov_b32_e32 v43, v71
	v_mov_b32_e32 v44, 0
	v_mov_b32_e32 v45, v71
	v_mov_b32_e32 v46, v71
	v_mov_b32_e32 v47, v71
	v_mov_b32_e32 v48, 0
	v_mov_b32_e32 v49, v71
	v_mov_b32_e32 v50, v71
	v_mov_b32_e32 v51, v71
	v_mov_b32_e32 v52, 0
	v_mov_b32_e32 v53, v71
	v_mov_b32_e32 v54, v71
	v_mov_b32_e32 v55, v71
	v_mov_b32_e32 v56, 0
	v_mov_b32_e32 v57, v71
	v_mov_b32_e32 v58, v71
	v_mov_b32_e32 v59, v71
	v_mov_b32_e32 v60, 0
	v_mov_b32_e32 v61, v71
	v_mov_b32_e32 v62, v71
	v_mov_b32_e32 v63, v71
	s_waitcnt vmcnt(0) lgkmcnt(0)
	s_barrier
	v_lshlrev_b32_e32 v186, 1, v130
	v_lshlrev_b32_e32 v187, 1, v131
	v_add3_u32 v186, 0, v186, v187
	v_add_u32_e32 v188, 0x4000, v186
	s_nop 0
	v_readfirstlane_b32 s82, v188
	v_lshl_add_u32 v188, v123, 1, 0
	s_nop 0
	v_readfirstlane_b32 s83, v186
	v_add3_u32 v188, v188, v187, s17
	s_nop 0
	v_readfirstlane_b32 s84, v188
	v_add_u32_e32 v188, 0x400, v186
	s_nop 0
	v_readfirstlane_b32 s85, v188
	v_lshl_add_u32 v188, v121, 1, 0
	v_add3_u32 v188, v188, v187, s17
	s_nop 0
	v_readfirstlane_b32 s86, v188
	v_add_u32_e32 v188, 0x800, v186
	s_nop 0
	v_readfirstlane_b32 s87, v188
	v_lshl_add_u32 v188, v122, 1, 0
	v_add3_u32 v187, v188, v187, s17
	s_nop 0
	v_readfirstlane_b32 s88, v187
	v_add_u32_e32 v186, 0xc00, v186
	s_nop 0
	v_readfirstlane_b32 s89, v186
	v_subrev_u32_e32 v189, s52, v96
	v_subrev_u32_e32 v190, s52, v104
	v_subrev_u32_e32 v191, s52, v98
	v_subrev_u32_e32 v192, s52, v106
	v_subrev_u32_e32 v193, s52, v100
	v_subrev_u32_e32 v194, s52, v108
	v_subrev_u32_e32 v195, s52, v102
	v_subrev_u32_e32 v196, s52, v110
	v_subrev_u32_e32 v192, 0x400, v192
	v_subrev_u32_e32 v191, 0x400, v191
	v_subrev_u32_e32 v194, 0x800, v194
	v_subrev_u32_e32 v193, 0x800, v193
	v_subrev_u32_e32 v196, 0xc00, v196
	v_subrev_u32_e32 v195, 0xc00, v195
	s_and_b32 s26, s24, 0x4000
	s_xor_b32 s25, s26, 0x4000
	s_lshl_b32 s25, s25, 1
	s_add_i32 s25, s25, 32
	s_lshl_b32 s26, s26, 1
	s_add_i32 s26, s26, 32
.LBB0_443:
	s_xor_b32 s25, s25, 0x8000
	s_xor_b32 s26, s26, 0x8000
	s_add_u32 s90, s52, s10
	s_addc_u32 s91, s53, s11
	s_addk_i32 s24, 0x4000
	s_add_i32 m0, s26, s83
	v_lshlrev_b32_e32 v70, 1, v129
	global_load_lds_dwordx4 v190, s[90:91]
	global_load_lds_dwordx4 v192, s[90:91] offset:1024
	global_load_lds_dwordx4 v194, s[90:91] offset:2048
	global_load_lds_dwordx4 v196, s[90:91] offset:3072
	s_add_i32 m0, s26, s82
	v_add3_u32 v151, s25, v124, v70
	global_load_lds_dwordx4 v189, s[90:91]
	global_load_lds_dwordx4 v191, s[90:91] offset:1024
	global_load_lds_dwordx4 v193, s[90:91] offset:2048
	global_load_lds_dwordx4 v195, s[90:91] offset:3072
	v_lshlrev_b32_e32 v152, 1, v117
	v_add3_u32 v70, s25, v125, v70
	v_add_u32_e32 v172, v151, v152
	v_add_u32_e32 v181, v70, v152
	ds_read_b128 v[152:155], v172
	ds_read_b128 v[160:163], v181 offset:16384
	ds_read_b128 v[164:167], v181 offset:18432
	ds_read_b128 v[176:179], v181 offset:20480
	ds_read_b128 v[182:185], v181 offset:22528
	ds_read_b128 v[156:159], v172 offset:2048
	ds_read_b128 v[168:171], v172 offset:4096
	ds_read_b128 v[172:175], v172 offset:6144
	v_lshlrev_b32_e32 v236, 1, v116
	v_add_u32_e32 v151, v151, v236
	v_add_u32_e32 v70, v70, v236
	ds_read_b128 v[204:207], v151
	ds_read_b128 v[208:211], v70 offset:16384
	ds_read_b128 v[212:215], v70 offset:18432
	ds_read_b128 v[216:219], v70 offset:20480
	ds_read_b128 v[220:223], v70 offset:22528
	ds_read_b128 v[224:227], v151 offset:2048
	ds_read_b128 v[228:231], v151 offset:4096
	ds_read_b128 v[232:235], v151 offset:6144
	s_setprio 1
	s_waitcnt lgkmcnt(11)
	v_mfma_f32_16x16x32_bf16 v[60:63], v[152:155], v[160:163], v[60:63]
	v_mfma_f32_16x16x32_bf16 v[56:59], v[152:155], v[164:167], v[56:59]
	v_mfma_f32_16x16x32_bf16 v[52:55], v[152:155], v[176:179], v[52:55]
	v_mfma_f32_16x16x32_bf16 v[48:51], v[152:155], v[182:185], v[48:51]
	s_waitcnt lgkmcnt(10)
	v_mfma_f32_16x16x32_bf16 v[44:47], v[156:159], v[160:163], v[44:47]
	v_mfma_f32_16x16x32_bf16 v[40:43], v[156:159], v[164:167], v[40:43]
	v_mfma_f32_16x16x32_bf16 v[36:39], v[156:159], v[176:179], v[36:39]
	v_mfma_f32_16x16x32_bf16 v[32:35], v[156:159], v[182:185], v[32:35]
	s_waitcnt lgkmcnt(9)
	v_mfma_f32_16x16x32_bf16 v[28:31], v[168:171], v[160:163], v[28:31]
	v_mfma_f32_16x16x32_bf16 v[24:27], v[168:171], v[164:167], v[24:27]
	v_mfma_f32_16x16x32_bf16 v[20:23], v[168:171], v[176:179], v[20:23]
	v_mfma_f32_16x16x32_bf16 v[16:19], v[168:171], v[182:185], v[16:19]
	s_waitcnt lgkmcnt(8)
	v_mfma_f32_16x16x32_bf16 v[12:15], v[172:175], v[160:163], v[12:15]
	v_mfma_f32_16x16x32_bf16 v[8:11], v[172:175], v[164:167], v[8:11]
	v_mfma_f32_16x16x32_bf16 v[4:7], v[172:175], v[176:179], v[4:7]
	v_mfma_f32_16x16x32_bf16 v[0:3], v[172:175], v[182:185], v[0:3]
	s_waitcnt lgkmcnt(3)
	v_mfma_f32_16x16x32_bf16 v[60:63], v[204:207], v[208:211], v[60:63]
	v_mfma_f32_16x16x32_bf16 v[56:59], v[204:207], v[212:215], v[56:59]
	v_mfma_f32_16x16x32_bf16 v[52:55], v[204:207], v[216:219], v[52:55]
	v_mfma_f32_16x16x32_bf16 v[48:51], v[204:207], v[220:223], v[48:51]
	s_waitcnt lgkmcnt(2)
	v_mfma_f32_16x16x32_bf16 v[44:47], v[224:227], v[208:211], v[44:47]
	v_mfma_f32_16x16x32_bf16 v[40:43], v[224:227], v[212:215], v[40:43]
	v_mfma_f32_16x16x32_bf16 v[36:39], v[224:227], v[216:219], v[36:39]
	v_mfma_f32_16x16x32_bf16 v[32:35], v[224:227], v[220:223], v[32:35]
	s_waitcnt lgkmcnt(1)
	v_mfma_f32_16x16x32_bf16 v[28:31], v[228:231], v[208:211], v[28:31]
	v_mfma_f32_16x16x32_bf16 v[24:27], v[228:231], v[212:215], v[24:27]
	v_mfma_f32_16x16x32_bf16 v[20:23], v[228:231], v[216:219], v[20:23]
	v_mfma_f32_16x16x32_bf16 v[16:19], v[228:231], v[220:223], v[16:19]
	s_waitcnt lgkmcnt(0)
	v_mfma_f32_16x16x32_bf16 v[12:15], v[232:235], v[208:211], v[12:15]
	v_mfma_f32_16x16x32_bf16 v[8:11], v[232:235], v[212:215], v[8:11]
	v_mfma_f32_16x16x32_bf16 v[4:7], v[232:235], v[216:219], v[4:7]
	v_mfma_f32_16x16x32_bf16 v[0:3], v[232:235], v[220:223], v[0:3]
	s_setprio 0
	s_add_u32 s10, s10, 0x80
	s_addc_u32 s11, s11, 0
	s_addk_i32 s24, 0x4000
	s_cmpk_eq_i32 s10, 0x780
	s_waitcnt vmcnt(0)
	s_barrier
	s_cbranch_scc0 .LBB0_443
	ds_read_b128 v[96:99], v69 offset:32768
	ds_read_b128 v[100:103], v69 offset:34816
	ds_read_b128 v[104:107], v135 offset:49152
	ds_read_b128 v[108:111], v135 offset:51200
	ds_read_b128 v[152:155], v69 offset:36864
	ds_read_b128 v[156:159], v69 offset:38912
	ds_read_b128 v[160:163], v135 offset:53248
	ds_read_b128 v[164:167], v135 offset:55296
	ds_read_b128 v[204:207], v136 offset:32768
	ds_read_b128 v[208:211], v136 offset:34816
	ds_read_b128 v[212:215], v137 offset:49152
	ds_read_b128 v[216:219], v137 offset:51200
	ds_read_b128 v[220:223], v136 offset:36864
	ds_read_b128 v[224:227], v136 offset:38912
	ds_read_b128 v[228:231], v137 offset:53248
	ds_read_b128 v[232:235], v137 offset:55296
	s_setprio 1
	s_waitcnt lgkmcnt(9)
	v_mfma_f32_16x16x32_bf16 v[4:7], v[156:159], v[160:163], v[4:7]
	s_waitcnt lgkmcnt(8)
	v_mfma_f32_16x16x32_bf16 v[0:3], v[156:159], v[164:167], v[0:3]
	v_mfma_f32_16x16x32_bf16 v[60:63], v[96:99], v[104:107], v[60:63]
	v_mfma_f32_16x16x32_bf16 v[56:59], v[96:99], v[108:111], v[56:59]
	v_mfma_f32_16x16x32_bf16 v[52:55], v[96:99], v[160:163], v[52:55]
	v_mfma_f32_16x16x32_bf16 v[48:51], v[96:99], v[164:167], v[48:51]
	v_mfma_f32_16x16x32_bf16 v[44:47], v[100:103], v[104:107], v[44:47]
	v_mfma_f32_16x16x32_bf16 v[40:43], v[100:103], v[108:111], v[40:43]
	v_mfma_f32_16x16x32_bf16 v[36:39], v[100:103], v[160:163], v[36:39]
	v_mfma_f32_16x16x32_bf16 v[32:35], v[100:103], v[164:167], v[32:35]
	v_mfma_f32_16x16x32_bf16 v[28:31], v[152:155], v[104:107], v[28:31]
	v_mfma_f32_16x16x32_bf16 v[24:27], v[152:155], v[108:111], v[24:27]
	v_mfma_f32_16x16x32_bf16 v[20:23], v[152:155], v[160:163], v[20:23]
	v_mfma_f32_16x16x32_bf16 v[16:19], v[152:155], v[164:167], v[16:19]
	v_mfma_f32_16x16x32_bf16 v[12:15], v[156:159], v[104:107], v[12:15]
	v_mfma_f32_16x16x32_bf16 v[8:11], v[156:159], v[108:111], v[8:11]
	s_waitcnt lgkmcnt(1)
	v_mfma_f32_16x16x32_bf16 v[4:7], v[224:227], v[228:231], v[4:7]
	s_waitcnt lgkmcnt(0)
	v_mfma_f32_16x16x32_bf16 v[0:3], v[224:227], v[232:235], v[0:3]
	v_mfma_f32_16x16x32_bf16 v[60:63], v[204:207], v[212:215], v[60:63]
	v_mfma_f32_16x16x32_bf16 v[56:59], v[204:207], v[216:219], v[56:59]
	v_mfma_f32_16x16x32_bf16 v[52:55], v[204:207], v[228:231], v[52:55]
	v_mfma_f32_16x16x32_bf16 v[48:51], v[204:207], v[232:235], v[48:51]
	v_mfma_f32_16x16x32_bf16 v[44:47], v[208:211], v[212:215], v[44:47]
	v_mfma_f32_16x16x32_bf16 v[40:43], v[208:211], v[216:219], v[40:43]
	v_mfma_f32_16x16x32_bf16 v[36:39], v[208:211], v[228:231], v[36:39]
	v_mfma_f32_16x16x32_bf16 v[32:35], v[208:211], v[232:235], v[32:35]
	v_mfma_f32_16x16x32_bf16 v[28:31], v[220:223], v[212:215], v[28:31]
	v_mfma_f32_16x16x32_bf16 v[24:27], v[220:223], v[216:219], v[24:27]
	v_mfma_f32_16x16x32_bf16 v[20:23], v[220:223], v[228:231], v[20:23]
	v_mfma_f32_16x16x32_bf16 v[16:19], v[220:223], v[232:235], v[16:19]
	v_mfma_f32_16x16x32_bf16 v[12:15], v[224:227], v[212:215], v[12:15]
	v_mfma_f32_16x16x32_bf16 v[8:11], v[224:227], v[216:219], v[8:11]
	s_setprio 0
	s_barrier
	ds_write2_b32 v134, v60, v56 offset1:16
	ds_write2_b32 v134, v61, v57 offset0:132 offset1:148
	v_add_u32_e32 v56, 0x400, v134
	ds_write2_b32 v56, v62, v58 offset0:8 offset1:24
	ds_write2_b32 v56, v63, v59 offset0:140 offset1:156
	ds_write2_b32 v134, v52, v48 offset0:32 offset1:48
	ds_write2_b32 v134, v53, v49 offset0:164 offset1:180
	ds_write2_b32 v56, v54, v50 offset0:40 offset1:56
	ds_write2_b32 v56, v55, v51 offset0:172 offset1:188
	v_add_u32_e32 v48, 0x2000, v134
	ds_write2_b32 v48, v44, v40 offset0:64 offset1:80
	ds_write2_b32 v48, v45, v41 offset0:196 offset1:212
	v_add_u32_e32 v40, 0x2400, v134
	ds_write2_b32 v40, v46, v42 offset0:72 offset1:88
	ds_write2_b32 v40, v47, v43 offset0:204 offset1:220
	ds_write2_b32 v48, v36, v32 offset0:96 offset1:112
	ds_write2_b32 v48, v37, v33 offset0:228 offset1:244
	ds_write2_b32 v40, v38, v34 offset0:104 offset1:120
	ds_write2_b32 v40, v39, v35 offset0:236 offset1:252
	v_add_u32_e32 v32, 0x4000, v134
	ds_write2_b32 v32, v28, v24 offset0:128 offset1:144
	v_add_u32_e32 v24, 0x4400, v134
	ds_write2_b32 v24, v29, v25 offset0:4 offset1:20
	ds_write2_b32 v24, v30, v26 offset0:136 offset1:152
	v_add_u32_e32 v25, 0x4800, v134
	ds_write2_b32 v25, v31, v27 offset0:12 offset1:28
	ds_write2_b32 v32, v20, v16 offset0:160 offset1:176
	ds_write2_b32 v24, v21, v17 offset0:36 offset1:52
	ds_write2_b32 v24, v22, v18 offset0:168 offset1:184
	ds_write2_b32 v25, v23, v19 offset0:44 offset1:60
	v_add_u32_e32 v16, 0x6000, v134
	ds_write2_b32 v16, v12, v8 offset0:192 offset1:208
	v_add_u32_e32 v8, 0x6400, v134
	ds_write2_b32 v8, v13, v9 offset0:68 offset1:84
	ds_write2_b32 v8, v14, v10 offset0:200 offset1:216
	v_add_u32_e32 v9, 0x6800, v134
	ds_write2_b32 v9, v15, v11 offset0:76 offset1:92
	ds_write2_b32 v16, v4, v0 offset0:224 offset1:240
	ds_write2_b32 v8, v5, v1 offset0:100 offset1:116
	ds_write2_b32 v8, v6, v2 offset0:232 offset1:248
	ds_write2_b32 v9, v7, v3 offset0:108 offset1:124
	v_or_b32_e32 v0, s22, v113
	v_lshlrev_b32_e32 v70, 2, v0
	v_lshl_add_u64 v[0:1], s[12:13], 0, v[70:71]
	v_lshl_add_u64 v[2:3], s[8:9], 0, v[70:71]
	v_add_u32_e32 v4, s23, v146
	s_mov_b32 s10, 0
	s_waitcnt lgkmcnt(0)
	s_barrier

.LBB0_604:
	s_ashr_i32 s10, s14, 31
	s_lshr_b32 s10, s10, 27
	s_add_i32 s10, s14, s10
	s_ashr_i32 s10, s10, 5
	s_lshl_b32 s15, s10, 7
	s_lshl_b32 s10, s10, 12
	s_lshl_b32 s11, s14, 7
	s_sub_i32 s16, s11, s10
	v_add_u32_e32 v0, s16, v106
	v_ashrrev_i32_e32 v1, 31, v0
	v_add_u32_e32 v2, 0x4000, v107
	v_lshlrev_b64 v[0:1], 11, v[0:1]
	v_readfirstlane_b32 s11, v2
	v_lshl_add_u64 v[0:1], v[66:67], 0, v[0:1]
	s_mov_b32 m0, s11
	v_readfirstlane_b32 s11, v107
	global_load_lds_dwordx4 v[0:1], off
	v_add_u32_e32 v0, s15, v106
	v_ashrrev_i32_e32 v1, 31, v0
	v_lshlrev_b64 v[0:1], 11, v[0:1]
	v_lshl_add_u64 v[2:3], v[72:73], 0, v[0:1]
	s_mov_b32 m0, s11
	v_readfirstlane_b32 s11, v130
	global_load_lds_dwordx4 v[2:3], off
	v_add_u32_e32 v2, s16, v108
	v_ashrrev_i32_e32 v3, 31, v2
	v_lshlrev_b64 v[2:3], 11, v[2:3]
	v_lshl_add_u64 v[2:3], v[68:69], 0, v[2:3]
	s_mov_b32 m0, s11
	v_add_u32_e32 v4, 0x400, v107
	global_load_lds_dwordx4 v[2:3], off
	v_add_u32_e32 v2, s15, v108
	v_ashrrev_i32_e32 v3, 31, v2
	v_lshlrev_b64 v[2:3], 11, v[2:3]
	v_readfirstlane_b32 s11, v4
	v_lshl_add_u64 v[2:3], v[74:75], 0, v[2:3]
	s_mov_b32 m0, s11
	v_readfirstlane_b32 s11, v131
	global_load_lds_dwordx4 v[2:3], off
	v_add_u32_e32 v2, s16, v110
	v_ashrrev_i32_e32 v3, 31, v2
	v_lshlrev_b64 v[2:3], 11, v[2:3]
	v_lshl_add_u64 v[2:3], v[66:67], 0, v[2:3]
	s_mov_b32 m0, s11
	v_add_u32_e32 v4, 0x800, v107
	global_load_lds_dwordx4 v[2:3], off
	v_add_u32_e32 v2, s15, v110
	v_ashrrev_i32_e32 v3, 31, v2
	v_lshlrev_b64 v[2:3], 11, v[2:3]
	v_readfirstlane_b32 s11, v4
	v_lshl_add_u64 v[2:3], v[72:73], 0, v[2:3]
	s_mov_b32 m0, s11
	v_readfirstlane_b32 s11, v132
	global_load_lds_dwordx4 v[2:3], off
	v_add_u32_e32 v2, s16, v112
	v_ashrrev_i32_e32 v3, 31, v2
	v_lshlrev_b64 v[2:3], 11, v[2:3]
	v_lshl_add_u64 v[2:3], v[70:71], 0, v[2:3]
	s_mov_b32 m0, s11
	v_add_u32_e32 v4, 0xc00, v107
	global_load_lds_dwordx4 v[2:3], off
	v_add_u32_e32 v2, s15, v112
	v_ashrrev_i32_e32 v3, 31, v2
	v_lshlrev_b64 v[2:3], 11, v[2:3]
	v_readfirstlane_b32 s11, v4
	v_lshl_add_u64 v[2:3], v[76:77], 0, v[2:3]
	s_mov_b32 m0, s11
	v_lshl_add_u64 v[92:93], v[80:81], 0, v[0:1]
	global_load_lds_dwordx4 v[2:3], off
	v_subrev_u32_e32 v0, s10, v123
	v_ashrrev_i32_e32 v1, 31, v0
	v_lshlrev_b64 v[0:1], 11, v[0:1]
	v_lshl_add_u64 v[94:95], v[82:83], 0, v[0:1]
	v_add_u32_e32 v0, s15, v124
	v_ashrrev_i32_e32 v1, 31, v0
	v_lshlrev_b64 v[0:1], 11, v[0:1]
	v_lshl_add_u64 v[96:97], v[84:85], 0, v[0:1]
	v_subrev_u32_e32 v0, s10, v125
	v_ashrrev_i32_e32 v1, 31, v0
	v_lshlrev_b64 v[0:1], 11, v[0:1]
	v_lshl_add_u64 v[98:99], v[78:79], 0, v[0:1]
	v_add_u32_e32 v0, s15, v126
	v_ashrrev_i32_e32 v1, 31, v0
	v_lshlrev_b64 v[0:1], 11, v[0:1]
	v_lshl_add_u64 v[100:101], v[80:81], 0, v[0:1]
	v_subrev_u32_e32 v0, s10, v64
	v_ashrrev_i32_e32 v1, 31, v0
	v_lshlrev_b64 v[0:1], 11, v[0:1]
	v_subrev_u32_e32 v2, s10, v122
	v_lshl_add_u64 v[102:103], v[86:87], 0, v[0:1]
	v_add_u32_e32 v0, s15, v127
	v_ashrrev_i32_e32 v3, 31, v2
	v_ashrrev_i32_e32 v1, 31, v0
	v_lshlrev_b64 v[2:3], 11, v[2:3]
	v_lshlrev_b64 v[0:1], 11, v[0:1]
	v_lshl_add_u64 v[90:91], v[78:79], 0, v[2:3]
	v_lshl_add_u64 v[104:105], v[88:89], 0, v[0:1]
	s_mov_b64 s[10:11], 0
	s_mov_b32 s17, 0
	v_mov_b32_e32 v0, 0
	v_mov_b32_e32 v1, v65
	v_mov_b32_e32 v2, v65
	v_mov_b32_e32 v3, v65
	v_mov_b32_e32 v4, 0
	v_mov_b32_e32 v5, v65
	v_mov_b32_e32 v6, v65
	v_mov_b32_e32 v7, v65
	v_mov_b32_e32 v8, 0
	v_mov_b32_e32 v9, v65
	v_mov_b32_e32 v10, v65
	v_mov_b32_e32 v11, v65
	v_mov_b32_e32 v12, 0
	v_mov_b32_e32 v13, v65
	v_mov_b32_e32 v14, v65
	v_mov_b32_e32 v15, v65
	v_mov_b32_e32 v16, 0
	v_mov_b32_e32 v17, v65
	v_mov_b32_e32 v18, v65
	v_mov_b32_e32 v19, v65
	v_mov_b32_e32 v20, 0
	v_mov_b32_e32 v21, v65
	v_mov_b32_e32 v22, v65
	v_mov_b32_e32 v23, v65
	v_mov_b32_e32 v24, 0
	v_mov_b32_e32 v25, v65
	v_mov_b32_e32 v26, v65
	v_mov_b32_e32 v27, v65
	v_mov_b32_e32 v28, 0
	v_mov_b32_e32 v29, v65
	v_mov_b32_e32 v30, v65
	v_mov_b32_e32 v31, v65
	v_mov_b32_e32 v32, 0
	v_mov_b32_e32 v33, v65
	v_mov_b32_e32 v34, v65
	v_mov_b32_e32 v35, v65
	v_mov_b32_e32 v36, 0
	v_mov_b32_e32 v37, v65
	v_mov_b32_e32 v38, v65
	v_mov_b32_e32 v39, v65
	v_mov_b32_e32 v40, 0
	v_mov_b32_e32 v41, v65
	v_mov_b32_e32 v42, v65
	v_mov_b32_e32 v43, v65
	v_mov_b32_e32 v44, 0
	v_mov_b32_e32 v45, v65
	v_mov_b32_e32 v46, v65
	v_mov_b32_e32 v47, v65
	v_mov_b32_e32 v48, 0
	v_mov_b32_e32 v49, v65
	v_mov_b32_e32 v50, v65
	v_mov_b32_e32 v51, v65
	v_mov_b32_e32 v52, 0
	v_mov_b32_e32 v53, v65
	v_mov_b32_e32 v54, v65
	v_mov_b32_e32 v55, v65
	v_mov_b32_e32 v56, 0
	v_mov_b32_e32 v57, v65
	v_mov_b32_e32 v58, v65
	v_mov_b32_e32 v59, v65
	v_mov_b32_e32 v60, 0
	v_mov_b32_e32 v61, v65
	v_mov_b32_e32 v62, v65
	v_mov_b32_e32 v63, v65
	s_waitcnt vmcnt(0) lgkmcnt(0)
	s_barrier
	v_add3_u32 v182, 0, v133, v134
	v_add_u32_e32 v183, 0x4000, v182
	s_nop 0
	v_readfirstlane_b32 s82, v183
	v_lshl_add_u32 v183, v109, 1, 0
	s_nop 0
	v_readfirstlane_b32 s83, v182
	v_add3_u32 v183, v183, v134, s13
	s_nop 0
	v_readfirstlane_b32 s84, v183
	v_add_u32_e32 v183, 0x400, v182
	s_nop 0
	v_readfirstlane_b32 s85, v183
	v_lshl_add_u32 v183, v111, 1, 0
	v_add3_u32 v183, v183, v134, s13
	s_nop 0
	v_readfirstlane_b32 s86, v183
	v_add_u32_e32 v183, 0x800, v182
	s_nop 0
	v_readfirstlane_b32 s87, v183
	v_lshl_add_u32 v183, v113, 1, 0
	v_add3_u32 v183, v183, v134, s13
	s_nop 0
	v_readfirstlane_b32 s88, v183
	v_add_u32_e32 v182, 0xc00, v182
	s_nop 0
	v_readfirstlane_b32 s89, v182
	v_subrev_u32_e32 v184, s52, v90
	v_subrev_u32_e32 v185, s52, v92
	v_subrev_u32_e32 v186, s52, v94
	v_subrev_u32_e32 v187, s52, v96
	v_subrev_u32_e32 v188, s52, v98
	v_subrev_u32_e32 v189, s52, v100
	v_subrev_u32_e32 v190, s52, v102
	v_subrev_u32_e32 v191, s52, v104
	v_subrev_u32_e32 v187, 0x400, v187
	v_subrev_u32_e32 v186, 0x400, v186
	v_subrev_u32_e32 v189, 0x800, v189
	v_subrev_u32_e32 v188, 0x800, v188
	v_subrev_u32_e32 v191, 0xc00, v191
	v_subrev_u32_e32 v190, 0xc00, v190
	s_and_b32 s19, s17, 0x4000
	s_xor_b32 s18, s19, 0x4000
	s_lshl_b32 s18, s18, 1
	s_add_i32 s18, s18, 32
	s_lshl_b32 s19, s19, 1
	s_add_i32 s19, s19, 32
.LBB0_605:
	s_xor_b32 s18, s18, 0x8000
	s_xor_b32 s19, s19, 0x8000
	s_add_u32 s90, s52, s10
	s_addc_u32 s91, s53, s11
	s_add_i32 m0, s19, s83
	v_lshl_add_u32 v137, v114, 1, s18
	global_load_lds_dwordx4 v185, s[90:91]
	global_load_lds_dwordx4 v187, s[90:91] offset:1024
	global_load_lds_dwordx4 v189, s[90:91] offset:2048
	global_load_lds_dwordx4 v191, s[90:91] offset:3072
	s_add_i32 m0, s19, s82
	v_lshl_add_u32 v170, v115, 1, s18
	global_load_lds_dwordx4 v184, s[90:91]
	global_load_lds_dwordx4 v186, s[90:91] offset:1024
	global_load_lds_dwordx4 v188, s[90:91] offset:2048
	global_load_lds_dwordx4 v190, s[90:91] offset:3072
	v_add_u32_e32 v158, v137, v135
	v_add_u32_e32 v166, v170, v135
	s_add_u32 s10, s10, 0x80
	s_addc_u32 s11, s11, 0
	ds_read_b128 v[138:141], v158
	ds_read_b128 v[146:149], v166 offset:16384
	ds_read_b128 v[150:153], v166 offset:18432
	ds_read_b128 v[162:165], v166 offset:20480
	ds_read_b128 v[166:169], v166 offset:22528
	ds_read_b128 v[142:145], v158 offset:2048
	ds_read_b128 v[154:157], v158 offset:4096
	ds_read_b128 v[158:161], v158 offset:6144
	v_add_u32_e32 v137, v137, v136
	v_add_u32_e32 v236, v170, v136
	ds_read_b128 v[204:207], v137
	ds_read_b128 v[208:211], v236 offset:16384
	ds_read_b128 v[212:215], v236 offset:18432
	ds_read_b128 v[216:219], v236 offset:20480
	ds_read_b128 v[220:223], v236 offset:22528
	ds_read_b128 v[224:227], v137 offset:2048
	ds_read_b128 v[228:231], v137 offset:4096
	ds_read_b128 v[232:235], v137 offset:6144
	s_setprio 1
	s_waitcnt lgkmcnt(11)
	v_mfma_f32_16x16x32_bf16 v[60:63], v[138:141], v[146:149], v[60:63]
	v_mfma_f32_16x16x32_bf16 v[56:59], v[138:141], v[150:153], v[56:59]
	v_mfma_f32_16x16x32_bf16 v[52:55], v[138:141], v[162:165], v[52:55]
	v_mfma_f32_16x16x32_bf16 v[48:51], v[138:141], v[166:169], v[48:51]
	s_waitcnt lgkmcnt(10)
	v_mfma_f32_16x16x32_bf16 v[44:47], v[142:145], v[146:149], v[44:47]
	v_mfma_f32_16x16x32_bf16 v[40:43], v[142:145], v[150:153], v[40:43]
	v_mfma_f32_16x16x32_bf16 v[36:39], v[142:145], v[162:165], v[36:39]
	v_mfma_f32_16x16x32_bf16 v[32:35], v[142:145], v[166:169], v[32:35]
	s_waitcnt lgkmcnt(9)
	v_mfma_f32_16x16x32_bf16 v[28:31], v[154:157], v[146:149], v[28:31]
	v_mfma_f32_16x16x32_bf16 v[24:27], v[154:157], v[150:153], v[24:27]
	v_mfma_f32_16x16x32_bf16 v[20:23], v[154:157], v[162:165], v[20:23]
	v_mfma_f32_16x16x32_bf16 v[16:19], v[154:157], v[166:169], v[16:19]
	s_waitcnt lgkmcnt(8)
	v_mfma_f32_16x16x32_bf16 v[12:15], v[158:161], v[146:149], v[12:15]
	v_mfma_f32_16x16x32_bf16 v[8:11], v[158:161], v[150:153], v[8:11]
	v_mfma_f32_16x16x32_bf16 v[4:7], v[158:161], v[162:165], v[4:7]
	v_mfma_f32_16x16x32_bf16 v[0:3], v[158:161], v[166:169], v[0:3]
	s_waitcnt lgkmcnt(3)
	v_mfma_f32_16x16x32_bf16 v[60:63], v[204:207], v[208:211], v[60:63]
	v_mfma_f32_16x16x32_bf16 v[56:59], v[204:207], v[212:215], v[56:59]
	v_mfma_f32_16x16x32_bf16 v[52:55], v[204:207], v[216:219], v[52:55]
	v_mfma_f32_16x16x32_bf16 v[48:51], v[204:207], v[220:223], v[48:51]
	s_waitcnt lgkmcnt(2)
	v_mfma_f32_16x16x32_bf16 v[44:47], v[224:227], v[208:211], v[44:47]
	v_mfma_f32_16x16x32_bf16 v[40:43], v[224:227], v[212:215], v[40:43]
	v_mfma_f32_16x16x32_bf16 v[36:39], v[224:227], v[216:219], v[36:39]
	v_mfma_f32_16x16x32_bf16 v[32:35], v[224:227], v[220:223], v[32:35]
	s_waitcnt lgkmcnt(1)
	v_mfma_f32_16x16x32_bf16 v[28:31], v[228:231], v[208:211], v[28:31]
	v_mfma_f32_16x16x32_bf16 v[24:27], v[228:231], v[212:215], v[24:27]
	v_mfma_f32_16x16x32_bf16 v[20:23], v[228:231], v[216:219], v[20:23]
	v_mfma_f32_16x16x32_bf16 v[16:19], v[228:231], v[220:223], v[16:19]
	s_waitcnt lgkmcnt(0)
	v_mfma_f32_16x16x32_bf16 v[12:15], v[232:235], v[208:211], v[12:15]
	v_mfma_f32_16x16x32_bf16 v[8:11], v[232:235], v[212:215], v[8:11]
	v_mfma_f32_16x16x32_bf16 v[4:7], v[232:235], v[216:219], v[4:7]
	v_mfma_f32_16x16x32_bf16 v[0:3], v[232:235], v[220:223], v[0:3]
	s_setprio 0
	s_cmpk_eq_i32 s10, 0x780
	s_waitcnt vmcnt(0)
	s_barrier
	s_cbranch_scc0 .LBB0_605
	ds_read_b128 v[90:93], v116 offset:55296
	ds_read_b128 v[94:97], v116 offset:53248
	ds_read_b128 v[98:101], v117 offset:38912
	ds_read_b128 v[102:105], v117 offset:36864
	ds_read_b128 v[138:141], v116 offset:51200
	ds_read_b128 v[142:145], v116 offset:49152
	ds_read_b128 v[146:149], v117 offset:34816
	ds_read_b128 v[150:153], v117 offset:32768
	ds_read_b128 v[204:207], v118 offset:32768
	ds_read_b128 v[208:211], v118 offset:34816
	ds_read_b128 v[212:215], v119 offset:49152
	ds_read_b128 v[216:219], v119 offset:51200
	ds_read_b128 v[220:223], v118 offset:36864
	ds_read_b128 v[224:227], v118 offset:38912
	ds_read_b128 v[228:231], v119 offset:53248
	ds_read_b128 v[232:235], v119 offset:55296
	s_setprio 1
	s_waitcnt lgkmcnt(13)
	v_mfma_f32_16x16x32_bf16 v[0:3], v[98:101], v[90:93], v[0:3]
	s_waitcnt lgkmcnt(8)
	v_mfma_f32_16x16x32_bf16 v[60:63], v[150:153], v[142:145], v[60:63]
	v_mfma_f32_16x16x32_bf16 v[56:59], v[150:153], v[138:141], v[56:59]
	v_mfma_f32_16x16x32_bf16 v[52:55], v[150:153], v[94:97], v[52:55]
	v_mfma_f32_16x16x32_bf16 v[48:51], v[150:153], v[90:93], v[48:51]
	v_mfma_f32_16x16x32_bf16 v[44:47], v[146:149], v[142:145], v[44:47]
	v_mfma_f32_16x16x32_bf16 v[40:43], v[146:149], v[138:141], v[40:43]
	v_mfma_f32_16x16x32_bf16 v[36:39], v[146:149], v[94:97], v[36:39]
	v_mfma_f32_16x16x32_bf16 v[32:35], v[146:149], v[90:93], v[32:35]
	v_mfma_f32_16x16x32_bf16 v[28:31], v[102:105], v[142:145], v[28:31]
	v_mfma_f32_16x16x32_bf16 v[24:27], v[102:105], v[138:141], v[24:27]
	v_mfma_f32_16x16x32_bf16 v[20:23], v[102:105], v[94:97], v[20:23]
	v_mfma_f32_16x16x32_bf16 v[16:19], v[102:105], v[90:93], v[16:19]
	v_mfma_f32_16x16x32_bf16 v[12:15], v[98:101], v[142:145], v[12:15]
	v_mfma_f32_16x16x32_bf16 v[8:11], v[98:101], v[138:141], v[8:11]
	v_mfma_f32_16x16x32_bf16 v[4:7], v[98:101], v[94:97], v[4:7]
	s_waitcnt lgkmcnt(0)
	v_mfma_f32_16x16x32_bf16 v[0:3], v[224:227], v[232:235], v[0:3]
	v_mfma_f32_16x16x32_bf16 v[60:63], v[204:207], v[212:215], v[60:63]
	v_mfma_f32_16x16x32_bf16 v[56:59], v[204:207], v[216:219], v[56:59]
	v_mfma_f32_16x16x32_bf16 v[52:55], v[204:207], v[228:231], v[52:55]
	v_mfma_f32_16x16x32_bf16 v[48:51], v[204:207], v[232:235], v[48:51]
	v_mfma_f32_16x16x32_bf16 v[44:47], v[208:211], v[212:215], v[44:47]
	v_mfma_f32_16x16x32_bf16 v[40:43], v[208:211], v[216:219], v[40:43]
	v_mfma_f32_16x16x32_bf16 v[36:39], v[208:211], v[228:231], v[36:39]
	v_mfma_f32_16x16x32_bf16 v[32:35], v[208:211], v[232:235], v[32:35]
	v_mfma_f32_16x16x32_bf16 v[28:31], v[220:223], v[212:215], v[28:31]
	v_mfma_f32_16x16x32_bf16 v[24:27], v[220:223], v[216:219], v[24:27]
	v_mfma_f32_16x16x32_bf16 v[20:23], v[220:223], v[228:231], v[20:23]
	v_mfma_f32_16x16x32_bf16 v[16:19], v[220:223], v[232:235], v[16:19]
	v_mfma_f32_16x16x32_bf16 v[12:15], v[224:227], v[212:215], v[12:15]
	v_mfma_f32_16x16x32_bf16 v[8:11], v[224:227], v[216:219], v[8:11]
	v_mfma_f32_16x16x32_bf16 v[4:7], v[224:227], v[228:231], v[4:7]
	s_setprio 0
	s_barrier
	ds_write2_b32 v120, v60, v56 offset1:16
	ds_write2_b32 v120, v61, v57 offset0:132 offset1:148
	v_add_u32_e32 v56, 0x400, v120
	ds_write2_b32 v56, v62, v58 offset0:8 offset1:24
	ds_write2_b32 v56, v63, v59 offset0:140 offset1:156
	ds_write2_b32 v120, v52, v48 offset0:32 offset1:48
	ds_write2_b32 v120, v53, v49 offset0:164 offset1:180
	ds_write2_b32 v56, v54, v50 offset0:40 offset1:56
	ds_write2_b32 v56, v55, v51 offset0:172 offset1:188
	v_add_u32_e32 v48, 0x2000, v120
	ds_write2_b32 v48, v44, v40 offset0:64 offset1:80
	ds_write2_b32 v48, v45, v41 offset0:196 offset1:212
	v_add_u32_e32 v40, 0x2400, v120
	ds_write2_b32 v40, v46, v42 offset0:72 offset1:88
	ds_write2_b32 v40, v47, v43 offset0:204 offset1:220
	ds_write2_b32 v48, v36, v32 offset0:96 offset1:112
	ds_write2_b32 v48, v37, v33 offset0:228 offset1:244
	ds_write2_b32 v40, v38, v34 offset0:104 offset1:120
	ds_write2_b32 v40, v39, v35 offset0:236 offset1:252
	v_add_u32_e32 v32, 0x4000, v120
	ds_write2_b32 v32, v28, v24 offset0:128 offset1:144
	v_add_u32_e32 v24, 0x4400, v120
	ds_write2_b32 v24, v29, v25 offset0:4 offset1:20
	ds_write2_b32 v24, v30, v26 offset0:136 offset1:152
	v_add_u32_e32 v25, 0x4800, v120
	ds_write2_b32 v25, v31, v27 offset0:12 offset1:28
	ds_write2_b32 v32, v20, v16 offset0:160 offset1:176
	ds_write2_b32 v24, v21, v17 offset0:36 offset1:52
	ds_write2_b32 v24, v22, v18 offset0:168 offset1:184
	ds_write2_b32 v25, v23, v19 offset0:44 offset1:60
	v_add_u32_e32 v16, 0x6000, v120
	ds_write2_b32 v16, v12, v8 offset0:192 offset1:208
	v_add_u32_e32 v8, 0x6400, v120
	ds_write2_b32 v8, v13, v9 offset0:68 offset1:84
	ds_write2_b32 v8, v14, v10 offset0:200 offset1:216
	v_add_u32_e32 v9, 0x6800, v120
	ds_write2_b32 v9, v15, v11 offset0:76 offset1:92
	ds_write2_b32 v16, v4, v0 offset0:224 offset1:240
	ds_write2_b32 v8, v5, v1 offset0:100 offset1:116
	ds_write2_b32 v8, v6, v2 offset0:232 offset1:248
	ds_write2_b32 v9, v7, v3 offset0:108 offset1:124
	v_or_b32_e32 v0, s16, v121
	v_ashrrev_i32_e32 v1, 31, v0
	v_lshl_add_u64 v[0:1], v[0:1], 1, s[4:5]
	v_add_u32_e32 v2, s15, v128
	s_mov_b32 s10, 0
	s_waitcnt lgkmcnt(0)
	s_barrier

.LBB0_615:
	s_ashr_i32 s12, s7, 31
	s_lshr_b32 s12, s12, 29
	s_add_i32 s12, s7, s12
	s_ashr_i32 s13, s12, 3
	s_lshl_b32 s14, s13, 10
	s_lshl_b32 s7, s7, 7
	s_sub_i32 s12, s7, s14
	v_add_u32_e32 v0, s13, v104
	s_add_i32 s12, s12, s6
	v_lshlrev_b32_e32 v2, 7, v0
	v_add_u32_e32 v0, s12, v105
	v_ashrrev_i32_e32 v1, 31, v0
	v_add_u32_e32 v3, 0x4000, v106
	v_lshlrev_b64 v[0:1], 11, v[0:1]
	v_readfirstlane_b32 s15, v3
	v_lshl_add_u64 v[0:1], v[64:65], 0, v[0:1]
	s_mov_b32 m0, s15
	v_readfirstlane_b32 s15, v106
	global_load_lds_dwordx4 v[0:1], off
	v_add_u32_e32 v0, v2, v105
	v_ashrrev_i32_e32 v1, 31, v0
	v_lshlrev_b64 v[0:1], 11, v[0:1]
	v_lshl_add_u64 v[0:1], v[70:71], 0, v[0:1]
	s_mov_b32 m0, s15
	v_readfirstlane_b32 s15, v130
	global_load_lds_dwordx4 v[0:1], off
	v_add_u32_e32 v0, s12, v107
	v_ashrrev_i32_e32 v1, 31, v0
	v_lshlrev_b64 v[0:1], 11, v[0:1]
	v_lshl_add_u64 v[0:1], v[66:67], 0, v[0:1]
	s_mov_b32 m0, s15
	v_add_u32_e32 v3, 0x400, v106
	global_load_lds_dwordx4 v[0:1], off
	v_add_u32_e32 v0, v2, v107
	v_ashrrev_i32_e32 v1, 31, v0
	v_lshlrev_b64 v[0:1], 11, v[0:1]
	v_readfirstlane_b32 s15, v3
	v_lshl_add_u64 v[0:1], v[72:73], 0, v[0:1]
	s_mov_b32 m0, s15
	v_readfirstlane_b32 s15, v131
	global_load_lds_dwordx4 v[0:1], off
	v_add_u32_e32 v0, s12, v109
	v_ashrrev_i32_e32 v1, 31, v0
	v_lshlrev_b64 v[0:1], 11, v[0:1]
	v_lshl_add_u64 v[0:1], v[64:65], 0, v[0:1]
	s_mov_b32 m0, s15
	v_add_u32_e32 v3, 0x800, v106
	global_load_lds_dwordx4 v[0:1], off
	v_add_u32_e32 v0, v2, v109
	v_ashrrev_i32_e32 v1, 31, v0
	v_lshlrev_b64 v[0:1], 11, v[0:1]
	v_readfirstlane_b32 s15, v3
	v_lshl_add_u64 v[0:1], v[70:71], 0, v[0:1]
	s_mov_b32 m0, s15
	v_readfirstlane_b32 s15, v132
	global_load_lds_dwordx4 v[0:1], off
	v_add_u32_e32 v0, s12, v111
	v_ashrrev_i32_e32 v1, 31, v0
	v_lshlrev_b64 v[0:1], 11, v[0:1]
	v_lshl_add_u64 v[0:1], v[68:69], 0, v[0:1]
	s_mov_b32 m0, s15
	s_add_i32 s7, s7, s6
	global_load_lds_dwordx4 v[0:1], off
	v_add_u32_e32 v0, v2, v111
	v_ashrrev_i32_e32 v1, 31, v0
	v_add_u32_e32 v2, 0xc00, v106
	v_lshlrev_b64 v[0:1], 11, v[0:1]
	v_readfirstlane_b32 s15, v2
	v_lshl_add_u64 v[0:1], v[74:75], 0, v[0:1]
	s_mov_b32 m0, s15
	s_lshl_b32 s13, s13, 7
	global_load_lds_dwordx4 v[0:1], off
	v_add_u32_e32 v0, s7, v105
	v_subrev_u32_e32 v0, s14, v0
	v_ashrrev_i32_e32 v1, 31, v0
	v_lshlrev_b64 v[0:1], 11, v[0:1]
	v_lshl_add_u64 v[88:89], v[76:77], 0, v[0:1]
	v_add_u32_e32 v0, s13, v121
	v_ashrrev_i32_e32 v1, 31, v0
	v_lshlrev_b64 v[0:1], 11, v[0:1]
	v_lshl_add_u64 v[90:91], v[78:79], 0, v[0:1]
	v_add_u32_e32 v0, s7, v122
	v_subrev_u32_e32 v0, s14, v0
	v_ashrrev_i32_e32 v1, 31, v0
	v_lshlrev_b64 v[0:1], 11, v[0:1]
	v_lshl_add_u64 v[92:93], v[80:81], 0, v[0:1]
	v_add_u32_e32 v0, s13, v123
	v_ashrrev_i32_e32 v1, 31, v0
	v_lshlrev_b64 v[0:1], 11, v[0:1]
	v_lshl_add_u64 v[94:95], v[82:83], 0, v[0:1]
	v_add_u32_e32 v0, s7, v124
	v_subrev_u32_e32 v0, s14, v0
	v_ashrrev_i32_e32 v1, 31, v0
	v_lshlrev_b64 v[0:1], 11, v[0:1]
	v_lshl_add_u64 v[96:97], v[76:77], 0, v[0:1]
	v_add_u32_e32 v0, s13, v125
	v_ashrrev_i32_e32 v1, 31, v0
	v_lshlrev_b64 v[0:1], 11, v[0:1]
	v_lshl_add_u64 v[98:99], v[78:79], 0, v[0:1]
	v_add_u32_e32 v0, s7, v126
	v_subrev_u32_e32 v0, s14, v0
	v_ashrrev_i32_e32 v1, 31, v0
	v_lshlrev_b64 v[0:1], 11, v[0:1]
	v_lshl_add_u64 v[100:101], v[84:85], 0, v[0:1]
	v_add_u32_e32 v0, s13, v127
	v_ashrrev_i32_e32 v1, 31, v0
	v_lshlrev_b64 v[0:1], 11, v[0:1]
	v_lshl_add_u64 v[102:103], v[86:87], 0, v[0:1]
	v_mov_b32_e32 v0, 0
	s_mov_b32 s14, 0
	s_mov_b64 s[6:7], 0
	v_mov_b32_e32 v1, v0
	v_mov_b32_e32 v2, v0
	v_mov_b32_e32 v3, v0
	v_mov_b32_e32 v4, v0
	v_mov_b32_e32 v5, v0
	v_mov_b32_e32 v6, v0
	v_mov_b32_e32 v7, v0
	v_mov_b32_e32 v8, v0
	v_mov_b32_e32 v9, v0
	v_mov_b32_e32 v10, v0
	v_mov_b32_e32 v11, v0
	v_mov_b32_e32 v12, v0
	v_mov_b32_e32 v13, v0
	v_mov_b32_e32 v14, v0
	v_mov_b32_e32 v15, v0
	v_mov_b32_e32 v16, v0
	v_mov_b32_e32 v17, v0
	v_mov_b32_e32 v18, v0
	v_mov_b32_e32 v19, v0
	v_mov_b32_e32 v20, v0
	v_mov_b32_e32 v21, v0
	v_mov_b32_e32 v22, v0
	v_mov_b32_e32 v23, v0
	v_mov_b32_e32 v24, v0
	v_mov_b32_e32 v25, v0
	v_mov_b32_e32 v26, v0
	v_mov_b32_e32 v27, v0
	v_mov_b32_e32 v28, v0
	v_mov_b32_e32 v29, v0
	v_mov_b32_e32 v30, v0
	v_mov_b32_e32 v31, v0
	v_mov_b32_e32 v32, v0
	v_mov_b32_e32 v33, v0
	v_mov_b32_e32 v34, v0
	v_mov_b32_e32 v35, v0
	v_mov_b32_e32 v36, v0
	v_mov_b32_e32 v37, v0
	v_mov_b32_e32 v38, v0
	v_mov_b32_e32 v39, v0
	v_mov_b32_e32 v40, v0
	v_mov_b32_e32 v41, v0
	v_mov_b32_e32 v42, v0
	v_mov_b32_e32 v43, v0
	v_mov_b32_e32 v44, v0
	v_mov_b32_e32 v45, v0
	v_mov_b32_e32 v46, v0
	v_mov_b32_e32 v47, v0
	v_mov_b32_e32 v48, v0
	v_mov_b32_e32 v49, v0
	v_mov_b32_e32 v50, v0
	v_mov_b32_e32 v51, v0
	v_mov_b32_e32 v52, v0
	v_mov_b32_e32 v53, v0
	v_mov_b32_e32 v54, v0
	v_mov_b32_e32 v55, v0
	v_mov_b32_e32 v56, v0
	v_mov_b32_e32 v57, v0
	v_mov_b32_e32 v58, v0
	v_mov_b32_e32 v59, v0
	v_mov_b32_e32 v60, v0
	v_mov_b32_e32 v61, v0
	v_mov_b32_e32 v62, v0
	v_mov_b32_e32 v63, v0
	s_waitcnt vmcnt(0) lgkmcnt(0)
	s_barrier
	v_add3_u32 v182, 0, v133, v134
	v_add_u32_e32 v183, 0x4000, v182
	s_nop 0
	v_readfirstlane_b32 s82, v183
	v_lshl_add_u32 v183, v108, 1, 0
	s_nop 0
	v_readfirstlane_b32 s83, v182
	v_add3_u32 v183, v183, v134, s9
	s_nop 0
	v_readfirstlane_b32 s84, v183
	v_add_u32_e32 v183, 0x400, v182
	s_nop 0
	v_readfirstlane_b32 s85, v183
	v_lshl_add_u32 v183, v110, 1, 0
	v_add3_u32 v183, v183, v134, s9
	s_nop 0
	v_readfirstlane_b32 s86, v183
	v_add_u32_e32 v183, 0x800, v182
	s_nop 0
	v_readfirstlane_b32 s87, v183
	v_lshl_add_u32 v183, v112, 1, 0
	v_add3_u32 v183, v183, v134, s9
	s_nop 0
	v_readfirstlane_b32 s88, v183
	v_add_u32_e32 v182, 0xc00, v182
	s_nop 0
	v_readfirstlane_b32 s89, v182
	v_subrev_u32_e32 v184, s52, v88
	v_subrev_u32_e32 v185, s52, v90
	v_subrev_u32_e32 v186, s52, v92
	v_subrev_u32_e32 v187, s52, v94
	v_subrev_u32_e32 v188, s52, v96
	v_subrev_u32_e32 v189, s52, v98
	v_subrev_u32_e32 v190, s52, v100
	v_subrev_u32_e32 v191, s52, v102
	v_subrev_u32_e32 v187, 0x400, v187
	v_subrev_u32_e32 v186, 0x400, v186
	v_subrev_u32_e32 v189, 0x800, v189
	v_subrev_u32_e32 v188, 0x800, v188
	v_subrev_u32_e32 v191, 0xc00, v191
	v_subrev_u32_e32 v190, 0xc00, v190
	s_and_b32 s16, s14, 0x4000
	s_xor_b32 s15, s16, 0x4000
	s_lshl_b32 s15, s15, 1
	s_add_i32 s15, s15, 32
	s_lshl_b32 s16, s16, 1
	s_add_i32 s16, s16, 32
.LBB0_616:
	s_xor_b32 s15, s15, 0x8000
	s_xor_b32 s16, s16, 0x8000
	s_add_u32 s90, s52, s6
	s_addc_u32 s91, s53, s7
	s_add_i32 m0, s16, s83
	v_lshl_add_u32 v137, v113, 1, s15
	global_load_lds_dwordx4 v185, s[90:91]
	global_load_lds_dwordx4 v187, s[90:91] offset:1024
	global_load_lds_dwordx4 v189, s[90:91] offset:2048
	global_load_lds_dwordx4 v191, s[90:91] offset:3072
	s_add_i32 m0, s16, s82
	v_lshl_add_u32 v170, v114, 1, s15
	global_load_lds_dwordx4 v184, s[90:91]
	global_load_lds_dwordx4 v186, s[90:91] offset:1024
	global_load_lds_dwordx4 v188, s[90:91] offset:2048
	global_load_lds_dwordx4 v190, s[90:91] offset:3072
	v_add_u32_e32 v158, v137, v135
	v_add_u32_e32 v166, v170, v135
	s_add_u32 s6, s6, 0x80
	s_addc_u32 s7, s7, 0
	ds_read_b128 v[138:141], v158
	ds_read_b128 v[146:149], v166 offset:16384
	ds_read_b128 v[150:153], v166 offset:18432
	ds_read_b128 v[162:165], v166 offset:20480
	ds_read_b128 v[166:169], v166 offset:22528
	ds_read_b128 v[142:145], v158 offset:2048
	ds_read_b128 v[154:157], v158 offset:4096
	ds_read_b128 v[158:161], v158 offset:6144
	v_add_u32_e32 v137, v137, v136
	v_add_u32_e32 v236, v170, v136
	ds_read_b128 v[204:207], v137
	ds_read_b128 v[208:211], v236 offset:16384
	ds_read_b128 v[212:215], v236 offset:18432
	ds_read_b128 v[216:219], v236 offset:20480
	ds_read_b128 v[220:223], v236 offset:22528
	ds_read_b128 v[224:227], v137 offset:2048
	ds_read_b128 v[228:231], v137 offset:4096
	ds_read_b128 v[232:235], v137 offset:6144
	s_setprio 1
	s_waitcnt lgkmcnt(11)
	v_mfma_f32_16x16x32_bf16 v[60:63], v[138:141], v[146:149], v[60:63]
	v_mfma_f32_16x16x32_bf16 v[56:59], v[138:141], v[150:153], v[56:59]
	v_mfma_f32_16x16x32_bf16 v[52:55], v[138:141], v[162:165], v[52:55]
	v_mfma_f32_16x16x32_bf16 v[48:51], v[138:141], v[166:169], v[48:51]
	s_waitcnt lgkmcnt(10)
	v_mfma_f32_16x16x32_bf16 v[44:47], v[142:145], v[146:149], v[44:47]
	v_mfma_f32_16x16x32_bf16 v[40:43], v[142:145], v[150:153], v[40:43]
	v_mfma_f32_16x16x32_bf16 v[36:39], v[142:145], v[162:165], v[36:39]
	v_mfma_f32_16x16x32_bf16 v[32:35], v[142:145], v[166:169], v[32:35]
	s_waitcnt lgkmcnt(9)
	v_mfma_f32_16x16x32_bf16 v[28:31], v[154:157], v[146:149], v[28:31]
	v_mfma_f32_16x16x32_bf16 v[24:27], v[154:157], v[150:153], v[24:27]
	v_mfma_f32_16x16x32_bf16 v[20:23], v[154:157], v[162:165], v[20:23]
	v_mfma_f32_16x16x32_bf16 v[16:19], v[154:157], v[166:169], v[16:19]
	s_waitcnt lgkmcnt(8)
	v_mfma_f32_16x16x32_bf16 v[12:15], v[158:161], v[146:149], v[12:15]
	v_mfma_f32_16x16x32_bf16 v[8:11], v[158:161], v[150:153], v[8:11]
	v_mfma_f32_16x16x32_bf16 v[4:7], v[158:161], v[162:165], v[4:7]
	v_mfma_f32_16x16x32_bf16 v[0:3], v[158:161], v[166:169], v[0:3]
	s_waitcnt lgkmcnt(3)
	v_mfma_f32_16x16x32_bf16 v[60:63], v[204:207], v[208:211], v[60:63]
	v_mfma_f32_16x16x32_bf16 v[56:59], v[204:207], v[212:215], v[56:59]
	v_mfma_f32_16x16x32_bf16 v[52:55], v[204:207], v[216:219], v[52:55]
	v_mfma_f32_16x16x32_bf16 v[48:51], v[204:207], v[220:223], v[48:51]
	s_waitcnt lgkmcnt(2)
	v_mfma_f32_16x16x32_bf16 v[44:47], v[224:227], v[208:211], v[44:47]
	v_mfma_f32_16x16x32_bf16 v[40:43], v[224:227], v[212:215], v[40:43]
	v_mfma_f32_16x16x32_bf16 v[36:39], v[224:227], v[216:219], v[36:39]
	v_mfma_f32_16x16x32_bf16 v[32:35], v[224:227], v[220:223], v[32:35]
	s_waitcnt lgkmcnt(1)
	v_mfma_f32_16x16x32_bf16 v[28:31], v[228:231], v[208:211], v[28:31]
	v_mfma_f32_16x16x32_bf16 v[24:27], v[228:231], v[212:215], v[24:27]
	v_mfma_f32_16x16x32_bf16 v[20:23], v[228:231], v[216:219], v[20:23]
	v_mfma_f32_16x16x32_bf16 v[16:19], v[228:231], v[220:223], v[16:19]
	s_waitcnt lgkmcnt(0)
	v_mfma_f32_16x16x32_bf16 v[12:15], v[232:235], v[208:211], v[12:15]
	v_mfma_f32_16x16x32_bf16 v[8:11], v[232:235], v[212:215], v[8:11]
	v_mfma_f32_16x16x32_bf16 v[4:7], v[232:235], v[216:219], v[4:7]
	v_mfma_f32_16x16x32_bf16 v[0:3], v[232:235], v[220:223], v[0:3]
	s_setprio 0
	s_cmpk_eq_i32 s6, 0x780
	s_waitcnt vmcnt(0)
	s_barrier
	s_cbranch_scc0 .LBB0_616
	ds_read_b128 v[88:91], v115 offset:55296
	ds_read_b128 v[92:95], v115 offset:53248
	ds_read_b128 v[96:99], v116 offset:38912
	ds_read_b128 v[100:103], v116 offset:36864
	ds_read_b128 v[138:141], v115 offset:51200
	ds_read_b128 v[142:145], v115 offset:49152
	ds_read_b128 v[146:149], v116 offset:34816
	ds_read_b128 v[150:153], v116 offset:32768
	ds_read_b128 v[204:207], v117 offset:32768
	ds_read_b128 v[208:211], v117 offset:34816
	ds_read_b128 v[212:215], v118 offset:49152
	ds_read_b128 v[216:219], v118 offset:51200
	ds_read_b128 v[220:223], v117 offset:36864
	ds_read_b128 v[224:227], v117 offset:38912
	ds_read_b128 v[228:231], v118 offset:53248
	ds_read_b128 v[232:235], v118 offset:55296
	s_setprio 1
	s_waitcnt lgkmcnt(13)
	v_mfma_f32_16x16x32_bf16 v[0:3], v[96:99], v[88:91], v[0:3]
	s_waitcnt lgkmcnt(8)
	v_mfma_f32_16x16x32_bf16 v[60:63], v[150:153], v[142:145], v[60:63]
	v_mfma_f32_16x16x32_bf16 v[56:59], v[150:153], v[138:141], v[56:59]
	v_mfma_f32_16x16x32_bf16 v[52:55], v[150:153], v[92:95], v[52:55]
	v_mfma_f32_16x16x32_bf16 v[48:51], v[150:153], v[88:91], v[48:51]
	v_mfma_f32_16x16x32_bf16 v[44:47], v[146:149], v[142:145], v[44:47]
	v_mfma_f32_16x16x32_bf16 v[40:43], v[146:149], v[138:141], v[40:43]
	v_mfma_f32_16x16x32_bf16 v[36:39], v[146:149], v[92:95], v[36:39]
	v_mfma_f32_16x16x32_bf16 v[32:35], v[146:149], v[88:91], v[32:35]
	v_mfma_f32_16x16x32_bf16 v[28:31], v[100:103], v[142:145], v[28:31]
	v_mfma_f32_16x16x32_bf16 v[24:27], v[100:103], v[138:141], v[24:27]
	v_mfma_f32_16x16x32_bf16 v[20:23], v[100:103], v[92:95], v[20:23]
	v_mfma_f32_16x16x32_bf16 v[16:19], v[100:103], v[88:91], v[16:19]
	v_mfma_f32_16x16x32_bf16 v[12:15], v[96:99], v[142:145], v[12:15]
	v_mfma_f32_16x16x32_bf16 v[8:11], v[96:99], v[138:141], v[8:11]
	v_mfma_f32_16x16x32_bf16 v[4:7], v[96:99], v[92:95], v[4:7]
	s_waitcnt lgkmcnt(0)
	v_mfma_f32_16x16x32_bf16 v[0:3], v[224:227], v[232:235], v[0:3]
	v_mfma_f32_16x16x32_bf16 v[60:63], v[204:207], v[212:215], v[60:63]
	v_mfma_f32_16x16x32_bf16 v[56:59], v[204:207], v[216:219], v[56:59]
	v_mfma_f32_16x16x32_bf16 v[52:55], v[204:207], v[228:231], v[52:55]
	v_mfma_f32_16x16x32_bf16 v[48:51], v[204:207], v[232:235], v[48:51]
	v_mfma_f32_16x16x32_bf16 v[44:47], v[208:211], v[212:215], v[44:47]
	v_mfma_f32_16x16x32_bf16 v[40:43], v[208:211], v[216:219], v[40:43]
	v_mfma_f32_16x16x32_bf16 v[36:39], v[208:211], v[228:231], v[36:39]
	v_mfma_f32_16x16x32_bf16 v[32:35], v[208:211], v[232:235], v[32:35]
	v_mfma_f32_16x16x32_bf16 v[28:31], v[220:223], v[212:215], v[28:31]
	v_mfma_f32_16x16x32_bf16 v[24:27], v[220:223], v[216:219], v[24:27]
	v_mfma_f32_16x16x32_bf16 v[20:23], v[220:223], v[228:231], v[20:23]
	v_mfma_f32_16x16x32_bf16 v[16:19], v[220:223], v[232:235], v[16:19]
	v_mfma_f32_16x16x32_bf16 v[12:15], v[224:227], v[212:215], v[12:15]
	v_mfma_f32_16x16x32_bf16 v[8:11], v[224:227], v[216:219], v[8:11]
	v_mfma_f32_16x16x32_bf16 v[4:7], v[224:227], v[228:231], v[4:7]
	s_setprio 0
	s_barrier
	ds_write2_b32 v119, v60, v56 offset1:16
	ds_write2_b32 v119, v61, v57 offset0:132 offset1:148
	v_add_u32_e32 v56, 0x400, v119
	ds_write2_b32 v56, v62, v58 offset0:8 offset1:24
	ds_write2_b32 v56, v63, v59 offset0:140 offset1:156
	ds_write2_b32 v119, v52, v48 offset0:32 offset1:48
	ds_write2_b32 v119, v53, v49 offset0:164 offset1:180
	ds_write2_b32 v56, v54, v50 offset0:40 offset1:56
	ds_write2_b32 v56, v55, v51 offset0:172 offset1:188
	v_add_u32_e32 v48, 0x2000, v119
	ds_write2_b32 v48, v44, v40 offset0:64 offset1:80
	ds_write2_b32 v48, v45, v41 offset0:196 offset1:212
	v_add_u32_e32 v40, 0x2400, v119
	ds_write2_b32 v40, v46, v42 offset0:72 offset1:88
	ds_write2_b32 v40, v47, v43 offset0:204 offset1:220
	ds_write2_b32 v48, v36, v32 offset0:96 offset1:112
	ds_write2_b32 v48, v37, v33 offset0:228 offset1:244
	ds_write2_b32 v40, v38, v34 offset0:104 offset1:120
	ds_write2_b32 v40, v39, v35 offset0:236 offset1:252
	v_add_u32_e32 v32, 0x4000, v119
	ds_write2_b32 v32, v28, v24 offset0:128 offset1:144
	v_add_u32_e32 v24, 0x4400, v119
	ds_write2_b32 v24, v29, v25 offset0:4 offset1:20
	ds_write2_b32 v24, v30, v26 offset0:136 offset1:152
	v_add_u32_e32 v25, 0x4800, v119
	ds_write2_b32 v25, v31, v27 offset0:12 offset1:28
	ds_write2_b32 v32, v20, v16 offset0:160 offset1:176
	ds_write2_b32 v24, v21, v17 offset0:36 offset1:52
	ds_write2_b32 v24, v22, v18 offset0:168 offset1:184
	ds_write2_b32 v25, v23, v19 offset0:44 offset1:60
	v_add_u32_e32 v16, 0x6000, v119
	ds_write2_b32 v16, v12, v8 offset0:192 offset1:208
	v_add_u32_e32 v8, 0x6400, v119
	ds_write2_b32 v8, v13, v9 offset0:68 offset1:84
	ds_write2_b32 v8, v14, v10 offset0:200 offset1:216
	v_add_u32_e32 v9, 0x6800, v119
	ds_write2_b32 v9, v15, v11 offset0:76 offset1:92
	ds_write2_b32 v16, v4, v0 offset0:224 offset1:240
	ds_write2_b32 v8, v5, v1 offset0:100 offset1:116
	ds_write2_b32 v8, v6, v2 offset0:232 offset1:248
	ds_write2_b32 v9, v7, v3 offset0:108 offset1:124
	v_or_b32_e32 v0, s12, v120
	v_ashrrev_i32_e32 v1, 31, v0
	v_lshl_add_u64 v[0:1], v[0:1], 1, s[4:5]
	v_add_u32_e32 v2, s13, v128
	s_mov_b32 s6, 0
	s_waitcnt lgkmcnt(0)
	s_barrier

.LBB0_681:
	s_ashr_i32 s14, s21, 31
	s_lshr_b32 s14, s14, 29
	s_add_i32 s14, s21, s14
	s_ashr_i32 s14, s14, 3
	s_lshl_b32 s22, s14, 7
	s_lshl_b32 s14, s14, 10
	s_lshl_b32 s15, s21, 7
	s_sub_i32 s23, s15, s14
	v_add_u32_e32 v0, s23, v106
	v_ashrrev_i32_e32 v1, 31, v0
	v_add_u32_e32 v2, 0x4000, v107
	v_lshlrev_b64 v[0:1], 13, v[0:1]
	v_readfirstlane_b32 s15, v2
	v_lshl_add_u64 v[0:1], v[66:67], 0, v[0:1]
	s_mov_b32 m0, s15
	v_readfirstlane_b32 s15, v107
	global_load_lds_dwordx4 v[0:1], off
	v_add_u32_e32 v0, s22, v106
	v_ashrrev_i32_e32 v1, 31, v0
	v_lshlrev_b64 v[0:1], 13, v[0:1]
	v_lshl_add_u64 v[2:3], v[72:73], 0, v[0:1]
	s_mov_b32 m0, s15
	v_readfirstlane_b32 s15, v130
	global_load_lds_dwordx4 v[2:3], off
	v_add_u32_e32 v2, s23, v108
	v_ashrrev_i32_e32 v3, 31, v2
	v_lshlrev_b64 v[2:3], 13, v[2:3]
	v_lshl_add_u64 v[2:3], v[68:69], 0, v[2:3]
	s_mov_b32 m0, s15
	v_add_u32_e32 v4, 0x400, v107
	global_load_lds_dwordx4 v[2:3], off
	v_add_u32_e32 v2, s22, v108
	v_ashrrev_i32_e32 v3, 31, v2
	v_lshlrev_b64 v[2:3], 13, v[2:3]
	v_readfirstlane_b32 s15, v4
	v_lshl_add_u64 v[2:3], v[74:75], 0, v[2:3]
	s_mov_b32 m0, s15
	v_readfirstlane_b32 s15, v131
	global_load_lds_dwordx4 v[2:3], off
	v_add_u32_e32 v2, s23, v110
	v_ashrrev_i32_e32 v3, 31, v2
	v_lshlrev_b64 v[2:3], 13, v[2:3]
	v_lshl_add_u64 v[2:3], v[66:67], 0, v[2:3]
	s_mov_b32 m0, s15
	v_add_u32_e32 v4, 0x800, v107
	global_load_lds_dwordx4 v[2:3], off
	v_add_u32_e32 v2, s22, v110
	v_ashrrev_i32_e32 v3, 31, v2
	v_lshlrev_b64 v[2:3], 13, v[2:3]
	v_readfirstlane_b32 s15, v4
	v_lshl_add_u64 v[2:3], v[72:73], 0, v[2:3]
	s_mov_b32 m0, s15
	v_readfirstlane_b32 s15, v132
	global_load_lds_dwordx4 v[2:3], off
	v_add_u32_e32 v2, s23, v112
	v_ashrrev_i32_e32 v3, 31, v2
	v_lshlrev_b64 v[2:3], 13, v[2:3]
	v_lshl_add_u64 v[2:3], v[70:71], 0, v[2:3]
	s_mov_b32 m0, s15
	v_add_u32_e32 v4, 0xc00, v107
	global_load_lds_dwordx4 v[2:3], off
	v_add_u32_e32 v2, s22, v112
	v_ashrrev_i32_e32 v3, 31, v2
	v_lshlrev_b64 v[2:3], 13, v[2:3]
	v_readfirstlane_b32 s15, v4
	v_lshl_add_u64 v[2:3], v[76:77], 0, v[2:3]
	s_mov_b32 m0, s15
	v_lshl_add_u64 v[92:93], v[80:81], 0, v[0:1]
	global_load_lds_dwordx4 v[2:3], off
	v_subrev_u32_e32 v0, s14, v123
	v_ashrrev_i32_e32 v1, 31, v0
	v_lshlrev_b64 v[0:1], 13, v[0:1]
	v_lshl_add_u64 v[94:95], v[82:83], 0, v[0:1]
	v_add_u32_e32 v0, s22, v124
	v_ashrrev_i32_e32 v1, 31, v0
	v_lshlrev_b64 v[0:1], 13, v[0:1]
	v_lshl_add_u64 v[96:97], v[84:85], 0, v[0:1]
	v_subrev_u32_e32 v0, s14, v125
	v_ashrrev_i32_e32 v1, 31, v0
	v_lshlrev_b64 v[0:1], 13, v[0:1]
	v_lshl_add_u64 v[98:99], v[78:79], 0, v[0:1]
	v_add_u32_e32 v0, s22, v126
	v_ashrrev_i32_e32 v1, 31, v0
	v_lshlrev_b64 v[0:1], 13, v[0:1]
	v_lshl_add_u64 v[100:101], v[80:81], 0, v[0:1]
	v_subrev_u32_e32 v0, s14, v64
	v_ashrrev_i32_e32 v1, 31, v0
	v_lshlrev_b64 v[0:1], 13, v[0:1]
	v_subrev_u32_e32 v2, s14, v122
	v_lshl_add_u64 v[102:103], v[86:87], 0, v[0:1]
	v_add_u32_e32 v0, s22, v127
	v_ashrrev_i32_e32 v3, 31, v2
	v_ashrrev_i32_e32 v1, 31, v0
	v_lshlrev_b64 v[2:3], 13, v[2:3]
	v_lshlrev_b64 v[0:1], 13, v[0:1]
	v_lshl_add_u64 v[90:91], v[78:79], 0, v[2:3]
	v_lshl_add_u64 v[104:105], v[88:89], 0, v[0:1]
	s_mov_b32 s24, 0
	s_mov_b64 s[14:15], 0
	v_mov_b32_e32 v0, 0
	v_mov_b32_e32 v1, v65
	v_mov_b32_e32 v2, v65
	v_mov_b32_e32 v3, v65
	v_mov_b32_e32 v4, 0
	v_mov_b32_e32 v5, v65
	v_mov_b32_e32 v6, v65
	v_mov_b32_e32 v7, v65
	v_mov_b32_e32 v8, 0
	v_mov_b32_e32 v9, v65
	v_mov_b32_e32 v10, v65
	v_mov_b32_e32 v11, v65
	v_mov_b32_e32 v12, 0
	v_mov_b32_e32 v13, v65
	v_mov_b32_e32 v14, v65
	v_mov_b32_e32 v15, v65
	v_mov_b32_e32 v16, 0
	v_mov_b32_e32 v17, v65
	v_mov_b32_e32 v18, v65
	v_mov_b32_e32 v19, v65
	v_mov_b32_e32 v20, 0
	v_mov_b32_e32 v21, v65
	v_mov_b32_e32 v22, v65
	v_mov_b32_e32 v23, v65
	v_mov_b32_e32 v24, 0
	v_mov_b32_e32 v25, v65
	v_mov_b32_e32 v26, v65
	v_mov_b32_e32 v27, v65
	v_mov_b32_e32 v28, 0
	v_mov_b32_e32 v29, v65
	v_mov_b32_e32 v30, v65
	v_mov_b32_e32 v31, v65
	v_mov_b32_e32 v32, 0
	v_mov_b32_e32 v33, v65
	v_mov_b32_e32 v34, v65
	v_mov_b32_e32 v35, v65
	v_mov_b32_e32 v36, 0
	v_mov_b32_e32 v37, v65
	v_mov_b32_e32 v38, v65
	v_mov_b32_e32 v39, v65
	v_mov_b32_e32 v40, 0
	v_mov_b32_e32 v41, v65
	v_mov_b32_e32 v42, v65
	v_mov_b32_e32 v43, v65
	v_mov_b32_e32 v44, 0
	v_mov_b32_e32 v45, v65
	v_mov_b32_e32 v46, v65
	v_mov_b32_e32 v47, v65
	v_mov_b32_e32 v48, 0
	v_mov_b32_e32 v49, v65
	v_mov_b32_e32 v50, v65
	v_mov_b32_e32 v51, v65
	v_mov_b32_e32 v52, 0
	v_mov_b32_e32 v53, v65
	v_mov_b32_e32 v54, v65
	v_mov_b32_e32 v55, v65
	v_mov_b32_e32 v56, 0
	v_mov_b32_e32 v57, v65
	v_mov_b32_e32 v58, v65
	v_mov_b32_e32 v59, v65
	v_mov_b32_e32 v60, 0
	v_mov_b32_e32 v61, v65
	v_mov_b32_e32 v62, v65
	v_mov_b32_e32 v63, v65
	s_waitcnt vmcnt(0) lgkmcnt(0)
	s_barrier
	v_add3_u32 v190, 0, v133, v134
	v_add_u32_e32 v191, 0x4000, v190
	s_nop 0
	v_readfirstlane_b32 s82, v191
	v_lshl_add_u32 v191, v109, 1, 0
	s_nop 0
	v_readfirstlane_b32 s83, v190
	v_add3_u32 v191, v191, v134, s17
	s_nop 0
	v_readfirstlane_b32 s84, v191
	v_add_u32_e32 v191, 0x400, v190
	s_nop 0
	v_readfirstlane_b32 s85, v191
	v_lshl_add_u32 v191, v111, 1, 0
	v_add3_u32 v191, v191, v134, s17
	s_nop 0
	v_readfirstlane_b32 s86, v191
	v_add_u32_e32 v191, 0x800, v190
	s_nop 0
	v_readfirstlane_b32 s87, v191
	v_lshl_add_u32 v191, v113, 1, 0
	v_add3_u32 v191, v191, v134, s17
	s_nop 0
	v_readfirstlane_b32 s88, v191
	v_add_u32_e32 v190, 0xc00, v190
	s_nop 0
	v_readfirstlane_b32 s89, v190
	v_subrev_u32_e32 v192, s52, v90
	v_subrev_u32_e32 v193, s52, v92
	v_subrev_u32_e32 v194, s52, v94
	v_subrev_u32_e32 v195, s52, v96
	v_subrev_u32_e32 v196, s52, v98
	v_subrev_u32_e32 v197, s52, v100
	v_subrev_u32_e32 v198, s52, v102
	v_subrev_u32_e32 v199, s52, v104
	v_subrev_u32_e32 v195, 0x400, v195
	v_subrev_u32_e32 v194, 0x400, v194
	v_subrev_u32_e32 v197, 0x800, v197
	v_subrev_u32_e32 v196, 0x800, v196
	v_subrev_u32_e32 v199, 0xc00, v199
	v_subrev_u32_e32 v198, 0xc00, v198
	s_and_b32 s26, s24, 0x4000
	s_xor_b32 s25, s26, 0x4000
	s_lshl_b32 s25, s25, 1
	s_add_i32 s25, s25, 32
	s_lshl_b32 s26, s26, 1
	s_add_i32 s26, s26, 32
.LBB0_682:
	s_xor_b32 s25, s25, 0x8000
	s_xor_b32 s26, s26, 0x8000
	s_add_u32 s90, s52, s14
	s_addc_u32 s91, s53, s15
	s_add_i32 m0, s26, s83
	v_add3_u32 v170, s25, v114, v135
	global_load_lds_dwordx4 v193, s[90:91]
	global_load_lds_dwordx4 v195, s[90:91] offset:1024
	global_load_lds_dwordx4 v197, s[90:91] offset:2048
	global_load_lds_dwordx4 v199, s[90:91] offset:3072
	s_add_i32 m0, s26, s82
	v_add3_u32 v171, s25, v115, v135
	global_load_lds_dwordx4 v192, s[90:91]
	global_load_lds_dwordx4 v194, s[90:91] offset:1024
	global_load_lds_dwordx4 v196, s[90:91] offset:2048
	global_load_lds_dwordx4 v198, s[90:91] offset:3072
	v_add_u32_e32 v158, v170, v136
	v_add_u32_e32 v166, v171, v136
	s_addk_i32 s24, 0x4000
	s_add_u32 s14, s14, 0x80
	s_addc_u32 s15, s15, 0
	ds_read_b128 v[138:141], v158
	ds_read_b128 v[146:149], v166 offset:16384
	ds_read_b128 v[150:153], v166 offset:18432
	ds_read_b128 v[162:165], v166 offset:20480
	ds_read_b128 v[166:169], v166 offset:22528
	ds_read_b128 v[142:145], v158 offset:2048
	ds_read_b128 v[154:157], v158 offset:4096
	ds_read_b128 v[158:161], v158 offset:6144
	v_add_u32_e32 v236, v170, v137
	v_add_u32_e32 v237, v171, v137
	ds_read_b128 v[204:207], v236
	ds_read_b128 v[208:211], v237 offset:16384
	ds_read_b128 v[212:215], v237 offset:18432
	ds_read_b128 v[216:219], v237 offset:20480
	ds_read_b128 v[220:223], v237 offset:22528
	ds_read_b128 v[224:227], v236 offset:2048
	ds_read_b128 v[228:231], v236 offset:4096
	ds_read_b128 v[232:235], v236 offset:6144
	s_setprio 1
	s_waitcnt lgkmcnt(11)
	v_mfma_f32_16x16x32_bf16 v[60:63], v[138:141], v[146:149], v[60:63]
	v_mfma_f32_16x16x32_bf16 v[56:59], v[138:141], v[150:153], v[56:59]
	v_mfma_f32_16x16x32_bf16 v[52:55], v[138:141], v[162:165], v[52:55]
	v_mfma_f32_16x16x32_bf16 v[48:51], v[138:141], v[166:169], v[48:51]
	s_waitcnt lgkmcnt(10)
	v_mfma_f32_16x16x32_bf16 v[44:47], v[142:145], v[146:149], v[44:47]
	v_mfma_f32_16x16x32_bf16 v[40:43], v[142:145], v[150:153], v[40:43]
	v_mfma_f32_16x16x32_bf16 v[36:39], v[142:145], v[162:165], v[36:39]
	v_mfma_f32_16x16x32_bf16 v[32:35], v[142:145], v[166:169], v[32:35]
	s_waitcnt lgkmcnt(9)
	v_mfma_f32_16x16x32_bf16 v[28:31], v[154:157], v[146:149], v[28:31]
	v_mfma_f32_16x16x32_bf16 v[24:27], v[154:157], v[150:153], v[24:27]
	v_mfma_f32_16x16x32_bf16 v[20:23], v[154:157], v[162:165], v[20:23]
	v_mfma_f32_16x16x32_bf16 v[16:19], v[154:157], v[166:169], v[16:19]
	s_waitcnt lgkmcnt(8)
	v_mfma_f32_16x16x32_bf16 v[12:15], v[158:161], v[146:149], v[12:15]
	v_mfma_f32_16x16x32_bf16 v[8:11], v[158:161], v[150:153], v[8:11]
	v_mfma_f32_16x16x32_bf16 v[4:7], v[158:161], v[162:165], v[4:7]
	v_mfma_f32_16x16x32_bf16 v[0:3], v[158:161], v[166:169], v[0:3]
	s_waitcnt lgkmcnt(3)
	v_mfma_f32_16x16x32_bf16 v[60:63], v[204:207], v[208:211], v[60:63]
	v_mfma_f32_16x16x32_bf16 v[56:59], v[204:207], v[212:215], v[56:59]
	v_mfma_f32_16x16x32_bf16 v[52:55], v[204:207], v[216:219], v[52:55]
	v_mfma_f32_16x16x32_bf16 v[48:51], v[204:207], v[220:223], v[48:51]
	s_waitcnt lgkmcnt(2)
	v_mfma_f32_16x16x32_bf16 v[44:47], v[224:227], v[208:211], v[44:47]
	v_mfma_f32_16x16x32_bf16 v[40:43], v[224:227], v[212:215], v[40:43]
	v_mfma_f32_16x16x32_bf16 v[36:39], v[224:227], v[216:219], v[36:39]
	v_mfma_f32_16x16x32_bf16 v[32:35], v[224:227], v[220:223], v[32:35]
	s_waitcnt lgkmcnt(1)
	v_mfma_f32_16x16x32_bf16 v[28:31], v[228:231], v[208:211], v[28:31]
	v_mfma_f32_16x16x32_bf16 v[24:27], v[228:231], v[212:215], v[24:27]
	v_mfma_f32_16x16x32_bf16 v[20:23], v[228:231], v[216:219], v[20:23]
	v_mfma_f32_16x16x32_bf16 v[16:19], v[228:231], v[220:223], v[16:19]
	s_waitcnt lgkmcnt(0)
	v_mfma_f32_16x16x32_bf16 v[12:15], v[232:235], v[208:211], v[12:15]
	v_mfma_f32_16x16x32_bf16 v[8:11], v[232:235], v[212:215], v[8:11]
	v_mfma_f32_16x16x32_bf16 v[4:7], v[232:235], v[216:219], v[4:7]
	v_mfma_f32_16x16x32_bf16 v[0:3], v[232:235], v[220:223], v[0:3]
	s_setprio 0
	s_cmpk_eq_i32 s14, 0x1f80
	s_waitcnt vmcnt(0)
	s_barrier
	s_cbranch_scc0 .LBB0_682
	ds_read_b128 v[90:93], v118 offset:55296
	ds_read_b128 v[94:97], v118 offset:53248
	ds_read_b128 v[98:101], v119 offset:38912
	ds_read_b128 v[102:105], v119 offset:36864
	ds_read_b128 v[138:141], v118 offset:51200
	ds_read_b128 v[142:145], v118 offset:49152
	ds_read_b128 v[146:149], v119 offset:34816
	ds_read_b128 v[150:153], v119 offset:32768
	ds_read_b128 v[204:207], v120 offset:32768
	ds_read_b128 v[208:211], v120 offset:34816
	ds_read_b128 v[212:215], v121 offset:49152
	ds_read_b128 v[216:219], v121 offset:51200
	ds_read_b128 v[220:223], v120 offset:36864
	ds_read_b128 v[224:227], v120 offset:38912
	ds_read_b128 v[228:231], v121 offset:53248
	ds_read_b128 v[232:235], v121 offset:55296
	s_setprio 1
	s_waitcnt lgkmcnt(13)
	v_mfma_f32_16x16x32_bf16 v[4:7], v[98:101], v[94:97], v[4:7]
	v_mfma_f32_16x16x32_bf16 v[0:3], v[98:101], v[90:93], v[0:3]
	s_waitcnt lgkmcnt(8)
	v_mfma_f32_16x16x32_bf16 v[60:63], v[150:153], v[142:145], v[60:63]
	v_mfma_f32_16x16x32_bf16 v[56:59], v[150:153], v[138:141], v[56:59]
	v_mfma_f32_16x16x32_bf16 v[52:55], v[150:153], v[94:97], v[52:55]
	v_mfma_f32_16x16x32_bf16 v[48:51], v[150:153], v[90:93], v[48:51]
	v_mfma_f32_16x16x32_bf16 v[44:47], v[146:149], v[142:145], v[44:47]
	v_mfma_f32_16x16x32_bf16 v[40:43], v[146:149], v[138:141], v[40:43]
	v_mfma_f32_16x16x32_bf16 v[36:39], v[146:149], v[94:97], v[36:39]
	v_mfma_f32_16x16x32_bf16 v[32:35], v[146:149], v[90:93], v[32:35]
	v_mfma_f32_16x16x32_bf16 v[28:31], v[102:105], v[142:145], v[28:31]
	v_mfma_f32_16x16x32_bf16 v[24:27], v[102:105], v[138:141], v[24:27]
	v_mfma_f32_16x16x32_bf16 v[20:23], v[102:105], v[94:97], v[20:23]
	v_mfma_f32_16x16x32_bf16 v[16:19], v[102:105], v[90:93], v[16:19]
	v_mfma_f32_16x16x32_bf16 v[12:15], v[98:101], v[142:145], v[12:15]
	v_mfma_f32_16x16x32_bf16 v[8:11], v[98:101], v[138:141], v[8:11]
	s_waitcnt lgkmcnt(1)
	v_mfma_f32_16x16x32_bf16 v[4:7], v[224:227], v[228:231], v[4:7]
	s_waitcnt lgkmcnt(0)
	v_mfma_f32_16x16x32_bf16 v[0:3], v[224:227], v[232:235], v[0:3]
	v_mfma_f32_16x16x32_bf16 v[60:63], v[204:207], v[212:215], v[60:63]
	v_mfma_f32_16x16x32_bf16 v[56:59], v[204:207], v[216:219], v[56:59]
	v_mfma_f32_16x16x32_bf16 v[52:55], v[204:207], v[228:231], v[52:55]
	v_mfma_f32_16x16x32_bf16 v[48:51], v[204:207], v[232:235], v[48:51]
	v_mfma_f32_16x16x32_bf16 v[44:47], v[208:211], v[212:215], v[44:47]
	v_mfma_f32_16x16x32_bf16 v[40:43], v[208:211], v[216:219], v[40:43]
	v_mfma_f32_16x16x32_bf16 v[36:39], v[208:211], v[228:231], v[36:39]
	v_mfma_f32_16x16x32_bf16 v[32:35], v[208:211], v[232:235], v[32:35]
	v_mfma_f32_16x16x32_bf16 v[28:31], v[220:223], v[212:215], v[28:31]
	v_mfma_f32_16x16x32_bf16 v[24:27], v[220:223], v[216:219], v[24:27]
	v_mfma_f32_16x16x32_bf16 v[20:23], v[220:223], v[228:231], v[20:23]
	v_mfma_f32_16x16x32_bf16 v[16:19], v[220:223], v[232:235], v[16:19]
	v_mfma_f32_16x16x32_bf16 v[12:15], v[224:227], v[212:215], v[12:15]
	v_mfma_f32_16x16x32_bf16 v[8:11], v[224:227], v[216:219], v[8:11]
	s_setprio 0
	s_barrier
	ds_write2_b32 v116, v60, v56 offset1:16
	ds_write2_b32 v116, v61, v57 offset0:132 offset1:148
	v_add_u32_e32 v56, 0x400, v116
	ds_write2_b32 v56, v62, v58 offset0:8 offset1:24
	ds_write2_b32 v56, v63, v59 offset0:140 offset1:156
	ds_write2_b32 v116, v52, v48 offset0:32 offset1:48
	ds_write2_b32 v116, v53, v49 offset0:164 offset1:180
	ds_write2_b32 v56, v54, v50 offset0:40 offset1:56
	ds_write2_b32 v56, v55, v51 offset0:172 offset1:188
	v_add_u32_e32 v48, 0x2000, v116
	ds_write2_b32 v48, v44, v40 offset0:64 offset1:80
	ds_write2_b32 v48, v45, v41 offset0:196 offset1:212
	v_add_u32_e32 v40, 0x2400, v116
	ds_write2_b32 v40, v46, v42 offset0:72 offset1:88
	ds_write2_b32 v40, v47, v43 offset0:204 offset1:220
	ds_write2_b32 v48, v36, v32 offset0:96 offset1:112
	ds_write2_b32 v48, v37, v33 offset0:228 offset1:244
	ds_write2_b32 v40, v38, v34 offset0:104 offset1:120
	ds_write2_b32 v40, v39, v35 offset0:236 offset1:252
	v_add_u32_e32 v32, 0x4000, v116
	ds_write2_b32 v32, v28, v24 offset0:128 offset1:144
	v_add_u32_e32 v24, 0x4400, v116
	ds_write2_b32 v24, v29, v25 offset0:4 offset1:20
	ds_write2_b32 v24, v30, v26 offset0:136 offset1:152
	v_add_u32_e32 v25, 0x4800, v116
	ds_write2_b32 v25, v31, v27 offset0:12 offset1:28
	ds_write2_b32 v32, v20, v16 offset0:160 offset1:176
	ds_write2_b32 v24, v21, v17 offset0:36 offset1:52
	ds_write2_b32 v24, v22, v18 offset0:168 offset1:184
	ds_write2_b32 v25, v23, v19 offset0:44 offset1:60
	v_add_u32_e32 v16, 0x6000, v116
	ds_write2_b32 v16, v12, v8 offset0:192 offset1:208
	v_add_u32_e32 v8, 0x6400, v116
	ds_write2_b32 v8, v13, v9 offset0:68 offset1:84
	ds_write2_b32 v8, v14, v10 offset0:200 offset1:216
	v_add_u32_e32 v9, 0x6800, v116
	ds_write2_b32 v9, v15, v11 offset0:76 offset1:92
	ds_write2_b32 v16, v4, v0 offset0:224 offset1:240
	ds_write2_b32 v8, v5, v1 offset0:100 offset1:116
	ds_write2_b32 v8, v6, v2 offset0:232 offset1:248
	ds_write2_b32 v9, v7, v3 offset0:108 offset1:124
	v_or_b32_e32 v0, s23, v117
	v_ashrrev_i32_e32 v1, 31, v0
	v_lshlrev_b64 v[2:3], 2, v[0:1]
	v_lshl_add_u64 v[0:1], s[12:13], 0, v[2:3]
	v_lshl_add_u64 v[2:3], s[10:11], 0, v[2:3]
	v_add_u32_e32 v4, s22, v128
	s_mov_b32 s14, 0
	s_waitcnt lgkmcnt(0)
	s_barrier

.LBB0_690:
	s_ashr_i32 s14, s16, 31
	s_lshr_b32 s14, s14, 29
	s_add_i32 s14, s16, s14
	s_ashr_i32 s14, s14, 3
	s_lshl_b32 s15, s14, 10
	s_lshl_b32 s23, s16, 7
	v_add_u32_e32 v0, s14, v104
	s_sub_i32 s23, s23, s15
	v_lshlrev_b32_e32 v2, 7, v0
	v_add_u32_e32 v0, s23, v105
	v_ashrrev_i32_e32 v1, 31, v0
	v_add_u32_e32 v3, 0x4000, v106
	v_lshlrev_b64 v[0:1], 13, v[0:1]
	v_readfirstlane_b32 s24, v3
	v_lshl_add_u64 v[0:1], v[64:65], 0, v[0:1]
	s_mov_b32 m0, s24
	v_readfirstlane_b32 s24, v106
	global_load_lds_dwordx4 v[0:1], off
	v_add_u32_e32 v0, v2, v105
	v_ashrrev_i32_e32 v1, 31, v0
	v_lshlrev_b64 v[0:1], 13, v[0:1]
	v_lshl_add_u64 v[0:1], v[70:71], 0, v[0:1]
	s_mov_b32 m0, s24
	v_readfirstlane_b32 s24, v131
	global_load_lds_dwordx4 v[0:1], off
	v_add_u32_e32 v0, s23, v107
	v_ashrrev_i32_e32 v1, 31, v0
	v_lshlrev_b64 v[0:1], 13, v[0:1]
	v_lshl_add_u64 v[0:1], v[66:67], 0, v[0:1]
	s_mov_b32 m0, s24
	v_add_u32_e32 v3, 0x400, v106
	global_load_lds_dwordx4 v[0:1], off
	v_add_u32_e32 v0, v2, v107
	v_ashrrev_i32_e32 v1, 31, v0
	v_lshlrev_b64 v[0:1], 13, v[0:1]
	v_readfirstlane_b32 s24, v3
	v_lshl_add_u64 v[0:1], v[72:73], 0, v[0:1]
	s_mov_b32 m0, s24
	v_readfirstlane_b32 s24, v132
	global_load_lds_dwordx4 v[0:1], off
	v_add_u32_e32 v0, s23, v109
	v_ashrrev_i32_e32 v1, 31, v0
	v_lshlrev_b64 v[0:1], 13, v[0:1]
	v_lshl_add_u64 v[0:1], v[64:65], 0, v[0:1]
	s_mov_b32 m0, s24
	v_add_u32_e32 v3, 0x800, v106
	global_load_lds_dwordx4 v[0:1], off
	v_add_u32_e32 v0, v2, v109
	v_ashrrev_i32_e32 v1, 31, v0
	v_lshlrev_b64 v[0:1], 13, v[0:1]
	v_readfirstlane_b32 s24, v3
	v_lshl_add_u64 v[0:1], v[70:71], 0, v[0:1]
	s_mov_b32 m0, s24
	v_readfirstlane_b32 s24, v133
	global_load_lds_dwordx4 v[0:1], off
	v_add_u32_e32 v0, s23, v111
	v_ashrrev_i32_e32 v1, 31, v0
	v_lshlrev_b64 v[0:1], 13, v[0:1]
	v_lshl_add_u64 v[0:1], v[68:69], 0, v[0:1]
	s_mov_b32 m0, s24
	s_mov_b32 s25, 0
	global_load_lds_dwordx4 v[0:1], off
	v_add_u32_e32 v0, v2, v111
	v_ashrrev_i32_e32 v1, 31, v0
	v_add_u32_e32 v2, 0xc00, v106
	v_lshlrev_b64 v[0:1], 13, v[0:1]
	v_readfirstlane_b32 s24, v2
	v_lshl_add_u64 v[0:1], v[74:75], 0, v[0:1]
	s_mov_b32 m0, s24
	s_lshl_b32 s24, s14, 7
	global_load_lds_dwordx4 v[0:1], off
	v_subrev_u32_e32 v0, s15, v121
	v_ashrrev_i32_e32 v1, 31, v0
	v_lshlrev_b64 v[0:1], 13, v[0:1]
	v_lshl_add_u64 v[88:89], v[76:77], 0, v[0:1]
	v_add_u32_e32 v0, s24, v122
	v_ashrrev_i32_e32 v1, 31, v0
	v_lshlrev_b64 v[0:1], 13, v[0:1]
	v_lshl_add_u64 v[90:91], v[78:79], 0, v[0:1]
	v_subrev_u32_e32 v0, s15, v123
	v_ashrrev_i32_e32 v1, 31, v0
	v_lshlrev_b64 v[0:1], 13, v[0:1]
	v_lshl_add_u64 v[92:93], v[80:81], 0, v[0:1]
	v_add_u32_e32 v0, s24, v124
	v_ashrrev_i32_e32 v1, 31, v0
	v_lshlrev_b64 v[0:1], 13, v[0:1]
	v_lshl_add_u64 v[94:95], v[82:83], 0, v[0:1]
	v_subrev_u32_e32 v0, s15, v125
	v_ashrrev_i32_e32 v1, 31, v0
	v_lshlrev_b64 v[0:1], 13, v[0:1]
	v_lshl_add_u64 v[96:97], v[76:77], 0, v[0:1]
	v_add_u32_e32 v0, s24, v126
	v_ashrrev_i32_e32 v1, 31, v0
	v_lshlrev_b64 v[0:1], 13, v[0:1]
	v_lshl_add_u64 v[98:99], v[78:79], 0, v[0:1]
	v_subrev_u32_e32 v0, s15, v127
	v_ashrrev_i32_e32 v1, 31, v0
	v_lshlrev_b64 v[0:1], 13, v[0:1]
	v_lshl_add_u64 v[100:101], v[84:85], 0, v[0:1]
	v_add_u32_e32 v0, s24, v128
	v_ashrrev_i32_e32 v1, 31, v0
	v_lshlrev_b64 v[0:1], 13, v[0:1]
	v_lshl_add_u64 v[102:103], v[86:87], 0, v[0:1]
	v_mov_b32_e32 v0, 0
	s_mov_b64 s[14:15], 0
	v_mov_b32_e32 v1, v0
	v_mov_b32_e32 v2, v0
	v_mov_b32_e32 v3, v0
	v_mov_b32_e32 v4, v0
	v_mov_b32_e32 v5, v0
	v_mov_b32_e32 v6, v0
	v_mov_b32_e32 v7, v0
	v_mov_b32_e32 v8, v0
	v_mov_b32_e32 v9, v0
	v_mov_b32_e32 v10, v0
	v_mov_b32_e32 v11, v0
	v_mov_b32_e32 v12, v0
	v_mov_b32_e32 v13, v0
	v_mov_b32_e32 v14, v0
	v_mov_b32_e32 v15, v0
	v_mov_b32_e32 v16, v0
	v_mov_b32_e32 v17, v0
	v_mov_b32_e32 v18, v0
	v_mov_b32_e32 v19, v0
	v_mov_b32_e32 v20, v0
	v_mov_b32_e32 v21, v0
	v_mov_b32_e32 v22, v0
	v_mov_b32_e32 v23, v0
	v_mov_b32_e32 v24, v0
	v_mov_b32_e32 v25, v0
	v_mov_b32_e32 v26, v0
	v_mov_b32_e32 v27, v0
	v_mov_b32_e32 v28, v0
	v_mov_b32_e32 v29, v0
	v_mov_b32_e32 v30, v0
	v_mov_b32_e32 v31, v0
	v_mov_b32_e32 v32, v0
	v_mov_b32_e32 v33, v0
	v_mov_b32_e32 v34, v0
	v_mov_b32_e32 v35, v0
	v_mov_b32_e32 v36, v0
	v_mov_b32_e32 v37, v0
	v_mov_b32_e32 v38, v0
	v_mov_b32_e32 v39, v0
	v_mov_b32_e32 v40, v0
	v_mov_b32_e32 v41, v0
	v_mov_b32_e32 v42, v0
	v_mov_b32_e32 v43, v0
	v_mov_b32_e32 v44, v0
	v_mov_b32_e32 v45, v0
	v_mov_b32_e32 v46, v0
	v_mov_b32_e32 v47, v0
	v_mov_b32_e32 v48, v0
	v_mov_b32_e32 v49, v0
	v_mov_b32_e32 v50, v0
	v_mov_b32_e32 v51, v0
	v_mov_b32_e32 v52, v0
	v_mov_b32_e32 v53, v0
	v_mov_b32_e32 v54, v0
	v_mov_b32_e32 v55, v0
	v_mov_b32_e32 v56, v0
	v_mov_b32_e32 v57, v0
	v_mov_b32_e32 v58, v0
	v_mov_b32_e32 v59, v0
	v_mov_b32_e32 v60, v0
	v_mov_b32_e32 v61, v0
	v_mov_b32_e32 v62, v0
	v_mov_b32_e32 v63, v0
	s_waitcnt vmcnt(0) lgkmcnt(0)
	s_barrier
	v_add3_u32 v190, 0, v134, v135
	v_add_u32_e32 v191, 0x4000, v190
	s_nop 0
	v_readfirstlane_b32 s82, v191
	v_lshl_add_u32 v191, v108, 1, 0
	s_nop 0
	v_readfirstlane_b32 s83, v190
	v_add3_u32 v191, v191, v135, s19
	s_nop 0
	v_readfirstlane_b32 s84, v191
	v_add_u32_e32 v191, 0x400, v190
	s_nop 0
	v_readfirstlane_b32 s85, v191
	v_lshl_add_u32 v191, v110, 1, 0
	v_add3_u32 v191, v191, v135, s19
	s_nop 0
	v_readfirstlane_b32 s86, v191
	v_add_u32_e32 v191, 0x800, v190
	s_nop 0
	v_readfirstlane_b32 s87, v191
	v_lshl_add_u32 v191, v112, 1, 0
	v_add3_u32 v191, v191, v135, s19
	s_nop 0
	v_readfirstlane_b32 s88, v191
	v_add_u32_e32 v190, 0xc00, v190
	s_nop 0
	v_readfirstlane_b32 s89, v190
	v_subrev_u32_e32 v192, s52, v88
	v_subrev_u32_e32 v193, s52, v90
	v_subrev_u32_e32 v194, s52, v92
	v_subrev_u32_e32 v195, s52, v94
	v_subrev_u32_e32 v196, s52, v96
	v_subrev_u32_e32 v197, s52, v98
	v_subrev_u32_e32 v198, s52, v100
	v_subrev_u32_e32 v199, s52, v102
	v_subrev_u32_e32 v195, 0x400, v195
	v_subrev_u32_e32 v194, 0x400, v194
	v_subrev_u32_e32 v197, 0x800, v197
	v_subrev_u32_e32 v196, 0x800, v196
	v_subrev_u32_e32 v199, 0xc00, v199
	v_subrev_u32_e32 v198, 0xc00, v198
	s_and_b32 s27, s25, 0x4000
	s_xor_b32 s26, s27, 0x4000
	s_lshl_b32 s26, s26, 1
	s_add_i32 s26, s26, 32
	s_lshl_b32 s27, s27, 1
	s_add_i32 s27, s27, 32
.LBB0_691:
	s_xor_b32 s26, s26, 0x8000
	s_xor_b32 s27, s27, 0x8000
	s_add_u32 s90, s52, s14
	s_addc_u32 s91, s53, s15
	s_add_i32 m0, s27, s83
	v_add3_u32 v139, s26, v113, v136
	global_load_lds_dwordx4 v193, s[90:91]
	global_load_lds_dwordx4 v195, s[90:91] offset:1024
	global_load_lds_dwordx4 v197, s[90:91] offset:2048
	global_load_lds_dwordx4 v199, s[90:91] offset:3072
	s_add_i32 m0, s27, s82
	v_add3_u32 v172, s26, v114, v136
	global_load_lds_dwordx4 v192, s[90:91]
	global_load_lds_dwordx4 v194, s[90:91] offset:1024
	global_load_lds_dwordx4 v196, s[90:91] offset:2048
	global_load_lds_dwordx4 v198, s[90:91] offset:3072
	v_add_u32_e32 v160, v139, v137
	v_add_u32_e32 v168, v172, v137
	s_addk_i32 s25, 0x4000
	s_add_u32 s14, s14, 0x80
	s_addc_u32 s15, s15, 0
	ds_read_b128 v[140:143], v160
	ds_read_b128 v[148:151], v168 offset:16384
	ds_read_b128 v[152:155], v168 offset:18432
	ds_read_b128 v[164:167], v168 offset:20480
	ds_read_b128 v[168:171], v168 offset:22528
	ds_read_b128 v[144:147], v160 offset:2048
	ds_read_b128 v[156:159], v160 offset:4096
	ds_read_b128 v[160:163], v160 offset:6144
	v_add_u32_e32 v139, v139, v138
	v_add_u32_e32 v236, v172, v138
	ds_read_b128 v[204:207], v139
	ds_read_b128 v[208:211], v236 offset:16384
	ds_read_b128 v[212:215], v236 offset:18432
	ds_read_b128 v[216:219], v236 offset:20480
	ds_read_b128 v[220:223], v236 offset:22528
	ds_read_b128 v[224:227], v139 offset:2048
	ds_read_b128 v[228:231], v139 offset:4096
	ds_read_b128 v[232:235], v139 offset:6144
	s_setprio 1
	s_waitcnt lgkmcnt(11)
	v_mfma_f32_16x16x32_bf16 v[60:63], v[140:143], v[148:151], v[60:63]
	v_mfma_f32_16x16x32_bf16 v[56:59], v[140:143], v[152:155], v[56:59]
	v_mfma_f32_16x16x32_bf16 v[52:55], v[140:143], v[164:167], v[52:55]
	v_mfma_f32_16x16x32_bf16 v[48:51], v[140:143], v[168:171], v[48:51]
	s_waitcnt lgkmcnt(10)
	v_mfma_f32_16x16x32_bf16 v[44:47], v[144:147], v[148:151], v[44:47]
	v_mfma_f32_16x16x32_bf16 v[40:43], v[144:147], v[152:155], v[40:43]
	v_mfma_f32_16x16x32_bf16 v[36:39], v[144:147], v[164:167], v[36:39]
	v_mfma_f32_16x16x32_bf16 v[32:35], v[144:147], v[168:171], v[32:35]
	s_waitcnt lgkmcnt(9)
	v_mfma_f32_16x16x32_bf16 v[28:31], v[156:159], v[148:151], v[28:31]
	v_mfma_f32_16x16x32_bf16 v[24:27], v[156:159], v[152:155], v[24:27]
	v_mfma_f32_16x16x32_bf16 v[20:23], v[156:159], v[164:167], v[20:23]
	v_mfma_f32_16x16x32_bf16 v[16:19], v[156:159], v[168:171], v[16:19]
	s_waitcnt lgkmcnt(8)
	v_mfma_f32_16x16x32_bf16 v[12:15], v[160:163], v[148:151], v[12:15]
	v_mfma_f32_16x16x32_bf16 v[8:11], v[160:163], v[152:155], v[8:11]
	v_mfma_f32_16x16x32_bf16 v[4:7], v[160:163], v[164:167], v[4:7]
	v_mfma_f32_16x16x32_bf16 v[0:3], v[160:163], v[168:171], v[0:3]
	s_waitcnt lgkmcnt(3)
	v_mfma_f32_16x16x32_bf16 v[60:63], v[204:207], v[208:211], v[60:63]
	v_mfma_f32_16x16x32_bf16 v[56:59], v[204:207], v[212:215], v[56:59]
	v_mfma_f32_16x16x32_bf16 v[52:55], v[204:207], v[216:219], v[52:55]
	v_mfma_f32_16x16x32_bf16 v[48:51], v[204:207], v[220:223], v[48:51]
	s_waitcnt lgkmcnt(2)
	v_mfma_f32_16x16x32_bf16 v[44:47], v[224:227], v[208:211], v[44:47]
	v_mfma_f32_16x16x32_bf16 v[40:43], v[224:227], v[212:215], v[40:43]
	v_mfma_f32_16x16x32_bf16 v[36:39], v[224:227], v[216:219], v[36:39]
	v_mfma_f32_16x16x32_bf16 v[32:35], v[224:227], v[220:223], v[32:35]
	s_waitcnt lgkmcnt(1)
	v_mfma_f32_16x16x32_bf16 v[28:31], v[228:231], v[208:211], v[28:31]
	v_mfma_f32_16x16x32_bf16 v[24:27], v[228:231], v[212:215], v[24:27]
	v_mfma_f32_16x16x32_bf16 v[20:23], v[228:231], v[216:219], v[20:23]
	v_mfma_f32_16x16x32_bf16 v[16:19], v[228:231], v[220:223], v[16:19]
	s_waitcnt lgkmcnt(0)
	v_mfma_f32_16x16x32_bf16 v[12:15], v[232:235], v[208:211], v[12:15]
	v_mfma_f32_16x16x32_bf16 v[8:11], v[232:235], v[212:215], v[8:11]
	v_mfma_f32_16x16x32_bf16 v[4:7], v[232:235], v[216:219], v[4:7]
	v_mfma_f32_16x16x32_bf16 v[0:3], v[232:235], v[220:223], v[0:3]
	s_setprio 0
	s_cmpk_eq_i32 s14, 0x1f80
	s_waitcnt vmcnt(0)
	s_barrier
	s_cbranch_scc0 .LBB0_691
	ds_read_b128 v[88:91], v117 offset:55296
	ds_read_b128 v[92:95], v117 offset:53248
	ds_read_b128 v[96:99], v118 offset:38912
	ds_read_b128 v[100:103], v118 offset:36864
	ds_read_b128 v[140:143], v117 offset:51200
	ds_read_b128 v[144:147], v117 offset:49152
	ds_read_b128 v[148:151], v118 offset:34816
	ds_read_b128 v[152:155], v118 offset:32768
	ds_read_b128 v[204:207], v119 offset:32768
	ds_read_b128 v[208:211], v119 offset:34816
	ds_read_b128 v[212:215], v120 offset:49152
	ds_read_b128 v[216:219], v120 offset:51200
	ds_read_b128 v[220:223], v119 offset:36864
	ds_read_b128 v[224:227], v119 offset:38912
	ds_read_b128 v[228:231], v120 offset:53248
	ds_read_b128 v[232:235], v120 offset:55296
	s_setprio 1
	s_waitcnt lgkmcnt(13)
	v_mfma_f32_16x16x32_bf16 v[4:7], v[96:99], v[92:95], v[4:7]
	v_mfma_f32_16x16x32_bf16 v[0:3], v[96:99], v[88:91], v[0:3]
	s_waitcnt lgkmcnt(8)
	v_mfma_f32_16x16x32_bf16 v[60:63], v[152:155], v[144:147], v[60:63]
	v_mfma_f32_16x16x32_bf16 v[56:59], v[152:155], v[140:143], v[56:59]
	v_mfma_f32_16x16x32_bf16 v[52:55], v[152:155], v[92:95], v[52:55]
	v_mfma_f32_16x16x32_bf16 v[48:51], v[152:155], v[88:91], v[48:51]
	v_mfma_f32_16x16x32_bf16 v[44:47], v[148:151], v[144:147], v[44:47]
	v_mfma_f32_16x16x32_bf16 v[40:43], v[148:151], v[140:143], v[40:43]
	v_mfma_f32_16x16x32_bf16 v[36:39], v[148:151], v[92:95], v[36:39]
	v_mfma_f32_16x16x32_bf16 v[32:35], v[148:151], v[88:91], v[32:35]
	v_mfma_f32_16x16x32_bf16 v[28:31], v[100:103], v[144:147], v[28:31]
	v_mfma_f32_16x16x32_bf16 v[24:27], v[100:103], v[140:143], v[24:27]
	v_mfma_f32_16x16x32_bf16 v[20:23], v[100:103], v[92:95], v[20:23]
	v_mfma_f32_16x16x32_bf16 v[16:19], v[100:103], v[88:91], v[16:19]
	v_mfma_f32_16x16x32_bf16 v[12:15], v[96:99], v[144:147], v[12:15]
	v_mfma_f32_16x16x32_bf16 v[8:11], v[96:99], v[140:143], v[8:11]
	s_waitcnt lgkmcnt(1)
	v_mfma_f32_16x16x32_bf16 v[4:7], v[224:227], v[228:231], v[4:7]
	s_waitcnt lgkmcnt(0)
	v_mfma_f32_16x16x32_bf16 v[0:3], v[224:227], v[232:235], v[0:3]
	v_mfma_f32_16x16x32_bf16 v[60:63], v[204:207], v[212:215], v[60:63]
	v_mfma_f32_16x16x32_bf16 v[56:59], v[204:207], v[216:219], v[56:59]
	v_mfma_f32_16x16x32_bf16 v[52:55], v[204:207], v[228:231], v[52:55]
	v_mfma_f32_16x16x32_bf16 v[48:51], v[204:207], v[232:235], v[48:51]
	v_mfma_f32_16x16x32_bf16 v[44:47], v[208:211], v[212:215], v[44:47]
	v_mfma_f32_16x16x32_bf16 v[40:43], v[208:211], v[216:219], v[40:43]
	v_mfma_f32_16x16x32_bf16 v[36:39], v[208:211], v[228:231], v[36:39]
	v_mfma_f32_16x16x32_bf16 v[32:35], v[208:211], v[232:235], v[32:35]
	v_mfma_f32_16x16x32_bf16 v[28:31], v[220:223], v[212:215], v[28:31]
	v_mfma_f32_16x16x32_bf16 v[24:27], v[220:223], v[216:219], v[24:27]
	v_mfma_f32_16x16x32_bf16 v[20:23], v[220:223], v[228:231], v[20:23]
	v_mfma_f32_16x16x32_bf16 v[16:19], v[220:223], v[232:235], v[16:19]
	v_mfma_f32_16x16x32_bf16 v[12:15], v[224:227], v[212:215], v[12:15]
	v_mfma_f32_16x16x32_bf16 v[8:11], v[224:227], v[216:219], v[8:11]
	s_setprio 0
	s_barrier
	ds_write2_b32 v115, v60, v56 offset1:16
	ds_write2_b32 v115, v61, v57 offset0:132 offset1:148
	v_add_u32_e32 v56, 0x400, v115
	ds_write2_b32 v56, v62, v58 offset0:8 offset1:24
	ds_write2_b32 v56, v63, v59 offset0:140 offset1:156
	ds_write2_b32 v115, v52, v48 offset0:32 offset1:48
	ds_write2_b32 v115, v53, v49 offset0:164 offset1:180
	ds_write2_b32 v56, v54, v50 offset0:40 offset1:56
	ds_write2_b32 v56, v55, v51 offset0:172 offset1:188
	v_add_u32_e32 v48, 0x2000, v115
	ds_write2_b32 v48, v44, v40 offset0:64 offset1:80
	ds_write2_b32 v48, v45, v41 offset0:196 offset1:212
	v_add_u32_e32 v40, 0x2400, v115
	ds_write2_b32 v40, v46, v42 offset0:72 offset1:88
	ds_write2_b32 v40, v47, v43 offset0:204 offset1:220
	ds_write2_b32 v48, v36, v32 offset0:96 offset1:112
	ds_write2_b32 v48, v37, v33 offset0:228 offset1:244
	ds_write2_b32 v40, v38, v34 offset0:104 offset1:120
	ds_write2_b32 v40, v39, v35 offset0:236 offset1:252
	v_add_u32_e32 v32, 0x4000, v115
	ds_write2_b32 v32, v28, v24 offset0:128 offset1:144
	v_add_u32_e32 v24, 0x4400, v115
	ds_write2_b32 v24, v29, v25 offset0:4 offset1:20
	ds_write2_b32 v24, v30, v26 offset0:136 offset1:152
	v_add_u32_e32 v25, 0x4800, v115
	ds_write2_b32 v25, v31, v27 offset0:12 offset1:28
	ds_write2_b32 v32, v20, v16 offset0:160 offset1:176
	ds_write2_b32 v24, v21, v17 offset0:36 offset1:52
	ds_write2_b32 v24, v22, v18 offset0:168 offset1:184
	ds_write2_b32 v25, v23, v19 offset0:44 offset1:60
	v_add_u32_e32 v16, 0x6000, v115
	ds_write2_b32 v16, v12, v8 offset0:192 offset1:208
	v_add_u32_e32 v8, 0x6400, v115
	ds_write2_b32 v8, v13, v9 offset0:68 offset1:84
	ds_write2_b32 v8, v14, v10 offset0:200 offset1:216
	v_add_u32_e32 v9, 0x6800, v115
	ds_write2_b32 v9, v15, v11 offset0:76 offset1:92
	ds_write2_b32 v16, v4, v0 offset0:224 offset1:240
	ds_write2_b32 v8, v5, v1 offset0:100 offset1:116
	ds_write2_b32 v8, v6, v2 offset0:232 offset1:248
	ds_write2_b32 v9, v7, v3 offset0:108 offset1:124
	v_or_b32_e32 v0, s23, v116
	v_ashrrev_i32_e32 v1, 31, v0
	v_lshlrev_b64 v[2:3], 2, v[0:1]
	v_lshl_add_u64 v[0:1], s[12:13], 0, v[2:3]
	v_lshl_add_u64 v[2:3], s[10:11], 0, v[2:3]
	v_add_u32_e32 v4, s24, v129
	s_mov_b32 s14, 0
	s_waitcnt lgkmcnt(0)
	s_barrier

.LBB0_701:
	s_and_b32 s14, s18, 0x380
	v_add_lshl_u32 v72, v141, s14, 13
	v_lshl_add_u64 v[98:99], v[86:87], 0, v[72:73]
	v_add_lshl_u32 v72, v143, s14, 13
	v_lshl_add_u64 v[100:101], v[90:91], 0, v[72:73]
	v_add_lshl_u32 v72, v145, s14, 13
	s_lshl_b32 s24, s23, 7
	v_lshl_add_u64 v[102:103], v[86:87], 0, v[72:73]
	v_add_lshl_u32 v72, v147, s14, 13
	s_ashr_i32 s14, s23, 3
	s_and_b32 s24, s24, 0x380
	v_add_u32_e32 v2, 0x4000, v135
	v_lshl_add_u64 v[104:105], v[94:95], 0, v[72:73]
	s_add_i32 s15, s14, s17
	v_add_lshl_u32 v72, s24, v134, 13
	v_readfirstlane_b32 s25, v2
	s_lshl_b32 s15, s15, 7
	v_lshl_add_u64 v[0:1], v[74:75], 0, v[72:73]
	s_mov_b32 m0, s25
	v_readfirstlane_b32 s25, v135
	global_load_lds_dwordx4 v[0:1], off
	v_add_u32_e32 v0, s15, v134
	v_ashrrev_i32_e32 v1, 31, v0
	v_lshlrev_b64 v[0:1], 13, v[0:1]
	v_lshl_add_u64 v[0:1], v[80:81], 0, v[0:1]
	s_mov_b32 m0, s25
	v_add_lshl_u32 v72, s24, v126, 13
	v_readfirstlane_b32 s25, v151
	global_load_lds_dwordx4 v[0:1], off
	v_lshl_add_u64 v[0:1], v[76:77], 0, v[72:73]
	s_mov_b32 m0, s25
	v_add_u32_e32 v2, 0x400, v135
	global_load_lds_dwordx4 v[0:1], off
	v_add_u32_e32 v0, s15, v126
	v_ashrrev_i32_e32 v1, 31, v0
	v_lshlrev_b64 v[0:1], 13, v[0:1]
	v_readfirstlane_b32 s25, v2
	v_lshl_add_u64 v[0:1], v[82:83], 0, v[0:1]
	s_mov_b32 m0, s25
	v_add_lshl_u32 v72, s24, v127, 13
	v_readfirstlane_b32 s25, v152
	global_load_lds_dwordx4 v[0:1], off
	v_lshl_add_u64 v[0:1], v[74:75], 0, v[72:73]
	s_mov_b32 m0, s25
	v_add_u32_e32 v2, 0x800, v135
	global_load_lds_dwordx4 v[0:1], off
	v_add_u32_e32 v0, s15, v127
	v_ashrrev_i32_e32 v1, 31, v0
	v_lshlrev_b64 v[0:1], 13, v[0:1]
	v_readfirstlane_b32 s25, v2
	v_lshl_add_u64 v[0:1], v[80:81], 0, v[0:1]
	s_mov_b32 m0, s25
	v_add_lshl_u32 v72, s24, v125, 13
	v_readfirstlane_b32 s25, v153
	global_load_lds_dwordx4 v[0:1], off
	v_lshl_add_u64 v[0:1], v[78:79], 0, v[72:73]
	s_mov_b32 m0, s25
	v_add_u32_e32 v2, 0xc00, v135
	global_load_lds_dwordx4 v[0:1], off
	v_add_u32_e32 v0, s15, v125
	v_ashrrev_i32_e32 v1, 31, v0
	v_lshlrev_b64 v[0:1], 13, v[0:1]
	v_readfirstlane_b32 s15, v2
	v_lshl_add_u64 v[0:1], v[84:85], 0, v[0:1]
	s_mov_b32 m0, s15
	s_lshl_b32 s25, s14, 7
	global_load_lds_dwordx4 v[0:1], off
	v_add_u32_e32 v0, s25, v142
	v_ashrrev_i32_e32 v1, 31, v0
	v_lshlrev_b64 v[0:1], 13, v[0:1]
	v_lshl_add_u64 v[106:107], v[88:89], 0, v[0:1]
	v_add_u32_e32 v0, s25, v144
	v_ashrrev_i32_e32 v1, 31, v0
	v_lshlrev_b64 v[0:1], 13, v[0:1]
	v_lshl_add_u64 v[108:109], v[92:93], 0, v[0:1]
	v_add_u32_e32 v0, s25, v146
	v_ashrrev_i32_e32 v1, 31, v0
	v_lshlrev_b64 v[0:1], 13, v[0:1]
	v_lshl_add_u64 v[110:111], v[88:89], 0, v[0:1]
	v_add_u32_e32 v0, s25, v148
	v_ashrrev_i32_e32 v1, 31, v0
	v_lshlrev_b64 v[0:1], 13, v[0:1]
	v_lshl_add_u64 v[112:113], v[96:97], 0, v[0:1]
	s_mov_b64 s[14:15], 0
	s_mov_b32 s26, 0
	v_mov_b32_e32 v0, 0
	v_mov_b32_e32 v1, v73
	v_mov_b32_e32 v2, v73
	v_mov_b32_e32 v3, v73
	v_mov_b32_e32 v4, 0
	v_mov_b32_e32 v5, v73
	v_mov_b32_e32 v6, v73
	v_mov_b32_e32 v7, v73
	v_mov_b32_e32 v8, 0
	v_mov_b32_e32 v9, v73
	v_mov_b32_e32 v10, v73
	v_mov_b32_e32 v11, v73
	v_mov_b32_e32 v12, 0
	v_mov_b32_e32 v13, v73
	v_mov_b32_e32 v14, v73
	v_mov_b32_e32 v15, v73
	v_mov_b32_e32 v16, 0
	v_mov_b32_e32 v17, v73
	v_mov_b32_e32 v18, v73
	v_mov_b32_e32 v19, v73
	v_mov_b32_e32 v20, 0
	v_mov_b32_e32 v21, v73
	v_mov_b32_e32 v22, v73
	v_mov_b32_e32 v23, v73
	v_mov_b32_e32 v24, 0
	v_mov_b32_e32 v25, v73
	v_mov_b32_e32 v26, v73
	v_mov_b32_e32 v27, v73
	v_mov_b32_e32 v28, 0
	v_mov_b32_e32 v29, v73
	v_mov_b32_e32 v30, v73
	v_mov_b32_e32 v31, v73
	v_mov_b32_e32 v32, 0
	v_mov_b32_e32 v33, v73
	v_mov_b32_e32 v34, v73
	v_mov_b32_e32 v35, v73
	v_mov_b32_e32 v36, 0
	v_mov_b32_e32 v37, v73
	v_mov_b32_e32 v38, v73
	v_mov_b32_e32 v39, v73
	v_mov_b32_e32 v40, 0
	v_mov_b32_e32 v41, v73
	v_mov_b32_e32 v42, v73
	v_mov_b32_e32 v43, v73
	v_mov_b32_e32 v44, 0
	v_mov_b32_e32 v45, v73
	v_mov_b32_e32 v46, v73
	v_mov_b32_e32 v47, v73
	v_mov_b32_e32 v48, 0
	v_mov_b32_e32 v49, v73
	v_mov_b32_e32 v50, v73
	v_mov_b32_e32 v51, v73
	v_mov_b32_e32 v52, 0
	v_mov_b32_e32 v53, v73
	v_mov_b32_e32 v54, v73
	v_mov_b32_e32 v55, v73
	v_mov_b32_e32 v56, 0
	v_mov_b32_e32 v57, v73
	v_mov_b32_e32 v58, v73
	v_mov_b32_e32 v59, v73
	v_mov_b32_e32 v60, 0
	v_mov_b32_e32 v61, v73
	v_mov_b32_e32 v62, v73
	v_mov_b32_e32 v63, v73
	s_waitcnt vmcnt(0) lgkmcnt(0)
	s_barrier
	v_lshlrev_b32_e32 v190, 1, v132
	v_lshlrev_b32_e32 v191, 1, v133
	v_add3_u32 v190, 0, v190, v191
	v_add_u32_e32 v192, 0x4000, v190
	s_nop 0
	v_readfirstlane_b32 s82, v192
	v_lshl_add_u32 v192, v118, 1, 0
	s_nop 0
	v_readfirstlane_b32 s83, v190
	v_add3_u32 v192, v192, v191, s19
	s_nop 0
	v_readfirstlane_b32 s84, v192
	v_add_u32_e32 v192, 0x400, v190
	s_nop 0
	v_readfirstlane_b32 s85, v192
	v_lshl_add_u32 v192, v119, 1, 0
	v_add3_u32 v192, v192, v191, s19
	s_nop 0
	v_readfirstlane_b32 s86, v192
	v_add_u32_e32 v192, 0x800, v190
	s_nop 0
	v_readfirstlane_b32 s87, v192
	v_lshl_add_u32 v192, v120, 1, 0
	v_add3_u32 v191, v192, v191, s19
	s_nop 0
	v_readfirstlane_b32 s88, v191
	v_add_u32_e32 v190, 0xc00, v190
	s_nop 0
	v_readfirstlane_b32 s89, v190
	v_subrev_u32_e32 v193, s52, v98
	v_subrev_u32_e32 v194, s52, v106
	v_subrev_u32_e32 v195, s52, v100
	v_subrev_u32_e32 v196, s52, v108
	v_subrev_u32_e32 v197, s52, v102
	v_subrev_u32_e32 v198, s52, v110
	v_subrev_u32_e32 v199, s52, v104
	v_subrev_u32_e32 v200, s52, v112
	v_subrev_u32_e32 v196, 0x400, v196
	v_subrev_u32_e32 v195, 0x400, v195
	v_subrev_u32_e32 v198, 0x800, v198
	v_subrev_u32_e32 v197, 0x800, v197
	v_subrev_u32_e32 v200, 0xc00, v200
	v_subrev_u32_e32 v199, 0xc00, v199
	s_and_b32 s28, s26, 0x4000
	s_xor_b32 s27, s28, 0x4000
	s_lshl_b32 s27, s27, 1
	s_add_i32 s27, s27, 32
	s_lshl_b32 s28, s28, 1
	s_add_i32 s28, s28, 32
.LBB0_702:
	s_xor_b32 s27, s27, 0x8000
	s_xor_b32 s28, s28, 0x8000
	s_add_u32 s90, s52, s14
	s_addc_u32 s91, s53, s15
	s_add_i32 m0, s28, s83
	v_lshlrev_b32_e32 v72, 1, v131
	global_load_lds_dwordx4 v194, s[90:91]
	global_load_lds_dwordx4 v196, s[90:91] offset:1024
	global_load_lds_dwordx4 v198, s[90:91] offset:2048
	global_load_lds_dwordx4 v200, s[90:91] offset:3072
	s_add_i32 m0, s28, s82
	v_add3_u32 v178, s27, v129, v72
	global_load_lds_dwordx4 v193, s[90:91]
	global_load_lds_dwordx4 v195, s[90:91] offset:1024
	global_load_lds_dwordx4 v197, s[90:91] offset:2048
	global_load_lds_dwordx4 v199, s[90:91] offset:3072
	v_lshlrev_b32_e32 v154, 1, v121
	v_add3_u32 v72, s27, v130, v72
	v_add_u32_e32 v174, v178, v154
	v_add_u32_e32 v179, v72, v154
	ds_read_b128 v[154:157], v174
	ds_read_b128 v[162:165], v179 offset:16384
	ds_read_b128 v[166:169], v179 offset:18432
	ds_read_b128 v[182:185], v179 offset:20480
	ds_read_b128 v[186:189], v179 offset:22528
	ds_read_b128 v[158:161], v174 offset:2048
	ds_read_b128 v[170:173], v174 offset:4096
	ds_read_b128 v[174:177], v174 offset:6144
	v_lshlrev_b32_e32 v236, 1, v122
	v_add_u32_e32 v237, v178, v236
	v_add_u32_e32 v72, v72, v236
	ds_read_b128 v[204:207], v237
	ds_read_b128 v[208:211], v72 offset:16384
	ds_read_b128 v[212:215], v72 offset:18432
	ds_read_b128 v[216:219], v72 offset:20480
	ds_read_b128 v[220:223], v72 offset:22528
	ds_read_b128 v[224:227], v237 offset:2048
	ds_read_b128 v[228:231], v237 offset:4096
	ds_read_b128 v[232:235], v237 offset:6144
	s_setprio 1
	s_waitcnt lgkmcnt(11)
	v_mfma_f32_16x16x32_bf16 v[60:63], v[154:157], v[162:165], v[60:63]
	v_mfma_f32_16x16x32_bf16 v[56:59], v[154:157], v[166:169], v[56:59]
	v_mfma_f32_16x16x32_bf16 v[52:55], v[154:157], v[182:185], v[52:55]
	v_mfma_f32_16x16x32_bf16 v[48:51], v[154:157], v[186:189], v[48:51]
	s_waitcnt lgkmcnt(10)
	v_mfma_f32_16x16x32_bf16 v[44:47], v[158:161], v[162:165], v[44:47]
	v_mfma_f32_16x16x32_bf16 v[40:43], v[158:161], v[166:169], v[40:43]
	v_mfma_f32_16x16x32_bf16 v[36:39], v[158:161], v[182:185], v[36:39]
	v_mfma_f32_16x16x32_bf16 v[32:35], v[158:161], v[186:189], v[32:35]
	s_waitcnt lgkmcnt(9)
	v_mfma_f32_16x16x32_bf16 v[28:31], v[170:173], v[162:165], v[28:31]
	v_mfma_f32_16x16x32_bf16 v[24:27], v[170:173], v[166:169], v[24:27]
	v_mfma_f32_16x16x32_bf16 v[20:23], v[170:173], v[182:185], v[20:23]
	v_mfma_f32_16x16x32_bf16 v[16:19], v[170:173], v[186:189], v[16:19]
	s_waitcnt lgkmcnt(8)
	v_mfma_f32_16x16x32_bf16 v[12:15], v[174:177], v[162:165], v[12:15]
	v_mfma_f32_16x16x32_bf16 v[8:11], v[174:177], v[166:169], v[8:11]
	v_mfma_f32_16x16x32_bf16 v[4:7], v[174:177], v[182:185], v[4:7]
	v_mfma_f32_16x16x32_bf16 v[0:3], v[174:177], v[186:189], v[0:3]
	s_waitcnt lgkmcnt(3)
	v_mfma_f32_16x16x32_bf16 v[60:63], v[204:207], v[208:211], v[60:63]
	v_mfma_f32_16x16x32_bf16 v[56:59], v[204:207], v[212:215], v[56:59]
	v_mfma_f32_16x16x32_bf16 v[52:55], v[204:207], v[216:219], v[52:55]
	v_mfma_f32_16x16x32_bf16 v[48:51], v[204:207], v[220:223], v[48:51]
	s_waitcnt lgkmcnt(2)
	v_mfma_f32_16x16x32_bf16 v[44:47], v[224:227], v[208:211], v[44:47]
	v_mfma_f32_16x16x32_bf16 v[40:43], v[224:227], v[212:215], v[40:43]
	v_mfma_f32_16x16x32_bf16 v[36:39], v[224:227], v[216:219], v[36:39]
	v_mfma_f32_16x16x32_bf16 v[32:35], v[224:227], v[220:223], v[32:35]
	s_waitcnt lgkmcnt(1)
	v_mfma_f32_16x16x32_bf16 v[28:31], v[228:231], v[208:211], v[28:31]
	v_mfma_f32_16x16x32_bf16 v[24:27], v[228:231], v[212:215], v[24:27]
	v_mfma_f32_16x16x32_bf16 v[20:23], v[228:231], v[216:219], v[20:23]
	v_mfma_f32_16x16x32_bf16 v[16:19], v[228:231], v[220:223], v[16:19]
	s_waitcnt lgkmcnt(0)
	v_mfma_f32_16x16x32_bf16 v[12:15], v[232:235], v[208:211], v[12:15]
	v_mfma_f32_16x16x32_bf16 v[8:11], v[232:235], v[212:215], v[8:11]
	v_mfma_f32_16x16x32_bf16 v[4:7], v[232:235], v[216:219], v[4:7]
	v_mfma_f32_16x16x32_bf16 v[0:3], v[232:235], v[220:223], v[0:3]
	s_setprio 0
	s_add_u32 s14, s14, 0x80
	s_addc_u32 s15, s15, 0
	s_cmpk_eq_i32 s14, 0x1f80
	s_waitcnt vmcnt(0)
	s_barrier
	s_cbranch_scc0 .LBB0_702
	ds_read_b128 v[98:101], v71 offset:32768
	ds_read_b128 v[102:105], v71 offset:34816
	ds_read_b128 v[106:109], v138 offset:49152
	ds_read_b128 v[110:113], v138 offset:51200
	ds_read_b128 v[154:157], v71 offset:36864
	ds_read_b128 v[158:161], v71 offset:38912
	ds_read_b128 v[162:165], v138 offset:53248
	ds_read_b128 v[166:169], v138 offset:55296
	ds_read_b128 v[204:207], v139 offset:32768
	ds_read_b128 v[208:211], v139 offset:34816
	ds_read_b128 v[212:215], v140 offset:49152
	ds_read_b128 v[216:219], v140 offset:51200
	ds_read_b128 v[220:223], v139 offset:36864
	ds_read_b128 v[224:227], v139 offset:38912
	ds_read_b128 v[228:231], v140 offset:53248
	ds_read_b128 v[232:235], v140 offset:55296
	s_setprio 1
	s_waitcnt lgkmcnt(9)
	v_mfma_f32_16x16x32_bf16 v[4:7], v[158:161], v[162:165], v[4:7]
	s_waitcnt lgkmcnt(8)
	v_mfma_f32_16x16x32_bf16 v[0:3], v[158:161], v[166:169], v[0:3]
	v_mfma_f32_16x16x32_bf16 v[60:63], v[98:101], v[106:109], v[60:63]
	v_mfma_f32_16x16x32_bf16 v[56:59], v[98:101], v[110:113], v[56:59]
	v_mfma_f32_16x16x32_bf16 v[52:55], v[98:101], v[162:165], v[52:55]
	v_mfma_f32_16x16x32_bf16 v[48:51], v[98:101], v[166:169], v[48:51]
	v_mfma_f32_16x16x32_bf16 v[44:47], v[102:105], v[106:109], v[44:47]
	v_mfma_f32_16x16x32_bf16 v[40:43], v[102:105], v[110:113], v[40:43]
	v_mfma_f32_16x16x32_bf16 v[36:39], v[102:105], v[162:165], v[36:39]
	v_mfma_f32_16x16x32_bf16 v[32:35], v[102:105], v[166:169], v[32:35]
	v_mfma_f32_16x16x32_bf16 v[28:31], v[154:157], v[106:109], v[28:31]
	v_mfma_f32_16x16x32_bf16 v[24:27], v[154:157], v[110:113], v[24:27]
	v_mfma_f32_16x16x32_bf16 v[20:23], v[154:157], v[162:165], v[20:23]
	v_mfma_f32_16x16x32_bf16 v[16:19], v[154:157], v[166:169], v[16:19]
	v_mfma_f32_16x16x32_bf16 v[12:15], v[158:161], v[106:109], v[12:15]
	v_mfma_f32_16x16x32_bf16 v[8:11], v[158:161], v[110:113], v[8:11]
	s_waitcnt lgkmcnt(1)
	v_mfma_f32_16x16x32_bf16 v[4:7], v[224:227], v[228:231], v[4:7]
	s_waitcnt lgkmcnt(0)
	v_mfma_f32_16x16x32_bf16 v[0:3], v[224:227], v[232:235], v[0:3]
	v_mfma_f32_16x16x32_bf16 v[60:63], v[204:207], v[212:215], v[60:63]
	v_mfma_f32_16x16x32_bf16 v[56:59], v[204:207], v[216:219], v[56:59]
	v_mfma_f32_16x16x32_bf16 v[52:55], v[204:207], v[228:231], v[52:55]
	v_mfma_f32_16x16x32_bf16 v[48:51], v[204:207], v[232:235], v[48:51]
	v_mfma_f32_16x16x32_bf16 v[44:47], v[208:211], v[212:215], v[44:47]
	v_mfma_f32_16x16x32_bf16 v[40:43], v[208:211], v[216:219], v[40:43]
	v_mfma_f32_16x16x32_bf16 v[36:39], v[208:211], v[228:231], v[36:39]
	v_mfma_f32_16x16x32_bf16 v[32:35], v[208:211], v[232:235], v[32:35]
	v_mfma_f32_16x16x32_bf16 v[28:31], v[220:223], v[212:215], v[28:31]
	v_mfma_f32_16x16x32_bf16 v[24:27], v[220:223], v[216:219], v[24:27]
	v_mfma_f32_16x16x32_bf16 v[20:23], v[220:223], v[228:231], v[20:23]
	v_mfma_f32_16x16x32_bf16 v[16:19], v[220:223], v[232:235], v[16:19]
	v_mfma_f32_16x16x32_bf16 v[12:15], v[224:227], v[212:215], v[12:15]
	v_mfma_f32_16x16x32_bf16 v[8:11], v[224:227], v[216:219], v[8:11]
	s_setprio 0
	s_barrier
	ds_write2_b32 v136, v60, v56 offset1:16
	ds_write2_b32 v136, v61, v57 offset0:132 offset1:148
	v_add_u32_e32 v56, 0x400, v136
	ds_write2_b32 v56, v62, v58 offset0:8 offset1:24
	ds_write2_b32 v56, v63, v59 offset0:140 offset1:156
	ds_write2_b32 v136, v52, v48 offset0:32 offset1:48
	ds_write2_b32 v136, v53, v49 offset0:164 offset1:180
	ds_write2_b32 v56, v54, v50 offset0:40 offset1:56
	ds_write2_b32 v56, v55, v51 offset0:172 offset1:188
	v_add_u32_e32 v48, 0x2000, v136
	ds_write2_b32 v48, v44, v40 offset0:64 offset1:80
	ds_write2_b32 v48, v45, v41 offset0:196 offset1:212
	v_add_u32_e32 v40, 0x2400, v136
	ds_write2_b32 v40, v46, v42 offset0:72 offset1:88
	ds_write2_b32 v40, v47, v43 offset0:204 offset1:220
	ds_write2_b32 v48, v36, v32 offset0:96 offset1:112
	ds_write2_b32 v48, v37, v33 offset0:228 offset1:244
	ds_write2_b32 v40, v38, v34 offset0:104 offset1:120
	ds_write2_b32 v40, v39, v35 offset0:236 offset1:252
	v_add_u32_e32 v32, 0x4000, v136
	ds_write2_b32 v32, v28, v24 offset0:128 offset1:144
	v_add_u32_e32 v24, 0x4400, v136
	ds_write2_b32 v24, v29, v25 offset0:4 offset1:20
	ds_write2_b32 v24, v30, v26 offset0:136 offset1:152
	v_add_u32_e32 v25, 0x4800, v136
	ds_write2_b32 v25, v31, v27 offset0:12 offset1:28
	ds_write2_b32 v32, v20, v16 offset0:160 offset1:176
	ds_write2_b32 v24, v21, v17 offset0:36 offset1:52
	ds_write2_b32 v24, v22, v18 offset0:168 offset1:184
	ds_write2_b32 v25, v23, v19 offset0:44 offset1:60
	v_add_u32_e32 v16, 0x6000, v136
	ds_write2_b32 v16, v12, v8 offset0:192 offset1:208
	v_add_u32_e32 v8, 0x6400, v136
	ds_write2_b32 v8, v13, v9 offset0:68 offset1:84
	ds_write2_b32 v8, v14, v10 offset0:200 offset1:216
	v_add_u32_e32 v9, 0x6800, v136
	ds_write2_b32 v9, v15, v11 offset0:76 offset1:92
	ds_write2_b32 v16, v4, v0 offset0:224 offset1:240
	ds_write2_b32 v8, v5, v1 offset0:100 offset1:116
	ds_write2_b32 v8, v6, v2 offset0:232 offset1:248
	ds_write2_b32 v9, v7, v3 offset0:108 offset1:124
	v_or_b32_e32 v0, s24, v137
	v_lshlrev_b32_e32 v72, 2, v0
	v_lshl_add_u64 v[0:1], s[12:13], 0, v[72:73]
	v_lshl_add_u64 v[2:3], s[10:11], 0, v[72:73]
	v_add_u32_e32 v4, s25, v149
	s_mov_b32 s14, 0
	s_waitcnt lgkmcnt(0)
	s_barrier

.LBB0_707:
	s_ashr_i32 s15, s16, 2
	s_add_i32 s10, s15, 0x80
	s_and_b32 s14, s16, 3
	s_ashr_i32 s18, s10, 3
	s_add_i32 s19, s18, s17
	s_lshl_b32 s10, s14, 11
	s_add_u32 s6, s6, s10
	s_addc_u32 s7, s7, 0
	s_add_u32 s16, s8, s10
	s_addc_u32 s17, s9, 0
	s_lshl_b32 s9, s15, 7
	s_lshl_b32 s8, s19, 7
	s_and_b32 s9, s9, 0x380
	v_lshlrev_b32_e32 v83, 1, v2
	v_lshlrev_b32_e32 v84, 1, v3
	v_add_lshl_u32 v0, s9, v134, 13
	v_mov_b32_e32 v1, 0
	v_add3_u32 v20, 32, v83, v84
	v_add_u32_e32 v2, s8, v134
	v_lshl_add_u64 v[4:5], s[16:17], 0, v[0:1]
	v_add_u32_e32 v0, 0x4000, v20
	v_ashrrev_i32_e32 v3, 31, v2
	v_mov_b32_e32 v71, v1
	v_readfirstlane_b32 s19, v0
	v_lshlrev_b64 v[2:3], 13, v[2:3]
	v_lshl_add_u64 v[4:5], v[4:5], 0, v[70:71]
	s_mov_b32 m0, s19
	v_lshl_add_u64 v[2:3], s[6:7], 0, v[2:3]
	v_readfirstlane_b32 s19, v20
	global_load_lds_dwordx4 v[4:5], off
	v_lshl_add_u64 v[2:3], v[2:3], 0, v[70:71]
	s_mov_b32 m0, s19
	v_add_lshl_u32 v0, v126, s9, 12
	s_movk_i32 s15, 0x4000
	global_load_lds_dwordx4 v[2:3], off
	v_lshlrev_b64 v[2:3], 1, v[0:1]
	v_lshl_add_u32 v0, v118, 1, 32
	v_add3_u32 v0, v0, v84, s15
	v_lshl_add_u64 v[4:5], s[16:17], 0, v[2:3]
	v_lshlrev_b64 v[6:7], 1, v[66:67]
	v_readfirstlane_b32 s19, v0
	v_lshl_add_u64 v[4:5], v[4:5], 0, v[6:7]
	s_mov_b32 m0, s19
	v_add_u32_e32 v0, 0x400, v20
	global_load_lds_dwordx4 v[4:5], off
	v_add_u32_e32 v4, s8, v126
	v_ashrrev_i32_e32 v5, 31, v4
	v_lshlrev_b64 v[4:5], 13, v[4:5]
	v_lshl_add_u64 v[8:9], s[6:7], 0, v[4:5]
	v_readfirstlane_b32 s19, v0
	v_lshl_add_u64 v[8:9], v[8:9], 0, v[6:7]
	s_mov_b32 m0, s19
	v_add_lshl_u32 v0, v127, s9, 12
	global_load_lds_dwordx4 v[8:9], off
	v_lshlrev_b64 v[8:9], 1, v[0:1]
	v_lshl_add_u32 v0, v119, 1, 32
	v_add3_u32 v0, v0, v84, s15
	v_lshl_add_u64 v[10:11], s[16:17], 0, v[8:9]
	v_readfirstlane_b32 s19, v0
	v_lshl_add_u64 v[10:11], v[10:11], 0, v[70:71]
	s_mov_b32 m0, s19
	v_add_u32_e32 v0, 0x800, v20
	global_load_lds_dwordx4 v[10:11], off
	v_add_u32_e32 v10, s8, v127
	v_ashrrev_i32_e32 v11, 31, v10
	v_lshlrev_b64 v[10:11], 13, v[10:11]
	v_lshl_add_u64 v[12:13], s[6:7], 0, v[10:11]
	v_readfirstlane_b32 s19, v0
	v_lshl_add_u64 v[12:13], v[12:13], 0, v[70:71]
	s_mov_b32 m0, s19
	v_add_lshl_u32 v0, v125, s9, 12
	global_load_lds_dwordx4 v[12:13], off
	v_lshlrev_b64 v[12:13], 1, v[0:1]
	v_lshl_add_u32 v0, v120, 1, 32
	v_add3_u32 v0, v0, v84, s15
	v_lshl_add_u64 v[14:15], s[16:17], 0, v[12:13]
	v_lshlrev_b64 v[16:17], 1, v[68:69]
	v_readfirstlane_b32 s16, v0
	v_lshl_add_u64 v[14:15], v[14:15], 0, v[16:17]
	s_mov_b32 m0, s16
	v_add_u32_e32 v0, 0xc00, v20
	global_load_lds_dwordx4 v[14:15], off
	v_add_u32_e32 v14, s8, v125
	v_ashrrev_i32_e32 v15, 31, v14
	v_lshlrev_b64 v[14:15], 13, v[14:15]
	v_lshl_add_u64 v[18:19], s[6:7], 0, v[14:15]
	v_readfirstlane_b32 s6, v0
	v_lshl_add_u64 v[18:19], v[18:19], 0, v[16:17]
	s_mov_b32 m0, s6
	s_mov_b32 s11, 0
	global_load_lds_dwordx4 v[18:19], off
	v_or_b32_e32 v0, s9, v124
	v_lshl_add_u64 v[6:7], s[10:11], 0, v[6:7]
	v_add_lshl_u32 v0, v0, v123, 13
	v_lshl_add_u64 v[18:19], s[10:11], 0, v[64:65]
	v_lshl_add_u64 v[2:3], v[6:7], 0, v[2:3]
	v_lshl_add_u64 v[20:21], v[18:19], 0, v[0:1]
	s_mov_b64 s[6:7], 0x800080
	v_lshl_add_u64 v[2:3], s[4:5], 0, v[2:3]
	v_lshl_add_u64 v[20:21], s[4:5], 0, v[20:21]
	s_lshl_b32 s16, s18, 7
	v_lshl_add_u64 v[68:69], v[2:3], 0, s[6:7]
	v_lshl_add_u64 v[2:3], v[6:7], 0, v[4:5]
	v_lshl_add_u64 v[64:65], v[20:21], 0, s[6:7]
	v_add3_u32 v20, v128, s16, v123
	s_mov_b64 s[16:17], 0x8600080
	v_lshl_add_u64 v[2:3], s[4:5], 0, v[2:3]
	v_lshl_add_u64 v[70:71], v[2:3], 0, s[16:17]
	v_lshl_add_u64 v[2:3], v[18:19], 0, v[8:9]
	v_lshl_add_u64 v[2:3], s[4:5], 0, v[2:3]
	v_lshl_add_u64 v[72:73], v[2:3], 0, s[6:7]
	v_lshl_add_u64 v[2:3], v[18:19], 0, v[10:11]
	v_ashrrev_i32_e32 v21, 31, v20
	v_lshl_add_u64 v[2:3], s[4:5], 0, v[2:3]
	v_lshlrev_b64 v[20:21], 13, v[20:21]
	v_lshl_add_u64 v[74:75], v[2:3], 0, s[16:17]
	v_lshl_add_u64 v[2:3], s[10:11], 0, v[16:17]
	v_lshl_add_u64 v[20:21], v[18:19], 0, v[20:21]
	v_lshl_add_u64 v[4:5], v[2:3], 0, v[12:13]
	v_lshl_add_u64 v[2:3], v[2:3], 0, v[14:15]
	v_lshl_add_u64 v[20:21], s[4:5], 0, v[20:21]
	v_lshl_add_u64 v[4:5], s[4:5], 0, v[4:5]
	v_lshl_add_u64 v[2:3], s[4:5], 0, v[2:3]
	v_lshl_add_u64 v[66:67], v[20:21], 0, s[16:17]
	v_lshl_add_u64 v[76:77], v[4:5], 0, s[6:7]
	v_lshl_add_u64 v[78:79], v[2:3], 0, s[16:17]
	s_mov_b64 s[4:5], 0
	v_mov_b32_e32 v0, v1
	v_mov_b32_e32 v2, v1
	v_mov_b32_e32 v3, v1
	v_mov_b32_e32 v4, v1
	v_mov_b32_e32 v5, v1
	v_mov_b32_e32 v6, v1
	v_mov_b32_e32 v7, v1
	v_mov_b32_e32 v8, v1
	v_mov_b32_e32 v9, v1
	v_mov_b32_e32 v10, v1
	v_mov_b32_e32 v11, v1
	v_mov_b32_e32 v12, v1
	v_mov_b32_e32 v13, v1
	v_mov_b32_e32 v14, v1
	v_mov_b32_e32 v15, v1
	v_mov_b32_e32 v16, v1
	v_mov_b32_e32 v17, v1
	v_mov_b32_e32 v18, v1
	v_mov_b32_e32 v19, v1
	v_mov_b32_e32 v20, v1
	v_mov_b32_e32 v21, v1
	v_mov_b32_e32 v22, v1
	v_mov_b32_e32 v23, v1
	v_mov_b32_e32 v24, v1
	v_mov_b32_e32 v25, v1
	v_mov_b32_e32 v26, v1
	v_mov_b32_e32 v27, v1
	v_mov_b32_e32 v28, v1
	v_mov_b32_e32 v29, v1
	v_mov_b32_e32 v30, v1
	v_mov_b32_e32 v31, v1
	v_mov_b32_e32 v32, v1
	v_mov_b32_e32 v33, v1
	v_mov_b32_e32 v34, v1
	v_mov_b32_e32 v35, v1
	v_mov_b32_e32 v36, v1
	v_mov_b32_e32 v37, v1
	v_mov_b32_e32 v38, v1
	v_mov_b32_e32 v39, v1
	v_mov_b32_e32 v40, v1
	v_mov_b32_e32 v41, v1
	v_mov_b32_e32 v42, v1
	v_mov_b32_e32 v43, v1
	v_mov_b32_e32 v44, v1
	v_mov_b32_e32 v45, v1
	v_mov_b32_e32 v46, v1
	v_mov_b32_e32 v47, v1
	v_mov_b32_e32 v48, v1
	v_mov_b32_e32 v49, v1
	v_mov_b32_e32 v50, v1
	v_mov_b32_e32 v51, v1
	v_mov_b32_e32 v52, v1
	v_mov_b32_e32 v53, v1
	v_mov_b32_e32 v54, v1
	v_mov_b32_e32 v55, v1
	v_mov_b32_e32 v56, v1
	v_mov_b32_e32 v57, v1
	v_mov_b32_e32 v58, v1
	v_mov_b32_e32 v59, v1
	v_mov_b32_e32 v60, v1
	v_mov_b32_e32 v61, v1
	v_mov_b32_e32 v62, v1
	v_mov_b32_e32 v63, v1
	s_waitcnt vmcnt(0) lgkmcnt(0)
	s_barrier
	v_add3_u32 v190, 0, v83, v84
	v_add_u32_e32 v191, 0x4000, v190
	s_nop 0
	v_readfirstlane_b32 s82, v191
	v_lshl_add_u32 v191, v118, 1, 0
	s_nop 0
	v_readfirstlane_b32 s83, v190
	v_add3_u32 v191, v191, v84, s15
	s_nop 0
	v_readfirstlane_b32 s84, v191
	v_add_u32_e32 v191, 0x400, v190
	s_nop 0
	v_readfirstlane_b32 s85, v191
	v_lshl_add_u32 v191, v119, 1, 0
	v_add3_u32 v191, v191, v84, s15
	s_nop 0
	v_readfirstlane_b32 s86, v191
	v_add_u32_e32 v191, 0x800, v190
	s_nop 0
	v_readfirstlane_b32 s87, v191
	v_lshl_add_u32 v191, v120, 1, 0
	v_add3_u32 v191, v191, v84, s15
	s_nop 0
	v_readfirstlane_b32 s88, v191
	v_add_u32_e32 v190, 0xc00, v190
	s_nop 0
	v_readfirstlane_b32 s89, v190
	v_subrev_u32_e32 v192, s52, v64
	v_subrev_u32_e32 v193, s52, v66
	v_subrev_u32_e32 v194, s52, v68
	v_subrev_u32_e32 v195, s52, v70
	v_subrev_u32_e32 v196, s52, v72
	v_subrev_u32_e32 v197, s52, v74
	v_subrev_u32_e32 v198, s52, v76
	v_subrev_u32_e32 v199, s52, v78
	v_subrev_u32_e32 v195, 0x400, v195
	v_subrev_u32_e32 v194, 0x400, v194
	v_subrev_u32_e32 v197, 0x800, v197
	v_subrev_u32_e32 v196, 0x800, v196
	v_subrev_u32_e32 v199, 0xc00, v199
	v_subrev_u32_e32 v198, 0xc00, v198
	s_and_b32 s7, s11, 0x4000
	s_xor_b32 s6, s7, 0x4000
	s_lshl_b32 s6, s6, 1
	s_add_i32 s6, s6, 32
	s_lshl_b32 s7, s7, 1
	s_add_i32 s7, s7, 32
.LBB0_708:
	s_xor_b32 s6, s6, 0x8000
	s_xor_b32 s7, s7, 0x8000
	s_add_u32 s90, s52, s4
	s_addc_u32 s91, s53, s5
	s_add_i32 m0, s7, s83
	v_lshlrev_b32_e32 v85, 1, v80
	global_load_lds_dwordx4 v193, s[90:91]
	global_load_lds_dwordx4 v195, s[90:91] offset:1024
	global_load_lds_dwordx4 v197, s[90:91] offset:2048
	global_load_lds_dwordx4 v199, s[90:91] offset:3072
	s_add_i32 m0, s7, s82
	v_add3_u32 v112, s6, v81, v85
	global_load_lds_dwordx4 v192, s[90:91]
	global_load_lds_dwordx4 v194, s[90:91] offset:1024
	global_load_lds_dwordx4 v196, s[90:91] offset:2048
	global_load_lds_dwordx4 v198, s[90:91] offset:3072
	v_lshlrev_b32_e32 v86, 1, v121
	v_add3_u32 v113, s6, v82, v85
	v_add_u32_e32 v87, v112, v86
	v_add_u32_e32 v123, v113, v86
	ds_read_b128 v[88:91], v87
	ds_read_b128 v[96:99], v123 offset:16384
	ds_read_b128 v[100:103], v123 offset:18432
	ds_read_b128 v[124:127], v123 offset:20480
	ds_read_b128 v[128:131], v123 offset:22528
	ds_read_b128 v[92:95], v87 offset:2048
	ds_read_b128 v[104:107], v87 offset:4096
	ds_read_b128 v[108:111], v87 offset:6144
	v_lshlrev_b32_e32 v87, 1, v122
	v_add_u32_e32 v236, v112, v87
	v_add_u32_e32 v112, v113, v87
	ds_read_b128 v[204:207], v236
	ds_read_b128 v[208:211], v112 offset:16384
	ds_read_b128 v[212:215], v112 offset:18432
	ds_read_b128 v[216:219], v112 offset:20480
	ds_read_b128 v[220:223], v112 offset:22528
	ds_read_b128 v[224:227], v236 offset:2048
	ds_read_b128 v[228:231], v236 offset:4096
	ds_read_b128 v[232:235], v236 offset:6144
	s_setprio 1
	s_waitcnt lgkmcnt(11)
	v_mfma_f32_16x16x32_bf16 v[60:63], v[88:91], v[96:99], v[60:63]
	v_mfma_f32_16x16x32_bf16 v[56:59], v[88:91], v[100:103], v[56:59]
	v_mfma_f32_16x16x32_bf16 v[52:55], v[88:91], v[124:127], v[52:55]
	v_mfma_f32_16x16x32_bf16 v[48:51], v[88:91], v[128:131], v[48:51]
	s_waitcnt lgkmcnt(10)
	v_mfma_f32_16x16x32_bf16 v[44:47], v[92:95], v[96:99], v[44:47]
	v_mfma_f32_16x16x32_bf16 v[40:43], v[92:95], v[100:103], v[40:43]
	v_mfma_f32_16x16x32_bf16 v[36:39], v[92:95], v[124:127], v[36:39]
	v_mfma_f32_16x16x32_bf16 v[32:35], v[92:95], v[128:131], v[32:35]
	s_waitcnt lgkmcnt(9)
	v_mfma_f32_16x16x32_bf16 v[28:31], v[104:107], v[96:99], v[28:31]
	v_mfma_f32_16x16x32_bf16 v[24:27], v[104:107], v[100:103], v[24:27]
	v_mfma_f32_16x16x32_bf16 v[20:23], v[104:107], v[124:127], v[20:23]
	v_mfma_f32_16x16x32_bf16 v[16:19], v[104:107], v[128:131], v[16:19]
	s_waitcnt lgkmcnt(8)
	v_mfma_f32_16x16x32_bf16 v[12:15], v[108:111], v[96:99], v[12:15]
	v_mfma_f32_16x16x32_bf16 v[8:11], v[108:111], v[100:103], v[8:11]
	v_mfma_f32_16x16x32_bf16 v[4:7], v[108:111], v[124:127], v[4:7]
	v_mfma_f32_16x16x32_bf16 v[0:3], v[108:111], v[128:131], v[0:3]
	s_waitcnt lgkmcnt(3)
	v_mfma_f32_16x16x32_bf16 v[60:63], v[204:207], v[208:211], v[60:63]
	v_mfma_f32_16x16x32_bf16 v[56:59], v[204:207], v[212:215], v[56:59]
	v_mfma_f32_16x16x32_bf16 v[52:55], v[204:207], v[216:219], v[52:55]
	v_mfma_f32_16x16x32_bf16 v[48:51], v[204:207], v[220:223], v[48:51]
	s_waitcnt lgkmcnt(2)
	v_mfma_f32_16x16x32_bf16 v[44:47], v[224:227], v[208:211], v[44:47]
	v_mfma_f32_16x16x32_bf16 v[40:43], v[224:227], v[212:215], v[40:43]
	v_mfma_f32_16x16x32_bf16 v[36:39], v[224:227], v[216:219], v[36:39]
	v_mfma_f32_16x16x32_bf16 v[32:35], v[224:227], v[220:223], v[32:35]
	s_waitcnt lgkmcnt(1)
	v_mfma_f32_16x16x32_bf16 v[28:31], v[228:231], v[208:211], v[28:31]
	v_mfma_f32_16x16x32_bf16 v[24:27], v[228:231], v[212:215], v[24:27]
	v_mfma_f32_16x16x32_bf16 v[20:23], v[228:231], v[216:219], v[20:23]
	v_mfma_f32_16x16x32_bf16 v[16:19], v[228:231], v[220:223], v[16:19]
	s_waitcnt lgkmcnt(0)
	v_mfma_f32_16x16x32_bf16 v[12:15], v[232:235], v[208:211], v[12:15]
	v_mfma_f32_16x16x32_bf16 v[8:11], v[232:235], v[212:215], v[8:11]
	v_mfma_f32_16x16x32_bf16 v[4:7], v[232:235], v[216:219], v[4:7]
	v_mfma_f32_16x16x32_bf16 v[0:3], v[232:235], v[220:223], v[0:3]
	s_setprio 0
	s_add_u32 s4, s4, 0x80
	s_addc_u32 s5, s5, 0
	s_cmpk_eq_i32 s4, 0x780
	s_waitcnt vmcnt(0)
	s_barrier
	s_cbranch_scc0 .LBB0_708
	v_add3_u32 v84, 32, v81, v85
	v_add3_u32 v85, 32, v82, v85
	v_add_u32_e32 v88, v84, v86
	v_add_u32_e32 v86, v85, v86
	ds_read_b128 v[64:67], v88 offset:32768
	ds_read_b128 v[68:71], v88 offset:34816
	ds_read_b128 v[72:75], v86 offset:49152
	ds_read_b128 v[76:79], v86 offset:51200
	ds_read_b128 v[80:83], v88 offset:36864
	ds_read_b128 v[88:91], v88 offset:38912
	ds_read_b128 v[92:95], v86 offset:53248
	ds_read_b128 v[96:99], v86 offset:55296
	v_add_u32_e32 v84, v84, v87
	v_add_u32_e32 v236, v85, v87
	ds_read_b128 v[204:207], v84 offset:32768
	ds_read_b128 v[208:211], v84 offset:34816
	ds_read_b128 v[212:215], v236 offset:49152
	ds_read_b128 v[216:219], v236 offset:51200
	ds_read_b128 v[220:223], v84 offset:36864
	ds_read_b128 v[224:227], v84 offset:38912
	ds_read_b128 v[228:231], v236 offset:53248
	ds_read_b128 v[232:235], v236 offset:55296
	s_setprio 1
	s_waitcnt lgkmcnt(8)
	v_mfma_f32_16x16x32_bf16 v[0:3], v[88:91], v[96:99], v[0:3]
	v_mfma_f32_16x16x32_bf16 v[60:63], v[64:67], v[72:75], v[60:63]
	v_mfma_f32_16x16x32_bf16 v[56:59], v[64:67], v[76:79], v[56:59]
	v_mfma_f32_16x16x32_bf16 v[52:55], v[64:67], v[92:95], v[52:55]
	v_mfma_f32_16x16x32_bf16 v[48:51], v[64:67], v[96:99], v[48:51]
	v_mfma_f32_16x16x32_bf16 v[44:47], v[68:71], v[72:75], v[44:47]
	v_mfma_f32_16x16x32_bf16 v[40:43], v[68:71], v[76:79], v[40:43]
	v_mfma_f32_16x16x32_bf16 v[36:39], v[68:71], v[92:95], v[36:39]
	v_mfma_f32_16x16x32_bf16 v[32:35], v[68:71], v[96:99], v[32:35]
	v_mfma_f32_16x16x32_bf16 v[28:31], v[80:83], v[72:75], v[28:31]
	v_mfma_f32_16x16x32_bf16 v[24:27], v[80:83], v[76:79], v[24:27]
	v_mfma_f32_16x16x32_bf16 v[20:23], v[80:83], v[92:95], v[20:23]
	v_mfma_f32_16x16x32_bf16 v[16:19], v[80:83], v[96:99], v[16:19]
	v_mfma_f32_16x16x32_bf16 v[12:15], v[88:91], v[72:75], v[12:15]
	v_mfma_f32_16x16x32_bf16 v[8:11], v[88:91], v[76:79], v[8:11]
	v_mfma_f32_16x16x32_bf16 v[4:7], v[88:91], v[92:95], v[4:7]
	s_waitcnt lgkmcnt(0)
	v_mfma_f32_16x16x32_bf16 v[0:3], v[224:227], v[232:235], v[0:3]
	v_mfma_f32_16x16x32_bf16 v[60:63], v[204:207], v[212:215], v[60:63]
	v_mfma_f32_16x16x32_bf16 v[56:59], v[204:207], v[216:219], v[56:59]
	v_mfma_f32_16x16x32_bf16 v[52:55], v[204:207], v[228:231], v[52:55]
	v_mfma_f32_16x16x32_bf16 v[48:51], v[204:207], v[232:235], v[48:51]
	v_mfma_f32_16x16x32_bf16 v[44:47], v[208:211], v[212:215], v[44:47]
	v_mfma_f32_16x16x32_bf16 v[40:43], v[208:211], v[216:219], v[40:43]
	v_mfma_f32_16x16x32_bf16 v[36:39], v[208:211], v[228:231], v[36:39]
	v_mfma_f32_16x16x32_bf16 v[32:35], v[208:211], v[232:235], v[32:35]
	v_mfma_f32_16x16x32_bf16 v[28:31], v[220:223], v[212:215], v[28:31]
	v_mfma_f32_16x16x32_bf16 v[24:27], v[220:223], v[216:219], v[24:27]
	v_mfma_f32_16x16x32_bf16 v[20:23], v[220:223], v[228:231], v[20:23]
	v_mfma_f32_16x16x32_bf16 v[16:19], v[220:223], v[232:235], v[16:19]
	v_mfma_f32_16x16x32_bf16 v[12:15], v[224:227], v[212:215], v[12:15]
	v_mfma_f32_16x16x32_bf16 v[8:11], v[224:227], v[216:219], v[8:11]
	v_mfma_f32_16x16x32_bf16 v[4:7], v[224:227], v[228:231], v[4:7]
	s_setprio 0
	v_lshl_or_b32 v64, v114, 2, v116
	v_mul_u32_u24_e32 v64, 0x210, v64
	v_add3_u32 v64, v115, v117, v64
	s_barrier
	ds_write2_b32 v64, v60, v56 offset1:16
	ds_write2_b32 v64, v61, v57 offset0:132 offset1:148
	v_add_u32_e32 v56, 0x400, v64
	ds_write2_b32 v56, v62, v58 offset0:8 offset1:24
	ds_write2_b32 v56, v63, v59 offset0:140 offset1:156
	ds_write2_b32 v64, v52, v48 offset0:32 offset1:48
	ds_write2_b32 v64, v53, v49 offset0:164 offset1:180
	ds_write2_b32 v56, v54, v50 offset0:40 offset1:56
	ds_write2_b32 v56, v55, v51 offset0:172 offset1:188
	v_add_u32_e32 v48, 0x2000, v64
	ds_write2_b32 v48, v44, v40 offset0:64 offset1:80
	ds_write2_b32 v48, v45, v41 offset0:196 offset1:212
	v_add_u32_e32 v40, 0x2400, v64
	ds_write2_b32 v40, v46, v42 offset0:72 offset1:88
	ds_write2_b32 v40, v47, v43 offset0:204 offset1:220
	ds_write2_b32 v48, v36, v32 offset0:96 offset1:112
	ds_write2_b32 v48, v37, v33 offset0:228 offset1:244
	ds_write2_b32 v40, v38, v34 offset0:104 offset1:120
	ds_write2_b32 v40, v39, v35 offset0:236 offset1:252
	v_add_u32_e32 v32, 0x4000, v64
	ds_write2_b32 v32, v28, v24 offset0:128 offset1:144
	v_add_u32_e32 v24, 0x4400, v64
	ds_write2_b32 v24, v29, v25 offset0:4 offset1:20
	ds_write2_b32 v24, v30, v26 offset0:136 offset1:152
	v_add_u32_e32 v25, 0x4800, v64
	ds_write2_b32 v25, v31, v27 offset0:12 offset1:28
	ds_write2_b32 v32, v20, v16 offset0:160 offset1:176
	ds_write2_b32 v24, v21, v17 offset0:36 offset1:52
	ds_write2_b32 v24, v22, v18 offset0:168 offset1:184
	ds_write2_b32 v25, v23, v19 offset0:44 offset1:60
	v_add_u32_e32 v16, 0x6000, v64
	ds_write2_b32 v16, v12, v8 offset0:192 offset1:208
	v_add_u32_e32 v8, 0x6400, v64
	ds_write2_b32 v8, v13, v9 offset0:68 offset1:84
	ds_write2_b32 v8, v14, v10 offset0:200 offset1:216
	v_add_u32_e32 v9, 0x6800, v64
	ds_write2_b32 v9, v15, v11 offset0:76 offset1:92
	ds_write2_b32 v16, v4, v0 offset0:224 offset1:240
	ds_write2_b32 v8, v5, v1 offset0:100 offset1:116
	ds_write2_b32 v8, v6, v2 offset0:232 offset1:248
	ds_write2_b32 v9, v7, v3 offset0:108 offset1:124
	v_lshlrev_b32_e32 v0, 4, v180
	v_and_b32_e32 v0, 0x70, v0
	s_lshl_b32 s5, s14, 23
	v_or_b32_e32 v0, s9, v0
	s_add_u32 s6, s12, s5
	s_addc_u32 s7, s13, 0
	v_lshlrev_b32_e32 v0, 2, v0
	v_mov_b32_e32 v1, 0
	v_lshrrev_b32_e32 v2, 3, v180
	v_and_b32_e32 v4, 7, v180
	v_lshl_add_u64 v[0:1], s[6:7], 0, v[0:1]
	s_mov_b64 s[6:7], 0x11600000
	v_mul_u32_u24_e32 v3, 0x210, v2
	v_lshlrev_b32_e32 v4, 6, v4
	s_mov_b32 s4, 0
	v_lshl_add_u64 v[0:1], v[0:1], 0, s[6:7]
	v_add3_u32 v3, v3, v4, 32
	s_mov_b32 s5, 0x38e38e39
	s_mov_b32 s6, 0x1ffffee
	s_movk_i32 s7, 0xf800
	s_waitcnt lgkmcnt(0)
	s_barrier

.LBB0_1813:
	s_ashr_i32 s16, s23, 31
	s_lshr_b32 s16, s16, 29
	s_add_i32 s16, s23, s16
	s_ashr_i32 s16, s16, 3
	s_lshl_b32 s24, s16, 7
	s_lshl_b32 s16, s16, 10
	s_lshl_b32 s17, s23, 7
	s_sub_i32 s25, s17, s16
	v_add_u32_e32 v0, s25, v106
	v_ashrrev_i32_e32 v1, 31, v0
	v_add_u32_e32 v2, 0x4000, v107
	v_lshlrev_b64 v[0:1], 11, v[0:1]
	v_readfirstlane_b32 s17, v2
	v_lshl_add_u64 v[0:1], v[66:67], 0, v[0:1]
	s_mov_b32 m0, s17
	v_readfirstlane_b32 s17, v107
	global_load_lds_dwordx4 v[0:1], off
	v_add_u32_e32 v0, s24, v106
	v_ashrrev_i32_e32 v1, 31, v0
	v_lshlrev_b64 v[0:1], 11, v[0:1]
	v_lshl_add_u64 v[2:3], v[72:73], 0, v[0:1]
	s_mov_b32 m0, s17
	v_readfirstlane_b32 s17, v130
	global_load_lds_dwordx4 v[2:3], off
	v_add_u32_e32 v2, s25, v108
	v_ashrrev_i32_e32 v3, 31, v2
	v_lshlrev_b64 v[2:3], 11, v[2:3]
	v_lshl_add_u64 v[2:3], v[68:69], 0, v[2:3]
	s_mov_b32 m0, s17
	v_add_u32_e32 v4, 0x400, v107
	global_load_lds_dwordx4 v[2:3], off
	v_add_u32_e32 v2, s24, v108
	v_ashrrev_i32_e32 v3, 31, v2
	v_lshlrev_b64 v[2:3], 11, v[2:3]
	v_readfirstlane_b32 s17, v4
	v_lshl_add_u64 v[2:3], v[74:75], 0, v[2:3]
	s_mov_b32 m0, s17
	v_readfirstlane_b32 s17, v131
	global_load_lds_dwordx4 v[2:3], off
	v_add_u32_e32 v2, s25, v110
	v_ashrrev_i32_e32 v3, 31, v2
	v_lshlrev_b64 v[2:3], 11, v[2:3]
	v_lshl_add_u64 v[2:3], v[66:67], 0, v[2:3]
	s_mov_b32 m0, s17
	v_add_u32_e32 v4, 0x800, v107
	global_load_lds_dwordx4 v[2:3], off
	v_add_u32_e32 v2, s24, v110
	v_ashrrev_i32_e32 v3, 31, v2
	v_lshlrev_b64 v[2:3], 11, v[2:3]
	v_readfirstlane_b32 s17, v4
	v_lshl_add_u64 v[2:3], v[72:73], 0, v[2:3]
	s_mov_b32 m0, s17
	v_readfirstlane_b32 s17, v132
	global_load_lds_dwordx4 v[2:3], off
	v_add_u32_e32 v2, s25, v112
	v_ashrrev_i32_e32 v3, 31, v2
	v_lshlrev_b64 v[2:3], 11, v[2:3]
	v_lshl_add_u64 v[2:3], v[70:71], 0, v[2:3]
	s_mov_b32 m0, s17
	v_add_u32_e32 v4, 0xc00, v107
	global_load_lds_dwordx4 v[2:3], off
	v_add_u32_e32 v2, s24, v112
	v_ashrrev_i32_e32 v3, 31, v2
	v_lshlrev_b64 v[2:3], 11, v[2:3]
	v_readfirstlane_b32 s17, v4
	v_lshl_add_u64 v[2:3], v[76:77], 0, v[2:3]
	s_mov_b32 m0, s17
	v_lshl_add_u64 v[92:93], v[80:81], 0, v[0:1]
	global_load_lds_dwordx4 v[2:3], off
	v_subrev_u32_e32 v0, s16, v123
	v_ashrrev_i32_e32 v1, 31, v0
	v_lshlrev_b64 v[0:1], 11, v[0:1]
	v_lshl_add_u64 v[94:95], v[82:83], 0, v[0:1]
	v_add_u32_e32 v0, s24, v124
	v_ashrrev_i32_e32 v1, 31, v0
	v_lshlrev_b64 v[0:1], 11, v[0:1]
	v_lshl_add_u64 v[96:97], v[84:85], 0, v[0:1]
	v_subrev_u32_e32 v0, s16, v125
	v_ashrrev_i32_e32 v1, 31, v0
	v_lshlrev_b64 v[0:1], 11, v[0:1]
	v_lshl_add_u64 v[98:99], v[78:79], 0, v[0:1]
	v_add_u32_e32 v0, s24, v126
	v_ashrrev_i32_e32 v1, 31, v0
	v_lshlrev_b64 v[0:1], 11, v[0:1]
	v_lshl_add_u64 v[100:101], v[80:81], 0, v[0:1]
	v_subrev_u32_e32 v0, s16, v64
	v_ashrrev_i32_e32 v1, 31, v0
	v_lshlrev_b64 v[0:1], 11, v[0:1]
	v_subrev_u32_e32 v2, s16, v122
	v_lshl_add_u64 v[102:103], v[86:87], 0, v[0:1]
	v_add_u32_e32 v0, s24, v127
	v_ashrrev_i32_e32 v3, 31, v2
	v_ashrrev_i32_e32 v1, 31, v0
	v_lshlrev_b64 v[2:3], 11, v[2:3]
	v_lshlrev_b64 v[0:1], 11, v[0:1]
	v_lshl_add_u64 v[90:91], v[78:79], 0, v[2:3]
	v_lshl_add_u64 v[104:105], v[88:89], 0, v[0:1]
	s_mov_b32 s26, 0
	s_mov_b64 s[16:17], 0
	v_mov_b32_e32 v0, 0
	v_mov_b32_e32 v1, v65
	v_mov_b32_e32 v2, v65
	v_mov_b32_e32 v3, v65
	v_mov_b32_e32 v4, 0
	v_mov_b32_e32 v5, v65
	v_mov_b32_e32 v6, v65
	v_mov_b32_e32 v7, v65
	v_mov_b32_e32 v8, 0
	v_mov_b32_e32 v9, v65
	v_mov_b32_e32 v10, v65
	v_mov_b32_e32 v11, v65
	v_mov_b32_e32 v12, 0
	v_mov_b32_e32 v13, v65
	v_mov_b32_e32 v14, v65
	v_mov_b32_e32 v15, v65
	v_mov_b32_e32 v16, 0
	v_mov_b32_e32 v17, v65
	v_mov_b32_e32 v18, v65
	v_mov_b32_e32 v19, v65
	v_mov_b32_e32 v20, 0
	v_mov_b32_e32 v21, v65
	v_mov_b32_e32 v22, v65
	v_mov_b32_e32 v23, v65
	v_mov_b32_e32 v24, 0
	v_mov_b32_e32 v25, v65
	v_mov_b32_e32 v26, v65
	v_mov_b32_e32 v27, v65
	v_mov_b32_e32 v28, 0
	v_mov_b32_e32 v29, v65
	v_mov_b32_e32 v30, v65
	v_mov_b32_e32 v31, v65
	s_waitcnt vmcnt(0)
	v_mov_b32_e32 v32, 0
	v_mov_b32_e32 v33, v65
	v_mov_b32_e32 v34, v65
	v_mov_b32_e32 v35, v65
	v_mov_b32_e32 v36, 0
	v_mov_b32_e32 v37, v65
	v_mov_b32_e32 v38, v65
	v_mov_b32_e32 v39, v65
	v_mov_b32_e32 v40, 0
	v_mov_b32_e32 v41, v65
	v_mov_b32_e32 v42, v65
	v_mov_b32_e32 v43, v65
	v_mov_b32_e32 v44, 0
	v_mov_b32_e32 v45, v65
	v_mov_b32_e32 v46, v65
	v_mov_b32_e32 v47, v65
	v_mov_b32_e32 v48, 0
	v_mov_b32_e32 v49, v65
	v_mov_b32_e32 v50, v65
	v_mov_b32_e32 v51, v65
	v_mov_b32_e32 v52, 0
	v_mov_b32_e32 v53, v65
	v_mov_b32_e32 v54, v65
	v_mov_b32_e32 v55, v65
	v_mov_b32_e32 v56, 0
	v_mov_b32_e32 v57, v65
	v_mov_b32_e32 v58, v65
	v_mov_b32_e32 v59, v65
	v_mov_b32_e32 v60, 0
	v_mov_b32_e32 v61, v65
	v_mov_b32_e32 v62, v65
	v_mov_b32_e32 v63, v65
	s_waitcnt lgkmcnt(0)
	s_barrier
	v_add3_u32 v186, 0, v133, v134
	v_add_u32_e32 v187, 0x4000, v186
	s_nop 0
	v_readfirstlane_b32 s82, v187
	v_lshl_add_u32 v187, v109, 1, 0
	s_nop 0
	v_readfirstlane_b32 s83, v186
	v_add3_u32 v187, v187, v134, s19
	s_nop 0
	v_readfirstlane_b32 s84, v187
	v_add_u32_e32 v187, 0x400, v186
	s_nop 0
	v_readfirstlane_b32 s85, v187
	v_lshl_add_u32 v187, v111, 1, 0
	v_add3_u32 v187, v187, v134, s19
	s_nop 0
	v_readfirstlane_b32 s86, v187
	v_add_u32_e32 v187, 0x800, v186
	s_nop 0
	v_readfirstlane_b32 s87, v187
	v_lshl_add_u32 v187, v113, 1, 0
	v_add3_u32 v187, v187, v134, s19
	s_nop 0
	v_readfirstlane_b32 s88, v187
	v_add_u32_e32 v186, 0xc00, v186
	s_nop 0
	v_readfirstlane_b32 s89, v186
	v_subrev_u32_e32 v188, s52, v90
	v_subrev_u32_e32 v189, s52, v92
	v_subrev_u32_e32 v190, s52, v94
	v_subrev_u32_e32 v191, s52, v96
	v_subrev_u32_e32 v192, s52, v98
	v_subrev_u32_e32 v193, s52, v100
	v_subrev_u32_e32 v194, s52, v102
	v_subrev_u32_e32 v195, s52, v104
	v_subrev_u32_e32 v191, 0x400, v191
	v_subrev_u32_e32 v190, 0x400, v190
	v_subrev_u32_e32 v193, 0x800, v193
	v_subrev_u32_e32 v192, 0x800, v192
	v_subrev_u32_e32 v195, 0xc00, v195
	v_subrev_u32_e32 v194, 0xc00, v194
	s_and_b32 s28, s26, 0x4000
	s_xor_b32 s27, s28, 0x4000
	s_lshl_b32 s27, s27, 1
	s_add_i32 s27, s27, 32
	s_lshl_b32 s28, s28, 1
	s_add_i32 s28, s28, 32
.LBB0_1814:
	s_xor_b32 s27, s27, 0x8000
	s_xor_b32 s28, s28, 0x8000
	s_add_u32 s90, s52, s16
	s_addc_u32 s91, s53, s17
	s_add_i32 m0, s28, s83
	v_add3_u32 v170, s27, v114, v135
	global_load_lds_dwordx4 v189, s[90:91]
	global_load_lds_dwordx4 v191, s[90:91] offset:1024
	global_load_lds_dwordx4 v193, s[90:91] offset:2048
	global_load_lds_dwordx4 v195, s[90:91] offset:3072
	s_add_i32 m0, s28, s82
	v_add3_u32 v171, s27, v115, v135
	global_load_lds_dwordx4 v188, s[90:91]
	global_load_lds_dwordx4 v190, s[90:91] offset:1024
	global_load_lds_dwordx4 v192, s[90:91] offset:2048
	global_load_lds_dwordx4 v194, s[90:91] offset:3072
	v_add_u32_e32 v158, v170, v136
	v_add_u32_e32 v166, v171, v136
	s_addk_i32 s26, 0x4000
	s_add_u32 s16, s16, 0x80
	s_addc_u32 s17, s17, 0
	ds_read_b128 v[138:141], v158
	ds_read_b128 v[146:149], v166 offset:16384
	ds_read_b128 v[150:153], v166 offset:18432
	ds_read_b128 v[162:165], v166 offset:20480
	ds_read_b128 v[166:169], v166 offset:22528
	ds_read_b128 v[142:145], v158 offset:2048
	ds_read_b128 v[154:157], v158 offset:4096
	ds_read_b128 v[158:161], v158 offset:6144
	v_add_u32_e32 v236, v170, v137
	v_add_u32_e32 v237, v171, v137
	ds_read_b128 v[204:207], v236
	ds_read_b128 v[208:211], v237 offset:16384
	ds_read_b128 v[212:215], v237 offset:18432
	ds_read_b128 v[216:219], v237 offset:20480
	ds_read_b128 v[220:223], v237 offset:22528
	ds_read_b128 v[224:227], v236 offset:2048
	ds_read_b128 v[228:231], v236 offset:4096
	ds_read_b128 v[232:235], v236 offset:6144
	s_setprio 1
	s_waitcnt lgkmcnt(11)
	v_mfma_f32_16x16x32_bf16 v[60:63], v[138:141], v[146:149], v[60:63]
	v_mfma_f32_16x16x32_bf16 v[56:59], v[138:141], v[150:153], v[56:59]
	v_mfma_f32_16x16x32_bf16 v[52:55], v[138:141], v[162:165], v[52:55]
	v_mfma_f32_16x16x32_bf16 v[48:51], v[138:141], v[166:169], v[48:51]
	s_waitcnt lgkmcnt(10)
	v_mfma_f32_16x16x32_bf16 v[44:47], v[142:145], v[146:149], v[44:47]
	v_mfma_f32_16x16x32_bf16 v[40:43], v[142:145], v[150:153], v[40:43]
	v_mfma_f32_16x16x32_bf16 v[36:39], v[142:145], v[162:165], v[36:39]
	v_mfma_f32_16x16x32_bf16 v[32:35], v[142:145], v[166:169], v[32:35]
	s_waitcnt lgkmcnt(9)
	v_mfma_f32_16x16x32_bf16 v[28:31], v[154:157], v[146:149], v[28:31]
	v_mfma_f32_16x16x32_bf16 v[24:27], v[154:157], v[150:153], v[24:27]
	v_mfma_f32_16x16x32_bf16 v[20:23], v[154:157], v[162:165], v[20:23]
	v_mfma_f32_16x16x32_bf16 v[16:19], v[154:157], v[166:169], v[16:19]
	s_waitcnt lgkmcnt(8)
	v_mfma_f32_16x16x32_bf16 v[12:15], v[158:161], v[146:149], v[12:15]
	v_mfma_f32_16x16x32_bf16 v[8:11], v[158:161], v[150:153], v[8:11]
	v_mfma_f32_16x16x32_bf16 v[4:7], v[158:161], v[162:165], v[4:7]
	v_mfma_f32_16x16x32_bf16 v[0:3], v[158:161], v[166:169], v[0:3]
	s_waitcnt lgkmcnt(3)
	v_mfma_f32_16x16x32_bf16 v[60:63], v[204:207], v[208:211], v[60:63]
	v_mfma_f32_16x16x32_bf16 v[56:59], v[204:207], v[212:215], v[56:59]
	v_mfma_f32_16x16x32_bf16 v[52:55], v[204:207], v[216:219], v[52:55]
	v_mfma_f32_16x16x32_bf16 v[48:51], v[204:207], v[220:223], v[48:51]
	s_waitcnt lgkmcnt(2)
	v_mfma_f32_16x16x32_bf16 v[44:47], v[224:227], v[208:211], v[44:47]
	v_mfma_f32_16x16x32_bf16 v[40:43], v[224:227], v[212:215], v[40:43]
	v_mfma_f32_16x16x32_bf16 v[36:39], v[224:227], v[216:219], v[36:39]
	v_mfma_f32_16x16x32_bf16 v[32:35], v[224:227], v[220:223], v[32:35]
	s_waitcnt lgkmcnt(1)
	v_mfma_f32_16x16x32_bf16 v[28:31], v[228:231], v[208:211], v[28:31]
	v_mfma_f32_16x16x32_bf16 v[24:27], v[228:231], v[212:215], v[24:27]
	v_mfma_f32_16x16x32_bf16 v[20:23], v[228:231], v[216:219], v[20:23]
	v_mfma_f32_16x16x32_bf16 v[16:19], v[228:231], v[220:223], v[16:19]
	s_waitcnt lgkmcnt(0)
	v_mfma_f32_16x16x32_bf16 v[12:15], v[232:235], v[208:211], v[12:15]
	v_mfma_f32_16x16x32_bf16 v[8:11], v[232:235], v[212:215], v[8:11]
	v_mfma_f32_16x16x32_bf16 v[4:7], v[232:235], v[216:219], v[4:7]
	v_mfma_f32_16x16x32_bf16 v[0:3], v[232:235], v[220:223], v[0:3]
	s_setprio 0
	s_cmpk_eq_i32 s16, 0x780
	s_waitcnt vmcnt(0)
	s_barrier
	s_cbranch_scc0 .LBB0_1814
	ds_read_b128 v[90:93], v118 offset:55296
	ds_read_b128 v[94:97], v118 offset:53248
	ds_read_b128 v[98:101], v119 offset:38912
	ds_read_b128 v[102:105], v119 offset:36864
	ds_read_b128 v[138:141], v118 offset:51200
	ds_read_b128 v[142:145], v118 offset:49152
	ds_read_b128 v[146:149], v119 offset:34816
	ds_read_b128 v[150:153], v119 offset:32768
	ds_read_b128 v[204:207], v120 offset:32768
	ds_read_b128 v[208:211], v120 offset:34816
	ds_read_b128 v[212:215], v121 offset:49152
	ds_read_b128 v[216:219], v121 offset:51200
	ds_read_b128 v[220:223], v120 offset:36864
	ds_read_b128 v[224:227], v120 offset:38912
	ds_read_b128 v[228:231], v121 offset:53248
	ds_read_b128 v[232:235], v121 offset:55296
	s_setprio 1
	s_waitcnt lgkmcnt(13)
	v_mfma_f32_16x16x32_bf16 v[4:7], v[98:101], v[94:97], v[4:7]
	v_mfma_f32_16x16x32_bf16 v[0:3], v[98:101], v[90:93], v[0:3]
	s_waitcnt lgkmcnt(8)
	v_mfma_f32_16x16x32_bf16 v[60:63], v[150:153], v[142:145], v[60:63]
	v_mfma_f32_16x16x32_bf16 v[56:59], v[150:153], v[138:141], v[56:59]
	v_mfma_f32_16x16x32_bf16 v[52:55], v[150:153], v[94:97], v[52:55]
	v_mfma_f32_16x16x32_bf16 v[48:51], v[150:153], v[90:93], v[48:51]
	v_mfma_f32_16x16x32_bf16 v[44:47], v[146:149], v[142:145], v[44:47]
	v_mfma_f32_16x16x32_bf16 v[40:43], v[146:149], v[138:141], v[40:43]
	v_mfma_f32_16x16x32_bf16 v[36:39], v[146:149], v[94:97], v[36:39]
	v_mfma_f32_16x16x32_bf16 v[32:35], v[146:149], v[90:93], v[32:35]
	v_mfma_f32_16x16x32_bf16 v[28:31], v[102:105], v[142:145], v[28:31]
	v_mfma_f32_16x16x32_bf16 v[24:27], v[102:105], v[138:141], v[24:27]
	v_mfma_f32_16x16x32_bf16 v[20:23], v[102:105], v[94:97], v[20:23]
	v_mfma_f32_16x16x32_bf16 v[16:19], v[102:105], v[90:93], v[16:19]
	v_mfma_f32_16x16x32_bf16 v[12:15], v[98:101], v[142:145], v[12:15]
	v_mfma_f32_16x16x32_bf16 v[8:11], v[98:101], v[138:141], v[8:11]
	s_waitcnt lgkmcnt(1)
	v_mfma_f32_16x16x32_bf16 v[4:7], v[224:227], v[228:231], v[4:7]
	s_waitcnt lgkmcnt(0)
	v_mfma_f32_16x16x32_bf16 v[0:3], v[224:227], v[232:235], v[0:3]
	v_mfma_f32_16x16x32_bf16 v[60:63], v[204:207], v[212:215], v[60:63]
	v_mfma_f32_16x16x32_bf16 v[56:59], v[204:207], v[216:219], v[56:59]
	v_mfma_f32_16x16x32_bf16 v[52:55], v[204:207], v[228:231], v[52:55]
	v_mfma_f32_16x16x32_bf16 v[48:51], v[204:207], v[232:235], v[48:51]
	v_mfma_f32_16x16x32_bf16 v[44:47], v[208:211], v[212:215], v[44:47]
	v_mfma_f32_16x16x32_bf16 v[40:43], v[208:211], v[216:219], v[40:43]
	v_mfma_f32_16x16x32_bf16 v[36:39], v[208:211], v[228:231], v[36:39]
	v_mfma_f32_16x16x32_bf16 v[32:35], v[208:211], v[232:235], v[32:35]
	v_mfma_f32_16x16x32_bf16 v[28:31], v[220:223], v[212:215], v[28:31]
	v_mfma_f32_16x16x32_bf16 v[24:27], v[220:223], v[216:219], v[24:27]
	v_mfma_f32_16x16x32_bf16 v[20:23], v[220:223], v[228:231], v[20:23]
	v_mfma_f32_16x16x32_bf16 v[16:19], v[220:223], v[232:235], v[16:19]
	v_mfma_f32_16x16x32_bf16 v[12:15], v[224:227], v[212:215], v[12:15]
	v_mfma_f32_16x16x32_bf16 v[8:11], v[224:227], v[216:219], v[8:11]
	s_setprio 0
	s_barrier
	ds_write2_b32 v116, v60, v56 offset1:16
	ds_write2_b32 v116, v61, v57 offset0:132 offset1:148
	v_add_u32_e32 v56, 0x400, v116
	ds_write2_b32 v56, v62, v58 offset0:8 offset1:24
	ds_write2_b32 v56, v63, v59 offset0:140 offset1:156
	ds_write2_b32 v116, v52, v48 offset0:32 offset1:48
	ds_write2_b32 v116, v53, v49 offset0:164 offset1:180
	ds_write2_b32 v56, v54, v50 offset0:40 offset1:56
	ds_write2_b32 v56, v55, v51 offset0:172 offset1:188
	v_add_u32_e32 v48, 0x2000, v116
	ds_write2_b32 v48, v44, v40 offset0:64 offset1:80
	ds_write2_b32 v48, v45, v41 offset0:196 offset1:212
	v_add_u32_e32 v40, 0x2400, v116
	ds_write2_b32 v40, v46, v42 offset0:72 offset1:88
	ds_write2_b32 v40, v47, v43 offset0:204 offset1:220
	ds_write2_b32 v48, v36, v32 offset0:96 offset1:112
	ds_write2_b32 v48, v37, v33 offset0:228 offset1:244
	ds_write2_b32 v40, v38, v34 offset0:104 offset1:120
	ds_write2_b32 v40, v39, v35 offset0:236 offset1:252
	v_add_u32_e32 v32, 0x4000, v116
	ds_write2_b32 v32, v28, v24 offset0:128 offset1:144
	v_add_u32_e32 v24, 0x4400, v116
	ds_write2_b32 v24, v29, v25 offset0:4 offset1:20
	ds_write2_b32 v24, v30, v26 offset0:136 offset1:152
	v_add_u32_e32 v25, 0x4800, v116
	ds_write2_b32 v25, v31, v27 offset0:12 offset1:28
	ds_write2_b32 v32, v20, v16 offset0:160 offset1:176
	ds_write2_b32 v24, v21, v17 offset0:36 offset1:52
	ds_write2_b32 v24, v22, v18 offset0:168 offset1:184
	ds_write2_b32 v25, v23, v19 offset0:44 offset1:60
	v_add_u32_e32 v16, 0x6000, v116
	ds_write2_b32 v16, v12, v8 offset0:192 offset1:208
	v_add_u32_e32 v8, 0x6400, v116
	ds_write2_b32 v8, v13, v9 offset0:68 offset1:84
	ds_write2_b32 v8, v14, v10 offset0:200 offset1:216
	v_add_u32_e32 v9, 0x6800, v116
	ds_write2_b32 v9, v15, v11 offset0:76 offset1:92
	ds_write2_b32 v16, v4, v0 offset0:224 offset1:240
	ds_write2_b32 v8, v5, v1 offset0:100 offset1:116
	ds_write2_b32 v8, v6, v2 offset0:232 offset1:248
	ds_write2_b32 v9, v7, v3 offset0:108 offset1:124
	v_or_b32_e32 v0, s25, v117
	v_ashrrev_i32_e32 v1, 31, v0
	v_lshlrev_b64 v[2:3], 2, v[0:1]
	v_lshl_add_u64 v[0:1], s[14:15], 0, v[2:3]
	v_lshl_add_u64 v[2:3], s[10:11], 0, v[2:3]
	v_add_u32_e32 v4, s24, v128
	s_mov_b32 s16, 0
	s_waitcnt lgkmcnt(0)
	s_barrier

.LBB0_1822:
	s_ashr_i32 s16, s18, 31
	s_lshr_b32 s16, s16, 29
	s_add_i32 s16, s18, s16
	s_ashr_i32 s16, s16, 3
	s_lshl_b32 s17, s16, 10
	s_lshl_b32 s25, s18, 7
	v_add_u32_e32 v0, s16, v104
	s_sub_i32 s25, s25, s17
	v_lshlrev_b32_e32 v2, 7, v0
	v_add_u32_e32 v0, s25, v105
	v_ashrrev_i32_e32 v1, 31, v0
	v_add_u32_e32 v3, 0x4000, v106
	v_lshlrev_b64 v[0:1], 11, v[0:1]
	v_readfirstlane_b32 s26, v3
	v_lshl_add_u64 v[0:1], v[64:65], 0, v[0:1]
	s_mov_b32 m0, s26
	v_readfirstlane_b32 s26, v106
	global_load_lds_dwordx4 v[0:1], off
	v_add_u32_e32 v0, v2, v105
	v_ashrrev_i32_e32 v1, 31, v0
	v_lshlrev_b64 v[0:1], 11, v[0:1]
	v_lshl_add_u64 v[0:1], v[70:71], 0, v[0:1]
	s_mov_b32 m0, s26
	v_readfirstlane_b32 s26, v131
	global_load_lds_dwordx4 v[0:1], off
	v_add_u32_e32 v0, s25, v107
	v_ashrrev_i32_e32 v1, 31, v0
	v_lshlrev_b64 v[0:1], 11, v[0:1]
	v_lshl_add_u64 v[0:1], v[66:67], 0, v[0:1]
	s_mov_b32 m0, s26
	v_add_u32_e32 v3, 0x400, v106
	global_load_lds_dwordx4 v[0:1], off
	v_add_u32_e32 v0, v2, v107
	v_ashrrev_i32_e32 v1, 31, v0
	v_lshlrev_b64 v[0:1], 11, v[0:1]
	v_readfirstlane_b32 s26, v3
	v_lshl_add_u64 v[0:1], v[72:73], 0, v[0:1]
	s_mov_b32 m0, s26
	v_readfirstlane_b32 s26, v132
	global_load_lds_dwordx4 v[0:1], off
	v_add_u32_e32 v0, s25, v109
	v_ashrrev_i32_e32 v1, 31, v0
	v_lshlrev_b64 v[0:1], 11, v[0:1]
	v_lshl_add_u64 v[0:1], v[64:65], 0, v[0:1]
	s_mov_b32 m0, s26
	v_add_u32_e32 v3, 0x800, v106
	global_load_lds_dwordx4 v[0:1], off
	v_add_u32_e32 v0, v2, v109
	v_ashrrev_i32_e32 v1, 31, v0
	v_lshlrev_b64 v[0:1], 11, v[0:1]
	v_readfirstlane_b32 s26, v3
	v_lshl_add_u64 v[0:1], v[70:71], 0, v[0:1]
	s_mov_b32 m0, s26
	v_readfirstlane_b32 s26, v133
	global_load_lds_dwordx4 v[0:1], off
	v_add_u32_e32 v0, s25, v111
	v_ashrrev_i32_e32 v1, 31, v0
	v_lshlrev_b64 v[0:1], 11, v[0:1]
	v_lshl_add_u64 v[0:1], v[68:69], 0, v[0:1]
	s_mov_b32 m0, s26
	s_mov_b32 s27, 0
	global_load_lds_dwordx4 v[0:1], off
	v_add_u32_e32 v0, v2, v111
	v_ashrrev_i32_e32 v1, 31, v0
	v_add_u32_e32 v2, 0xc00, v106
	v_lshlrev_b64 v[0:1], 11, v[0:1]
	v_readfirstlane_b32 s26, v2
	v_lshl_add_u64 v[0:1], v[74:75], 0, v[0:1]
	s_mov_b32 m0, s26
	s_lshl_b32 s26, s16, 7
	global_load_lds_dwordx4 v[0:1], off
	v_subrev_u32_e32 v0, s17, v121
	v_ashrrev_i32_e32 v1, 31, v0
	v_lshlrev_b64 v[0:1], 11, v[0:1]
	v_lshl_add_u64 v[88:89], v[76:77], 0, v[0:1]
	v_add_u32_e32 v0, s26, v122
	v_ashrrev_i32_e32 v1, 31, v0
	v_lshlrev_b64 v[0:1], 11, v[0:1]
	v_lshl_add_u64 v[90:91], v[78:79], 0, v[0:1]
	v_subrev_u32_e32 v0, s17, v123
	v_ashrrev_i32_e32 v1, 31, v0
	v_lshlrev_b64 v[0:1], 11, v[0:1]
	v_lshl_add_u64 v[92:93], v[80:81], 0, v[0:1]
	v_add_u32_e32 v0, s26, v124
	v_ashrrev_i32_e32 v1, 31, v0
	v_lshlrev_b64 v[0:1], 11, v[0:1]
	v_lshl_add_u64 v[94:95], v[82:83], 0, v[0:1]
	v_subrev_u32_e32 v0, s17, v125
	v_ashrrev_i32_e32 v1, 31, v0
	v_lshlrev_b64 v[0:1], 11, v[0:1]
	v_lshl_add_u64 v[96:97], v[76:77], 0, v[0:1]
	v_add_u32_e32 v0, s26, v126
	v_ashrrev_i32_e32 v1, 31, v0
	v_lshlrev_b64 v[0:1], 11, v[0:1]
	v_lshl_add_u64 v[98:99], v[78:79], 0, v[0:1]
	v_subrev_u32_e32 v0, s17, v127
	v_ashrrev_i32_e32 v1, 31, v0
	v_lshlrev_b64 v[0:1], 11, v[0:1]
	v_lshl_add_u64 v[100:101], v[84:85], 0, v[0:1]
	v_add_u32_e32 v0, s26, v128
	v_ashrrev_i32_e32 v1, 31, v0
	v_lshlrev_b64 v[0:1], 11, v[0:1]
	v_lshl_add_u64 v[102:103], v[86:87], 0, v[0:1]
	v_mov_b32_e32 v0, 0
	s_mov_b64 s[16:17], 0
	v_mov_b32_e32 v1, v0
	v_mov_b32_e32 v2, v0
	v_mov_b32_e32 v3, v0
	v_mov_b32_e32 v4, v0
	v_mov_b32_e32 v5, v0
	v_mov_b32_e32 v6, v0
	v_mov_b32_e32 v7, v0
	v_mov_b32_e32 v8, v0
	v_mov_b32_e32 v9, v0
	v_mov_b32_e32 v10, v0
	v_mov_b32_e32 v11, v0
	v_mov_b32_e32 v12, v0
	v_mov_b32_e32 v13, v0
	v_mov_b32_e32 v14, v0
	v_mov_b32_e32 v15, v0
	v_mov_b32_e32 v16, v0
	v_mov_b32_e32 v17, v0
	v_mov_b32_e32 v18, v0
	v_mov_b32_e32 v19, v0
	v_mov_b32_e32 v20, v0
	v_mov_b32_e32 v21, v0
	v_mov_b32_e32 v22, v0
	v_mov_b32_e32 v23, v0
	v_mov_b32_e32 v24, v0
	v_mov_b32_e32 v25, v0
	v_mov_b32_e32 v26, v0
	v_mov_b32_e32 v27, v0
	v_mov_b32_e32 v28, v0
	v_mov_b32_e32 v29, v0
	v_mov_b32_e32 v30, v0
	v_mov_b32_e32 v31, v0
	s_waitcnt vmcnt(0)
	v_mov_b32_e32 v32, v0
	v_mov_b32_e32 v33, v0
	v_mov_b32_e32 v34, v0
	v_mov_b32_e32 v35, v0
	v_mov_b32_e32 v36, v0
	v_mov_b32_e32 v37, v0
	v_mov_b32_e32 v38, v0
	v_mov_b32_e32 v39, v0
	v_mov_b32_e32 v40, v0
	v_mov_b32_e32 v41, v0
	v_mov_b32_e32 v42, v0
	v_mov_b32_e32 v43, v0
	v_mov_b32_e32 v44, v0
	v_mov_b32_e32 v45, v0
	v_mov_b32_e32 v46, v0
	v_mov_b32_e32 v47, v0
	v_mov_b32_e32 v48, v0
	v_mov_b32_e32 v49, v0
	v_mov_b32_e32 v50, v0
	v_mov_b32_e32 v51, v0
	v_mov_b32_e32 v52, v0
	v_mov_b32_e32 v53, v0
	v_mov_b32_e32 v54, v0
	v_mov_b32_e32 v55, v0
	v_mov_b32_e32 v56, v0
	v_mov_b32_e32 v57, v0
	v_mov_b32_e32 v58, v0
	v_mov_b32_e32 v59, v0
	v_mov_b32_e32 v60, v0
	v_mov_b32_e32 v61, v0
	v_mov_b32_e32 v62, v0
	v_mov_b32_e32 v63, v0
	s_waitcnt lgkmcnt(0)
	s_barrier
	v_add3_u32 v186, 0, v134, v135
	v_add_u32_e32 v187, 0x4000, v186
	s_nop 0
	v_readfirstlane_b32 s82, v187
	v_lshl_add_u32 v187, v108, 1, 0
	s_nop 0
	v_readfirstlane_b32 s83, v186
	v_add3_u32 v187, v187, v135, s21
	s_nop 0
	v_readfirstlane_b32 s84, v187
	v_add_u32_e32 v187, 0x400, v186
	s_nop 0
	v_readfirstlane_b32 s85, v187
	v_lshl_add_u32 v187, v110, 1, 0
	v_add3_u32 v187, v187, v135, s21
	s_nop 0
	v_readfirstlane_b32 s86, v187
	v_add_u32_e32 v187, 0x800, v186
	s_nop 0
	v_readfirstlane_b32 s87, v187
	v_lshl_add_u32 v187, v112, 1, 0
	v_add3_u32 v187, v187, v135, s21
	s_nop 0
	v_readfirstlane_b32 s88, v187
	v_add_u32_e32 v186, 0xc00, v186
	s_nop 0
	v_readfirstlane_b32 s89, v186
	v_subrev_u32_e32 v188, s52, v88
	v_subrev_u32_e32 v189, s52, v90
	v_subrev_u32_e32 v190, s52, v92
	v_subrev_u32_e32 v191, s52, v94
	v_subrev_u32_e32 v192, s52, v96
	v_subrev_u32_e32 v193, s52, v98
	v_subrev_u32_e32 v194, s52, v100
	v_subrev_u32_e32 v195, s52, v102
	v_subrev_u32_e32 v191, 0x400, v191
	v_subrev_u32_e32 v190, 0x400, v190
	v_subrev_u32_e32 v193, 0x800, v193
	v_subrev_u32_e32 v192, 0x800, v192
	v_subrev_u32_e32 v195, 0xc00, v195
	v_subrev_u32_e32 v194, 0xc00, v194
	s_and_b32 s29, s27, 0x4000
	s_xor_b32 s28, s29, 0x4000
	s_lshl_b32 s28, s28, 1
	s_add_i32 s28, s28, 32
	s_lshl_b32 s29, s29, 1
	s_add_i32 s29, s29, 32
.LBB0_1823:
	s_xor_b32 s28, s28, 0x8000
	s_xor_b32 s29, s29, 0x8000
	s_add_u32 s90, s52, s16
	s_addc_u32 s91, s53, s17
	s_add_i32 m0, s29, s83
	v_add3_u32 v139, s28, v113, v136
	global_load_lds_dwordx4 v189, s[90:91]
	global_load_lds_dwordx4 v191, s[90:91] offset:1024
	global_load_lds_dwordx4 v193, s[90:91] offset:2048
	global_load_lds_dwordx4 v195, s[90:91] offset:3072
	s_add_i32 m0, s29, s82
	v_add3_u32 v172, s28, v114, v136
	global_load_lds_dwordx4 v188, s[90:91]
	global_load_lds_dwordx4 v190, s[90:91] offset:1024
	global_load_lds_dwordx4 v192, s[90:91] offset:2048
	global_load_lds_dwordx4 v194, s[90:91] offset:3072
	v_add_u32_e32 v160, v139, v137
	v_add_u32_e32 v168, v172, v137
	s_add_u32 s16, s16, 0x80
	s_addc_u32 s17, s17, 0
	ds_read_b128 v[140:143], v160
	ds_read_b128 v[148:151], v168 offset:16384
	ds_read_b128 v[152:155], v168 offset:18432
	ds_read_b128 v[164:167], v168 offset:20480
	ds_read_b128 v[168:171], v168 offset:22528
	ds_read_b128 v[144:147], v160 offset:2048
	ds_read_b128 v[156:159], v160 offset:4096
	ds_read_b128 v[160:163], v160 offset:6144
	v_add_u32_e32 v139, v139, v138
	v_add_u32_e32 v236, v172, v138
	ds_read_b128 v[204:207], v139
	ds_read_b128 v[208:211], v236 offset:16384
	ds_read_b128 v[212:215], v236 offset:18432
	ds_read_b128 v[216:219], v236 offset:20480
	ds_read_b128 v[220:223], v236 offset:22528
	ds_read_b128 v[224:227], v139 offset:2048
	ds_read_b128 v[228:231], v139 offset:4096
	ds_read_b128 v[232:235], v139 offset:6144
	s_setprio 1
	s_waitcnt lgkmcnt(11)
	v_mfma_f32_16x16x32_bf16 v[60:63], v[140:143], v[148:151], v[60:63]
	v_mfma_f32_16x16x32_bf16 v[56:59], v[140:143], v[152:155], v[56:59]
	v_mfma_f32_16x16x32_bf16 v[52:55], v[140:143], v[164:167], v[52:55]
	v_mfma_f32_16x16x32_bf16 v[48:51], v[140:143], v[168:171], v[48:51]
	s_waitcnt lgkmcnt(10)
	v_mfma_f32_16x16x32_bf16 v[44:47], v[144:147], v[148:151], v[44:47]
	v_mfma_f32_16x16x32_bf16 v[40:43], v[144:147], v[152:155], v[40:43]
	v_mfma_f32_16x16x32_bf16 v[36:39], v[144:147], v[164:167], v[36:39]
	v_mfma_f32_16x16x32_bf16 v[32:35], v[144:147], v[168:171], v[32:35]
	s_waitcnt lgkmcnt(9)
	v_mfma_f32_16x16x32_bf16 v[28:31], v[156:159], v[148:151], v[28:31]
	v_mfma_f32_16x16x32_bf16 v[24:27], v[156:159], v[152:155], v[24:27]
	v_mfma_f32_16x16x32_bf16 v[20:23], v[156:159], v[164:167], v[20:23]
	v_mfma_f32_16x16x32_bf16 v[16:19], v[156:159], v[168:171], v[16:19]
	s_waitcnt lgkmcnt(8)
	v_mfma_f32_16x16x32_bf16 v[12:15], v[160:163], v[148:151], v[12:15]
	v_mfma_f32_16x16x32_bf16 v[8:11], v[160:163], v[152:155], v[8:11]
	v_mfma_f32_16x16x32_bf16 v[4:7], v[160:163], v[164:167], v[4:7]
	v_mfma_f32_16x16x32_bf16 v[0:3], v[160:163], v[168:171], v[0:3]
	s_waitcnt lgkmcnt(3)
	v_mfma_f32_16x16x32_bf16 v[60:63], v[204:207], v[208:211], v[60:63]
	v_mfma_f32_16x16x32_bf16 v[56:59], v[204:207], v[212:215], v[56:59]
	v_mfma_f32_16x16x32_bf16 v[52:55], v[204:207], v[216:219], v[52:55]
	v_mfma_f32_16x16x32_bf16 v[48:51], v[204:207], v[220:223], v[48:51]
	s_waitcnt lgkmcnt(2)
	v_mfma_f32_16x16x32_bf16 v[44:47], v[224:227], v[208:211], v[44:47]
	v_mfma_f32_16x16x32_bf16 v[40:43], v[224:227], v[212:215], v[40:43]
	v_mfma_f32_16x16x32_bf16 v[36:39], v[224:227], v[216:219], v[36:39]
	v_mfma_f32_16x16x32_bf16 v[32:35], v[224:227], v[220:223], v[32:35]
	s_waitcnt lgkmcnt(1)
	v_mfma_f32_16x16x32_bf16 v[28:31], v[228:231], v[208:211], v[28:31]
	v_mfma_f32_16x16x32_bf16 v[24:27], v[228:231], v[212:215], v[24:27]
	v_mfma_f32_16x16x32_bf16 v[20:23], v[228:231], v[216:219], v[20:23]
	v_mfma_f32_16x16x32_bf16 v[16:19], v[228:231], v[220:223], v[16:19]
	s_waitcnt lgkmcnt(0)
	v_mfma_f32_16x16x32_bf16 v[12:15], v[232:235], v[208:211], v[12:15]
	v_mfma_f32_16x16x32_bf16 v[8:11], v[232:235], v[212:215], v[8:11]
	v_mfma_f32_16x16x32_bf16 v[4:7], v[232:235], v[216:219], v[4:7]
	v_mfma_f32_16x16x32_bf16 v[0:3], v[232:235], v[220:223], v[0:3]
	s_setprio 0
	s_cmpk_eq_i32 s16, 0x780
	s_waitcnt vmcnt(0)
	s_barrier
	s_cbranch_scc0 .LBB0_1823
	ds_read_b128 v[88:91], v117 offset:55296
	ds_read_b128 v[92:95], v117 offset:53248
	ds_read_b128 v[96:99], v118 offset:38912
	ds_read_b128 v[100:103], v118 offset:36864
	ds_read_b128 v[140:143], v117 offset:51200
	ds_read_b128 v[144:147], v117 offset:49152
	ds_read_b128 v[148:151], v118 offset:34816
	ds_read_b128 v[152:155], v118 offset:32768
	ds_read_b128 v[204:207], v119 offset:32768
	ds_read_b128 v[208:211], v119 offset:34816
	ds_read_b128 v[212:215], v120 offset:49152
	ds_read_b128 v[216:219], v120 offset:51200
	ds_read_b128 v[220:223], v119 offset:36864
	ds_read_b128 v[224:227], v119 offset:38912
	ds_read_b128 v[228:231], v120 offset:53248
	ds_read_b128 v[232:235], v120 offset:55296
	s_setprio 1
	s_waitcnt lgkmcnt(13)
	v_mfma_f32_16x16x32_bf16 v[4:7], v[96:99], v[92:95], v[4:7]
	v_mfma_f32_16x16x32_bf16 v[0:3], v[96:99], v[88:91], v[0:3]
	s_waitcnt lgkmcnt(8)
	v_mfma_f32_16x16x32_bf16 v[60:63], v[152:155], v[144:147], v[60:63]
	v_mfma_f32_16x16x32_bf16 v[56:59], v[152:155], v[140:143], v[56:59]
	v_mfma_f32_16x16x32_bf16 v[52:55], v[152:155], v[92:95], v[52:55]
	v_mfma_f32_16x16x32_bf16 v[48:51], v[152:155], v[88:91], v[48:51]
	v_mfma_f32_16x16x32_bf16 v[44:47], v[148:151], v[144:147], v[44:47]
	v_mfma_f32_16x16x32_bf16 v[40:43], v[148:151], v[140:143], v[40:43]
	v_mfma_f32_16x16x32_bf16 v[36:39], v[148:151], v[92:95], v[36:39]
	v_mfma_f32_16x16x32_bf16 v[32:35], v[148:151], v[88:91], v[32:35]
	v_mfma_f32_16x16x32_bf16 v[28:31], v[100:103], v[144:147], v[28:31]
	v_mfma_f32_16x16x32_bf16 v[24:27], v[100:103], v[140:143], v[24:27]
	v_mfma_f32_16x16x32_bf16 v[20:23], v[100:103], v[92:95], v[20:23]
	v_mfma_f32_16x16x32_bf16 v[16:19], v[100:103], v[88:91], v[16:19]
	v_mfma_f32_16x16x32_bf16 v[12:15], v[96:99], v[144:147], v[12:15]
	v_mfma_f32_16x16x32_bf16 v[8:11], v[96:99], v[140:143], v[8:11]
	s_waitcnt lgkmcnt(1)
	v_mfma_f32_16x16x32_bf16 v[4:7], v[224:227], v[228:231], v[4:7]
	s_waitcnt lgkmcnt(0)
	v_mfma_f32_16x16x32_bf16 v[0:3], v[224:227], v[232:235], v[0:3]
	v_mfma_f32_16x16x32_bf16 v[60:63], v[204:207], v[212:215], v[60:63]
	v_mfma_f32_16x16x32_bf16 v[56:59], v[204:207], v[216:219], v[56:59]
	v_mfma_f32_16x16x32_bf16 v[52:55], v[204:207], v[228:231], v[52:55]
	v_mfma_f32_16x16x32_bf16 v[48:51], v[204:207], v[232:235], v[48:51]
	v_mfma_f32_16x16x32_bf16 v[44:47], v[208:211], v[212:215], v[44:47]
	v_mfma_f32_16x16x32_bf16 v[40:43], v[208:211], v[216:219], v[40:43]
	v_mfma_f32_16x16x32_bf16 v[36:39], v[208:211], v[228:231], v[36:39]
	v_mfma_f32_16x16x32_bf16 v[32:35], v[208:211], v[232:235], v[32:35]
	v_mfma_f32_16x16x32_bf16 v[28:31], v[220:223], v[212:215], v[28:31]
	v_mfma_f32_16x16x32_bf16 v[24:27], v[220:223], v[216:219], v[24:27]
	v_mfma_f32_16x16x32_bf16 v[20:23], v[220:223], v[228:231], v[20:23]
	v_mfma_f32_16x16x32_bf16 v[16:19], v[220:223], v[232:235], v[16:19]
	v_mfma_f32_16x16x32_bf16 v[12:15], v[224:227], v[212:215], v[12:15]
	v_mfma_f32_16x16x32_bf16 v[8:11], v[224:227], v[216:219], v[8:11]
	s_setprio 0
	s_barrier
	ds_write2_b32 v115, v60, v56 offset1:16
	ds_write2_b32 v115, v61, v57 offset0:132 offset1:148
	v_add_u32_e32 v56, 0x400, v115
	ds_write2_b32 v56, v62, v58 offset0:8 offset1:24
	ds_write2_b32 v56, v63, v59 offset0:140 offset1:156
	ds_write2_b32 v115, v52, v48 offset0:32 offset1:48
	ds_write2_b32 v115, v53, v49 offset0:164 offset1:180
	ds_write2_b32 v56, v54, v50 offset0:40 offset1:56
	ds_write2_b32 v56, v55, v51 offset0:172 offset1:188
	v_add_u32_e32 v48, 0x2000, v115
	ds_write2_b32 v48, v44, v40 offset0:64 offset1:80
	ds_write2_b32 v48, v45, v41 offset0:196 offset1:212
	v_add_u32_e32 v40, 0x2400, v115
	ds_write2_b32 v40, v46, v42 offset0:72 offset1:88
	ds_write2_b32 v40, v47, v43 offset0:204 offset1:220
	ds_write2_b32 v48, v36, v32 offset0:96 offset1:112
	ds_write2_b32 v48, v37, v33 offset0:228 offset1:244
	ds_write2_b32 v40, v38, v34 offset0:104 offset1:120
	ds_write2_b32 v40, v39, v35 offset0:236 offset1:252
	v_add_u32_e32 v32, 0x4000, v115
	ds_write2_b32 v32, v28, v24 offset0:128 offset1:144
	v_add_u32_e32 v24, 0x4400, v115
	ds_write2_b32 v24, v29, v25 offset0:4 offset1:20
	ds_write2_b32 v24, v30, v26 offset0:136 offset1:152
	v_add_u32_e32 v25, 0x4800, v115
	ds_write2_b32 v25, v31, v27 offset0:12 offset1:28
	ds_write2_b32 v32, v20, v16 offset0:160 offset1:176
	ds_write2_b32 v24, v21, v17 offset0:36 offset1:52
	ds_write2_b32 v24, v22, v18 offset0:168 offset1:184
	ds_write2_b32 v25, v23, v19 offset0:44 offset1:60
	v_add_u32_e32 v16, 0x6000, v115
	ds_write2_b32 v16, v12, v8 offset0:192 offset1:208
	v_add_u32_e32 v8, 0x6400, v115
	ds_write2_b32 v8, v13, v9 offset0:68 offset1:84
	ds_write2_b32 v8, v14, v10 offset0:200 offset1:216
	v_add_u32_e32 v9, 0x6800, v115
	ds_write2_b32 v9, v15, v11 offset0:76 offset1:92
	ds_write2_b32 v16, v4, v0 offset0:224 offset1:240
	ds_write2_b32 v8, v5, v1 offset0:100 offset1:116
	ds_write2_b32 v8, v6, v2 offset0:232 offset1:248
	ds_write2_b32 v9, v7, v3 offset0:108 offset1:124
	v_or_b32_e32 v0, s25, v116
	v_ashrrev_i32_e32 v1, 31, v0
	v_lshlrev_b64 v[2:3], 2, v[0:1]
	v_lshl_add_u64 v[0:1], s[14:15], 0, v[2:3]
	v_lshl_add_u64 v[2:3], s[10:11], 0, v[2:3]
	v_add_u32_e32 v4, s26, v129
	s_mov_b32 s16, 0
	s_waitcnt lgkmcnt(0)
	s_barrier

.LBB0_1833:
	s_and_b32 s12, s18, 0x380
	v_add_lshl_u32 v70, v138, s12, 11
	v_lshl_add_u64 v[96:97], v[84:85], 0, v[70:71]
	v_add_lshl_u32 v70, v140, s12, 11
	v_lshl_add_u64 v[98:99], v[88:89], 0, v[70:71]
	v_add_lshl_u32 v70, v142, s12, 11
	s_lshl_b32 s24, s23, 7
	v_lshl_add_u64 v[100:101], v[84:85], 0, v[70:71]
	v_add_lshl_u32 v70, v144, s12, 11
	s_ashr_i32 s12, s23, 3
	s_and_b32 s24, s24, 0x380
	v_add_u32_e32 v2, 0x4000, v133
	v_lshl_add_u64 v[102:103], v[92:93], 0, v[70:71]
	s_add_i32 s13, s12, s17
	v_add_lshl_u32 v70, s24, v132, 11
	v_readfirstlane_b32 s25, v2
	s_lshl_b32 s13, s13, 7
	v_lshl_add_u64 v[0:1], v[72:73], 0, v[70:71]
	s_mov_b32 m0, s25
	v_readfirstlane_b32 s25, v133
	global_load_lds_dwordx4 v[0:1], off
	v_add_u32_e32 v0, s13, v132
	v_ashrrev_i32_e32 v1, 31, v0
	v_lshlrev_b64 v[0:1], 11, v[0:1]
	v_lshl_add_u64 v[0:1], v[78:79], 0, v[0:1]
	s_mov_b32 m0, s25
	v_add_lshl_u32 v70, s24, v119, 11
	v_readfirstlane_b32 s25, v148
	global_load_lds_dwordx4 v[0:1], off
	v_lshl_add_u64 v[0:1], v[74:75], 0, v[70:71]
	s_mov_b32 m0, s25
	v_add_u32_e32 v2, 0x400, v133
	global_load_lds_dwordx4 v[0:1], off
	v_add_u32_e32 v0, s13, v119
	v_ashrrev_i32_e32 v1, 31, v0
	v_lshlrev_b64 v[0:1], 11, v[0:1]
	v_readfirstlane_b32 s25, v2
	v_lshl_add_u64 v[0:1], v[80:81], 0, v[0:1]
	s_mov_b32 m0, s25
	v_add_lshl_u32 v70, s24, v120, 11
	v_readfirstlane_b32 s25, v149
	global_load_lds_dwordx4 v[0:1], off
	v_lshl_add_u64 v[0:1], v[72:73], 0, v[70:71]
	s_mov_b32 m0, s25
	v_add_u32_e32 v2, 0x800, v133
	global_load_lds_dwordx4 v[0:1], off
	v_add_u32_e32 v0, s13, v120
	v_ashrrev_i32_e32 v1, 31, v0
	v_lshlrev_b64 v[0:1], 11, v[0:1]
	v_readfirstlane_b32 s25, v2
	v_lshl_add_u64 v[0:1], v[78:79], 0, v[0:1]
	s_mov_b32 m0, s25
	v_add_lshl_u32 v70, s24, v118, 11
	v_readfirstlane_b32 s25, v150
	global_load_lds_dwordx4 v[0:1], off
	v_lshl_add_u64 v[0:1], v[76:77], 0, v[70:71]
	s_mov_b32 m0, s25
	v_add_u32_e32 v2, 0xc00, v133
	global_load_lds_dwordx4 v[0:1], off
	v_add_u32_e32 v0, s13, v118
	v_ashrrev_i32_e32 v1, 31, v0
	v_lshlrev_b64 v[0:1], 11, v[0:1]
	v_readfirstlane_b32 s13, v2
	v_lshl_add_u64 v[0:1], v[82:83], 0, v[0:1]
	s_mov_b32 m0, s13
	s_lshl_b32 s25, s12, 7
	global_load_lds_dwordx4 v[0:1], off
	v_add_u32_e32 v0, s25, v139
	v_ashrrev_i32_e32 v1, 31, v0
	v_lshlrev_b64 v[0:1], 11, v[0:1]
	v_lshl_add_u64 v[104:105], v[86:87], 0, v[0:1]
	v_add_u32_e32 v0, s25, v141
	v_ashrrev_i32_e32 v1, 31, v0
	v_lshlrev_b64 v[0:1], 11, v[0:1]
	v_lshl_add_u64 v[106:107], v[90:91], 0, v[0:1]
	v_add_u32_e32 v0, s25, v143
	v_ashrrev_i32_e32 v1, 31, v0
	v_lshlrev_b64 v[0:1], 11, v[0:1]
	v_lshl_add_u64 v[108:109], v[86:87], 0, v[0:1]
	v_add_u32_e32 v0, s25, v145
	v_ashrrev_i32_e32 v1, 31, v0
	v_lshlrev_b64 v[0:1], 11, v[0:1]
	v_lshl_add_u64 v[110:111], v[94:95], 0, v[0:1]
	s_mov_b64 s[12:13], 0
	s_mov_b32 s26, 0
	v_mov_b32_e32 v0, 0
	v_mov_b32_e32 v1, v71
	v_mov_b32_e32 v2, v71
	v_mov_b32_e32 v3, v71
	v_mov_b32_e32 v4, 0
	v_mov_b32_e32 v5, v71
	v_mov_b32_e32 v6, v71
	v_mov_b32_e32 v7, v71
	v_mov_b32_e32 v8, 0
	v_mov_b32_e32 v9, v71
	v_mov_b32_e32 v10, v71
	v_mov_b32_e32 v11, v71
	v_mov_b32_e32 v12, 0
	v_mov_b32_e32 v13, v71
	v_mov_b32_e32 v14, v71
	v_mov_b32_e32 v15, v71
	v_mov_b32_e32 v16, 0
	v_mov_b32_e32 v17, v71
	v_mov_b32_e32 v18, v71
	v_mov_b32_e32 v19, v71
	v_mov_b32_e32 v20, 0
	v_mov_b32_e32 v21, v71
	v_mov_b32_e32 v22, v71
	v_mov_b32_e32 v23, v71
	v_mov_b32_e32 v24, 0
	v_mov_b32_e32 v25, v71
	v_mov_b32_e32 v26, v71
	v_mov_b32_e32 v27, v71
	v_mov_b32_e32 v28, 0
	v_mov_b32_e32 v29, v71
	v_mov_b32_e32 v30, v71
	v_mov_b32_e32 v31, v71
	s_waitcnt vmcnt(0)
	v_mov_b32_e32 v32, 0
	v_mov_b32_e32 v33, v71
	v_mov_b32_e32 v34, v71
	v_mov_b32_e32 v35, v71
	v_mov_b32_e32 v36, 0
	v_mov_b32_e32 v37, v71
	v_mov_b32_e32 v38, v71
	v_mov_b32_e32 v39, v71
	v_mov_b32_e32 v40, 0
	v_mov_b32_e32 v41, v71
	v_mov_b32_e32 v42, v71
	v_mov_b32_e32 v43, v71
	v_mov_b32_e32 v44, 0
	v_mov_b32_e32 v45, v71
	v_mov_b32_e32 v46, v71
	v_mov_b32_e32 v47, v71
	v_mov_b32_e32 v48, 0
	v_mov_b32_e32 v49, v71
	v_mov_b32_e32 v50, v71
	v_mov_b32_e32 v51, v71
	v_mov_b32_e32 v52, 0
	v_mov_b32_e32 v53, v71
	v_mov_b32_e32 v54, v71
	v_mov_b32_e32 v55, v71
	v_mov_b32_e32 v56, 0
	v_mov_b32_e32 v57, v71
	v_mov_b32_e32 v58, v71
	v_mov_b32_e32 v59, v71
	v_mov_b32_e32 v60, 0
	v_mov_b32_e32 v61, v71
	v_mov_b32_e32 v62, v71
	v_mov_b32_e32 v63, v71
	s_waitcnt lgkmcnt(0)
	s_barrier
	v_lshlrev_b32_e32 v186, 1, v130
	v_lshlrev_b32_e32 v187, 1, v131
	v_add3_u32 v186, 0, v186, v187
	v_add_u32_e32 v188, 0x4000, v186
	s_nop 0
	v_readfirstlane_b32 s82, v188
	v_lshl_add_u32 v188, v123, 1, 0
	s_nop 0
	v_readfirstlane_b32 s83, v186
	v_add3_u32 v188, v188, v187, s19
	s_nop 0
	v_readfirstlane_b32 s84, v188
	v_add_u32_e32 v188, 0x400, v186
	s_nop 0
	v_readfirstlane_b32 s85, v188
	v_lshl_add_u32 v188, v121, 1, 0
	v_add3_u32 v188, v188, v187, s19
	s_nop 0
	v_readfirstlane_b32 s86, v188
	v_add_u32_e32 v188, 0x800, v186
	s_nop 0
	v_readfirstlane_b32 s87, v188
	v_lshl_add_u32 v188, v122, 1, 0
	v_add3_u32 v187, v188, v187, s19
	s_nop 0
	v_readfirstlane_b32 s88, v187
	v_add_u32_e32 v186, 0xc00, v186
	s_nop 0
	v_readfirstlane_b32 s89, v186
	v_subrev_u32_e32 v189, s52, v96
	v_subrev_u32_e32 v190, s52, v104
	v_subrev_u32_e32 v191, s52, v98
	v_subrev_u32_e32 v192, s52, v106
	v_subrev_u32_e32 v193, s52, v100
	v_subrev_u32_e32 v194, s52, v108
	v_subrev_u32_e32 v195, s52, v102
	v_subrev_u32_e32 v196, s52, v110
	v_subrev_u32_e32 v192, 0x400, v192
	v_subrev_u32_e32 v191, 0x400, v191
	v_subrev_u32_e32 v194, 0x800, v194
	v_subrev_u32_e32 v193, 0x800, v193
	v_subrev_u32_e32 v196, 0xc00, v196
	v_subrev_u32_e32 v195, 0xc00, v195
	s_and_b32 s28, s26, 0x4000
	s_xor_b32 s27, s28, 0x4000
	s_lshl_b32 s27, s27, 1
	s_add_i32 s27, s27, 32
	s_lshl_b32 s28, s28, 1
	s_add_i32 s28, s28, 32
.LBB0_1834:
	s_xor_b32 s27, s27, 0x8000
	s_xor_b32 s28, s28, 0x8000
	s_add_u32 s90, s52, s12
	s_addc_u32 s91, s53, s13
	s_addk_i32 s26, 0x4000
	s_add_i32 m0, s28, s83
	v_lshlrev_b32_e32 v70, 1, v129
	global_load_lds_dwordx4 v190, s[90:91]
	global_load_lds_dwordx4 v192, s[90:91] offset:1024
	global_load_lds_dwordx4 v194, s[90:91] offset:2048
	global_load_lds_dwordx4 v196, s[90:91] offset:3072
	s_add_i32 m0, s28, s82
	v_add3_u32 v151, s27, v124, v70
	global_load_lds_dwordx4 v189, s[90:91]
	global_load_lds_dwordx4 v191, s[90:91] offset:1024
	global_load_lds_dwordx4 v193, s[90:91] offset:2048
	global_load_lds_dwordx4 v195, s[90:91] offset:3072
	v_add3_u32 v70, s27, v125, v70
	v_lshlrev_b32_e32 v152, 1, v117
	v_add_u32_e32 v172, v151, v152
	v_add_u32_e32 v182, v70, v152
	ds_read_b128 v[152:155], v172
	ds_read_b128 v[160:163], v182 offset:16384
	ds_read_b128 v[164:167], v182 offset:18432
	ds_read_b128 v[176:179], v182 offset:20480
	ds_read_b128 v[182:185], v182 offset:22528
	ds_read_b128 v[156:159], v172 offset:2048
	ds_read_b128 v[168:171], v172 offset:4096
	ds_read_b128 v[172:175], v172 offset:6144
	v_lshlrev_b32_e32 v236, 1, v116
	v_add_u32_e32 v151, v151, v236
	v_add_u32_e32 v70, v70, v236
	ds_read_b128 v[204:207], v151
	ds_read_b128 v[208:211], v70 offset:16384
	ds_read_b128 v[212:215], v70 offset:18432
	ds_read_b128 v[216:219], v70 offset:20480
	ds_read_b128 v[220:223], v70 offset:22528
	ds_read_b128 v[224:227], v151 offset:2048
	ds_read_b128 v[228:231], v151 offset:4096
	ds_read_b128 v[232:235], v151 offset:6144
	s_setprio 1
	s_waitcnt lgkmcnt(11)
	v_mfma_f32_16x16x32_bf16 v[60:63], v[152:155], v[160:163], v[60:63]
	v_mfma_f32_16x16x32_bf16 v[56:59], v[152:155], v[164:167], v[56:59]
	v_mfma_f32_16x16x32_bf16 v[52:55], v[152:155], v[176:179], v[52:55]
	v_mfma_f32_16x16x32_bf16 v[48:51], v[152:155], v[182:185], v[48:51]
	s_waitcnt lgkmcnt(10)
	v_mfma_f32_16x16x32_bf16 v[44:47], v[156:159], v[160:163], v[44:47]
	v_mfma_f32_16x16x32_bf16 v[40:43], v[156:159], v[164:167], v[40:43]
	v_mfma_f32_16x16x32_bf16 v[36:39], v[156:159], v[176:179], v[36:39]
	v_mfma_f32_16x16x32_bf16 v[32:35], v[156:159], v[182:185], v[32:35]
	s_waitcnt lgkmcnt(9)
	v_mfma_f32_16x16x32_bf16 v[28:31], v[168:171], v[160:163], v[28:31]
	v_mfma_f32_16x16x32_bf16 v[24:27], v[168:171], v[164:167], v[24:27]
	v_mfma_f32_16x16x32_bf16 v[20:23], v[168:171], v[176:179], v[20:23]
	v_mfma_f32_16x16x32_bf16 v[16:19], v[168:171], v[182:185], v[16:19]
	s_waitcnt lgkmcnt(8)
	v_mfma_f32_16x16x32_bf16 v[12:15], v[172:175], v[160:163], v[12:15]
	v_mfma_f32_16x16x32_bf16 v[8:11], v[172:175], v[164:167], v[8:11]
	v_mfma_f32_16x16x32_bf16 v[4:7], v[172:175], v[176:179], v[4:7]
	v_mfma_f32_16x16x32_bf16 v[0:3], v[172:175], v[182:185], v[0:3]
	s_waitcnt lgkmcnt(3)
	v_mfma_f32_16x16x32_bf16 v[60:63], v[204:207], v[208:211], v[60:63]
	v_mfma_f32_16x16x32_bf16 v[56:59], v[204:207], v[212:215], v[56:59]
	v_mfma_f32_16x16x32_bf16 v[52:55], v[204:207], v[216:219], v[52:55]
	v_mfma_f32_16x16x32_bf16 v[48:51], v[204:207], v[220:223], v[48:51]
	s_waitcnt lgkmcnt(2)
	v_mfma_f32_16x16x32_bf16 v[44:47], v[224:227], v[208:211], v[44:47]
	v_mfma_f32_16x16x32_bf16 v[40:43], v[224:227], v[212:215], v[40:43]
	v_mfma_f32_16x16x32_bf16 v[36:39], v[224:227], v[216:219], v[36:39]
	v_mfma_f32_16x16x32_bf16 v[32:35], v[224:227], v[220:223], v[32:35]
	s_waitcnt lgkmcnt(1)
	v_mfma_f32_16x16x32_bf16 v[28:31], v[228:231], v[208:211], v[28:31]
	v_mfma_f32_16x16x32_bf16 v[24:27], v[228:231], v[212:215], v[24:27]
	v_mfma_f32_16x16x32_bf16 v[20:23], v[228:231], v[216:219], v[20:23]
	v_mfma_f32_16x16x32_bf16 v[16:19], v[228:231], v[220:223], v[16:19]
	s_waitcnt lgkmcnt(0)
	v_mfma_f32_16x16x32_bf16 v[12:15], v[232:235], v[208:211], v[12:15]
	v_mfma_f32_16x16x32_bf16 v[8:11], v[232:235], v[212:215], v[8:11]
	v_mfma_f32_16x16x32_bf16 v[4:7], v[232:235], v[216:219], v[4:7]
	v_mfma_f32_16x16x32_bf16 v[0:3], v[232:235], v[220:223], v[0:3]
	s_setprio 0
	s_add_u32 s12, s12, 0x80
	s_addc_u32 s13, s13, 0
	s_addk_i32 s26, 0x4000
	s_cmpk_eq_i32 s12, 0x780
	s_waitcnt vmcnt(0)
	s_barrier
	s_cbranch_scc0 .LBB0_1834
	ds_read_b128 v[96:99], v69 offset:32768
	ds_read_b128 v[100:103], v69 offset:34816
	ds_read_b128 v[104:107], v135 offset:49152
	ds_read_b128 v[108:111], v135 offset:51200
	ds_read_b128 v[152:155], v69 offset:36864
	ds_read_b128 v[156:159], v69 offset:38912
	ds_read_b128 v[160:163], v135 offset:53248
	ds_read_b128 v[164:167], v135 offset:55296
	ds_read_b128 v[204:207], v136 offset:32768
	ds_read_b128 v[208:211], v136 offset:34816
	ds_read_b128 v[212:215], v137 offset:49152
	ds_read_b128 v[216:219], v137 offset:51200
	ds_read_b128 v[220:223], v136 offset:36864
	ds_read_b128 v[224:227], v136 offset:38912
	ds_read_b128 v[228:231], v137 offset:53248
	ds_read_b128 v[232:235], v137 offset:55296
	s_setprio 1
	s_waitcnt lgkmcnt(9)
	v_mfma_f32_16x16x32_bf16 v[4:7], v[156:159], v[160:163], v[4:7]
	s_waitcnt lgkmcnt(8)
	v_mfma_f32_16x16x32_bf16 v[0:3], v[156:159], v[164:167], v[0:3]
	v_mfma_f32_16x16x32_bf16 v[60:63], v[96:99], v[104:107], v[60:63]
	v_mfma_f32_16x16x32_bf16 v[56:59], v[96:99], v[108:111], v[56:59]
	v_mfma_f32_16x16x32_bf16 v[52:55], v[96:99], v[160:163], v[52:55]
	v_mfma_f32_16x16x32_bf16 v[48:51], v[96:99], v[164:167], v[48:51]
	v_mfma_f32_16x16x32_bf16 v[44:47], v[100:103], v[104:107], v[44:47]
	v_mfma_f32_16x16x32_bf16 v[40:43], v[100:103], v[108:111], v[40:43]
	v_mfma_f32_16x16x32_bf16 v[36:39], v[100:103], v[160:163], v[36:39]
	v_mfma_f32_16x16x32_bf16 v[32:35], v[100:103], v[164:167], v[32:35]
	v_mfma_f32_16x16x32_bf16 v[28:31], v[152:155], v[104:107], v[28:31]
	v_mfma_f32_16x16x32_bf16 v[24:27], v[152:155], v[108:111], v[24:27]
	v_mfma_f32_16x16x32_bf16 v[20:23], v[152:155], v[160:163], v[20:23]
	v_mfma_f32_16x16x32_bf16 v[16:19], v[152:155], v[164:167], v[16:19]
	v_mfma_f32_16x16x32_bf16 v[12:15], v[156:159], v[104:107], v[12:15]
	v_mfma_f32_16x16x32_bf16 v[8:11], v[156:159], v[108:111], v[8:11]
	s_waitcnt lgkmcnt(1)
	v_mfma_f32_16x16x32_bf16 v[4:7], v[224:227], v[228:231], v[4:7]
	s_waitcnt lgkmcnt(0)
	v_mfma_f32_16x16x32_bf16 v[0:3], v[224:227], v[232:235], v[0:3]
	v_mfma_f32_16x16x32_bf16 v[60:63], v[204:207], v[212:215], v[60:63]
	v_mfma_f32_16x16x32_bf16 v[56:59], v[204:207], v[216:219], v[56:59]
	v_mfma_f32_16x16x32_bf16 v[52:55], v[204:207], v[228:231], v[52:55]
	v_mfma_f32_16x16x32_bf16 v[48:51], v[204:207], v[232:235], v[48:51]
	v_mfma_f32_16x16x32_bf16 v[44:47], v[208:211], v[212:215], v[44:47]
	v_mfma_f32_16x16x32_bf16 v[40:43], v[208:211], v[216:219], v[40:43]
	v_mfma_f32_16x16x32_bf16 v[36:39], v[208:211], v[228:231], v[36:39]
	v_mfma_f32_16x16x32_bf16 v[32:35], v[208:211], v[232:235], v[32:35]
	v_mfma_f32_16x16x32_bf16 v[28:31], v[220:223], v[212:215], v[28:31]
	v_mfma_f32_16x16x32_bf16 v[24:27], v[220:223], v[216:219], v[24:27]
	v_mfma_f32_16x16x32_bf16 v[20:23], v[220:223], v[228:231], v[20:23]
	v_mfma_f32_16x16x32_bf16 v[16:19], v[220:223], v[232:235], v[16:19]
	v_mfma_f32_16x16x32_bf16 v[12:15], v[224:227], v[212:215], v[12:15]
	v_mfma_f32_16x16x32_bf16 v[8:11], v[224:227], v[216:219], v[8:11]
	s_setprio 0
	s_barrier
	ds_write2_b32 v134, v60, v56 offset1:16
	ds_write2_b32 v134, v61, v57 offset0:132 offset1:148
	v_add_u32_e32 v56, 0x400, v134
	ds_write2_b32 v56, v62, v58 offset0:8 offset1:24
	ds_write2_b32 v56, v63, v59 offset0:140 offset1:156
	ds_write2_b32 v134, v52, v48 offset0:32 offset1:48
	ds_write2_b32 v134, v53, v49 offset0:164 offset1:180
	ds_write2_b32 v56, v54, v50 offset0:40 offset1:56
	ds_write2_b32 v56, v55, v51 offset0:172 offset1:188
	v_add_u32_e32 v48, 0x2000, v134
	ds_write2_b32 v48, v44, v40 offset0:64 offset1:80
	ds_write2_b32 v48, v45, v41 offset0:196 offset1:212
	v_add_u32_e32 v40, 0x2400, v134
	ds_write2_b32 v40, v46, v42 offset0:72 offset1:88
	ds_write2_b32 v40, v47, v43 offset0:204 offset1:220
	ds_write2_b32 v48, v36, v32 offset0:96 offset1:112
	ds_write2_b32 v48, v37, v33 offset0:228 offset1:244
	ds_write2_b32 v40, v38, v34 offset0:104 offset1:120
	ds_write2_b32 v40, v39, v35 offset0:236 offset1:252
	v_add_u32_e32 v32, 0x4000, v134
	ds_write2_b32 v32, v28, v24 offset0:128 offset1:144
	v_add_u32_e32 v24, 0x4400, v134
	ds_write2_b32 v24, v29, v25 offset0:4 offset1:20
	ds_write2_b32 v24, v30, v26 offset0:136 offset1:152
	v_add_u32_e32 v25, 0x4800, v134
	ds_write2_b32 v25, v31, v27 offset0:12 offset1:28
	ds_write2_b32 v32, v20, v16 offset0:160 offset1:176
	ds_write2_b32 v24, v21, v17 offset0:36 offset1:52
	ds_write2_b32 v24, v22, v18 offset0:168 offset1:184
	ds_write2_b32 v25, v23, v19 offset0:44 offset1:60
	v_add_u32_e32 v16, 0x6000, v134
	ds_write2_b32 v16, v12, v8 offset0:192 offset1:208
	v_add_u32_e32 v8, 0x6400, v134
	ds_write2_b32 v8, v13, v9 offset0:68 offset1:84
	ds_write2_b32 v8, v14, v10 offset0:200 offset1:216
	v_add_u32_e32 v9, 0x6800, v134
	ds_write2_b32 v9, v15, v11 offset0:76 offset1:92
	ds_write2_b32 v16, v4, v0 offset0:224 offset1:240
	ds_write2_b32 v8, v5, v1 offset0:100 offset1:116
	ds_write2_b32 v8, v6, v2 offset0:232 offset1:248
	ds_write2_b32 v9, v7, v3 offset0:108 offset1:124
	v_or_b32_e32 v0, s24, v113
	v_lshlrev_b32_e32 v70, 2, v0
	v_lshl_add_u64 v[0:1], s[14:15], 0, v[70:71]
	v_lshl_add_u64 v[2:3], s[10:11], 0, v[70:71]
	v_add_u32_e32 v4, s25, v146
	s_mov_b32 s12, 0
	s_waitcnt lgkmcnt(0)
	s_barrier

.LBB0_1997:
	s_ashr_i32 s12, s16, 31
	s_lshr_b32 s12, s12, 27
	s_add_i32 s12, s16, s12
	s_ashr_i32 s12, s12, 5
	s_lshl_b32 s17, s12, 7
	s_lshl_b32 s12, s12, 12
	s_lshl_b32 s13, s16, 7
	s_sub_i32 s18, s13, s12
	v_add_u32_e32 v0, s18, v106
	v_ashrrev_i32_e32 v1, 31, v0
	v_add_u32_e32 v2, 0x4000, v107
	v_lshlrev_b64 v[0:1], 11, v[0:1]
	v_readfirstlane_b32 s13, v2
	v_lshl_add_u64 v[0:1], v[66:67], 0, v[0:1]
	s_mov_b32 m0, s13
	v_readfirstlane_b32 s13, v107
	global_load_lds_dwordx4 v[0:1], off
	v_add_u32_e32 v0, s17, v106
	v_ashrrev_i32_e32 v1, 31, v0
	v_lshlrev_b64 v[0:1], 11, v[0:1]
	v_lshl_add_u64 v[2:3], v[72:73], 0, v[0:1]
	s_mov_b32 m0, s13
	v_readfirstlane_b32 s13, v130
	global_load_lds_dwordx4 v[2:3], off
	v_add_u32_e32 v2, s18, v108
	v_ashrrev_i32_e32 v3, 31, v2
	v_lshlrev_b64 v[2:3], 11, v[2:3]
	v_lshl_add_u64 v[2:3], v[68:69], 0, v[2:3]
	s_mov_b32 m0, s13
	v_add_u32_e32 v4, 0x400, v107
	global_load_lds_dwordx4 v[2:3], off
	v_add_u32_e32 v2, s17, v108
	v_ashrrev_i32_e32 v3, 31, v2
	v_lshlrev_b64 v[2:3], 11, v[2:3]
	v_readfirstlane_b32 s13, v4
	v_lshl_add_u64 v[2:3], v[74:75], 0, v[2:3]
	s_mov_b32 m0, s13
	v_readfirstlane_b32 s13, v131
	global_load_lds_dwordx4 v[2:3], off
	v_add_u32_e32 v2, s18, v110
	v_ashrrev_i32_e32 v3, 31, v2
	v_lshlrev_b64 v[2:3], 11, v[2:3]
	v_lshl_add_u64 v[2:3], v[66:67], 0, v[2:3]
	s_mov_b32 m0, s13
	v_add_u32_e32 v4, 0x800, v107
	global_load_lds_dwordx4 v[2:3], off
	v_add_u32_e32 v2, s17, v110
	v_ashrrev_i32_e32 v3, 31, v2
	v_lshlrev_b64 v[2:3], 11, v[2:3]
	v_readfirstlane_b32 s13, v4
	v_lshl_add_u64 v[2:3], v[72:73], 0, v[2:3]
	s_mov_b32 m0, s13
	v_readfirstlane_b32 s13, v132
	global_load_lds_dwordx4 v[2:3], off
	v_add_u32_e32 v2, s18, v112
	v_ashrrev_i32_e32 v3, 31, v2
	v_lshlrev_b64 v[2:3], 11, v[2:3]
	v_lshl_add_u64 v[2:3], v[70:71], 0, v[2:3]
	s_mov_b32 m0, s13
	v_add_u32_e32 v4, 0xc00, v107
	global_load_lds_dwordx4 v[2:3], off
	v_add_u32_e32 v2, s17, v112
	v_ashrrev_i32_e32 v3, 31, v2
	v_lshlrev_b64 v[2:3], 11, v[2:3]
	v_readfirstlane_b32 s13, v4
	v_lshl_add_u64 v[2:3], v[76:77], 0, v[2:3]
	s_mov_b32 m0, s13
	v_lshl_add_u64 v[92:93], v[80:81], 0, v[0:1]
	global_load_lds_dwordx4 v[2:3], off
	v_subrev_u32_e32 v0, s12, v123
	v_ashrrev_i32_e32 v1, 31, v0
	v_lshlrev_b64 v[0:1], 11, v[0:1]
	v_lshl_add_u64 v[94:95], v[82:83], 0, v[0:1]
	v_add_u32_e32 v0, s17, v124
	v_ashrrev_i32_e32 v1, 31, v0
	v_lshlrev_b64 v[0:1], 11, v[0:1]
	v_lshl_add_u64 v[96:97], v[84:85], 0, v[0:1]
	v_subrev_u32_e32 v0, s12, v125
	v_ashrrev_i32_e32 v1, 31, v0
	v_lshlrev_b64 v[0:1], 11, v[0:1]
	v_lshl_add_u64 v[98:99], v[78:79], 0, v[0:1]
	v_add_u32_e32 v0, s17, v126
	v_ashrrev_i32_e32 v1, 31, v0
	v_lshlrev_b64 v[0:1], 11, v[0:1]
	v_lshl_add_u64 v[100:101], v[80:81], 0, v[0:1]
	v_subrev_u32_e32 v0, s12, v64
	v_ashrrev_i32_e32 v1, 31, v0
	v_lshlrev_b64 v[0:1], 11, v[0:1]
	v_subrev_u32_e32 v2, s12, v122
	v_lshl_add_u64 v[102:103], v[86:87], 0, v[0:1]
	v_add_u32_e32 v0, s17, v127
	v_ashrrev_i32_e32 v3, 31, v2
	v_ashrrev_i32_e32 v1, 31, v0
	v_lshlrev_b64 v[2:3], 11, v[2:3]
	v_lshlrev_b64 v[0:1], 11, v[0:1]
	v_lshl_add_u64 v[90:91], v[78:79], 0, v[2:3]
	v_lshl_add_u64 v[104:105], v[88:89], 0, v[0:1]
	s_mov_b64 s[12:13], 0
	s_mov_b32 s19, 0
	v_mov_b32_e32 v0, 0
	v_mov_b32_e32 v1, v65
	v_mov_b32_e32 v2, v65
	v_mov_b32_e32 v3, v65
	v_mov_b32_e32 v4, 0
	v_mov_b32_e32 v5, v65
	v_mov_b32_e32 v6, v65
	v_mov_b32_e32 v7, v65
	v_mov_b32_e32 v8, 0
	v_mov_b32_e32 v9, v65
	v_mov_b32_e32 v10, v65
	v_mov_b32_e32 v11, v65
	v_mov_b32_e32 v12, 0
	v_mov_b32_e32 v13, v65
	v_mov_b32_e32 v14, v65
	v_mov_b32_e32 v15, v65
	v_mov_b32_e32 v16, 0
	v_mov_b32_e32 v17, v65
	v_mov_b32_e32 v18, v65
	v_mov_b32_e32 v19, v65
	v_mov_b32_e32 v20, 0
	v_mov_b32_e32 v21, v65
	v_mov_b32_e32 v22, v65
	v_mov_b32_e32 v23, v65
	v_mov_b32_e32 v24, 0
	v_mov_b32_e32 v25, v65
	v_mov_b32_e32 v26, v65
	v_mov_b32_e32 v27, v65
	v_mov_b32_e32 v28, 0
	v_mov_b32_e32 v29, v65
	v_mov_b32_e32 v30, v65
	v_mov_b32_e32 v31, v65
	v_mov_b32_e32 v32, 0
	v_mov_b32_e32 v33, v65
	v_mov_b32_e32 v34, v65
	v_mov_b32_e32 v35, v65
	v_mov_b32_e32 v36, 0
	v_mov_b32_e32 v37, v65
	v_mov_b32_e32 v38, v65
	v_mov_b32_e32 v39, v65
	v_mov_b32_e32 v40, 0
	v_mov_b32_e32 v41, v65
	v_mov_b32_e32 v42, v65
	v_mov_b32_e32 v43, v65
	v_mov_b32_e32 v44, 0
	v_mov_b32_e32 v45, v65
	v_mov_b32_e32 v46, v65
	v_mov_b32_e32 v47, v65
	v_mov_b32_e32 v48, 0
	v_mov_b32_e32 v49, v65
	v_mov_b32_e32 v50, v65
	v_mov_b32_e32 v51, v65
	v_mov_b32_e32 v52, 0
	v_mov_b32_e32 v53, v65
	v_mov_b32_e32 v54, v65
	v_mov_b32_e32 v55, v65
	v_mov_b32_e32 v56, 0
	v_mov_b32_e32 v57, v65
	v_mov_b32_e32 v58, v65
	v_mov_b32_e32 v59, v65
	v_mov_b32_e32 v60, 0
	v_mov_b32_e32 v61, v65
	v_mov_b32_e32 v62, v65
	v_mov_b32_e32 v63, v65
	s_waitcnt vmcnt(0) lgkmcnt(0)
	s_barrier
	v_add3_u32 v182, 0, v133, v134
	v_add_u32_e32 v183, 0x4000, v182
	s_nop 0
	v_readfirstlane_b32 s82, v183
	v_lshl_add_u32 v183, v109, 1, 0
	s_nop 0
	v_readfirstlane_b32 s83, v182
	v_add3_u32 v183, v183, v134, s15
	s_nop 0
	v_readfirstlane_b32 s84, v183
	v_add_u32_e32 v183, 0x400, v182
	s_nop 0
	v_readfirstlane_b32 s85, v183
	v_lshl_add_u32 v183, v111, 1, 0
	v_add3_u32 v183, v183, v134, s15
	s_nop 0
	v_readfirstlane_b32 s86, v183
	v_add_u32_e32 v183, 0x800, v182
	s_nop 0
	v_readfirstlane_b32 s87, v183
	v_lshl_add_u32 v183, v113, 1, 0
	v_add3_u32 v183, v183, v134, s15
	s_nop 0
	v_readfirstlane_b32 s88, v183
	v_add_u32_e32 v182, 0xc00, v182
	s_nop 0
	v_readfirstlane_b32 s89, v182
	v_subrev_u32_e32 v184, s52, v90
	v_subrev_u32_e32 v185, s52, v92
	v_subrev_u32_e32 v186, s52, v94
	v_subrev_u32_e32 v187, s52, v96
	v_subrev_u32_e32 v188, s52, v98
	v_subrev_u32_e32 v189, s52, v100
	v_subrev_u32_e32 v190, s52, v102
	v_subrev_u32_e32 v191, s52, v104
	v_subrev_u32_e32 v187, 0x400, v187
	v_subrev_u32_e32 v186, 0x400, v186
	v_subrev_u32_e32 v189, 0x800, v189
	v_subrev_u32_e32 v188, 0x800, v188
	v_subrev_u32_e32 v191, 0xc00, v191
	v_subrev_u32_e32 v190, 0xc00, v190
	s_and_b32 s21, s19, 0x4000
	s_xor_b32 s20, s21, 0x4000
	s_lshl_b32 s20, s20, 1
	s_add_i32 s20, s20, 32
	s_lshl_b32 s21, s21, 1
	s_add_i32 s21, s21, 32
.LBB0_1998:
	s_xor_b32 s20, s20, 0x8000
	s_xor_b32 s21, s21, 0x8000
	s_add_u32 s90, s52, s12
	s_addc_u32 s91, s53, s13
	s_add_i32 m0, s21, s83
	v_lshl_add_u32 v137, v114, 1, s20
	global_load_lds_dwordx4 v185, s[90:91]
	global_load_lds_dwordx4 v187, s[90:91] offset:1024
	global_load_lds_dwordx4 v189, s[90:91] offset:2048
	global_load_lds_dwordx4 v191, s[90:91] offset:3072
	s_add_i32 m0, s21, s82
	v_lshl_add_u32 v170, v115, 1, s20
	global_load_lds_dwordx4 v184, s[90:91]
	global_load_lds_dwordx4 v186, s[90:91] offset:1024
	global_load_lds_dwordx4 v188, s[90:91] offset:2048
	global_load_lds_dwordx4 v190, s[90:91] offset:3072
	v_add_u32_e32 v158, v137, v135
	v_add_u32_e32 v166, v170, v135
	s_add_u32 s12, s12, 0x80
	s_addc_u32 s13, s13, 0
	ds_read_b128 v[138:141], v158
	ds_read_b128 v[146:149], v166 offset:16384
	ds_read_b128 v[150:153], v166 offset:18432
	ds_read_b128 v[162:165], v166 offset:20480
	ds_read_b128 v[166:169], v166 offset:22528
	ds_read_b128 v[142:145], v158 offset:2048
	ds_read_b128 v[154:157], v158 offset:4096
	ds_read_b128 v[158:161], v158 offset:6144
	v_add_u32_e32 v137, v137, v136
	v_add_u32_e32 v236, v170, v136
	ds_read_b128 v[204:207], v137
	ds_read_b128 v[208:211], v236 offset:16384
	ds_read_b128 v[212:215], v236 offset:18432
	ds_read_b128 v[216:219], v236 offset:20480
	ds_read_b128 v[220:223], v236 offset:22528
	ds_read_b128 v[224:227], v137 offset:2048
	ds_read_b128 v[228:231], v137 offset:4096
	ds_read_b128 v[232:235], v137 offset:6144
	s_setprio 1
	s_waitcnt lgkmcnt(11)
	v_mfma_f32_16x16x32_bf16 v[60:63], v[138:141], v[146:149], v[60:63]
	v_mfma_f32_16x16x32_bf16 v[56:59], v[138:141], v[150:153], v[56:59]
	v_mfma_f32_16x16x32_bf16 v[52:55], v[138:141], v[162:165], v[52:55]
	v_mfma_f32_16x16x32_bf16 v[48:51], v[138:141], v[166:169], v[48:51]
	s_waitcnt lgkmcnt(10)
	v_mfma_f32_16x16x32_bf16 v[44:47], v[142:145], v[146:149], v[44:47]
	v_mfma_f32_16x16x32_bf16 v[40:43], v[142:145], v[150:153], v[40:43]
	v_mfma_f32_16x16x32_bf16 v[36:39], v[142:145], v[162:165], v[36:39]
	v_mfma_f32_16x16x32_bf16 v[32:35], v[142:145], v[166:169], v[32:35]
	s_waitcnt lgkmcnt(9)
	v_mfma_f32_16x16x32_bf16 v[28:31], v[154:157], v[146:149], v[28:31]
	v_mfma_f32_16x16x32_bf16 v[24:27], v[154:157], v[150:153], v[24:27]
	v_mfma_f32_16x16x32_bf16 v[20:23], v[154:157], v[162:165], v[20:23]
	v_mfma_f32_16x16x32_bf16 v[16:19], v[154:157], v[166:169], v[16:19]
	s_waitcnt lgkmcnt(8)
	v_mfma_f32_16x16x32_bf16 v[12:15], v[158:161], v[146:149], v[12:15]
	v_mfma_f32_16x16x32_bf16 v[8:11], v[158:161], v[150:153], v[8:11]
	v_mfma_f32_16x16x32_bf16 v[4:7], v[158:161], v[162:165], v[4:7]
	v_mfma_f32_16x16x32_bf16 v[0:3], v[158:161], v[166:169], v[0:3]
	s_waitcnt lgkmcnt(3)
	v_mfma_f32_16x16x32_bf16 v[60:63], v[204:207], v[208:211], v[60:63]
	v_mfma_f32_16x16x32_bf16 v[56:59], v[204:207], v[212:215], v[56:59]
	v_mfma_f32_16x16x32_bf16 v[52:55], v[204:207], v[216:219], v[52:55]
	v_mfma_f32_16x16x32_bf16 v[48:51], v[204:207], v[220:223], v[48:51]
	s_waitcnt lgkmcnt(2)
	v_mfma_f32_16x16x32_bf16 v[44:47], v[224:227], v[208:211], v[44:47]
	v_mfma_f32_16x16x32_bf16 v[40:43], v[224:227], v[212:215], v[40:43]
	v_mfma_f32_16x16x32_bf16 v[36:39], v[224:227], v[216:219], v[36:39]
	v_mfma_f32_16x16x32_bf16 v[32:35], v[224:227], v[220:223], v[32:35]
	s_waitcnt lgkmcnt(1)
	v_mfma_f32_16x16x32_bf16 v[28:31], v[228:231], v[208:211], v[28:31]
	v_mfma_f32_16x16x32_bf16 v[24:27], v[228:231], v[212:215], v[24:27]
	v_mfma_f32_16x16x32_bf16 v[20:23], v[228:231], v[216:219], v[20:23]
	v_mfma_f32_16x16x32_bf16 v[16:19], v[228:231], v[220:223], v[16:19]
	s_waitcnt lgkmcnt(0)
	v_mfma_f32_16x16x32_bf16 v[12:15], v[232:235], v[208:211], v[12:15]
	v_mfma_f32_16x16x32_bf16 v[8:11], v[232:235], v[212:215], v[8:11]
	v_mfma_f32_16x16x32_bf16 v[4:7], v[232:235], v[216:219], v[4:7]
	v_mfma_f32_16x16x32_bf16 v[0:3], v[232:235], v[220:223], v[0:3]
	s_setprio 0
	s_cmpk_eq_i32 s12, 0x780
	s_waitcnt vmcnt(0)
	s_barrier
	s_cbranch_scc0 .LBB0_1998
	ds_read_b128 v[90:93], v116 offset:55296
	ds_read_b128 v[94:97], v116 offset:53248
	ds_read_b128 v[98:101], v117 offset:38912
	ds_read_b128 v[102:105], v117 offset:36864
	ds_read_b128 v[138:141], v116 offset:51200
	ds_read_b128 v[142:145], v116 offset:49152
	ds_read_b128 v[146:149], v117 offset:34816
	ds_read_b128 v[150:153], v117 offset:32768
	ds_read_b128 v[204:207], v118 offset:32768
	ds_read_b128 v[208:211], v118 offset:34816
	ds_read_b128 v[212:215], v119 offset:49152
	ds_read_b128 v[216:219], v119 offset:51200
	ds_read_b128 v[220:223], v118 offset:36864
	ds_read_b128 v[224:227], v118 offset:38912
	ds_read_b128 v[228:231], v119 offset:53248
	ds_read_b128 v[232:235], v119 offset:55296
	s_setprio 1
	s_waitcnt lgkmcnt(13)
	v_mfma_f32_16x16x32_bf16 v[0:3], v[98:101], v[90:93], v[0:3]
	s_waitcnt lgkmcnt(8)
	v_mfma_f32_16x16x32_bf16 v[60:63], v[150:153], v[142:145], v[60:63]
	v_mfma_f32_16x16x32_bf16 v[56:59], v[150:153], v[138:141], v[56:59]
	v_mfma_f32_16x16x32_bf16 v[52:55], v[150:153], v[94:97], v[52:55]
	v_mfma_f32_16x16x32_bf16 v[48:51], v[150:153], v[90:93], v[48:51]
	v_mfma_f32_16x16x32_bf16 v[44:47], v[146:149], v[142:145], v[44:47]
	v_mfma_f32_16x16x32_bf16 v[40:43], v[146:149], v[138:141], v[40:43]
	v_mfma_f32_16x16x32_bf16 v[36:39], v[146:149], v[94:97], v[36:39]
	v_mfma_f32_16x16x32_bf16 v[32:35], v[146:149], v[90:93], v[32:35]
	v_mfma_f32_16x16x32_bf16 v[28:31], v[102:105], v[142:145], v[28:31]
	v_mfma_f32_16x16x32_bf16 v[24:27], v[102:105], v[138:141], v[24:27]
	v_mfma_f32_16x16x32_bf16 v[20:23], v[102:105], v[94:97], v[20:23]
	v_mfma_f32_16x16x32_bf16 v[16:19], v[102:105], v[90:93], v[16:19]
	v_mfma_f32_16x16x32_bf16 v[12:15], v[98:101], v[142:145], v[12:15]
	v_mfma_f32_16x16x32_bf16 v[8:11], v[98:101], v[138:141], v[8:11]
	v_mfma_f32_16x16x32_bf16 v[4:7], v[98:101], v[94:97], v[4:7]
	s_waitcnt lgkmcnt(0)
	v_mfma_f32_16x16x32_bf16 v[0:3], v[224:227], v[232:235], v[0:3]
	v_mfma_f32_16x16x32_bf16 v[60:63], v[204:207], v[212:215], v[60:63]
	v_mfma_f32_16x16x32_bf16 v[56:59], v[204:207], v[216:219], v[56:59]
	v_mfma_f32_16x16x32_bf16 v[52:55], v[204:207], v[228:231], v[52:55]
	v_mfma_f32_16x16x32_bf16 v[48:51], v[204:207], v[232:235], v[48:51]
	v_mfma_f32_16x16x32_bf16 v[44:47], v[208:211], v[212:215], v[44:47]
	v_mfma_f32_16x16x32_bf16 v[40:43], v[208:211], v[216:219], v[40:43]
	v_mfma_f32_16x16x32_bf16 v[36:39], v[208:211], v[228:231], v[36:39]
	v_mfma_f32_16x16x32_bf16 v[32:35], v[208:211], v[232:235], v[32:35]
	v_mfma_f32_16x16x32_bf16 v[28:31], v[220:223], v[212:215], v[28:31]
	v_mfma_f32_16x16x32_bf16 v[24:27], v[220:223], v[216:219], v[24:27]
	v_mfma_f32_16x16x32_bf16 v[20:23], v[220:223], v[228:231], v[20:23]
	v_mfma_f32_16x16x32_bf16 v[16:19], v[220:223], v[232:235], v[16:19]
	v_mfma_f32_16x16x32_bf16 v[12:15], v[224:227], v[212:215], v[12:15]
	v_mfma_f32_16x16x32_bf16 v[8:11], v[224:227], v[216:219], v[8:11]
	v_mfma_f32_16x16x32_bf16 v[4:7], v[224:227], v[228:231], v[4:7]
	s_setprio 0
	s_barrier
	ds_write2_b32 v120, v60, v56 offset1:16
	ds_write2_b32 v120, v61, v57 offset0:132 offset1:148
	v_add_u32_e32 v56, 0x400, v120
	ds_write2_b32 v56, v62, v58 offset0:8 offset1:24
	ds_write2_b32 v56, v63, v59 offset0:140 offset1:156
	ds_write2_b32 v120, v52, v48 offset0:32 offset1:48
	ds_write2_b32 v120, v53, v49 offset0:164 offset1:180
	ds_write2_b32 v56, v54, v50 offset0:40 offset1:56
	ds_write2_b32 v56, v55, v51 offset0:172 offset1:188
	v_add_u32_e32 v48, 0x2000, v120
	ds_write2_b32 v48, v44, v40 offset0:64 offset1:80
	ds_write2_b32 v48, v45, v41 offset0:196 offset1:212
	v_add_u32_e32 v40, 0x2400, v120
	ds_write2_b32 v40, v46, v42 offset0:72 offset1:88
	ds_write2_b32 v40, v47, v43 offset0:204 offset1:220
	ds_write2_b32 v48, v36, v32 offset0:96 offset1:112
	ds_write2_b32 v48, v37, v33 offset0:228 offset1:244
	ds_write2_b32 v40, v38, v34 offset0:104 offset1:120
	ds_write2_b32 v40, v39, v35 offset0:236 offset1:252
	v_add_u32_e32 v32, 0x4000, v120
	ds_write2_b32 v32, v28, v24 offset0:128 offset1:144
	v_add_u32_e32 v24, 0x4400, v120
	ds_write2_b32 v24, v29, v25 offset0:4 offset1:20
	ds_write2_b32 v24, v30, v26 offset0:136 offset1:152
	v_add_u32_e32 v25, 0x4800, v120
	ds_write2_b32 v25, v31, v27 offset0:12 offset1:28
	ds_write2_b32 v32, v20, v16 offset0:160 offset1:176
	ds_write2_b32 v24, v21, v17 offset0:36 offset1:52
	ds_write2_b32 v24, v22, v18 offset0:168 offset1:184
	ds_write2_b32 v25, v23, v19 offset0:44 offset1:60
	v_add_u32_e32 v16, 0x6000, v120
	ds_write2_b32 v16, v12, v8 offset0:192 offset1:208
	v_add_u32_e32 v8, 0x6400, v120
	ds_write2_b32 v8, v13, v9 offset0:68 offset1:84
	ds_write2_b32 v8, v14, v10 offset0:200 offset1:216
	v_add_u32_e32 v9, 0x6800, v120
	ds_write2_b32 v9, v15, v11 offset0:76 offset1:92
	ds_write2_b32 v16, v4, v0 offset0:224 offset1:240
	ds_write2_b32 v8, v5, v1 offset0:100 offset1:116
	ds_write2_b32 v8, v6, v2 offset0:232 offset1:248
	ds_write2_b32 v9, v7, v3 offset0:108 offset1:124
	v_or_b32_e32 v0, s18, v121
	v_ashrrev_i32_e32 v1, 31, v0
	v_lshl_add_u64 v[0:1], v[0:1], 1, s[6:7]
	v_add_u32_e32 v2, s17, v128
	s_mov_b32 s12, 0
	s_waitcnt lgkmcnt(0)
	s_barrier

.LBB0_2008:
	s_ashr_i32 s14, s9, 31
	s_lshr_b32 s14, s14, 29
	s_add_i32 s14, s9, s14
	s_ashr_i32 s15, s14, 3
	s_lshl_b32 s16, s15, 10
	s_lshl_b32 s9, s9, 7
	s_sub_i32 s14, s9, s16
	v_add_u32_e32 v0, s15, v104
	s_add_i32 s14, s14, s8
	v_lshlrev_b32_e32 v2, 7, v0
	v_add_u32_e32 v0, s14, v105
	v_ashrrev_i32_e32 v1, 31, v0
	v_add_u32_e32 v3, 0x4000, v106
	v_lshlrev_b64 v[0:1], 11, v[0:1]
	v_readfirstlane_b32 s17, v3
	v_lshl_add_u64 v[0:1], v[64:65], 0, v[0:1]
	s_mov_b32 m0, s17
	v_readfirstlane_b32 s17, v106
	global_load_lds_dwordx4 v[0:1], off
	v_add_u32_e32 v0, v2, v105
	v_ashrrev_i32_e32 v1, 31, v0
	v_lshlrev_b64 v[0:1], 11, v[0:1]
	v_lshl_add_u64 v[0:1], v[70:71], 0, v[0:1]
	s_mov_b32 m0, s17
	v_readfirstlane_b32 s17, v130
	global_load_lds_dwordx4 v[0:1], off
	v_add_u32_e32 v0, s14, v107
	v_ashrrev_i32_e32 v1, 31, v0
	v_lshlrev_b64 v[0:1], 11, v[0:1]
	v_lshl_add_u64 v[0:1], v[66:67], 0, v[0:1]
	s_mov_b32 m0, s17
	v_add_u32_e32 v3, 0x400, v106
	global_load_lds_dwordx4 v[0:1], off
	v_add_u32_e32 v0, v2, v107
	v_ashrrev_i32_e32 v1, 31, v0
	v_lshlrev_b64 v[0:1], 11, v[0:1]
	v_readfirstlane_b32 s17, v3
	v_lshl_add_u64 v[0:1], v[72:73], 0, v[0:1]
	s_mov_b32 m0, s17
	v_readfirstlane_b32 s17, v131
	global_load_lds_dwordx4 v[0:1], off
	v_add_u32_e32 v0, s14, v109
	v_ashrrev_i32_e32 v1, 31, v0
	v_lshlrev_b64 v[0:1], 11, v[0:1]
	v_lshl_add_u64 v[0:1], v[64:65], 0, v[0:1]
	s_mov_b32 m0, s17
	v_add_u32_e32 v3, 0x800, v106
	global_load_lds_dwordx4 v[0:1], off
	v_add_u32_e32 v0, v2, v109
	v_ashrrev_i32_e32 v1, 31, v0
	v_lshlrev_b64 v[0:1], 11, v[0:1]
	v_readfirstlane_b32 s17, v3
	v_lshl_add_u64 v[0:1], v[70:71], 0, v[0:1]
	s_mov_b32 m0, s17
	v_readfirstlane_b32 s17, v132
	global_load_lds_dwordx4 v[0:1], off
	v_add_u32_e32 v0, s14, v111
	v_ashrrev_i32_e32 v1, 31, v0
	v_lshlrev_b64 v[0:1], 11, v[0:1]
	v_lshl_add_u64 v[0:1], v[68:69], 0, v[0:1]
	s_mov_b32 m0, s17
	s_add_i32 s9, s9, s8
	global_load_lds_dwordx4 v[0:1], off
	v_add_u32_e32 v0, v2, v111
	v_ashrrev_i32_e32 v1, 31, v0
	v_add_u32_e32 v2, 0xc00, v106
	v_lshlrev_b64 v[0:1], 11, v[0:1]
	v_readfirstlane_b32 s17, v2
	v_lshl_add_u64 v[0:1], v[74:75], 0, v[0:1]
	s_mov_b32 m0, s17
	s_lshl_b32 s15, s15, 7
	global_load_lds_dwordx4 v[0:1], off
	v_add_u32_e32 v0, s9, v105
	v_subrev_u32_e32 v0, s16, v0
	v_ashrrev_i32_e32 v1, 31, v0
	v_lshlrev_b64 v[0:1], 11, v[0:1]
	v_lshl_add_u64 v[88:89], v[76:77], 0, v[0:1]
	v_add_u32_e32 v0, s15, v121
	v_ashrrev_i32_e32 v1, 31, v0
	v_lshlrev_b64 v[0:1], 11, v[0:1]
	v_lshl_add_u64 v[90:91], v[78:79], 0, v[0:1]
	v_add_u32_e32 v0, s9, v122
	v_subrev_u32_e32 v0, s16, v0
	v_ashrrev_i32_e32 v1, 31, v0
	v_lshlrev_b64 v[0:1], 11, v[0:1]
	v_lshl_add_u64 v[92:93], v[80:81], 0, v[0:1]
	v_add_u32_e32 v0, s15, v123
	v_ashrrev_i32_e32 v1, 31, v0
	v_lshlrev_b64 v[0:1], 11, v[0:1]
	v_lshl_add_u64 v[94:95], v[82:83], 0, v[0:1]
	v_add_u32_e32 v0, s9, v124
	v_subrev_u32_e32 v0, s16, v0
	v_ashrrev_i32_e32 v1, 31, v0
	v_lshlrev_b64 v[0:1], 11, v[0:1]
	v_lshl_add_u64 v[96:97], v[76:77], 0, v[0:1]
	v_add_u32_e32 v0, s15, v125
	v_ashrrev_i32_e32 v1, 31, v0
	v_lshlrev_b64 v[0:1], 11, v[0:1]
	v_lshl_add_u64 v[98:99], v[78:79], 0, v[0:1]
	v_add_u32_e32 v0, s9, v126
	v_subrev_u32_e32 v0, s16, v0
	v_ashrrev_i32_e32 v1, 31, v0
	v_lshlrev_b64 v[0:1], 11, v[0:1]
	v_lshl_add_u64 v[100:101], v[84:85], 0, v[0:1]
	v_add_u32_e32 v0, s15, v127
	v_ashrrev_i32_e32 v1, 31, v0
	v_lshlrev_b64 v[0:1], 11, v[0:1]
	v_lshl_add_u64 v[102:103], v[86:87], 0, v[0:1]
	v_mov_b32_e32 v0, 0
	s_mov_b32 s16, 0
	s_mov_b64 s[8:9], 0
	v_mov_b32_e32 v1, v0
	v_mov_b32_e32 v2, v0
	v_mov_b32_e32 v3, v0
	v_mov_b32_e32 v4, v0
	v_mov_b32_e32 v5, v0
	v_mov_b32_e32 v6, v0
	v_mov_b32_e32 v7, v0
	v_mov_b32_e32 v8, v0
	v_mov_b32_e32 v9, v0
	v_mov_b32_e32 v10, v0
	v_mov_b32_e32 v11, v0
	v_mov_b32_e32 v12, v0
	v_mov_b32_e32 v13, v0
	v_mov_b32_e32 v14, v0
	v_mov_b32_e32 v15, v0
	v_mov_b32_e32 v16, v0
	v_mov_b32_e32 v17, v0
	v_mov_b32_e32 v18, v0
	v_mov_b32_e32 v19, v0
	v_mov_b32_e32 v20, v0
	v_mov_b32_e32 v21, v0
	v_mov_b32_e32 v22, v0
	v_mov_b32_e32 v23, v0
	v_mov_b32_e32 v24, v0
	v_mov_b32_e32 v25, v0
	v_mov_b32_e32 v26, v0
	v_mov_b32_e32 v27, v0
	v_mov_b32_e32 v28, v0
	v_mov_b32_e32 v29, v0
	v_mov_b32_e32 v30, v0
	v_mov_b32_e32 v31, v0
	v_mov_b32_e32 v32, v0
	v_mov_b32_e32 v33, v0
	v_mov_b32_e32 v34, v0
	v_mov_b32_e32 v35, v0
	v_mov_b32_e32 v36, v0
	v_mov_b32_e32 v37, v0
	v_mov_b32_e32 v38, v0
	v_mov_b32_e32 v39, v0
	v_mov_b32_e32 v40, v0
	v_mov_b32_e32 v41, v0
	v_mov_b32_e32 v42, v0
	v_mov_b32_e32 v43, v0
	v_mov_b32_e32 v44, v0
	v_mov_b32_e32 v45, v0
	v_mov_b32_e32 v46, v0
	v_mov_b32_e32 v47, v0
	v_mov_b32_e32 v48, v0
	v_mov_b32_e32 v49, v0
	v_mov_b32_e32 v50, v0
	v_mov_b32_e32 v51, v0
	v_mov_b32_e32 v52, v0
	v_mov_b32_e32 v53, v0
	v_mov_b32_e32 v54, v0
	v_mov_b32_e32 v55, v0
	v_mov_b32_e32 v56, v0
	v_mov_b32_e32 v57, v0
	v_mov_b32_e32 v58, v0
	v_mov_b32_e32 v59, v0
	v_mov_b32_e32 v60, v0
	v_mov_b32_e32 v61, v0
	v_mov_b32_e32 v62, v0
	v_mov_b32_e32 v63, v0
	s_waitcnt vmcnt(0) lgkmcnt(0)
	s_barrier
	v_add3_u32 v182, 0, v133, v134
	v_add_u32_e32 v183, 0x4000, v182
	s_nop 0
	v_readfirstlane_b32 s82, v183
	v_lshl_add_u32 v183, v108, 1, 0
	s_nop 0
	v_readfirstlane_b32 s83, v182
	v_add3_u32 v183, v183, v134, s11
	s_nop 0
	v_readfirstlane_b32 s84, v183
	v_add_u32_e32 v183, 0x400, v182
	s_nop 0
	v_readfirstlane_b32 s85, v183
	v_lshl_add_u32 v183, v110, 1, 0
	v_add3_u32 v183, v183, v134, s11
	s_nop 0
	v_readfirstlane_b32 s86, v183
	v_add_u32_e32 v183, 0x800, v182
	s_nop 0
	v_readfirstlane_b32 s87, v183
	v_lshl_add_u32 v183, v112, 1, 0
	v_add3_u32 v183, v183, v134, s11
	s_nop 0
	v_readfirstlane_b32 s88, v183
	v_add_u32_e32 v182, 0xc00, v182
	s_nop 0
	v_readfirstlane_b32 s89, v182
	v_subrev_u32_e32 v184, s52, v88
	v_subrev_u32_e32 v185, s52, v90
	v_subrev_u32_e32 v186, s52, v92
	v_subrev_u32_e32 v187, s52, v94
	v_subrev_u32_e32 v188, s52, v96
	v_subrev_u32_e32 v189, s52, v98
	v_subrev_u32_e32 v190, s52, v100
	v_subrev_u32_e32 v191, s52, v102
	v_subrev_u32_e32 v187, 0x400, v187
	v_subrev_u32_e32 v186, 0x400, v186
	v_subrev_u32_e32 v189, 0x800, v189
	v_subrev_u32_e32 v188, 0x800, v188
	v_subrev_u32_e32 v191, 0xc00, v191
	v_subrev_u32_e32 v190, 0xc00, v190
	s_and_b32 s18, s16, 0x4000
	s_xor_b32 s17, s18, 0x4000
	s_lshl_b32 s17, s17, 1
	s_add_i32 s17, s17, 32
	s_lshl_b32 s18, s18, 1
	s_add_i32 s18, s18, 32
.LBB0_2009:
	s_xor_b32 s17, s17, 0x8000
	s_xor_b32 s18, s18, 0x8000
	s_add_u32 s90, s52, s8
	s_addc_u32 s91, s53, s9
	s_add_i32 m0, s18, s83
	v_lshl_add_u32 v137, v113, 1, s17
	global_load_lds_dwordx4 v185, s[90:91]
	global_load_lds_dwordx4 v187, s[90:91] offset:1024
	global_load_lds_dwordx4 v189, s[90:91] offset:2048
	global_load_lds_dwordx4 v191, s[90:91] offset:3072
	s_add_i32 m0, s18, s82
	v_lshl_add_u32 v170, v114, 1, s17
	global_load_lds_dwordx4 v184, s[90:91]
	global_load_lds_dwordx4 v186, s[90:91] offset:1024
	global_load_lds_dwordx4 v188, s[90:91] offset:2048
	global_load_lds_dwordx4 v190, s[90:91] offset:3072
	v_add_u32_e32 v158, v137, v135
	v_add_u32_e32 v166, v170, v135
	s_add_u32 s8, s8, 0x80
	s_addc_u32 s9, s9, 0
	ds_read_b128 v[138:141], v158
	ds_read_b128 v[146:149], v166 offset:16384
	ds_read_b128 v[150:153], v166 offset:18432
	ds_read_b128 v[162:165], v166 offset:20480
	ds_read_b128 v[166:169], v166 offset:22528
	ds_read_b128 v[142:145], v158 offset:2048
	ds_read_b128 v[154:157], v158 offset:4096
	ds_read_b128 v[158:161], v158 offset:6144
	v_add_u32_e32 v137, v137, v136
	v_add_u32_e32 v236, v170, v136
	ds_read_b128 v[204:207], v137
	ds_read_b128 v[208:211], v236 offset:16384
	ds_read_b128 v[212:215], v236 offset:18432
	ds_read_b128 v[216:219], v236 offset:20480
	ds_read_b128 v[220:223], v236 offset:22528
	ds_read_b128 v[224:227], v137 offset:2048
	ds_read_b128 v[228:231], v137 offset:4096
	ds_read_b128 v[232:235], v137 offset:6144
	s_setprio 1
	s_waitcnt lgkmcnt(11)
	v_mfma_f32_16x16x32_bf16 v[60:63], v[138:141], v[146:149], v[60:63]
	v_mfma_f32_16x16x32_bf16 v[56:59], v[138:141], v[150:153], v[56:59]
	v_mfma_f32_16x16x32_bf16 v[52:55], v[138:141], v[162:165], v[52:55]
	v_mfma_f32_16x16x32_bf16 v[48:51], v[138:141], v[166:169], v[48:51]
	s_waitcnt lgkmcnt(10)
	v_mfma_f32_16x16x32_bf16 v[44:47], v[142:145], v[146:149], v[44:47]
	v_mfma_f32_16x16x32_bf16 v[40:43], v[142:145], v[150:153], v[40:43]
	v_mfma_f32_16x16x32_bf16 v[36:39], v[142:145], v[162:165], v[36:39]
	v_mfma_f32_16x16x32_bf16 v[32:35], v[142:145], v[166:169], v[32:35]
	s_waitcnt lgkmcnt(9)
	v_mfma_f32_16x16x32_bf16 v[28:31], v[154:157], v[146:149], v[28:31]
	v_mfma_f32_16x16x32_bf16 v[24:27], v[154:157], v[150:153], v[24:27]
	v_mfma_f32_16x16x32_bf16 v[20:23], v[154:157], v[162:165], v[20:23]
	v_mfma_f32_16x16x32_bf16 v[16:19], v[154:157], v[166:169], v[16:19]
	s_waitcnt lgkmcnt(8)
	v_mfma_f32_16x16x32_bf16 v[12:15], v[158:161], v[146:149], v[12:15]
	v_mfma_f32_16x16x32_bf16 v[8:11], v[158:161], v[150:153], v[8:11]
	v_mfma_f32_16x16x32_bf16 v[4:7], v[158:161], v[162:165], v[4:7]
	v_mfma_f32_16x16x32_bf16 v[0:3], v[158:161], v[166:169], v[0:3]
	s_waitcnt lgkmcnt(3)
	v_mfma_f32_16x16x32_bf16 v[60:63], v[204:207], v[208:211], v[60:63]
	v_mfma_f32_16x16x32_bf16 v[56:59], v[204:207], v[212:215], v[56:59]
	v_mfma_f32_16x16x32_bf16 v[52:55], v[204:207], v[216:219], v[52:55]
	v_mfma_f32_16x16x32_bf16 v[48:51], v[204:207], v[220:223], v[48:51]
	s_waitcnt lgkmcnt(2)
	v_mfma_f32_16x16x32_bf16 v[44:47], v[224:227], v[208:211], v[44:47]
	v_mfma_f32_16x16x32_bf16 v[40:43], v[224:227], v[212:215], v[40:43]
	v_mfma_f32_16x16x32_bf16 v[36:39], v[224:227], v[216:219], v[36:39]
	v_mfma_f32_16x16x32_bf16 v[32:35], v[224:227], v[220:223], v[32:35]
	s_waitcnt lgkmcnt(1)
	v_mfma_f32_16x16x32_bf16 v[28:31], v[228:231], v[208:211], v[28:31]
	v_mfma_f32_16x16x32_bf16 v[24:27], v[228:231], v[212:215], v[24:27]
	v_mfma_f32_16x16x32_bf16 v[20:23], v[228:231], v[216:219], v[20:23]
	v_mfma_f32_16x16x32_bf16 v[16:19], v[228:231], v[220:223], v[16:19]
	s_waitcnt lgkmcnt(0)
	v_mfma_f32_16x16x32_bf16 v[12:15], v[232:235], v[208:211], v[12:15]
	v_mfma_f32_16x16x32_bf16 v[8:11], v[232:235], v[212:215], v[8:11]
	v_mfma_f32_16x16x32_bf16 v[4:7], v[232:235], v[216:219], v[4:7]
	v_mfma_f32_16x16x32_bf16 v[0:3], v[232:235], v[220:223], v[0:3]
	s_setprio 0
	s_cmpk_eq_i32 s8, 0x780
	s_waitcnt vmcnt(0)
	s_barrier
	s_cbranch_scc0 .LBB0_2009
	ds_read_b128 v[88:91], v115 offset:55296
	ds_read_b128 v[92:95], v115 offset:53248
	ds_read_b128 v[96:99], v116 offset:38912
	ds_read_b128 v[100:103], v116 offset:36864
	ds_read_b128 v[138:141], v115 offset:51200
	ds_read_b128 v[142:145], v115 offset:49152
	ds_read_b128 v[146:149], v116 offset:34816
	ds_read_b128 v[150:153], v116 offset:32768
	ds_read_b128 v[204:207], v117 offset:32768
	ds_read_b128 v[208:211], v117 offset:34816
	ds_read_b128 v[212:215], v118 offset:49152
	ds_read_b128 v[216:219], v118 offset:51200
	ds_read_b128 v[220:223], v117 offset:36864
	ds_read_b128 v[224:227], v117 offset:38912
	ds_read_b128 v[228:231], v118 offset:53248
	ds_read_b128 v[232:235], v118 offset:55296
	s_setprio 1
	s_waitcnt lgkmcnt(13)
	v_mfma_f32_16x16x32_bf16 v[0:3], v[96:99], v[88:91], v[0:3]
	s_waitcnt lgkmcnt(8)
	v_mfma_f32_16x16x32_bf16 v[60:63], v[150:153], v[142:145], v[60:63]
	v_mfma_f32_16x16x32_bf16 v[56:59], v[150:153], v[138:141], v[56:59]
	v_mfma_f32_16x16x32_bf16 v[52:55], v[150:153], v[92:95], v[52:55]
	v_mfma_f32_16x16x32_bf16 v[48:51], v[150:153], v[88:91], v[48:51]
	v_mfma_f32_16x16x32_bf16 v[44:47], v[146:149], v[142:145], v[44:47]
	v_mfma_f32_16x16x32_bf16 v[40:43], v[146:149], v[138:141], v[40:43]
	v_mfma_f32_16x16x32_bf16 v[36:39], v[146:149], v[92:95], v[36:39]
	v_mfma_f32_16x16x32_bf16 v[32:35], v[146:149], v[88:91], v[32:35]
	v_mfma_f32_16x16x32_bf16 v[28:31], v[100:103], v[142:145], v[28:31]
	v_mfma_f32_16x16x32_bf16 v[24:27], v[100:103], v[138:141], v[24:27]
	v_mfma_f32_16x16x32_bf16 v[20:23], v[100:103], v[92:95], v[20:23]
	v_mfma_f32_16x16x32_bf16 v[16:19], v[100:103], v[88:91], v[16:19]
	v_mfma_f32_16x16x32_bf16 v[12:15], v[96:99], v[142:145], v[12:15]
	v_mfma_f32_16x16x32_bf16 v[8:11], v[96:99], v[138:141], v[8:11]
	v_mfma_f32_16x16x32_bf16 v[4:7], v[96:99], v[92:95], v[4:7]
	s_waitcnt lgkmcnt(0)
	v_mfma_f32_16x16x32_bf16 v[0:3], v[224:227], v[232:235], v[0:3]
	v_mfma_f32_16x16x32_bf16 v[60:63], v[204:207], v[212:215], v[60:63]
	v_mfma_f32_16x16x32_bf16 v[56:59], v[204:207], v[216:219], v[56:59]
	v_mfma_f32_16x16x32_bf16 v[52:55], v[204:207], v[228:231], v[52:55]
	v_mfma_f32_16x16x32_bf16 v[48:51], v[204:207], v[232:235], v[48:51]
	v_mfma_f32_16x16x32_bf16 v[44:47], v[208:211], v[212:215], v[44:47]
	v_mfma_f32_16x16x32_bf16 v[40:43], v[208:211], v[216:219], v[40:43]
	v_mfma_f32_16x16x32_bf16 v[36:39], v[208:211], v[228:231], v[36:39]
	v_mfma_f32_16x16x32_bf16 v[32:35], v[208:211], v[232:235], v[32:35]
	v_mfma_f32_16x16x32_bf16 v[28:31], v[220:223], v[212:215], v[28:31]
	v_mfma_f32_16x16x32_bf16 v[24:27], v[220:223], v[216:219], v[24:27]
	v_mfma_f32_16x16x32_bf16 v[20:23], v[220:223], v[228:231], v[20:23]
	v_mfma_f32_16x16x32_bf16 v[16:19], v[220:223], v[232:235], v[16:19]
	v_mfma_f32_16x16x32_bf16 v[12:15], v[224:227], v[212:215], v[12:15]
	v_mfma_f32_16x16x32_bf16 v[8:11], v[224:227], v[216:219], v[8:11]
	v_mfma_f32_16x16x32_bf16 v[4:7], v[224:227], v[228:231], v[4:7]
	s_setprio 0
	s_barrier
	ds_write2_b32 v119, v60, v56 offset1:16
	ds_write2_b32 v119, v61, v57 offset0:132 offset1:148
	v_add_u32_e32 v56, 0x400, v119
	ds_write2_b32 v56, v62, v58 offset0:8 offset1:24
	ds_write2_b32 v56, v63, v59 offset0:140 offset1:156
	ds_write2_b32 v119, v52, v48 offset0:32 offset1:48
	ds_write2_b32 v119, v53, v49 offset0:164 offset1:180
	ds_write2_b32 v56, v54, v50 offset0:40 offset1:56
	ds_write2_b32 v56, v55, v51 offset0:172 offset1:188
	v_add_u32_e32 v48, 0x2000, v119
	ds_write2_b32 v48, v44, v40 offset0:64 offset1:80
	ds_write2_b32 v48, v45, v41 offset0:196 offset1:212
	v_add_u32_e32 v40, 0x2400, v119
	ds_write2_b32 v40, v46, v42 offset0:72 offset1:88
	ds_write2_b32 v40, v47, v43 offset0:204 offset1:220
	ds_write2_b32 v48, v36, v32 offset0:96 offset1:112
	ds_write2_b32 v48, v37, v33 offset0:228 offset1:244
	ds_write2_b32 v40, v38, v34 offset0:104 offset1:120
	ds_write2_b32 v40, v39, v35 offset0:236 offset1:252
	v_add_u32_e32 v32, 0x4000, v119
	ds_write2_b32 v32, v28, v24 offset0:128 offset1:144
	v_add_u32_e32 v24, 0x4400, v119
	ds_write2_b32 v24, v29, v25 offset0:4 offset1:20
	ds_write2_b32 v24, v30, v26 offset0:136 offset1:152
	v_add_u32_e32 v25, 0x4800, v119
	ds_write2_b32 v25, v31, v27 offset0:12 offset1:28
	ds_write2_b32 v32, v20, v16 offset0:160 offset1:176
	ds_write2_b32 v24, v21, v17 offset0:36 offset1:52
	ds_write2_b32 v24, v22, v18 offset0:168 offset1:184
	ds_write2_b32 v25, v23, v19 offset0:44 offset1:60
	v_add_u32_e32 v16, 0x6000, v119
	ds_write2_b32 v16, v12, v8 offset0:192 offset1:208
	v_add_u32_e32 v8, 0x6400, v119
	ds_write2_b32 v8, v13, v9 offset0:68 offset1:84
	ds_write2_b32 v8, v14, v10 offset0:200 offset1:216
	v_add_u32_e32 v9, 0x6800, v119
	ds_write2_b32 v9, v15, v11 offset0:76 offset1:92
	ds_write2_b32 v16, v4, v0 offset0:224 offset1:240
	ds_write2_b32 v8, v5, v1 offset0:100 offset1:116
	ds_write2_b32 v8, v6, v2 offset0:232 offset1:248
	ds_write2_b32 v9, v7, v3 offset0:108 offset1:124
	v_or_b32_e32 v0, s14, v120
	v_ashrrev_i32_e32 v1, 31, v0
	v_lshl_add_u64 v[0:1], v[0:1], 1, s[6:7]
	v_add_u32_e32 v2, s15, v128
	s_mov_b32 s8, 0
	s_waitcnt lgkmcnt(0)
	s_barrier

.LBB0_2075:
	s_ashr_i32 s16, s23, 31
	s_lshr_b32 s16, s16, 29
	s_add_i32 s16, s23, s16
	s_ashr_i32 s16, s16, 3
	s_lshl_b32 s24, s16, 7
	s_lshl_b32 s16, s16, 10
	s_lshl_b32 s17, s23, 7
	s_sub_i32 s25, s17, s16
	v_add_u32_e32 v0, s25, v106
	v_ashrrev_i32_e32 v1, 31, v0
	v_add_u32_e32 v2, 0x4000, v107
	v_lshlrev_b64 v[0:1], 13, v[0:1]
	v_readfirstlane_b32 s17, v2
	v_lshl_add_u64 v[0:1], v[66:67], 0, v[0:1]
	s_mov_b32 m0, s17
	v_readfirstlane_b32 s17, v107
	global_load_lds_dwordx4 v[0:1], off
	v_add_u32_e32 v0, s24, v106
	v_ashrrev_i32_e32 v1, 31, v0
	v_lshlrev_b64 v[0:1], 13, v[0:1]
	v_lshl_add_u64 v[2:3], v[72:73], 0, v[0:1]
	s_mov_b32 m0, s17
	v_readfirstlane_b32 s17, v130
	global_load_lds_dwordx4 v[2:3], off
	v_add_u32_e32 v2, s25, v108
	v_ashrrev_i32_e32 v3, 31, v2
	v_lshlrev_b64 v[2:3], 13, v[2:3]
	v_lshl_add_u64 v[2:3], v[68:69], 0, v[2:3]
	s_mov_b32 m0, s17
	v_add_u32_e32 v4, 0x400, v107
	global_load_lds_dwordx4 v[2:3], off
	v_add_u32_e32 v2, s24, v108
	v_ashrrev_i32_e32 v3, 31, v2
	v_lshlrev_b64 v[2:3], 13, v[2:3]
	v_readfirstlane_b32 s17, v4
	v_lshl_add_u64 v[2:3], v[74:75], 0, v[2:3]
	s_mov_b32 m0, s17
	v_readfirstlane_b32 s17, v131
	global_load_lds_dwordx4 v[2:3], off
	v_add_u32_e32 v2, s25, v110
	v_ashrrev_i32_e32 v3, 31, v2
	v_lshlrev_b64 v[2:3], 13, v[2:3]
	v_lshl_add_u64 v[2:3], v[66:67], 0, v[2:3]
	s_mov_b32 m0, s17
	v_add_u32_e32 v4, 0x800, v107
	global_load_lds_dwordx4 v[2:3], off
	v_add_u32_e32 v2, s24, v110
	v_ashrrev_i32_e32 v3, 31, v2
	v_lshlrev_b64 v[2:3], 13, v[2:3]
	v_readfirstlane_b32 s17, v4
	v_lshl_add_u64 v[2:3], v[72:73], 0, v[2:3]
	s_mov_b32 m0, s17
	v_readfirstlane_b32 s17, v132
	global_load_lds_dwordx4 v[2:3], off
	v_add_u32_e32 v2, s25, v112
	v_ashrrev_i32_e32 v3, 31, v2
	v_lshlrev_b64 v[2:3], 13, v[2:3]
	v_lshl_add_u64 v[2:3], v[70:71], 0, v[2:3]
	s_mov_b32 m0, s17
	v_add_u32_e32 v4, 0xc00, v107
	global_load_lds_dwordx4 v[2:3], off
	v_add_u32_e32 v2, s24, v112
	v_ashrrev_i32_e32 v3, 31, v2
	v_lshlrev_b64 v[2:3], 13, v[2:3]
	v_readfirstlane_b32 s17, v4
	v_lshl_add_u64 v[2:3], v[76:77], 0, v[2:3]
	s_mov_b32 m0, s17
	v_lshl_add_u64 v[92:93], v[80:81], 0, v[0:1]
	global_load_lds_dwordx4 v[2:3], off
	v_subrev_u32_e32 v0, s16, v123
	v_ashrrev_i32_e32 v1, 31, v0
	v_lshlrev_b64 v[0:1], 13, v[0:1]
	v_lshl_add_u64 v[94:95], v[82:83], 0, v[0:1]
	v_add_u32_e32 v0, s24, v124
	v_ashrrev_i32_e32 v1, 31, v0
	v_lshlrev_b64 v[0:1], 13, v[0:1]
	v_lshl_add_u64 v[96:97], v[84:85], 0, v[0:1]
	v_subrev_u32_e32 v0, s16, v125
	v_ashrrev_i32_e32 v1, 31, v0
	v_lshlrev_b64 v[0:1], 13, v[0:1]
	v_lshl_add_u64 v[98:99], v[78:79], 0, v[0:1]
	v_add_u32_e32 v0, s24, v126
	v_ashrrev_i32_e32 v1, 31, v0
	v_lshlrev_b64 v[0:1], 13, v[0:1]
	v_lshl_add_u64 v[100:101], v[80:81], 0, v[0:1]
	v_subrev_u32_e32 v0, s16, v64
	v_ashrrev_i32_e32 v1, 31, v0
	v_lshlrev_b64 v[0:1], 13, v[0:1]
	v_subrev_u32_e32 v2, s16, v122
	v_lshl_add_u64 v[102:103], v[86:87], 0, v[0:1]
	v_add_u32_e32 v0, s24, v127
	v_ashrrev_i32_e32 v3, 31, v2
	v_ashrrev_i32_e32 v1, 31, v0
	v_lshlrev_b64 v[2:3], 13, v[2:3]
	v_lshlrev_b64 v[0:1], 13, v[0:1]
	v_lshl_add_u64 v[90:91], v[78:79], 0, v[2:3]
	v_lshl_add_u64 v[104:105], v[88:89], 0, v[0:1]
	s_mov_b32 s26, 0
	s_mov_b64 s[16:17], 0
	v_mov_b32_e32 v0, 0
	v_mov_b32_e32 v1, v65
	v_mov_b32_e32 v2, v65
	v_mov_b32_e32 v3, v65
	v_mov_b32_e32 v4, 0
	v_mov_b32_e32 v5, v65
	v_mov_b32_e32 v6, v65
	v_mov_b32_e32 v7, v65
	v_mov_b32_e32 v8, 0
	v_mov_b32_e32 v9, v65
	v_mov_b32_e32 v10, v65
	v_mov_b32_e32 v11, v65
	v_mov_b32_e32 v12, 0
	v_mov_b32_e32 v13, v65
	v_mov_b32_e32 v14, v65
	v_mov_b32_e32 v15, v65
	v_mov_b32_e32 v16, 0
	v_mov_b32_e32 v17, v65
	v_mov_b32_e32 v18, v65
	v_mov_b32_e32 v19, v65
	v_mov_b32_e32 v20, 0
	v_mov_b32_e32 v21, v65
	v_mov_b32_e32 v22, v65
	v_mov_b32_e32 v23, v65
	v_mov_b32_e32 v24, 0
	v_mov_b32_e32 v25, v65
	v_mov_b32_e32 v26, v65
	v_mov_b32_e32 v27, v65
	v_mov_b32_e32 v28, 0
	v_mov_b32_e32 v29, v65
	v_mov_b32_e32 v30, v65
	v_mov_b32_e32 v31, v65
	s_waitcnt vmcnt(0)
	v_mov_b32_e32 v32, 0
	v_mov_b32_e32 v33, v65
	v_mov_b32_e32 v34, v65
	v_mov_b32_e32 v35, v65
	v_mov_b32_e32 v36, 0
	v_mov_b32_e32 v37, v65
	v_mov_b32_e32 v38, v65
	v_mov_b32_e32 v39, v65
	v_mov_b32_e32 v40, 0
	v_mov_b32_e32 v41, v65
	v_mov_b32_e32 v42, v65
	v_mov_b32_e32 v43, v65
	v_mov_b32_e32 v44, 0
	v_mov_b32_e32 v45, v65
	v_mov_b32_e32 v46, v65
	v_mov_b32_e32 v47, v65
	v_mov_b32_e32 v48, 0
	v_mov_b32_e32 v49, v65
	v_mov_b32_e32 v50, v65
	v_mov_b32_e32 v51, v65
	v_mov_b32_e32 v52, 0
	v_mov_b32_e32 v53, v65
	v_mov_b32_e32 v54, v65
	v_mov_b32_e32 v55, v65
	v_mov_b32_e32 v56, 0
	v_mov_b32_e32 v57, v65
	v_mov_b32_e32 v58, v65
	v_mov_b32_e32 v59, v65
	v_mov_b32_e32 v60, 0
	v_mov_b32_e32 v61, v65
	v_mov_b32_e32 v62, v65
	v_mov_b32_e32 v63, v65
	s_waitcnt lgkmcnt(0)
	s_barrier
	v_add3_u32 v190, 0, v133, v134
	v_add_u32_e32 v191, 0x4000, v190
	s_nop 0
	v_readfirstlane_b32 s82, v191
	v_lshl_add_u32 v191, v109, 1, 0
	s_nop 0
	v_readfirstlane_b32 s83, v190
	v_add3_u32 v191, v191, v134, s19
	s_nop 0
	v_readfirstlane_b32 s84, v191
	v_add_u32_e32 v191, 0x400, v190
	s_nop 0
	v_readfirstlane_b32 s85, v191
	v_lshl_add_u32 v191, v111, 1, 0
	v_add3_u32 v191, v191, v134, s19
	s_nop 0
	v_readfirstlane_b32 s86, v191
	v_add_u32_e32 v191, 0x800, v190
	s_nop 0
	v_readfirstlane_b32 s87, v191
	v_lshl_add_u32 v191, v113, 1, 0
	v_add3_u32 v191, v191, v134, s19
	s_nop 0
	v_readfirstlane_b32 s88, v191
	v_add_u32_e32 v190, 0xc00, v190
	s_nop 0
	v_readfirstlane_b32 s89, v190
	v_subrev_u32_e32 v192, s52, v90
	v_subrev_u32_e32 v193, s52, v92
	v_subrev_u32_e32 v194, s52, v94
	v_subrev_u32_e32 v195, s52, v96
	v_subrev_u32_e32 v196, s52, v98
	v_subrev_u32_e32 v197, s52, v100
	v_subrev_u32_e32 v198, s52, v102
	v_subrev_u32_e32 v199, s52, v104
	v_subrev_u32_e32 v195, 0x400, v195
	v_subrev_u32_e32 v194, 0x400, v194
	v_subrev_u32_e32 v197, 0x800, v197
	v_subrev_u32_e32 v196, 0x800, v196
	v_subrev_u32_e32 v199, 0xc00, v199
	v_subrev_u32_e32 v198, 0xc00, v198
	s_and_b32 s28, s26, 0x4000
	s_xor_b32 s27, s28, 0x4000
	s_lshl_b32 s27, s27, 1
	s_add_i32 s27, s27, 32
	s_lshl_b32 s28, s28, 1
	s_add_i32 s28, s28, 32
.LBB0_2076:
	s_xor_b32 s27, s27, 0x8000
	s_xor_b32 s28, s28, 0x8000
	s_add_u32 s90, s52, s16
	s_addc_u32 s91, s53, s17
	s_add_i32 m0, s28, s83
	v_add3_u32 v170, s27, v114, v135
	global_load_lds_dwordx4 v193, s[90:91]
	global_load_lds_dwordx4 v195, s[90:91] offset:1024
	global_load_lds_dwordx4 v197, s[90:91] offset:2048
	global_load_lds_dwordx4 v199, s[90:91] offset:3072
	s_add_i32 m0, s28, s82
	v_add3_u32 v171, s27, v115, v135
	global_load_lds_dwordx4 v192, s[90:91]
	global_load_lds_dwordx4 v194, s[90:91] offset:1024
	global_load_lds_dwordx4 v196, s[90:91] offset:2048
	global_load_lds_dwordx4 v198, s[90:91] offset:3072
	v_add_u32_e32 v158, v170, v136
	v_add_u32_e32 v166, v171, v136
	s_addk_i32 s26, 0x4000
	s_add_u32 s16, s16, 0x80
	s_addc_u32 s17, s17, 0
	ds_read_b128 v[138:141], v158
	ds_read_b128 v[146:149], v166 offset:16384
	ds_read_b128 v[150:153], v166 offset:18432
	ds_read_b128 v[162:165], v166 offset:20480
	ds_read_b128 v[166:169], v166 offset:22528
	ds_read_b128 v[142:145], v158 offset:2048
	ds_read_b128 v[154:157], v158 offset:4096
	ds_read_b128 v[158:161], v158 offset:6144
	v_add_u32_e32 v236, v170, v137
	v_add_u32_e32 v237, v171, v137
	ds_read_b128 v[204:207], v236
	ds_read_b128 v[208:211], v237 offset:16384
	ds_read_b128 v[212:215], v237 offset:18432
	ds_read_b128 v[216:219], v237 offset:20480
	ds_read_b128 v[220:223], v237 offset:22528
	ds_read_b128 v[224:227], v236 offset:2048
	ds_read_b128 v[228:231], v236 offset:4096
	ds_read_b128 v[232:235], v236 offset:6144
	s_setprio 1
	s_waitcnt lgkmcnt(11)
	v_mfma_f32_16x16x32_bf16 v[60:63], v[138:141], v[146:149], v[60:63]
	v_mfma_f32_16x16x32_bf16 v[56:59], v[138:141], v[150:153], v[56:59]
	v_mfma_f32_16x16x32_bf16 v[52:55], v[138:141], v[162:165], v[52:55]
	v_mfma_f32_16x16x32_bf16 v[48:51], v[138:141], v[166:169], v[48:51]
	s_waitcnt lgkmcnt(10)
	v_mfma_f32_16x16x32_bf16 v[44:47], v[142:145], v[146:149], v[44:47]
	v_mfma_f32_16x16x32_bf16 v[40:43], v[142:145], v[150:153], v[40:43]
	v_mfma_f32_16x16x32_bf16 v[36:39], v[142:145], v[162:165], v[36:39]
	v_mfma_f32_16x16x32_bf16 v[32:35], v[142:145], v[166:169], v[32:35]
	s_waitcnt lgkmcnt(9)
	v_mfma_f32_16x16x32_bf16 v[28:31], v[154:157], v[146:149], v[28:31]
	v_mfma_f32_16x16x32_bf16 v[24:27], v[154:157], v[150:153], v[24:27]
	v_mfma_f32_16x16x32_bf16 v[20:23], v[154:157], v[162:165], v[20:23]
	v_mfma_f32_16x16x32_bf16 v[16:19], v[154:157], v[166:169], v[16:19]
	s_waitcnt lgkmcnt(8)
	v_mfma_f32_16x16x32_bf16 v[12:15], v[158:161], v[146:149], v[12:15]
	v_mfma_f32_16x16x32_bf16 v[8:11], v[158:161], v[150:153], v[8:11]
	v_mfma_f32_16x16x32_bf16 v[4:7], v[158:161], v[162:165], v[4:7]
	v_mfma_f32_16x16x32_bf16 v[0:3], v[158:161], v[166:169], v[0:3]
	s_waitcnt lgkmcnt(3)
	v_mfma_f32_16x16x32_bf16 v[60:63], v[204:207], v[208:211], v[60:63]
	v_mfma_f32_16x16x32_bf16 v[56:59], v[204:207], v[212:215], v[56:59]
	v_mfma_f32_16x16x32_bf16 v[52:55], v[204:207], v[216:219], v[52:55]
	v_mfma_f32_16x16x32_bf16 v[48:51], v[204:207], v[220:223], v[48:51]
	s_waitcnt lgkmcnt(2)
	v_mfma_f32_16x16x32_bf16 v[44:47], v[224:227], v[208:211], v[44:47]
	v_mfma_f32_16x16x32_bf16 v[40:43], v[224:227], v[212:215], v[40:43]
	v_mfma_f32_16x16x32_bf16 v[36:39], v[224:227], v[216:219], v[36:39]
	v_mfma_f32_16x16x32_bf16 v[32:35], v[224:227], v[220:223], v[32:35]
	s_waitcnt lgkmcnt(1)
	v_mfma_f32_16x16x32_bf16 v[28:31], v[228:231], v[208:211], v[28:31]
	v_mfma_f32_16x16x32_bf16 v[24:27], v[228:231], v[212:215], v[24:27]
	v_mfma_f32_16x16x32_bf16 v[20:23], v[228:231], v[216:219], v[20:23]
	v_mfma_f32_16x16x32_bf16 v[16:19], v[228:231], v[220:223], v[16:19]
	s_waitcnt lgkmcnt(0)
	v_mfma_f32_16x16x32_bf16 v[12:15], v[232:235], v[208:211], v[12:15]
	v_mfma_f32_16x16x32_bf16 v[8:11], v[232:235], v[212:215], v[8:11]
	v_mfma_f32_16x16x32_bf16 v[4:7], v[232:235], v[216:219], v[4:7]
	v_mfma_f32_16x16x32_bf16 v[0:3], v[232:235], v[220:223], v[0:3]
	s_setprio 0
	s_cmpk_eq_i32 s16, 0x1f80
	s_waitcnt vmcnt(0)
	s_barrier
	s_cbranch_scc0 .LBB0_2076
	ds_read_b128 v[90:93], v118 offset:55296
	ds_read_b128 v[94:97], v118 offset:53248
	ds_read_b128 v[98:101], v119 offset:38912
	ds_read_b128 v[102:105], v119 offset:36864
	ds_read_b128 v[138:141], v118 offset:51200
	ds_read_b128 v[142:145], v118 offset:49152
	ds_read_b128 v[146:149], v119 offset:34816
	ds_read_b128 v[150:153], v119 offset:32768
	ds_read_b128 v[204:207], v120 offset:32768
	ds_read_b128 v[208:211], v120 offset:34816
	ds_read_b128 v[212:215], v121 offset:49152
	ds_read_b128 v[216:219], v121 offset:51200
	ds_read_b128 v[220:223], v120 offset:36864
	ds_read_b128 v[224:227], v120 offset:38912
	ds_read_b128 v[228:231], v121 offset:53248
	ds_read_b128 v[232:235], v121 offset:55296
	s_setprio 1
	s_waitcnt lgkmcnt(13)
	v_mfma_f32_16x16x32_bf16 v[4:7], v[98:101], v[94:97], v[4:7]
	v_mfma_f32_16x16x32_bf16 v[0:3], v[98:101], v[90:93], v[0:3]
	s_waitcnt lgkmcnt(8)
	v_mfma_f32_16x16x32_bf16 v[60:63], v[150:153], v[142:145], v[60:63]
	v_mfma_f32_16x16x32_bf16 v[56:59], v[150:153], v[138:141], v[56:59]
	v_mfma_f32_16x16x32_bf16 v[52:55], v[150:153], v[94:97], v[52:55]
	v_mfma_f32_16x16x32_bf16 v[48:51], v[150:153], v[90:93], v[48:51]
	v_mfma_f32_16x16x32_bf16 v[44:47], v[146:149], v[142:145], v[44:47]
	v_mfma_f32_16x16x32_bf16 v[40:43], v[146:149], v[138:141], v[40:43]
	v_mfma_f32_16x16x32_bf16 v[36:39], v[146:149], v[94:97], v[36:39]
	v_mfma_f32_16x16x32_bf16 v[32:35], v[146:149], v[90:93], v[32:35]
	v_mfma_f32_16x16x32_bf16 v[28:31], v[102:105], v[142:145], v[28:31]
	v_mfma_f32_16x16x32_bf16 v[24:27], v[102:105], v[138:141], v[24:27]
	v_mfma_f32_16x16x32_bf16 v[20:23], v[102:105], v[94:97], v[20:23]
	v_mfma_f32_16x16x32_bf16 v[16:19], v[102:105], v[90:93], v[16:19]
	v_mfma_f32_16x16x32_bf16 v[12:15], v[98:101], v[142:145], v[12:15]
	v_mfma_f32_16x16x32_bf16 v[8:11], v[98:101], v[138:141], v[8:11]
	s_waitcnt lgkmcnt(1)
	v_mfma_f32_16x16x32_bf16 v[4:7], v[224:227], v[228:231], v[4:7]
	s_waitcnt lgkmcnt(0)
	v_mfma_f32_16x16x32_bf16 v[0:3], v[224:227], v[232:235], v[0:3]
	v_mfma_f32_16x16x32_bf16 v[60:63], v[204:207], v[212:215], v[60:63]
	v_mfma_f32_16x16x32_bf16 v[56:59], v[204:207], v[216:219], v[56:59]
	v_mfma_f32_16x16x32_bf16 v[52:55], v[204:207], v[228:231], v[52:55]
	v_mfma_f32_16x16x32_bf16 v[48:51], v[204:207], v[232:235], v[48:51]
	v_mfma_f32_16x16x32_bf16 v[44:47], v[208:211], v[212:215], v[44:47]
	v_mfma_f32_16x16x32_bf16 v[40:43], v[208:211], v[216:219], v[40:43]
	v_mfma_f32_16x16x32_bf16 v[36:39], v[208:211], v[228:231], v[36:39]
	v_mfma_f32_16x16x32_bf16 v[32:35], v[208:211], v[232:235], v[32:35]
	v_mfma_f32_16x16x32_bf16 v[28:31], v[220:223], v[212:215], v[28:31]
	v_mfma_f32_16x16x32_bf16 v[24:27], v[220:223], v[216:219], v[24:27]
	v_mfma_f32_16x16x32_bf16 v[20:23], v[220:223], v[228:231], v[20:23]
	v_mfma_f32_16x16x32_bf16 v[16:19], v[220:223], v[232:235], v[16:19]
	v_mfma_f32_16x16x32_bf16 v[12:15], v[224:227], v[212:215], v[12:15]
	v_mfma_f32_16x16x32_bf16 v[8:11], v[224:227], v[216:219], v[8:11]
	s_setprio 0
	s_barrier
	ds_write2_b32 v116, v60, v56 offset1:16
	ds_write2_b32 v116, v61, v57 offset0:132 offset1:148
	v_add_u32_e32 v56, 0x400, v116
	ds_write2_b32 v56, v62, v58 offset0:8 offset1:24
	ds_write2_b32 v56, v63, v59 offset0:140 offset1:156
	ds_write2_b32 v116, v52, v48 offset0:32 offset1:48
	ds_write2_b32 v116, v53, v49 offset0:164 offset1:180
	ds_write2_b32 v56, v54, v50 offset0:40 offset1:56
	ds_write2_b32 v56, v55, v51 offset0:172 offset1:188
	v_add_u32_e32 v48, 0x2000, v116
	ds_write2_b32 v48, v44, v40 offset0:64 offset1:80
	ds_write2_b32 v48, v45, v41 offset0:196 offset1:212
	v_add_u32_e32 v40, 0x2400, v116
	ds_write2_b32 v40, v46, v42 offset0:72 offset1:88
	ds_write2_b32 v40, v47, v43 offset0:204 offset1:220
	ds_write2_b32 v48, v36, v32 offset0:96 offset1:112
	ds_write2_b32 v48, v37, v33 offset0:228 offset1:244
	ds_write2_b32 v40, v38, v34 offset0:104 offset1:120
	ds_write2_b32 v40, v39, v35 offset0:236 offset1:252
	v_add_u32_e32 v32, 0x4000, v116
	ds_write2_b32 v32, v28, v24 offset0:128 offset1:144
	v_add_u32_e32 v24, 0x4400, v116
	ds_write2_b32 v24, v29, v25 offset0:4 offset1:20
	ds_write2_b32 v24, v30, v26 offset0:136 offset1:152
	v_add_u32_e32 v25, 0x4800, v116
	ds_write2_b32 v25, v31, v27 offset0:12 offset1:28
	ds_write2_b32 v32, v20, v16 offset0:160 offset1:176
	ds_write2_b32 v24, v21, v17 offset0:36 offset1:52
	ds_write2_b32 v24, v22, v18 offset0:168 offset1:184
	ds_write2_b32 v25, v23, v19 offset0:44 offset1:60
	v_add_u32_e32 v16, 0x6000, v116
	ds_write2_b32 v16, v12, v8 offset0:192 offset1:208
	v_add_u32_e32 v8, 0x6400, v116
	ds_write2_b32 v8, v13, v9 offset0:68 offset1:84
	ds_write2_b32 v8, v14, v10 offset0:200 offset1:216
	v_add_u32_e32 v9, 0x6800, v116
	ds_write2_b32 v9, v15, v11 offset0:76 offset1:92
	ds_write2_b32 v16, v4, v0 offset0:224 offset1:240
	ds_write2_b32 v8, v5, v1 offset0:100 offset1:116
	ds_write2_b32 v8, v6, v2 offset0:232 offset1:248
	ds_write2_b32 v9, v7, v3 offset0:108 offset1:124
	v_or_b32_e32 v0, s25, v117
	v_ashrrev_i32_e32 v1, 31, v0
	v_lshlrev_b64 v[2:3], 2, v[0:1]
	v_lshl_add_u64 v[0:1], s[14:15], 0, v[2:3]
	v_lshl_add_u64 v[2:3], s[12:13], 0, v[2:3]
	v_add_u32_e32 v4, s24, v128
	s_mov_b32 s16, 0
	s_waitcnt lgkmcnt(0)
	s_barrier

.LBB0_2084:
	s_ashr_i32 s16, s18, 31
	s_lshr_b32 s16, s16, 29
	s_add_i32 s16, s18, s16
	s_ashr_i32 s16, s16, 3
	s_lshl_b32 s17, s16, 10
	s_lshl_b32 s25, s18, 7
	v_add_u32_e32 v0, s16, v104
	s_sub_i32 s25, s25, s17
	v_lshlrev_b32_e32 v2, 7, v0
	v_add_u32_e32 v0, s25, v105
	v_ashrrev_i32_e32 v1, 31, v0
	v_add_u32_e32 v3, 0x4000, v106
	v_lshlrev_b64 v[0:1], 13, v[0:1]
	v_readfirstlane_b32 s26, v3
	v_lshl_add_u64 v[0:1], v[64:65], 0, v[0:1]
	s_mov_b32 m0, s26
	v_readfirstlane_b32 s26, v106
	global_load_lds_dwordx4 v[0:1], off
	v_add_u32_e32 v0, v2, v105
	v_ashrrev_i32_e32 v1, 31, v0
	v_lshlrev_b64 v[0:1], 13, v[0:1]
	v_lshl_add_u64 v[0:1], v[70:71], 0, v[0:1]
	s_mov_b32 m0, s26
	v_readfirstlane_b32 s26, v131
	global_load_lds_dwordx4 v[0:1], off
	v_add_u32_e32 v0, s25, v107
	v_ashrrev_i32_e32 v1, 31, v0
	v_lshlrev_b64 v[0:1], 13, v[0:1]
	v_lshl_add_u64 v[0:1], v[66:67], 0, v[0:1]
	s_mov_b32 m0, s26
	v_add_u32_e32 v3, 0x400, v106
	global_load_lds_dwordx4 v[0:1], off
	v_add_u32_e32 v0, v2, v107
	v_ashrrev_i32_e32 v1, 31, v0
	v_lshlrev_b64 v[0:1], 13, v[0:1]
	v_readfirstlane_b32 s26, v3
	v_lshl_add_u64 v[0:1], v[72:73], 0, v[0:1]
	s_mov_b32 m0, s26
	v_readfirstlane_b32 s26, v132
	global_load_lds_dwordx4 v[0:1], off
	v_add_u32_e32 v0, s25, v109
	v_ashrrev_i32_e32 v1, 31, v0
	v_lshlrev_b64 v[0:1], 13, v[0:1]
	v_lshl_add_u64 v[0:1], v[64:65], 0, v[0:1]
	s_mov_b32 m0, s26
	v_add_u32_e32 v3, 0x800, v106
	global_load_lds_dwordx4 v[0:1], off
	v_add_u32_e32 v0, v2, v109
	v_ashrrev_i32_e32 v1, 31, v0
	v_lshlrev_b64 v[0:1], 13, v[0:1]
	v_readfirstlane_b32 s26, v3
	v_lshl_add_u64 v[0:1], v[70:71], 0, v[0:1]
	s_mov_b32 m0, s26
	v_readfirstlane_b32 s26, v133
	global_load_lds_dwordx4 v[0:1], off
	v_add_u32_e32 v0, s25, v111
	v_ashrrev_i32_e32 v1, 31, v0
	v_lshlrev_b64 v[0:1], 13, v[0:1]
	v_lshl_add_u64 v[0:1], v[68:69], 0, v[0:1]
	s_mov_b32 m0, s26
	s_mov_b32 s27, 0
	global_load_lds_dwordx4 v[0:1], off
	v_add_u32_e32 v0, v2, v111
	v_ashrrev_i32_e32 v1, 31, v0
	v_add_u32_e32 v2, 0xc00, v106
	v_lshlrev_b64 v[0:1], 13, v[0:1]
	v_readfirstlane_b32 s26, v2
	v_lshl_add_u64 v[0:1], v[74:75], 0, v[0:1]
	s_mov_b32 m0, s26
	s_lshl_b32 s26, s16, 7
	global_load_lds_dwordx4 v[0:1], off
	v_subrev_u32_e32 v0, s17, v121
	v_ashrrev_i32_e32 v1, 31, v0
	v_lshlrev_b64 v[0:1], 13, v[0:1]
	v_lshl_add_u64 v[88:89], v[76:77], 0, v[0:1]
	v_add_u32_e32 v0, s26, v122
	v_ashrrev_i32_e32 v1, 31, v0
	v_lshlrev_b64 v[0:1], 13, v[0:1]
	v_lshl_add_u64 v[90:91], v[78:79], 0, v[0:1]
	v_subrev_u32_e32 v0, s17, v123
	v_ashrrev_i32_e32 v1, 31, v0
	v_lshlrev_b64 v[0:1], 13, v[0:1]
	v_lshl_add_u64 v[92:93], v[80:81], 0, v[0:1]
	v_add_u32_e32 v0, s26, v124
	v_ashrrev_i32_e32 v1, 31, v0
	v_lshlrev_b64 v[0:1], 13, v[0:1]
	v_lshl_add_u64 v[94:95], v[82:83], 0, v[0:1]
	v_subrev_u32_e32 v0, s17, v125
	v_ashrrev_i32_e32 v1, 31, v0
	v_lshlrev_b64 v[0:1], 13, v[0:1]
	v_lshl_add_u64 v[96:97], v[76:77], 0, v[0:1]
	v_add_u32_e32 v0, s26, v126
	v_ashrrev_i32_e32 v1, 31, v0
	v_lshlrev_b64 v[0:1], 13, v[0:1]
	v_lshl_add_u64 v[98:99], v[78:79], 0, v[0:1]
	v_subrev_u32_e32 v0, s17, v127
	v_ashrrev_i32_e32 v1, 31, v0
	v_lshlrev_b64 v[0:1], 13, v[0:1]
	v_lshl_add_u64 v[100:101], v[84:85], 0, v[0:1]
	v_add_u32_e32 v0, s26, v128
	v_ashrrev_i32_e32 v1, 31, v0
	v_lshlrev_b64 v[0:1], 13, v[0:1]
	v_lshl_add_u64 v[102:103], v[86:87], 0, v[0:1]
	v_mov_b32_e32 v0, 0
	s_mov_b64 s[16:17], 0
	v_mov_b32_e32 v1, v0
	v_mov_b32_e32 v2, v0
	v_mov_b32_e32 v3, v0
	v_mov_b32_e32 v4, v0
	v_mov_b32_e32 v5, v0
	v_mov_b32_e32 v6, v0
	v_mov_b32_e32 v7, v0
	v_mov_b32_e32 v8, v0
	v_mov_b32_e32 v9, v0
	v_mov_b32_e32 v10, v0
	v_mov_b32_e32 v11, v0
	v_mov_b32_e32 v12, v0
	v_mov_b32_e32 v13, v0
	v_mov_b32_e32 v14, v0
	v_mov_b32_e32 v15, v0
	v_mov_b32_e32 v16, v0
	v_mov_b32_e32 v17, v0
	v_mov_b32_e32 v18, v0
	v_mov_b32_e32 v19, v0
	v_mov_b32_e32 v20, v0
	v_mov_b32_e32 v21, v0
	v_mov_b32_e32 v22, v0
	v_mov_b32_e32 v23, v0
	v_mov_b32_e32 v24, v0
	v_mov_b32_e32 v25, v0
	v_mov_b32_e32 v26, v0
	v_mov_b32_e32 v27, v0
	v_mov_b32_e32 v28, v0
	v_mov_b32_e32 v29, v0
	v_mov_b32_e32 v30, v0
	v_mov_b32_e32 v31, v0
	s_waitcnt vmcnt(0)
	v_mov_b32_e32 v32, v0
	v_mov_b32_e32 v33, v0
	v_mov_b32_e32 v34, v0
	v_mov_b32_e32 v35, v0
	v_mov_b32_e32 v36, v0
	v_mov_b32_e32 v37, v0
	v_mov_b32_e32 v38, v0
	v_mov_b32_e32 v39, v0
	v_mov_b32_e32 v40, v0
	v_mov_b32_e32 v41, v0
	v_mov_b32_e32 v42, v0
	v_mov_b32_e32 v43, v0
	v_mov_b32_e32 v44, v0
	v_mov_b32_e32 v45, v0
	v_mov_b32_e32 v46, v0
	v_mov_b32_e32 v47, v0
	v_mov_b32_e32 v48, v0
	v_mov_b32_e32 v49, v0
	v_mov_b32_e32 v50, v0
	v_mov_b32_e32 v51, v0
	v_mov_b32_e32 v52, v0
	v_mov_b32_e32 v53, v0
	v_mov_b32_e32 v54, v0
	v_mov_b32_e32 v55, v0
	v_mov_b32_e32 v56, v0
	v_mov_b32_e32 v57, v0
	v_mov_b32_e32 v58, v0
	v_mov_b32_e32 v59, v0
	v_mov_b32_e32 v60, v0
	v_mov_b32_e32 v61, v0
	v_mov_b32_e32 v62, v0
	v_mov_b32_e32 v63, v0
	s_waitcnt lgkmcnt(0)
	s_barrier
	v_add3_u32 v190, 0, v134, v135
	v_add_u32_e32 v191, 0x4000, v190
	s_nop 0
	v_readfirstlane_b32 s82, v191
	v_lshl_add_u32 v191, v108, 1, 0
	s_nop 0
	v_readfirstlane_b32 s83, v190
	v_add3_u32 v191, v191, v135, s21
	s_nop 0
	v_readfirstlane_b32 s84, v191
	v_add_u32_e32 v191, 0x400, v190
	s_nop 0
	v_readfirstlane_b32 s85, v191
	v_lshl_add_u32 v191, v110, 1, 0
	v_add3_u32 v191, v191, v135, s21
	s_nop 0
	v_readfirstlane_b32 s86, v191
	v_add_u32_e32 v191, 0x800, v190
	s_nop 0
	v_readfirstlane_b32 s87, v191
	v_lshl_add_u32 v191, v112, 1, 0
	v_add3_u32 v191, v191, v135, s21
	s_nop 0
	v_readfirstlane_b32 s88, v191
	v_add_u32_e32 v190, 0xc00, v190
	s_nop 0
	v_readfirstlane_b32 s89, v190
	v_subrev_u32_e32 v192, s52, v88
	v_subrev_u32_e32 v193, s52, v90
	v_subrev_u32_e32 v194, s52, v92
	v_subrev_u32_e32 v195, s52, v94
	v_subrev_u32_e32 v196, s52, v96
	v_subrev_u32_e32 v197, s52, v98
	v_subrev_u32_e32 v198, s52, v100
	v_subrev_u32_e32 v199, s52, v102
	v_subrev_u32_e32 v195, 0x400, v195
	v_subrev_u32_e32 v194, 0x400, v194
	v_subrev_u32_e32 v197, 0x800, v197
	v_subrev_u32_e32 v196, 0x800, v196
	v_subrev_u32_e32 v199, 0xc00, v199
	v_subrev_u32_e32 v198, 0xc00, v198
	s_and_b32 s29, s27, 0x4000
	s_xor_b32 s28, s29, 0x4000
	s_lshl_b32 s28, s28, 1
	s_add_i32 s28, s28, 32
	s_lshl_b32 s29, s29, 1
	s_add_i32 s29, s29, 32
.LBB0_2085:
	s_xor_b32 s28, s28, 0x8000
	s_xor_b32 s29, s29, 0x8000
	s_add_u32 s90, s52, s16
	s_addc_u32 s91, s53, s17
	s_add_i32 m0, s29, s83
	v_add3_u32 v139, s28, v113, v136
	global_load_lds_dwordx4 v193, s[90:91]
	global_load_lds_dwordx4 v195, s[90:91] offset:1024
	global_load_lds_dwordx4 v197, s[90:91] offset:2048
	global_load_lds_dwordx4 v199, s[90:91] offset:3072
	s_add_i32 m0, s29, s82
	v_add3_u32 v172, s28, v114, v136
	global_load_lds_dwordx4 v192, s[90:91]
	global_load_lds_dwordx4 v194, s[90:91] offset:1024
	global_load_lds_dwordx4 v196, s[90:91] offset:2048
	global_load_lds_dwordx4 v198, s[90:91] offset:3072
	v_add_u32_e32 v160, v139, v137
	v_add_u32_e32 v168, v172, v137
	s_addk_i32 s27, 0x4000
	s_add_u32 s16, s16, 0x80
	s_addc_u32 s17, s17, 0
	ds_read_b128 v[140:143], v160
	ds_read_b128 v[148:151], v168 offset:16384
	ds_read_b128 v[152:155], v168 offset:18432
	ds_read_b128 v[164:167], v168 offset:20480
	ds_read_b128 v[168:171], v168 offset:22528
	ds_read_b128 v[144:147], v160 offset:2048
	ds_read_b128 v[156:159], v160 offset:4096
	ds_read_b128 v[160:163], v160 offset:6144
	v_add_u32_e32 v139, v139, v138
	v_add_u32_e32 v236, v172, v138
	ds_read_b128 v[204:207], v139
	ds_read_b128 v[208:211], v236 offset:16384
	ds_read_b128 v[212:215], v236 offset:18432
	ds_read_b128 v[216:219], v236 offset:20480
	ds_read_b128 v[220:223], v236 offset:22528
	ds_read_b128 v[224:227], v139 offset:2048
	ds_read_b128 v[228:231], v139 offset:4096
	ds_read_b128 v[232:235], v139 offset:6144
	s_setprio 1
	s_waitcnt lgkmcnt(11)
	v_mfma_f32_16x16x32_bf16 v[60:63], v[140:143], v[148:151], v[60:63]
	v_mfma_f32_16x16x32_bf16 v[56:59], v[140:143], v[152:155], v[56:59]
	v_mfma_f32_16x16x32_bf16 v[52:55], v[140:143], v[164:167], v[52:55]
	v_mfma_f32_16x16x32_bf16 v[48:51], v[140:143], v[168:171], v[48:51]
	s_waitcnt lgkmcnt(10)
	v_mfma_f32_16x16x32_bf16 v[44:47], v[144:147], v[148:151], v[44:47]
	v_mfma_f32_16x16x32_bf16 v[40:43], v[144:147], v[152:155], v[40:43]
	v_mfma_f32_16x16x32_bf16 v[36:39], v[144:147], v[164:167], v[36:39]
	v_mfma_f32_16x16x32_bf16 v[32:35], v[144:147], v[168:171], v[32:35]
	s_waitcnt lgkmcnt(9)
	v_mfma_f32_16x16x32_bf16 v[28:31], v[156:159], v[148:151], v[28:31]
	v_mfma_f32_16x16x32_bf16 v[24:27], v[156:159], v[152:155], v[24:27]
	v_mfma_f32_16x16x32_bf16 v[20:23], v[156:159], v[164:167], v[20:23]
	v_mfma_f32_16x16x32_bf16 v[16:19], v[156:159], v[168:171], v[16:19]
	s_waitcnt lgkmcnt(8)
	v_mfma_f32_16x16x32_bf16 v[12:15], v[160:163], v[148:151], v[12:15]
	v_mfma_f32_16x16x32_bf16 v[8:11], v[160:163], v[152:155], v[8:11]
	v_mfma_f32_16x16x32_bf16 v[4:7], v[160:163], v[164:167], v[4:7]
	v_mfma_f32_16x16x32_bf16 v[0:3], v[160:163], v[168:171], v[0:3]
	s_waitcnt lgkmcnt(3)
	v_mfma_f32_16x16x32_bf16 v[60:63], v[204:207], v[208:211], v[60:63]
	v_mfma_f32_16x16x32_bf16 v[56:59], v[204:207], v[212:215], v[56:59]
	v_mfma_f32_16x16x32_bf16 v[52:55], v[204:207], v[216:219], v[52:55]
	v_mfma_f32_16x16x32_bf16 v[48:51], v[204:207], v[220:223], v[48:51]
	s_waitcnt lgkmcnt(2)
	v_mfma_f32_16x16x32_bf16 v[44:47], v[224:227], v[208:211], v[44:47]
	v_mfma_f32_16x16x32_bf16 v[40:43], v[224:227], v[212:215], v[40:43]
	v_mfma_f32_16x16x32_bf16 v[36:39], v[224:227], v[216:219], v[36:39]
	v_mfma_f32_16x16x32_bf16 v[32:35], v[224:227], v[220:223], v[32:35]
	s_waitcnt lgkmcnt(1)
	v_mfma_f32_16x16x32_bf16 v[28:31], v[228:231], v[208:211], v[28:31]
	v_mfma_f32_16x16x32_bf16 v[24:27], v[228:231], v[212:215], v[24:27]
	v_mfma_f32_16x16x32_bf16 v[20:23], v[228:231], v[216:219], v[20:23]
	v_mfma_f32_16x16x32_bf16 v[16:19], v[228:231], v[220:223], v[16:19]
	s_waitcnt lgkmcnt(0)
	v_mfma_f32_16x16x32_bf16 v[12:15], v[232:235], v[208:211], v[12:15]
	v_mfma_f32_16x16x32_bf16 v[8:11], v[232:235], v[212:215], v[8:11]
	v_mfma_f32_16x16x32_bf16 v[4:7], v[232:235], v[216:219], v[4:7]
	v_mfma_f32_16x16x32_bf16 v[0:3], v[232:235], v[220:223], v[0:3]
	s_setprio 0
	s_cmpk_eq_i32 s16, 0x1f80
	s_waitcnt vmcnt(0)
	s_barrier
	s_cbranch_scc0 .LBB0_2085
	ds_read_b128 v[88:91], v117 offset:55296
	ds_read_b128 v[92:95], v117 offset:53248
	ds_read_b128 v[96:99], v118 offset:38912
	ds_read_b128 v[100:103], v118 offset:36864
	ds_read_b128 v[140:143], v117 offset:51200
	ds_read_b128 v[144:147], v117 offset:49152
	ds_read_b128 v[148:151], v118 offset:34816
	ds_read_b128 v[152:155], v118 offset:32768
	ds_read_b128 v[204:207], v119 offset:32768
	ds_read_b128 v[208:211], v119 offset:34816
	ds_read_b128 v[212:215], v120 offset:49152
	ds_read_b128 v[216:219], v120 offset:51200
	ds_read_b128 v[220:223], v119 offset:36864
	ds_read_b128 v[224:227], v119 offset:38912
	ds_read_b128 v[228:231], v120 offset:53248
	ds_read_b128 v[232:235], v120 offset:55296
	s_setprio 1
	s_waitcnt lgkmcnt(13)
	v_mfma_f32_16x16x32_bf16 v[4:7], v[96:99], v[92:95], v[4:7]
	v_mfma_f32_16x16x32_bf16 v[0:3], v[96:99], v[88:91], v[0:3]
	s_waitcnt lgkmcnt(8)
	v_mfma_f32_16x16x32_bf16 v[60:63], v[152:155], v[144:147], v[60:63]
	v_mfma_f32_16x16x32_bf16 v[56:59], v[152:155], v[140:143], v[56:59]
	v_mfma_f32_16x16x32_bf16 v[52:55], v[152:155], v[92:95], v[52:55]
	v_mfma_f32_16x16x32_bf16 v[48:51], v[152:155], v[88:91], v[48:51]
	v_mfma_f32_16x16x32_bf16 v[44:47], v[148:151], v[144:147], v[44:47]
	v_mfma_f32_16x16x32_bf16 v[40:43], v[148:151], v[140:143], v[40:43]
	v_mfma_f32_16x16x32_bf16 v[36:39], v[148:151], v[92:95], v[36:39]
	v_mfma_f32_16x16x32_bf16 v[32:35], v[148:151], v[88:91], v[32:35]
	v_mfma_f32_16x16x32_bf16 v[28:31], v[100:103], v[144:147], v[28:31]
	v_mfma_f32_16x16x32_bf16 v[24:27], v[100:103], v[140:143], v[24:27]
	v_mfma_f32_16x16x32_bf16 v[20:23], v[100:103], v[92:95], v[20:23]
	v_mfma_f32_16x16x32_bf16 v[16:19], v[100:103], v[88:91], v[16:19]
	v_mfma_f32_16x16x32_bf16 v[12:15], v[96:99], v[144:147], v[12:15]
	v_mfma_f32_16x16x32_bf16 v[8:11], v[96:99], v[140:143], v[8:11]
	s_waitcnt lgkmcnt(1)
	v_mfma_f32_16x16x32_bf16 v[4:7], v[224:227], v[228:231], v[4:7]
	s_waitcnt lgkmcnt(0)
	v_mfma_f32_16x16x32_bf16 v[0:3], v[224:227], v[232:235], v[0:3]
	v_mfma_f32_16x16x32_bf16 v[60:63], v[204:207], v[212:215], v[60:63]
	v_mfma_f32_16x16x32_bf16 v[56:59], v[204:207], v[216:219], v[56:59]
	v_mfma_f32_16x16x32_bf16 v[52:55], v[204:207], v[228:231], v[52:55]
	v_mfma_f32_16x16x32_bf16 v[48:51], v[204:207], v[232:235], v[48:51]
	v_mfma_f32_16x16x32_bf16 v[44:47], v[208:211], v[212:215], v[44:47]
	v_mfma_f32_16x16x32_bf16 v[40:43], v[208:211], v[216:219], v[40:43]
	v_mfma_f32_16x16x32_bf16 v[36:39], v[208:211], v[228:231], v[36:39]
	v_mfma_f32_16x16x32_bf16 v[32:35], v[208:211], v[232:235], v[32:35]
	v_mfma_f32_16x16x32_bf16 v[28:31], v[220:223], v[212:215], v[28:31]
	v_mfma_f32_16x16x32_bf16 v[24:27], v[220:223], v[216:219], v[24:27]
	v_mfma_f32_16x16x32_bf16 v[20:23], v[220:223], v[228:231], v[20:23]
	v_mfma_f32_16x16x32_bf16 v[16:19], v[220:223], v[232:235], v[16:19]
	v_mfma_f32_16x16x32_bf16 v[12:15], v[224:227], v[212:215], v[12:15]
	v_mfma_f32_16x16x32_bf16 v[8:11], v[224:227], v[216:219], v[8:11]
	s_setprio 0
	s_barrier
	ds_write2_b32 v115, v60, v56 offset1:16
	ds_write2_b32 v115, v61, v57 offset0:132 offset1:148
	v_add_u32_e32 v56, 0x400, v115
	ds_write2_b32 v56, v62, v58 offset0:8 offset1:24
	ds_write2_b32 v56, v63, v59 offset0:140 offset1:156
	ds_write2_b32 v115, v52, v48 offset0:32 offset1:48
	ds_write2_b32 v115, v53, v49 offset0:164 offset1:180
	ds_write2_b32 v56, v54, v50 offset0:40 offset1:56
	ds_write2_b32 v56, v55, v51 offset0:172 offset1:188
	v_add_u32_e32 v48, 0x2000, v115
	ds_write2_b32 v48, v44, v40 offset0:64 offset1:80
	ds_write2_b32 v48, v45, v41 offset0:196 offset1:212
	v_add_u32_e32 v40, 0x2400, v115
	ds_write2_b32 v40, v46, v42 offset0:72 offset1:88
	ds_write2_b32 v40, v47, v43 offset0:204 offset1:220
	ds_write2_b32 v48, v36, v32 offset0:96 offset1:112
	ds_write2_b32 v48, v37, v33 offset0:228 offset1:244
	ds_write2_b32 v40, v38, v34 offset0:104 offset1:120
	ds_write2_b32 v40, v39, v35 offset0:236 offset1:252
	v_add_u32_e32 v32, 0x4000, v115
	ds_write2_b32 v32, v28, v24 offset0:128 offset1:144
	v_add_u32_e32 v24, 0x4400, v115
	ds_write2_b32 v24, v29, v25 offset0:4 offset1:20
	ds_write2_b32 v24, v30, v26 offset0:136 offset1:152
	v_add_u32_e32 v25, 0x4800, v115
	ds_write2_b32 v25, v31, v27 offset0:12 offset1:28
	ds_write2_b32 v32, v20, v16 offset0:160 offset1:176
	ds_write2_b32 v24, v21, v17 offset0:36 offset1:52
	ds_write2_b32 v24, v22, v18 offset0:168 offset1:184
	ds_write2_b32 v25, v23, v19 offset0:44 offset1:60
	v_add_u32_e32 v16, 0x6000, v115
	ds_write2_b32 v16, v12, v8 offset0:192 offset1:208
	v_add_u32_e32 v8, 0x6400, v115
	ds_write2_b32 v8, v13, v9 offset0:68 offset1:84
	ds_write2_b32 v8, v14, v10 offset0:200 offset1:216
	v_add_u32_e32 v9, 0x6800, v115
	ds_write2_b32 v9, v15, v11 offset0:76 offset1:92
	ds_write2_b32 v16, v4, v0 offset0:224 offset1:240
	ds_write2_b32 v8, v5, v1 offset0:100 offset1:116
	ds_write2_b32 v8, v6, v2 offset0:232 offset1:248
	ds_write2_b32 v9, v7, v3 offset0:108 offset1:124
	v_or_b32_e32 v0, s25, v116
	v_ashrrev_i32_e32 v1, 31, v0
	v_lshlrev_b64 v[2:3], 2, v[0:1]
	v_lshl_add_u64 v[0:1], s[14:15], 0, v[2:3]
	v_lshl_add_u64 v[2:3], s[12:13], 0, v[2:3]
	v_add_u32_e32 v4, s26, v129
	s_mov_b32 s16, 0
	s_waitcnt lgkmcnt(0)
	s_barrier

.LBB0_2095:
	s_and_b32 s16, s20, 0x380
	v_add_lshl_u32 v72, v141, s16, 13
	v_lshl_add_u64 v[98:99], v[86:87], 0, v[72:73]
	v_add_lshl_u32 v72, v143, s16, 13
	v_lshl_add_u64 v[100:101], v[90:91], 0, v[72:73]
	v_add_lshl_u32 v72, v145, s16, 13
	s_lshl_b32 s26, s25, 7
	v_lshl_add_u64 v[102:103], v[86:87], 0, v[72:73]
	v_add_lshl_u32 v72, v147, s16, 13
	s_ashr_i32 s16, s25, 3
	s_and_b32 s26, s26, 0x380
	v_add_u32_e32 v2, 0x4000, v135
	v_lshl_add_u64 v[104:105], v[94:95], 0, v[72:73]
	s_add_i32 s17, s16, s19
	v_add_lshl_u32 v72, s26, v134, 13
	v_readfirstlane_b32 s27, v2
	s_lshl_b32 s17, s17, 7
	v_lshl_add_u64 v[0:1], v[74:75], 0, v[72:73]
	s_mov_b32 m0, s27
	v_readfirstlane_b32 s27, v135
	global_load_lds_dwordx4 v[0:1], off
	v_add_u32_e32 v0, s17, v134
	v_ashrrev_i32_e32 v1, 31, v0
	v_lshlrev_b64 v[0:1], 13, v[0:1]
	v_lshl_add_u64 v[0:1], v[80:81], 0, v[0:1]
	s_mov_b32 m0, s27
	v_add_lshl_u32 v72, s26, v126, 13
	v_readfirstlane_b32 s27, v151
	global_load_lds_dwordx4 v[0:1], off
	v_lshl_add_u64 v[0:1], v[76:77], 0, v[72:73]
	s_mov_b32 m0, s27
	v_add_u32_e32 v2, 0x400, v135
	global_load_lds_dwordx4 v[0:1], off
	v_add_u32_e32 v0, s17, v126
	v_ashrrev_i32_e32 v1, 31, v0
	v_lshlrev_b64 v[0:1], 13, v[0:1]
	v_readfirstlane_b32 s27, v2
	v_lshl_add_u64 v[0:1], v[82:83], 0, v[0:1]
	s_mov_b32 m0, s27
	v_add_lshl_u32 v72, s26, v127, 13
	v_readfirstlane_b32 s27, v152
	global_load_lds_dwordx4 v[0:1], off
	v_lshl_add_u64 v[0:1], v[74:75], 0, v[72:73]
	s_mov_b32 m0, s27
	v_add_u32_e32 v2, 0x800, v135
	global_load_lds_dwordx4 v[0:1], off
	v_add_u32_e32 v0, s17, v127
	v_ashrrev_i32_e32 v1, 31, v0
	v_lshlrev_b64 v[0:1], 13, v[0:1]
	v_readfirstlane_b32 s27, v2
	v_lshl_add_u64 v[0:1], v[80:81], 0, v[0:1]
	s_mov_b32 m0, s27
	v_add_lshl_u32 v72, s26, v125, 13
	v_readfirstlane_b32 s27, v153
	global_load_lds_dwordx4 v[0:1], off
	v_lshl_add_u64 v[0:1], v[78:79], 0, v[72:73]
	s_mov_b32 m0, s27
	v_add_u32_e32 v2, 0xc00, v135
	global_load_lds_dwordx4 v[0:1], off
	v_add_u32_e32 v0, s17, v125
	v_ashrrev_i32_e32 v1, 31, v0
	v_lshlrev_b64 v[0:1], 13, v[0:1]
	v_readfirstlane_b32 s17, v2
	v_lshl_add_u64 v[0:1], v[84:85], 0, v[0:1]
	s_mov_b32 m0, s17
	s_lshl_b32 s27, s16, 7
	global_load_lds_dwordx4 v[0:1], off
	v_add_u32_e32 v0, s27, v142
	v_ashrrev_i32_e32 v1, 31, v0
	v_lshlrev_b64 v[0:1], 13, v[0:1]
	v_lshl_add_u64 v[106:107], v[88:89], 0, v[0:1]
	v_add_u32_e32 v0, s27, v144
	v_ashrrev_i32_e32 v1, 31, v0
	v_lshlrev_b64 v[0:1], 13, v[0:1]
	v_lshl_add_u64 v[108:109], v[92:93], 0, v[0:1]
	v_add_u32_e32 v0, s27, v146
	v_ashrrev_i32_e32 v1, 31, v0
	v_lshlrev_b64 v[0:1], 13, v[0:1]
	v_lshl_add_u64 v[110:111], v[88:89], 0, v[0:1]
	v_add_u32_e32 v0, s27, v148
	v_ashrrev_i32_e32 v1, 31, v0
	v_lshlrev_b64 v[0:1], 13, v[0:1]
	v_lshl_add_u64 v[112:113], v[96:97], 0, v[0:1]
	s_mov_b64 s[16:17], 0
	s_mov_b32 s28, 0
	v_mov_b32_e32 v0, 0
	v_mov_b32_e32 v1, v73
	v_mov_b32_e32 v2, v73
	v_mov_b32_e32 v3, v73
	v_mov_b32_e32 v4, 0
	v_mov_b32_e32 v5, v73
	v_mov_b32_e32 v6, v73
	v_mov_b32_e32 v7, v73
	v_mov_b32_e32 v8, 0
	v_mov_b32_e32 v9, v73
	v_mov_b32_e32 v10, v73
	v_mov_b32_e32 v11, v73
	v_mov_b32_e32 v12, 0
	v_mov_b32_e32 v13, v73
	v_mov_b32_e32 v14, v73
	v_mov_b32_e32 v15, v73
	v_mov_b32_e32 v16, 0
	v_mov_b32_e32 v17, v73
	v_mov_b32_e32 v18, v73
	v_mov_b32_e32 v19, v73
	v_mov_b32_e32 v20, 0
	v_mov_b32_e32 v21, v73
	v_mov_b32_e32 v22, v73
	v_mov_b32_e32 v23, v73
	v_mov_b32_e32 v24, 0
	v_mov_b32_e32 v25, v73
	v_mov_b32_e32 v26, v73
	v_mov_b32_e32 v27, v73
	v_mov_b32_e32 v28, 0
	v_mov_b32_e32 v29, v73
	v_mov_b32_e32 v30, v73
	v_mov_b32_e32 v31, v73
	s_waitcnt vmcnt(0)
	v_mov_b32_e32 v32, 0
	v_mov_b32_e32 v33, v73
	v_mov_b32_e32 v34, v73
	v_mov_b32_e32 v35, v73
	v_mov_b32_e32 v36, 0
	v_mov_b32_e32 v37, v73
	v_mov_b32_e32 v38, v73
	v_mov_b32_e32 v39, v73
	v_mov_b32_e32 v40, 0
	v_mov_b32_e32 v41, v73
	v_mov_b32_e32 v42, v73
	v_mov_b32_e32 v43, v73
	v_mov_b32_e32 v44, 0
	v_mov_b32_e32 v45, v73
	v_mov_b32_e32 v46, v73
	v_mov_b32_e32 v47, v73
	v_mov_b32_e32 v48, 0
	v_mov_b32_e32 v49, v73
	v_mov_b32_e32 v50, v73
	v_mov_b32_e32 v51, v73
	v_mov_b32_e32 v52, 0
	v_mov_b32_e32 v53, v73
	v_mov_b32_e32 v54, v73
	v_mov_b32_e32 v55, v73
	v_mov_b32_e32 v56, 0
	v_mov_b32_e32 v57, v73
	v_mov_b32_e32 v58, v73
	v_mov_b32_e32 v59, v73
	v_mov_b32_e32 v60, 0
	v_mov_b32_e32 v61, v73
	v_mov_b32_e32 v62, v73
	v_mov_b32_e32 v63, v73
	s_waitcnt lgkmcnt(0)
	s_barrier
	v_lshlrev_b32_e32 v190, 1, v132
	v_lshlrev_b32_e32 v191, 1, v133
	v_add3_u32 v190, 0, v190, v191
	v_add_u32_e32 v192, 0x4000, v190
	s_nop 0
	v_readfirstlane_b32 s82, v192
	v_lshl_add_u32 v192, v118, 1, 0
	s_nop 0
	v_readfirstlane_b32 s83, v190
	v_add3_u32 v192, v192, v191, s21
	s_nop 0
	v_readfirstlane_b32 s84, v192
	v_add_u32_e32 v192, 0x400, v190
	s_nop 0
	v_readfirstlane_b32 s85, v192
	v_lshl_add_u32 v192, v119, 1, 0
	v_add3_u32 v192, v192, v191, s21
	s_nop 0
	v_readfirstlane_b32 s86, v192
	v_add_u32_e32 v192, 0x800, v190
	s_nop 0
	v_readfirstlane_b32 s87, v192
	v_lshl_add_u32 v192, v120, 1, 0
	v_add3_u32 v191, v192, v191, s21
	s_nop 0
	v_readfirstlane_b32 s88, v191
	v_add_u32_e32 v190, 0xc00, v190
	s_nop 0
	v_readfirstlane_b32 s89, v190
	v_subrev_u32_e32 v193, s52, v98
	v_subrev_u32_e32 v194, s52, v106
	v_subrev_u32_e32 v195, s52, v100
	v_subrev_u32_e32 v196, s52, v108
	v_subrev_u32_e32 v197, s52, v102
	v_subrev_u32_e32 v198, s52, v110
	v_subrev_u32_e32 v199, s52, v104
	v_subrev_u32_e32 v200, s52, v112
	v_subrev_u32_e32 v196, 0x400, v196
	v_subrev_u32_e32 v195, 0x400, v195
	v_subrev_u32_e32 v198, 0x800, v198
	v_subrev_u32_e32 v197, 0x800, v197
	v_subrev_u32_e32 v200, 0xc00, v200
	v_subrev_u32_e32 v199, 0xc00, v199
	s_and_b32 s30, s28, 0x4000
	s_xor_b32 s29, s30, 0x4000
	s_lshl_b32 s29, s29, 1
	s_add_i32 s29, s29, 32
	s_lshl_b32 s30, s30, 1
	s_add_i32 s30, s30, 32
.LBB0_2096:
	s_xor_b32 s29, s29, 0x8000
	s_xor_b32 s30, s30, 0x8000
	s_add_u32 s90, s52, s16
	s_addc_u32 s91, s53, s17
	s_add_i32 m0, s30, s83
	v_lshlrev_b32_e32 v72, 1, v131
	global_load_lds_dwordx4 v194, s[90:91]
	global_load_lds_dwordx4 v196, s[90:91] offset:1024
	global_load_lds_dwordx4 v198, s[90:91] offset:2048
	global_load_lds_dwordx4 v200, s[90:91] offset:3072
	s_add_i32 m0, s30, s82
	v_add3_u32 v178, s29, v129, v72
	global_load_lds_dwordx4 v193, s[90:91]
	global_load_lds_dwordx4 v195, s[90:91] offset:1024
	global_load_lds_dwordx4 v197, s[90:91] offset:2048
	global_load_lds_dwordx4 v199, s[90:91] offset:3072
	v_lshlrev_b32_e32 v154, 1, v121
	v_add3_u32 v72, s29, v130, v72
	v_add_u32_e32 v174, v178, v154
	v_add_u32_e32 v179, v72, v154
	ds_read_b128 v[154:157], v174
	ds_read_b128 v[162:165], v179 offset:16384
	ds_read_b128 v[166:169], v179 offset:18432
	ds_read_b128 v[182:185], v179 offset:20480
	ds_read_b128 v[186:189], v179 offset:22528
	ds_read_b128 v[158:161], v174 offset:2048
	ds_read_b128 v[170:173], v174 offset:4096
	ds_read_b128 v[174:177], v174 offset:6144
	v_lshlrev_b32_e32 v236, 1, v122
	v_add_u32_e32 v237, v178, v236
	v_add_u32_e32 v72, v72, v236
	ds_read_b128 v[204:207], v237
	ds_read_b128 v[208:211], v72 offset:16384
	ds_read_b128 v[212:215], v72 offset:18432
	ds_read_b128 v[216:219], v72 offset:20480
	ds_read_b128 v[220:223], v72 offset:22528
	ds_read_b128 v[224:227], v237 offset:2048
	ds_read_b128 v[228:231], v237 offset:4096
	ds_read_b128 v[232:235], v237 offset:6144
	s_setprio 1
	s_waitcnt lgkmcnt(11)
	v_mfma_f32_16x16x32_bf16 v[60:63], v[154:157], v[162:165], v[60:63]
	v_mfma_f32_16x16x32_bf16 v[56:59], v[154:157], v[166:169], v[56:59]
	v_mfma_f32_16x16x32_bf16 v[52:55], v[154:157], v[182:185], v[52:55]
	v_mfma_f32_16x16x32_bf16 v[48:51], v[154:157], v[186:189], v[48:51]
	s_waitcnt lgkmcnt(10)
	v_mfma_f32_16x16x32_bf16 v[44:47], v[158:161], v[162:165], v[44:47]
	v_mfma_f32_16x16x32_bf16 v[40:43], v[158:161], v[166:169], v[40:43]
	v_mfma_f32_16x16x32_bf16 v[36:39], v[158:161], v[182:185], v[36:39]
	v_mfma_f32_16x16x32_bf16 v[32:35], v[158:161], v[186:189], v[32:35]
	s_waitcnt lgkmcnt(9)
	v_mfma_f32_16x16x32_bf16 v[28:31], v[170:173], v[162:165], v[28:31]
	v_mfma_f32_16x16x32_bf16 v[24:27], v[170:173], v[166:169], v[24:27]
	v_mfma_f32_16x16x32_bf16 v[20:23], v[170:173], v[182:185], v[20:23]
	v_mfma_f32_16x16x32_bf16 v[16:19], v[170:173], v[186:189], v[16:19]
	s_waitcnt lgkmcnt(8)
	v_mfma_f32_16x16x32_bf16 v[12:15], v[174:177], v[162:165], v[12:15]
	v_mfma_f32_16x16x32_bf16 v[8:11], v[174:177], v[166:169], v[8:11]
	v_mfma_f32_16x16x32_bf16 v[4:7], v[174:177], v[182:185], v[4:7]
	v_mfma_f32_16x16x32_bf16 v[0:3], v[174:177], v[186:189], v[0:3]
	s_waitcnt lgkmcnt(3)
	v_mfma_f32_16x16x32_bf16 v[60:63], v[204:207], v[208:211], v[60:63]
	v_mfma_f32_16x16x32_bf16 v[56:59], v[204:207], v[212:215], v[56:59]
	v_mfma_f32_16x16x32_bf16 v[52:55], v[204:207], v[216:219], v[52:55]
	v_mfma_f32_16x16x32_bf16 v[48:51], v[204:207], v[220:223], v[48:51]
	s_waitcnt lgkmcnt(2)
	v_mfma_f32_16x16x32_bf16 v[44:47], v[224:227], v[208:211], v[44:47]
	v_mfma_f32_16x16x32_bf16 v[40:43], v[224:227], v[212:215], v[40:43]
	v_mfma_f32_16x16x32_bf16 v[36:39], v[224:227], v[216:219], v[36:39]
	v_mfma_f32_16x16x32_bf16 v[32:35], v[224:227], v[220:223], v[32:35]
	s_waitcnt lgkmcnt(1)
	v_mfma_f32_16x16x32_bf16 v[28:31], v[228:231], v[208:211], v[28:31]
	v_mfma_f32_16x16x32_bf16 v[24:27], v[228:231], v[212:215], v[24:27]
	v_mfma_f32_16x16x32_bf16 v[20:23], v[228:231], v[216:219], v[20:23]
	v_mfma_f32_16x16x32_bf16 v[16:19], v[228:231], v[220:223], v[16:19]
	s_waitcnt lgkmcnt(0)
	v_mfma_f32_16x16x32_bf16 v[12:15], v[232:235], v[208:211], v[12:15]
	v_mfma_f32_16x16x32_bf16 v[8:11], v[232:235], v[212:215], v[8:11]
	v_mfma_f32_16x16x32_bf16 v[4:7], v[232:235], v[216:219], v[4:7]
	v_mfma_f32_16x16x32_bf16 v[0:3], v[232:235], v[220:223], v[0:3]
	s_setprio 0
	s_add_u32 s16, s16, 0x80
	s_addc_u32 s17, s17, 0
	s_cmpk_eq_i32 s16, 0x1f80
	s_waitcnt vmcnt(0)
	s_barrier
	s_cbranch_scc0 .LBB0_2096
	ds_read_b128 v[98:101], v71 offset:32768
	ds_read_b128 v[102:105], v71 offset:34816
	ds_read_b128 v[106:109], v138 offset:49152
	ds_read_b128 v[110:113], v138 offset:51200
	ds_read_b128 v[154:157], v71 offset:36864
	ds_read_b128 v[158:161], v71 offset:38912
	ds_read_b128 v[162:165], v138 offset:53248
	ds_read_b128 v[166:169], v138 offset:55296
	ds_read_b128 v[204:207], v139 offset:32768
	ds_read_b128 v[208:211], v139 offset:34816
	ds_read_b128 v[212:215], v140 offset:49152
	ds_read_b128 v[216:219], v140 offset:51200
	ds_read_b128 v[220:223], v139 offset:36864
	ds_read_b128 v[224:227], v139 offset:38912
	ds_read_b128 v[228:231], v140 offset:53248
	ds_read_b128 v[232:235], v140 offset:55296
	s_setprio 1
	s_waitcnt lgkmcnt(9)
	v_mfma_f32_16x16x32_bf16 v[4:7], v[158:161], v[162:165], v[4:7]
	s_waitcnt lgkmcnt(8)
	v_mfma_f32_16x16x32_bf16 v[0:3], v[158:161], v[166:169], v[0:3]
	v_mfma_f32_16x16x32_bf16 v[60:63], v[98:101], v[106:109], v[60:63]
	v_mfma_f32_16x16x32_bf16 v[56:59], v[98:101], v[110:113], v[56:59]
	v_mfma_f32_16x16x32_bf16 v[52:55], v[98:101], v[162:165], v[52:55]
	v_mfma_f32_16x16x32_bf16 v[48:51], v[98:101], v[166:169], v[48:51]
	v_mfma_f32_16x16x32_bf16 v[44:47], v[102:105], v[106:109], v[44:47]
	v_mfma_f32_16x16x32_bf16 v[40:43], v[102:105], v[110:113], v[40:43]
	v_mfma_f32_16x16x32_bf16 v[36:39], v[102:105], v[162:165], v[36:39]
	v_mfma_f32_16x16x32_bf16 v[32:35], v[102:105], v[166:169], v[32:35]
	v_mfma_f32_16x16x32_bf16 v[28:31], v[154:157], v[106:109], v[28:31]
	v_mfma_f32_16x16x32_bf16 v[24:27], v[154:157], v[110:113], v[24:27]
	v_mfma_f32_16x16x32_bf16 v[20:23], v[154:157], v[162:165], v[20:23]
	v_mfma_f32_16x16x32_bf16 v[16:19], v[154:157], v[166:169], v[16:19]
	v_mfma_f32_16x16x32_bf16 v[12:15], v[158:161], v[106:109], v[12:15]
	v_mfma_f32_16x16x32_bf16 v[8:11], v[158:161], v[110:113], v[8:11]
	s_waitcnt lgkmcnt(1)
	v_mfma_f32_16x16x32_bf16 v[4:7], v[224:227], v[228:231], v[4:7]
	s_waitcnt lgkmcnt(0)
	v_mfma_f32_16x16x32_bf16 v[0:3], v[224:227], v[232:235], v[0:3]
	v_mfma_f32_16x16x32_bf16 v[60:63], v[204:207], v[212:215], v[60:63]
	v_mfma_f32_16x16x32_bf16 v[56:59], v[204:207], v[216:219], v[56:59]
	v_mfma_f32_16x16x32_bf16 v[52:55], v[204:207], v[228:231], v[52:55]
	v_mfma_f32_16x16x32_bf16 v[48:51], v[204:207], v[232:235], v[48:51]
	v_mfma_f32_16x16x32_bf16 v[44:47], v[208:211], v[212:215], v[44:47]
	v_mfma_f32_16x16x32_bf16 v[40:43], v[208:211], v[216:219], v[40:43]
	v_mfma_f32_16x16x32_bf16 v[36:39], v[208:211], v[228:231], v[36:39]
	v_mfma_f32_16x16x32_bf16 v[32:35], v[208:211], v[232:235], v[32:35]
	v_mfma_f32_16x16x32_bf16 v[28:31], v[220:223], v[212:215], v[28:31]
	v_mfma_f32_16x16x32_bf16 v[24:27], v[220:223], v[216:219], v[24:27]
	v_mfma_f32_16x16x32_bf16 v[20:23], v[220:223], v[228:231], v[20:23]
	v_mfma_f32_16x16x32_bf16 v[16:19], v[220:223], v[232:235], v[16:19]
	v_mfma_f32_16x16x32_bf16 v[12:15], v[224:227], v[212:215], v[12:15]
	v_mfma_f32_16x16x32_bf16 v[8:11], v[224:227], v[216:219], v[8:11]
	s_setprio 0
	s_barrier
	ds_write2_b32 v136, v60, v56 offset1:16
	ds_write2_b32 v136, v61, v57 offset0:132 offset1:148
	v_add_u32_e32 v56, 0x400, v136
	ds_write2_b32 v56, v62, v58 offset0:8 offset1:24
	ds_write2_b32 v56, v63, v59 offset0:140 offset1:156
	ds_write2_b32 v136, v52, v48 offset0:32 offset1:48
	ds_write2_b32 v136, v53, v49 offset0:164 offset1:180
	ds_write2_b32 v56, v54, v50 offset0:40 offset1:56
	ds_write2_b32 v56, v55, v51 offset0:172 offset1:188
	v_add_u32_e32 v48, 0x2000, v136
	ds_write2_b32 v48, v44, v40 offset0:64 offset1:80
	ds_write2_b32 v48, v45, v41 offset0:196 offset1:212
	v_add_u32_e32 v40, 0x2400, v136
	ds_write2_b32 v40, v46, v42 offset0:72 offset1:88
	ds_write2_b32 v40, v47, v43 offset0:204 offset1:220
	ds_write2_b32 v48, v36, v32 offset0:96 offset1:112
	ds_write2_b32 v48, v37, v33 offset0:228 offset1:244
	ds_write2_b32 v40, v38, v34 offset0:104 offset1:120
	ds_write2_b32 v40, v39, v35 offset0:236 offset1:252
	v_add_u32_e32 v32, 0x4000, v136
	ds_write2_b32 v32, v28, v24 offset0:128 offset1:144
	v_add_u32_e32 v24, 0x4400, v136
	ds_write2_b32 v24, v29, v25 offset0:4 offset1:20
	ds_write2_b32 v24, v30, v26 offset0:136 offset1:152
	v_add_u32_e32 v25, 0x4800, v136
	ds_write2_b32 v25, v31, v27 offset0:12 offset1:28
	ds_write2_b32 v32, v20, v16 offset0:160 offset1:176
	ds_write2_b32 v24, v21, v17 offset0:36 offset1:52
	ds_write2_b32 v24, v22, v18 offset0:168 offset1:184
	ds_write2_b32 v25, v23, v19 offset0:44 offset1:60
	v_add_u32_e32 v16, 0x6000, v136
	ds_write2_b32 v16, v12, v8 offset0:192 offset1:208
	v_add_u32_e32 v8, 0x6400, v136
	ds_write2_b32 v8, v13, v9 offset0:68 offset1:84
	ds_write2_b32 v8, v14, v10 offset0:200 offset1:216
	v_add_u32_e32 v9, 0x6800, v136
	ds_write2_b32 v9, v15, v11 offset0:76 offset1:92
	ds_write2_b32 v16, v4, v0 offset0:224 offset1:240
	ds_write2_b32 v8, v5, v1 offset0:100 offset1:116
	ds_write2_b32 v8, v6, v2 offset0:232 offset1:248
	ds_write2_b32 v9, v7, v3 offset0:108 offset1:124
	v_or_b32_e32 v0, s26, v137
	v_lshlrev_b32_e32 v72, 2, v0
	v_lshl_add_u64 v[0:1], s[14:15], 0, v[72:73]
	v_lshl_add_u64 v[2:3], s[12:13], 0, v[72:73]
	v_add_u32_e32 v4, s27, v149
	s_mov_b32 s16, 0
	s_waitcnt lgkmcnt(0)
	s_barrier

.LBB0_2101:
	s_ashr_i32 s17, s18, 2
	s_add_i32 s12, s17, 0x80
	s_and_b32 s16, s18, 3
	s_ashr_i32 s20, s12, 3
	s_add_i32 s21, s20, s19
	s_lshl_b32 s12, s16, 11
	s_add_u32 s8, s8, s12
	s_addc_u32 s9, s9, 0
	s_add_u32 s18, s10, s12
	s_addc_u32 s19, s11, 0
	s_lshl_b32 s11, s17, 7
	s_lshl_b32 s10, s21, 7
	s_and_b32 s11, s11, 0x380
	v_lshlrev_b32_e32 v83, 1, v2
	v_lshlrev_b32_e32 v84, 1, v3
	v_add_lshl_u32 v0, s11, v134, 13
	v_mov_b32_e32 v1, 0
	v_add3_u32 v20, 32, v83, v84
	v_add_u32_e32 v2, s10, v134
	v_lshl_add_u64 v[4:5], s[18:19], 0, v[0:1]
	v_add_u32_e32 v0, 0x4000, v20
	v_ashrrev_i32_e32 v3, 31, v2
	v_mov_b32_e32 v71, v1
	v_readfirstlane_b32 s21, v0
	v_lshlrev_b64 v[2:3], 13, v[2:3]
	v_lshl_add_u64 v[4:5], v[4:5], 0, v[70:71]
	s_mov_b32 m0, s21
	v_lshl_add_u64 v[2:3], s[8:9], 0, v[2:3]
	v_readfirstlane_b32 s21, v20
	global_load_lds_dwordx4 v[4:5], off
	v_lshl_add_u64 v[2:3], v[2:3], 0, v[70:71]
	s_mov_b32 m0, s21
	v_add_lshl_u32 v0, v126, s11, 12
	s_movk_i32 s17, 0x4000
	global_load_lds_dwordx4 v[2:3], off
	v_lshlrev_b64 v[2:3], 1, v[0:1]
	v_lshl_add_u32 v0, v118, 1, 32
	v_add3_u32 v0, v0, v84, s17
	v_lshl_add_u64 v[4:5], s[18:19], 0, v[2:3]
	v_lshlrev_b64 v[6:7], 1, v[66:67]
	v_readfirstlane_b32 s21, v0
	v_lshl_add_u64 v[4:5], v[4:5], 0, v[6:7]
	s_mov_b32 m0, s21
	v_add_u32_e32 v0, 0x400, v20
	global_load_lds_dwordx4 v[4:5], off
	v_add_u32_e32 v4, s10, v126
	v_ashrrev_i32_e32 v5, 31, v4
	v_lshlrev_b64 v[4:5], 13, v[4:5]
	v_lshl_add_u64 v[8:9], s[8:9], 0, v[4:5]
	v_readfirstlane_b32 s21, v0
	v_lshl_add_u64 v[8:9], v[8:9], 0, v[6:7]
	s_mov_b32 m0, s21
	v_add_lshl_u32 v0, v127, s11, 12
	global_load_lds_dwordx4 v[8:9], off
	v_lshlrev_b64 v[8:9], 1, v[0:1]
	v_lshl_add_u32 v0, v119, 1, 32
	v_add3_u32 v0, v0, v84, s17
	v_lshl_add_u64 v[10:11], s[18:19], 0, v[8:9]
	v_readfirstlane_b32 s21, v0
	v_lshl_add_u64 v[10:11], v[10:11], 0, v[70:71]
	s_mov_b32 m0, s21
	v_add_u32_e32 v0, 0x800, v20
	global_load_lds_dwordx4 v[10:11], off
	v_add_u32_e32 v10, s10, v127
	v_ashrrev_i32_e32 v11, 31, v10
	v_lshlrev_b64 v[10:11], 13, v[10:11]
	v_lshl_add_u64 v[12:13], s[8:9], 0, v[10:11]
	v_readfirstlane_b32 s21, v0
	v_lshl_add_u64 v[12:13], v[12:13], 0, v[70:71]
	s_mov_b32 m0, s21
	v_add_lshl_u32 v0, v125, s11, 12
	global_load_lds_dwordx4 v[12:13], off
	v_lshlrev_b64 v[12:13], 1, v[0:1]
	v_lshl_add_u32 v0, v120, 1, 32
	v_add3_u32 v0, v0, v84, s17
	v_lshl_add_u64 v[14:15], s[18:19], 0, v[12:13]
	v_lshlrev_b64 v[16:17], 1, v[68:69]
	v_readfirstlane_b32 s18, v0
	v_lshl_add_u64 v[14:15], v[14:15], 0, v[16:17]
	s_mov_b32 m0, s18
	v_add_u32_e32 v0, 0xc00, v20
	global_load_lds_dwordx4 v[14:15], off
	v_add_u32_e32 v14, s10, v125
	v_ashrrev_i32_e32 v15, 31, v14
	v_lshlrev_b64 v[14:15], 13, v[14:15]
	v_lshl_add_u64 v[18:19], s[8:9], 0, v[14:15]
	v_readfirstlane_b32 s8, v0
	v_lshl_add_u64 v[18:19], v[18:19], 0, v[16:17]
	s_mov_b32 m0, s8
	s_mov_b32 s13, 0
	global_load_lds_dwordx4 v[18:19], off
	v_or_b32_e32 v0, s11, v124
	v_lshl_add_u64 v[6:7], s[12:13], 0, v[6:7]
	v_add_lshl_u32 v0, v0, v123, 13
	v_lshl_add_u64 v[18:19], s[12:13], 0, v[64:65]
	v_lshl_add_u64 v[2:3], v[6:7], 0, v[2:3]
	v_lshl_add_u64 v[20:21], v[18:19], 0, v[0:1]
	s_mov_b64 s[8:9], 0x800080
	v_lshl_add_u64 v[2:3], s[6:7], 0, v[2:3]
	v_lshl_add_u64 v[20:21], s[6:7], 0, v[20:21]
	s_lshl_b32 s18, s20, 7
	v_lshl_add_u64 v[68:69], v[2:3], 0, s[8:9]
	v_lshl_add_u64 v[2:3], v[6:7], 0, v[4:5]
	v_lshl_add_u64 v[64:65], v[20:21], 0, s[8:9]
	v_add3_u32 v20, v128, s18, v123
	s_mov_b64 s[18:19], 0x8600080
	v_lshl_add_u64 v[2:3], s[6:7], 0, v[2:3]
	v_lshl_add_u64 v[70:71], v[2:3], 0, s[18:19]
	v_lshl_add_u64 v[2:3], v[18:19], 0, v[8:9]
	v_lshl_add_u64 v[2:3], s[6:7], 0, v[2:3]
	v_lshl_add_u64 v[72:73], v[2:3], 0, s[8:9]
	v_lshl_add_u64 v[2:3], v[18:19], 0, v[10:11]
	v_ashrrev_i32_e32 v21, 31, v20
	v_lshl_add_u64 v[2:3], s[6:7], 0, v[2:3]
	v_lshlrev_b64 v[20:21], 13, v[20:21]
	v_lshl_add_u64 v[74:75], v[2:3], 0, s[18:19]
	v_lshl_add_u64 v[2:3], s[12:13], 0, v[16:17]
	v_lshl_add_u64 v[20:21], v[18:19], 0, v[20:21]
	v_lshl_add_u64 v[4:5], v[2:3], 0, v[12:13]
	v_lshl_add_u64 v[2:3], v[2:3], 0, v[14:15]
	v_lshl_add_u64 v[20:21], s[6:7], 0, v[20:21]
	v_lshl_add_u64 v[4:5], s[6:7], 0, v[4:5]
	v_lshl_add_u64 v[2:3], s[6:7], 0, v[2:3]
	v_lshl_add_u64 v[66:67], v[20:21], 0, s[18:19]
	v_lshl_add_u64 v[76:77], v[4:5], 0, s[8:9]
	v_lshl_add_u64 v[78:79], v[2:3], 0, s[18:19]
	s_mov_b64 s[6:7], 0
	v_mov_b32_e32 v0, v1
	v_mov_b32_e32 v2, v1
	v_mov_b32_e32 v3, v1
	v_mov_b32_e32 v4, v1
	v_mov_b32_e32 v5, v1
	v_mov_b32_e32 v6, v1
	v_mov_b32_e32 v7, v1
	v_mov_b32_e32 v8, v1
	v_mov_b32_e32 v9, v1
	v_mov_b32_e32 v10, v1
	v_mov_b32_e32 v11, v1
	v_mov_b32_e32 v12, v1
	v_mov_b32_e32 v13, v1
	v_mov_b32_e32 v14, v1
	v_mov_b32_e32 v15, v1
	v_mov_b32_e32 v16, v1
	v_mov_b32_e32 v17, v1
	v_mov_b32_e32 v18, v1
	v_mov_b32_e32 v19, v1
	v_mov_b32_e32 v20, v1
	v_mov_b32_e32 v21, v1
	v_mov_b32_e32 v22, v1
	v_mov_b32_e32 v23, v1
	v_mov_b32_e32 v24, v1
	v_mov_b32_e32 v25, v1
	v_mov_b32_e32 v26, v1
	v_mov_b32_e32 v27, v1
	v_mov_b32_e32 v28, v1
	v_mov_b32_e32 v29, v1
	v_mov_b32_e32 v30, v1
	v_mov_b32_e32 v31, v1
	s_waitcnt vmcnt(0)
	v_mov_b32_e32 v32, v1
	v_mov_b32_e32 v33, v1
	v_mov_b32_e32 v34, v1
	v_mov_b32_e32 v35, v1
	v_mov_b32_e32 v36, v1
	v_mov_b32_e32 v37, v1
	v_mov_b32_e32 v38, v1
	v_mov_b32_e32 v39, v1
	v_mov_b32_e32 v40, v1
	v_mov_b32_e32 v41, v1
	v_mov_b32_e32 v42, v1
	v_mov_b32_e32 v43, v1
	v_mov_b32_e32 v44, v1
	v_mov_b32_e32 v45, v1
	v_mov_b32_e32 v46, v1
	v_mov_b32_e32 v47, v1
	v_mov_b32_e32 v48, v1
	v_mov_b32_e32 v49, v1
	v_mov_b32_e32 v50, v1
	v_mov_b32_e32 v51, v1
	v_mov_b32_e32 v52, v1
	v_mov_b32_e32 v53, v1
	v_mov_b32_e32 v54, v1
	v_mov_b32_e32 v55, v1
	v_mov_b32_e32 v56, v1
	v_mov_b32_e32 v57, v1
	v_mov_b32_e32 v58, v1
	v_mov_b32_e32 v59, v1
	v_mov_b32_e32 v60, v1
	v_mov_b32_e32 v61, v1
	v_mov_b32_e32 v62, v1
	v_mov_b32_e32 v63, v1
	s_waitcnt lgkmcnt(0)
	s_barrier
	v_add3_u32 v190, 0, v83, v84
	v_add_u32_e32 v191, 0x4000, v190
	s_nop 0
	v_readfirstlane_b32 s82, v191
	v_lshl_add_u32 v191, v118, 1, 0
	s_nop 0
	v_readfirstlane_b32 s83, v190
	v_add3_u32 v191, v191, v84, s17
	s_nop 0
	v_readfirstlane_b32 s84, v191
	v_add_u32_e32 v191, 0x400, v190
	s_nop 0
	v_readfirstlane_b32 s85, v191
	v_lshl_add_u32 v191, v119, 1, 0
	v_add3_u32 v191, v191, v84, s17
	s_nop 0
	v_readfirstlane_b32 s86, v191
	v_add_u32_e32 v191, 0x800, v190
	s_nop 0
	v_readfirstlane_b32 s87, v191
	v_lshl_add_u32 v191, v120, 1, 0
	v_add3_u32 v191, v191, v84, s17
	s_nop 0
	v_readfirstlane_b32 s88, v191
	v_add_u32_e32 v190, 0xc00, v190
	s_nop 0
	v_readfirstlane_b32 s89, v190
	v_subrev_u32_e32 v192, s52, v64
	v_subrev_u32_e32 v193, s52, v66
	v_subrev_u32_e32 v194, s52, v68
	v_subrev_u32_e32 v195, s52, v70
	v_subrev_u32_e32 v196, s52, v72
	v_subrev_u32_e32 v197, s52, v74
	v_subrev_u32_e32 v198, s52, v76
	v_subrev_u32_e32 v199, s52, v78
	v_subrev_u32_e32 v195, 0x400, v195
	v_subrev_u32_e32 v194, 0x400, v194
	v_subrev_u32_e32 v197, 0x800, v197
	v_subrev_u32_e32 v196, 0x800, v196
	v_subrev_u32_e32 v199, 0xc00, v199
	v_subrev_u32_e32 v198, 0xc00, v198
	s_and_b32 s9, s13, 0x4000
	s_xor_b32 s8, s9, 0x4000
	s_lshl_b32 s8, s8, 1
	s_add_i32 s8, s8, 32
	s_lshl_b32 s9, s9, 1
	s_add_i32 s9, s9, 32
.LBB0_2102:
	s_xor_b32 s8, s8, 0x8000
	s_xor_b32 s9, s9, 0x8000
	s_add_u32 s90, s52, s6
	s_addc_u32 s91, s53, s7
	s_add_i32 m0, s9, s83
	v_lshlrev_b32_e32 v85, 1, v80
	global_load_lds_dwordx4 v193, s[90:91]
	global_load_lds_dwordx4 v195, s[90:91] offset:1024
	global_load_lds_dwordx4 v197, s[90:91] offset:2048
	global_load_lds_dwordx4 v199, s[90:91] offset:3072
	s_add_i32 m0, s9, s82
	v_add3_u32 v112, s8, v81, v85
	global_load_lds_dwordx4 v192, s[90:91]
	global_load_lds_dwordx4 v194, s[90:91] offset:1024
	global_load_lds_dwordx4 v196, s[90:91] offset:2048
	global_load_lds_dwordx4 v198, s[90:91] offset:3072
	v_lshlrev_b32_e32 v86, 1, v121
	v_add3_u32 v113, s8, v82, v85
	v_add_u32_e32 v87, v112, v86
	v_add_u32_e32 v123, v113, v86
	ds_read_b128 v[88:91], v87
	ds_read_b128 v[96:99], v123 offset:16384
	ds_read_b128 v[100:103], v123 offset:18432
	ds_read_b128 v[124:127], v123 offset:20480
	ds_read_b128 v[128:131], v123 offset:22528
	ds_read_b128 v[92:95], v87 offset:2048
	ds_read_b128 v[104:107], v87 offset:4096
	ds_read_b128 v[108:111], v87 offset:6144
	v_lshlrev_b32_e32 v87, 1, v122
	v_add_u32_e32 v236, v112, v87
	v_add_u32_e32 v112, v113, v87
	ds_read_b128 v[204:207], v236
	ds_read_b128 v[208:211], v112 offset:16384
	ds_read_b128 v[212:215], v112 offset:18432
	ds_read_b128 v[216:219], v112 offset:20480
	ds_read_b128 v[220:223], v112 offset:22528
	ds_read_b128 v[224:227], v236 offset:2048
	ds_read_b128 v[228:231], v236 offset:4096
	ds_read_b128 v[232:235], v236 offset:6144
	s_setprio 1
	s_waitcnt lgkmcnt(11)
	v_mfma_f32_16x16x32_bf16 v[60:63], v[88:91], v[96:99], v[60:63]
	v_mfma_f32_16x16x32_bf16 v[56:59], v[88:91], v[100:103], v[56:59]
	v_mfma_f32_16x16x32_bf16 v[52:55], v[88:91], v[124:127], v[52:55]
	v_mfma_f32_16x16x32_bf16 v[48:51], v[88:91], v[128:131], v[48:51]
	s_waitcnt lgkmcnt(10)
	v_mfma_f32_16x16x32_bf16 v[44:47], v[92:95], v[96:99], v[44:47]
	v_mfma_f32_16x16x32_bf16 v[40:43], v[92:95], v[100:103], v[40:43]
	v_mfma_f32_16x16x32_bf16 v[36:39], v[92:95], v[124:127], v[36:39]
	v_mfma_f32_16x16x32_bf16 v[32:35], v[92:95], v[128:131], v[32:35]
	s_waitcnt lgkmcnt(9)
	v_mfma_f32_16x16x32_bf16 v[28:31], v[104:107], v[96:99], v[28:31]
	v_mfma_f32_16x16x32_bf16 v[24:27], v[104:107], v[100:103], v[24:27]
	v_mfma_f32_16x16x32_bf16 v[20:23], v[104:107], v[124:127], v[20:23]
	v_mfma_f32_16x16x32_bf16 v[16:19], v[104:107], v[128:131], v[16:19]
	s_waitcnt lgkmcnt(8)
	v_mfma_f32_16x16x32_bf16 v[12:15], v[108:111], v[96:99], v[12:15]
	v_mfma_f32_16x16x32_bf16 v[8:11], v[108:111], v[100:103], v[8:11]
	v_mfma_f32_16x16x32_bf16 v[4:7], v[108:111], v[124:127], v[4:7]
	v_mfma_f32_16x16x32_bf16 v[0:3], v[108:111], v[128:131], v[0:3]
	s_waitcnt lgkmcnt(3)
	v_mfma_f32_16x16x32_bf16 v[60:63], v[204:207], v[208:211], v[60:63]
	v_mfma_f32_16x16x32_bf16 v[56:59], v[204:207], v[212:215], v[56:59]
	v_mfma_f32_16x16x32_bf16 v[52:55], v[204:207], v[216:219], v[52:55]
	v_mfma_f32_16x16x32_bf16 v[48:51], v[204:207], v[220:223], v[48:51]
	s_waitcnt lgkmcnt(2)
	v_mfma_f32_16x16x32_bf16 v[44:47], v[224:227], v[208:211], v[44:47]
	v_mfma_f32_16x16x32_bf16 v[40:43], v[224:227], v[212:215], v[40:43]
	v_mfma_f32_16x16x32_bf16 v[36:39], v[224:227], v[216:219], v[36:39]
	v_mfma_f32_16x16x32_bf16 v[32:35], v[224:227], v[220:223], v[32:35]
	s_waitcnt lgkmcnt(1)
	v_mfma_f32_16x16x32_bf16 v[28:31], v[228:231], v[208:211], v[28:31]
	v_mfma_f32_16x16x32_bf16 v[24:27], v[228:231], v[212:215], v[24:27]
	v_mfma_f32_16x16x32_bf16 v[20:23], v[228:231], v[216:219], v[20:23]
	v_mfma_f32_16x16x32_bf16 v[16:19], v[228:231], v[220:223], v[16:19]
	s_waitcnt lgkmcnt(0)
	v_mfma_f32_16x16x32_bf16 v[12:15], v[232:235], v[208:211], v[12:15]
	v_mfma_f32_16x16x32_bf16 v[8:11], v[232:235], v[212:215], v[8:11]
	v_mfma_f32_16x16x32_bf16 v[4:7], v[232:235], v[216:219], v[4:7]
	v_mfma_f32_16x16x32_bf16 v[0:3], v[232:235], v[220:223], v[0:3]
	s_setprio 0
	s_add_u32 s6, s6, 0x80
	s_addc_u32 s7, s7, 0
	s_cmpk_eq_i32 s6, 0x780
	s_waitcnt vmcnt(0)
	s_barrier
	s_cbranch_scc0 .LBB0_2102
	v_add3_u32 v84, 32, v81, v85
	v_add3_u32 v85, 32, v82, v85
	v_add_u32_e32 v88, v84, v86
	v_add_u32_e32 v86, v85, v86
	ds_read_b128 v[64:67], v88 offset:32768
	ds_read_b128 v[68:71], v88 offset:34816
	ds_read_b128 v[72:75], v86 offset:49152
	ds_read_b128 v[76:79], v86 offset:51200
	ds_read_b128 v[80:83], v88 offset:36864
	ds_read_b128 v[88:91], v88 offset:38912
	ds_read_b128 v[92:95], v86 offset:53248
	ds_read_b128 v[96:99], v86 offset:55296
	v_add_u32_e32 v84, v84, v87
	v_add_u32_e32 v236, v85, v87
	ds_read_b128 v[204:207], v84 offset:32768
	ds_read_b128 v[208:211], v84 offset:34816
	ds_read_b128 v[212:215], v236 offset:49152
	ds_read_b128 v[216:219], v236 offset:51200
	ds_read_b128 v[220:223], v84 offset:36864
	ds_read_b128 v[224:227], v84 offset:38912
	ds_read_b128 v[228:231], v236 offset:53248
	ds_read_b128 v[232:235], v236 offset:55296
	s_setprio 1
	s_waitcnt lgkmcnt(8)
	v_mfma_f32_16x16x32_bf16 v[0:3], v[88:91], v[96:99], v[0:3]
	v_mfma_f32_16x16x32_bf16 v[60:63], v[64:67], v[72:75], v[60:63]
	v_mfma_f32_16x16x32_bf16 v[56:59], v[64:67], v[76:79], v[56:59]
	v_mfma_f32_16x16x32_bf16 v[52:55], v[64:67], v[92:95], v[52:55]
	v_mfma_f32_16x16x32_bf16 v[48:51], v[64:67], v[96:99], v[48:51]
	v_mfma_f32_16x16x32_bf16 v[44:47], v[68:71], v[72:75], v[44:47]
	v_mfma_f32_16x16x32_bf16 v[40:43], v[68:71], v[76:79], v[40:43]
	v_mfma_f32_16x16x32_bf16 v[36:39], v[68:71], v[92:95], v[36:39]
	v_mfma_f32_16x16x32_bf16 v[32:35], v[68:71], v[96:99], v[32:35]
	v_mfma_f32_16x16x32_bf16 v[28:31], v[80:83], v[72:75], v[28:31]
	v_mfma_f32_16x16x32_bf16 v[24:27], v[80:83], v[76:79], v[24:27]
	v_mfma_f32_16x16x32_bf16 v[20:23], v[80:83], v[92:95], v[20:23]
	v_mfma_f32_16x16x32_bf16 v[16:19], v[80:83], v[96:99], v[16:19]
	v_mfma_f32_16x16x32_bf16 v[12:15], v[88:91], v[72:75], v[12:15]
	v_mfma_f32_16x16x32_bf16 v[8:11], v[88:91], v[76:79], v[8:11]
	v_mfma_f32_16x16x32_bf16 v[4:7], v[88:91], v[92:95], v[4:7]
	s_waitcnt lgkmcnt(0)
	v_mfma_f32_16x16x32_bf16 v[0:3], v[224:227], v[232:235], v[0:3]
	v_mfma_f32_16x16x32_bf16 v[60:63], v[204:207], v[212:215], v[60:63]
	v_mfma_f32_16x16x32_bf16 v[56:59], v[204:207], v[216:219], v[56:59]
	v_mfma_f32_16x16x32_bf16 v[52:55], v[204:207], v[228:231], v[52:55]
	v_mfma_f32_16x16x32_bf16 v[48:51], v[204:207], v[232:235], v[48:51]
	v_mfma_f32_16x16x32_bf16 v[44:47], v[208:211], v[212:215], v[44:47]
	v_mfma_f32_16x16x32_bf16 v[40:43], v[208:211], v[216:219], v[40:43]
	v_mfma_f32_16x16x32_bf16 v[36:39], v[208:211], v[228:231], v[36:39]
	v_mfma_f32_16x16x32_bf16 v[32:35], v[208:211], v[232:235], v[32:35]
	v_mfma_f32_16x16x32_bf16 v[28:31], v[220:223], v[212:215], v[28:31]
	v_mfma_f32_16x16x32_bf16 v[24:27], v[220:223], v[216:219], v[24:27]
	v_mfma_f32_16x16x32_bf16 v[20:23], v[220:223], v[228:231], v[20:23]
	v_mfma_f32_16x16x32_bf16 v[16:19], v[220:223], v[232:235], v[16:19]
	v_mfma_f32_16x16x32_bf16 v[12:15], v[224:227], v[212:215], v[12:15]
	v_mfma_f32_16x16x32_bf16 v[8:11], v[224:227], v[216:219], v[8:11]
	v_mfma_f32_16x16x32_bf16 v[4:7], v[224:227], v[228:231], v[4:7]
	s_setprio 0
	v_lshl_or_b32 v64, v114, 2, v116
	v_mul_u32_u24_e32 v64, 0x210, v64
	v_add3_u32 v64, v115, v117, v64
	s_barrier
	ds_write2_b32 v64, v60, v56 offset1:16
	ds_write2_b32 v64, v61, v57 offset0:132 offset1:148
	v_add_u32_e32 v56, 0x400, v64
	ds_write2_b32 v56, v62, v58 offset0:8 offset1:24
	ds_write2_b32 v56, v63, v59 offset0:140 offset1:156
	ds_write2_b32 v64, v52, v48 offset0:32 offset1:48
	ds_write2_b32 v64, v53, v49 offset0:164 offset1:180
	ds_write2_b32 v56, v54, v50 offset0:40 offset1:56
	ds_write2_b32 v56, v55, v51 offset0:172 offset1:188
	v_add_u32_e32 v48, 0x2000, v64
	ds_write2_b32 v48, v44, v40 offset0:64 offset1:80
	ds_write2_b32 v48, v45, v41 offset0:196 offset1:212
	v_add_u32_e32 v40, 0x2400, v64
	ds_write2_b32 v40, v46, v42 offset0:72 offset1:88
	ds_write2_b32 v40, v47, v43 offset0:204 offset1:220
	ds_write2_b32 v48, v36, v32 offset0:96 offset1:112
	ds_write2_b32 v48, v37, v33 offset0:228 offset1:244
	ds_write2_b32 v40, v38, v34 offset0:104 offset1:120
	ds_write2_b32 v40, v39, v35 offset0:236 offset1:252
	v_add_u32_e32 v32, 0x4000, v64
	ds_write2_b32 v32, v28, v24 offset0:128 offset1:144
	v_add_u32_e32 v24, 0x4400, v64
	ds_write2_b32 v24, v29, v25 offset0:4 offset1:20
	ds_write2_b32 v24, v30, v26 offset0:136 offset1:152
	v_add_u32_e32 v25, 0x4800, v64
	ds_write2_b32 v25, v31, v27 offset0:12 offset1:28
	ds_write2_b32 v32, v20, v16 offset0:160 offset1:176
	ds_write2_b32 v24, v21, v17 offset0:36 offset1:52
	ds_write2_b32 v24, v22, v18 offset0:168 offset1:184
	ds_write2_b32 v25, v23, v19 offset0:44 offset1:60
	v_add_u32_e32 v16, 0x6000, v64
	ds_write2_b32 v16, v12, v8 offset0:192 offset1:208
	v_add_u32_e32 v8, 0x6400, v64
	ds_write2_b32 v8, v13, v9 offset0:68 offset1:84
	ds_write2_b32 v8, v14, v10 offset0:200 offset1:216
	v_add_u32_e32 v9, 0x6800, v64
	ds_write2_b32 v9, v15, v11 offset0:76 offset1:92
	ds_write2_b32 v16, v4, v0 offset0:224 offset1:240
	ds_write2_b32 v8, v5, v1 offset0:100 offset1:116
	ds_write2_b32 v8, v6, v2 offset0:232 offset1:248
	ds_write2_b32 v9, v7, v3 offset0:108 offset1:124
	v_lshlrev_b32_e32 v0, 4, v180
	v_and_b32_e32 v0, 0x70, v0
	s_lshl_b32 s7, s16, 23
	v_or_b32_e32 v0, s11, v0
	s_add_u32 s8, s14, s7
	s_addc_u32 s9, s15, 0
	v_lshlrev_b32_e32 v0, 2, v0
	v_mov_b32_e32 v1, 0
	v_lshrrev_b32_e32 v2, 3, v180
	v_and_b32_e32 v4, 7, v180
	v_lshl_add_u64 v[0:1], s[8:9], 0, v[0:1]
	s_mov_b64 s[8:9], 0x11600000
	v_mul_u32_u24_e32 v3, 0x210, v2
	v_lshlrev_b32_e32 v4, 6, v4
	s_mov_b32 s6, 0
	v_lshl_add_u64 v[0:1], v[0:1], 0, s[8:9]
	v_add3_u32 v3, v3, v4, 32
	s_mov_b32 s7, 0x38e38e39
	s_mov_b32 s8, 0x1ffffee
	s_movk_i32 s9, 0xf800
	s_waitcnt lgkmcnt(0)
	s_barrier

.LBB0_2269:
	s_mul_hi_i32 s8, s49, 0x92492493
	s_add_i32 s8, s8, s49
	s_lshr_b32 s9, s8, 31
	s_ashr_i32 s8, s8, 2
	s_add_i32 s8, s8, s9
	s_mul_i32 s9, s8, -7
	s_add_i32 s28, s9, s49
	s_lshl_b32 s29, s28, 7
	v_add_u32_e32 v0, s29, v106
	v_ashrrev_i32_e32 v1, 31, v0
	v_add_u32_e32 v2, 0x4000, v107
	v_lshlrev_b64 v[0:1], 11, v[0:1]
	v_readfirstlane_b32 s9, v2
	s_lshl_b32 s36, s8, 7
	v_lshl_add_u64 v[0:1], v[66:67], 0, v[0:1]
	s_mov_b32 m0, s9
	v_readfirstlane_b32 s9, v107
	global_load_lds_dwordx4 v[0:1], off
	v_add_u32_e32 v0, s36, v106
	v_ashrrev_i32_e32 v1, 31, v0
	v_lshlrev_b64 v[0:1], 11, v[0:1]
	v_lshl_add_u64 v[2:3], v[72:73], 0, v[0:1]
	s_mov_b32 m0, s9
	v_readfirstlane_b32 s9, v131
	global_load_lds_dwordx4 v[2:3], off
	v_add_u32_e32 v2, s29, v108
	v_ashrrev_i32_e32 v3, 31, v2
	v_lshlrev_b64 v[2:3], 11, v[2:3]
	v_lshl_add_u64 v[2:3], v[68:69], 0, v[2:3]
	s_mov_b32 m0, s9
	v_add_u32_e32 v4, 0x400, v107
	global_load_lds_dwordx4 v[2:3], off
	v_add_u32_e32 v2, s36, v108
	v_ashrrev_i32_e32 v3, 31, v2
	v_lshlrev_b64 v[2:3], 11, v[2:3]
	v_readfirstlane_b32 s9, v4
	v_lshl_add_u64 v[2:3], v[74:75], 0, v[2:3]
	s_mov_b32 m0, s9
	v_readfirstlane_b32 s9, v132
	global_load_lds_dwordx4 v[2:3], off
	v_add_u32_e32 v2, s29, v110
	v_ashrrev_i32_e32 v3, 31, v2
	v_lshlrev_b64 v[2:3], 11, v[2:3]
	v_lshl_add_u64 v[2:3], v[66:67], 0, v[2:3]
	s_mov_b32 m0, s9
	v_add_u32_e32 v4, 0x800, v107
	global_load_lds_dwordx4 v[2:3], off
	v_add_u32_e32 v2, s36, v110
	v_ashrrev_i32_e32 v3, 31, v2
	v_lshlrev_b64 v[2:3], 11, v[2:3]
	v_readfirstlane_b32 s9, v4
	v_lshl_add_u64 v[2:3], v[72:73], 0, v[2:3]
	s_mov_b32 m0, s9
	v_readfirstlane_b32 s9, v133
	global_load_lds_dwordx4 v[2:3], off
	v_add_u32_e32 v2, s29, v112
	v_ashrrev_i32_e32 v3, 31, v2
	v_lshlrev_b64 v[2:3], 11, v[2:3]
	v_lshl_add_u64 v[2:3], v[70:71], 0, v[2:3]
	s_mov_b32 m0, s9
	v_add_u32_e32 v4, 0xc00, v107
	global_load_lds_dwordx4 v[2:3], off
	v_add_u32_e32 v2, s36, v112
	v_ashrrev_i32_e32 v3, 31, v2
	v_lshlrev_b64 v[2:3], 11, v[2:3]
	v_readfirstlane_b32 s9, v4
	v_lshl_add_u64 v[2:3], v[76:77], 0, v[2:3]
	s_mov_b32 m0, s9
	s_mulk_i32 s8, 0x380
	global_load_lds_dwordx4 v[2:3], off
	v_lshl_add_u64 v[92:93], v[80:81], 0, v[0:1]
	v_subrev_u32_e32 v0, s8, v123
	v_ashrrev_i32_e32 v1, 31, v0
	v_lshlrev_b64 v[0:1], 11, v[0:1]
	v_lshl_add_u64 v[94:95], v[82:83], 0, v[0:1]
	v_add_u32_e32 v0, s36, v124
	v_ashrrev_i32_e32 v1, 31, v0
	v_lshlrev_b64 v[0:1], 11, v[0:1]
	v_lshl_add_u64 v[96:97], v[84:85], 0, v[0:1]
	v_subrev_u32_e32 v0, s8, v125
	v_ashrrev_i32_e32 v1, 31, v0
	v_lshlrev_b64 v[0:1], 11, v[0:1]
	v_lshl_add_u64 v[98:99], v[78:79], 0, v[0:1]
	v_add_u32_e32 v0, s36, v126
	v_ashrrev_i32_e32 v1, 31, v0
	v_lshlrev_b64 v[0:1], 11, v[0:1]
	v_lshl_add_u64 v[100:101], v[80:81], 0, v[0:1]
	v_subrev_u32_e32 v0, s8, v127
	v_ashrrev_i32_e32 v1, 31, v0
	v_lshlrev_b64 v[0:1], 11, v[0:1]
	v_subrev_u32_e32 v2, s8, v122
	v_lshl_add_u64 v[102:103], v[86:87], 0, v[0:1]
	v_add_u32_e32 v0, s36, v128
	v_ashrrev_i32_e32 v3, 31, v2
	v_ashrrev_i32_e32 v1, 31, v0
	v_lshlrev_b64 v[2:3], 11, v[2:3]
	v_lshlrev_b64 v[0:1], 11, v[0:1]
	v_lshl_add_u64 v[90:91], v[78:79], 0, v[2:3]
	v_lshl_add_u64 v[104:105], v[88:89], 0, v[0:1]
	s_mov_b64 s[8:9], 0
	s_mov_b32 s30, 0
	v_mov_b32_e32 v0, v65
	v_mov_b32_e32 v1, v65
	v_mov_b32_e32 v2, v65
	v_mov_b32_e32 v3, v65
	v_mov_b32_e32 v4, v65
	v_mov_b32_e32 v5, v65
	v_mov_b32_e32 v6, v65
	v_mov_b32_e32 v7, v65
	v_mov_b32_e32 v8, v65
	v_mov_b32_e32 v9, v65
	v_mov_b32_e32 v10, v65
	v_mov_b32_e32 v11, v65
	v_mov_b32_e32 v12, v65
	v_mov_b32_e32 v13, v65
	v_mov_b32_e32 v14, v65
	v_mov_b32_e32 v15, v65
	v_mov_b32_e32 v16, v65
	v_mov_b32_e32 v17, v65
	v_mov_b32_e32 v18, v65
	v_mov_b32_e32 v19, v65
	v_mov_b32_e32 v20, v65
	v_mov_b32_e32 v21, v65
	v_mov_b32_e32 v22, v65
	v_mov_b32_e32 v23, v65
	v_mov_b32_e32 v24, v65
	v_mov_b32_e32 v25, v65
	v_mov_b32_e32 v26, v65
	v_mov_b32_e32 v27, v65
	v_mov_b32_e32 v28, v65
	v_mov_b32_e32 v29, v65
	v_mov_b32_e32 v30, v65
	v_mov_b32_e32 v31, v65
	s_waitcnt vmcnt(0)
	v_mov_b32_e32 v32, v65
	v_mov_b32_e32 v33, v65
	v_mov_b32_e32 v34, v65
	v_mov_b32_e32 v35, v65
	v_mov_b32_e32 v36, v65
	v_mov_b32_e32 v37, v65
	v_mov_b32_e32 v38, v65
	v_mov_b32_e32 v39, v65
	v_mov_b32_e32 v40, v65
	v_mov_b32_e32 v41, v65
	v_mov_b32_e32 v42, v65
	v_mov_b32_e32 v43, v65
	v_mov_b32_e32 v44, v65
	v_mov_b32_e32 v45, v65
	v_mov_b32_e32 v46, v65
	v_mov_b32_e32 v47, v65
	v_mov_b32_e32 v48, v65
	v_mov_b32_e32 v49, v65
	v_mov_b32_e32 v50, v65
	v_mov_b32_e32 v51, v65
	v_mov_b32_e32 v52, v65
	v_mov_b32_e32 v53, v65
	v_mov_b32_e32 v54, v65
	v_mov_b32_e32 v55, v65
	v_mov_b32_e32 v56, v65
	v_mov_b32_e32 v57, v65
	v_mov_b32_e32 v58, v65
	v_mov_b32_e32 v59, v65
	v_mov_b32_e32 v60, v65
	v_mov_b32_e32 v61, v65
	v_mov_b32_e32 v62, v65
	v_mov_b32_e32 v63, v65
	s_waitcnt lgkmcnt(0)
	s_barrier
	v_add3_u32 v182, 0, v134, v135
	v_add_u32_e32 v183, 0x4000, v182
	s_nop 0
	v_readfirstlane_b32 s82, v183
	v_lshl_add_u32 v183, v109, 1, 0
	s_nop 0
	v_readfirstlane_b32 s83, v182
	v_add3_u32 v183, v183, v135, s43
	s_nop 0
	v_readfirstlane_b32 s84, v183
	v_add_u32_e32 v183, 0x400, v182
	s_nop 0
	v_readfirstlane_b32 s85, v183
	v_lshl_add_u32 v183, v111, 1, 0
	v_add3_u32 v183, v183, v135, s43
	s_nop 0
	v_readfirstlane_b32 s86, v183
	v_add_u32_e32 v183, 0x800, v182
	s_nop 0
	v_readfirstlane_b32 s87, v183
	v_lshl_add_u32 v183, v113, 1, 0
	v_add3_u32 v183, v183, v135, s43
	s_nop 0
	v_readfirstlane_b32 s88, v183
	v_add_u32_e32 v182, 0xc00, v182
	s_nop 0
	v_readfirstlane_b32 s89, v182
	v_subrev_u32_e32 v184, s52, v90
	v_subrev_u32_e32 v185, s52, v92
	v_subrev_u32_e32 v186, s52, v94
	v_subrev_u32_e32 v187, s52, v96
	v_subrev_u32_e32 v188, s52, v98
	v_subrev_u32_e32 v189, s52, v100
	v_subrev_u32_e32 v190, s52, v102
	v_subrev_u32_e32 v191, s52, v104
	v_subrev_u32_e32 v187, 0x400, v187
	v_subrev_u32_e32 v186, 0x400, v186
	v_subrev_u32_e32 v189, 0x800, v189
	v_subrev_u32_e32 v188, 0x800, v188
	v_subrev_u32_e32 v191, 0xc00, v191
	v_subrev_u32_e32 v190, 0xc00, v190
	s_and_b32 s34, s30, 0x4000
	s_xor_b32 s31, s34, 0x4000
	s_lshl_b32 s31, s31, 1
	s_add_i32 s31, s31, 32
	s_lshl_b32 s34, s34, 1
	s_add_i32 s34, s34, 32
.LBB0_2270:
	s_xor_b32 s31, s31, 0x8000
	s_xor_b32 s34, s34, 0x8000
	s_add_u32 s90, s52, s8
	s_addc_u32 s91, s53, s9
	s_add_i32 m0, s34, s83
	v_lshl_add_u32 v64, v114, 1, s31
	global_load_lds_dwordx4 v185, s[90:91]
	global_load_lds_dwordx4 v187, s[90:91] offset:1024
	global_load_lds_dwordx4 v189, s[90:91] offset:2048
	global_load_lds_dwordx4 v191, s[90:91] offset:3072
	s_add_i32 m0, s34, s82
	v_lshl_add_u32 v139, v115, 1, s31
	global_load_lds_dwordx4 v184, s[90:91]
	global_load_lds_dwordx4 v186, s[90:91] offset:1024
	global_load_lds_dwordx4 v188, s[90:91] offset:2048
	global_load_lds_dwordx4 v190, s[90:91] offset:3072
	v_add_u32_e32 v160, v64, v136
	v_add_u32_e32 v168, v139, v136
	s_add_u32 s8, s8, 0x80
	s_addc_u32 s9, s9, 0
	ds_read_b128 v[140:143], v160
	ds_read_b128 v[148:151], v168 offset:16384
	ds_read_b128 v[152:155], v168 offset:18432
	ds_read_b128 v[164:167], v168 offset:20480
	ds_read_b128 v[168:171], v168 offset:22528
	ds_read_b128 v[144:147], v160 offset:2048
	ds_read_b128 v[156:159], v160 offset:4096
	ds_read_b128 v[160:163], v160 offset:6144
	v_add_u32_e32 v64, v64, v137
	v_add_u32_e32 v139, v139, v137
	ds_read_b128 v[204:207], v64
	ds_read_b128 v[208:211], v139 offset:16384
	ds_read_b128 v[212:215], v139 offset:18432
	ds_read_b128 v[216:219], v139 offset:20480
	ds_read_b128 v[220:223], v139 offset:22528
	ds_read_b128 v[224:227], v64 offset:2048
	ds_read_b128 v[228:231], v64 offset:4096
	ds_read_b128 v[232:235], v64 offset:6144
	s_setprio 1
	s_waitcnt lgkmcnt(11)
	v_mfma_f32_16x16x32_bf16 v[60:63], v[140:143], v[148:151], v[60:63]
	v_mfma_f32_16x16x32_bf16 v[56:59], v[140:143], v[152:155], v[56:59]
	v_mfma_f32_16x16x32_bf16 v[52:55], v[140:143], v[164:167], v[52:55]
	v_mfma_f32_16x16x32_bf16 v[48:51], v[140:143], v[168:171], v[48:51]
	s_waitcnt lgkmcnt(10)
	v_mfma_f32_16x16x32_bf16 v[44:47], v[144:147], v[148:151], v[44:47]
	v_mfma_f32_16x16x32_bf16 v[40:43], v[144:147], v[152:155], v[40:43]
	v_mfma_f32_16x16x32_bf16 v[36:39], v[144:147], v[164:167], v[36:39]
	v_mfma_f32_16x16x32_bf16 v[32:35], v[144:147], v[168:171], v[32:35]
	s_waitcnt lgkmcnt(9)
	v_mfma_f32_16x16x32_bf16 v[28:31], v[156:159], v[148:151], v[28:31]
	v_mfma_f32_16x16x32_bf16 v[24:27], v[156:159], v[152:155], v[24:27]
	v_mfma_f32_16x16x32_bf16 v[20:23], v[156:159], v[164:167], v[20:23]
	v_mfma_f32_16x16x32_bf16 v[16:19], v[156:159], v[168:171], v[16:19]
	s_waitcnt lgkmcnt(8)
	v_mfma_f32_16x16x32_bf16 v[12:15], v[160:163], v[148:151], v[12:15]
	v_mfma_f32_16x16x32_bf16 v[8:11], v[160:163], v[152:155], v[8:11]
	v_mfma_f32_16x16x32_bf16 v[4:7], v[160:163], v[164:167], v[4:7]
	v_mfma_f32_16x16x32_bf16 v[0:3], v[160:163], v[168:171], v[0:3]
	s_waitcnt lgkmcnt(3)
	v_mfma_f32_16x16x32_bf16 v[60:63], v[204:207], v[208:211], v[60:63]
	v_mfma_f32_16x16x32_bf16 v[56:59], v[204:207], v[212:215], v[56:59]
	v_mfma_f32_16x16x32_bf16 v[52:55], v[204:207], v[216:219], v[52:55]
	v_mfma_f32_16x16x32_bf16 v[48:51], v[204:207], v[220:223], v[48:51]
	s_waitcnt lgkmcnt(2)
	v_mfma_f32_16x16x32_bf16 v[44:47], v[224:227], v[208:211], v[44:47]
	v_mfma_f32_16x16x32_bf16 v[40:43], v[224:227], v[212:215], v[40:43]
	v_mfma_f32_16x16x32_bf16 v[36:39], v[224:227], v[216:219], v[36:39]
	v_mfma_f32_16x16x32_bf16 v[32:35], v[224:227], v[220:223], v[32:35]
	s_waitcnt lgkmcnt(1)
	v_mfma_f32_16x16x32_bf16 v[28:31], v[228:231], v[208:211], v[28:31]
	v_mfma_f32_16x16x32_bf16 v[24:27], v[228:231], v[212:215], v[24:27]
	v_mfma_f32_16x16x32_bf16 v[20:23], v[228:231], v[216:219], v[20:23]
	v_mfma_f32_16x16x32_bf16 v[16:19], v[228:231], v[220:223], v[16:19]
	s_waitcnt lgkmcnt(0)
	v_mfma_f32_16x16x32_bf16 v[12:15], v[232:235], v[208:211], v[12:15]
	v_mfma_f32_16x16x32_bf16 v[8:11], v[232:235], v[212:215], v[8:11]
	v_mfma_f32_16x16x32_bf16 v[4:7], v[232:235], v[216:219], v[4:7]
	v_mfma_f32_16x16x32_bf16 v[0:3], v[232:235], v[220:223], v[0:3]
	s_setprio 0
	s_cmpk_eq_i32 s8, 0x780
	s_waitcnt vmcnt(0)
	s_barrier
	s_cbranch_scc0 .LBB0_2270
	ds_read_b128 v[90:93], v116 offset:55296
	ds_read_b128 v[94:97], v116 offset:53248
	ds_read_b128 v[98:101], v117 offset:38912
	ds_read_b128 v[102:105], v117 offset:36864
	ds_read_b128 v[140:143], v116 offset:51200
	ds_read_b128 v[144:147], v116 offset:49152
	ds_read_b128 v[148:151], v117 offset:34816
	ds_read_b128 v[152:155], v117 offset:32768
	ds_read_b128 v[204:207], v118 offset:32768
	ds_read_b128 v[208:211], v118 offset:34816
	ds_read_b128 v[212:215], v119 offset:49152
	ds_read_b128 v[216:219], v119 offset:51200
	ds_read_b128 v[220:223], v118 offset:36864
	ds_read_b128 v[224:227], v118 offset:38912
	ds_read_b128 v[228:231], v119 offset:53248
	ds_read_b128 v[232:235], v119 offset:55296
	s_setprio 1
	s_waitcnt lgkmcnt(12)
	v_mfma_f32_16x16x32_bf16 v[20:23], v[102:105], v[94:97], v[20:23]
	v_mfma_f32_16x16x32_bf16 v[16:19], v[102:105], v[90:93], v[16:19]
	s_waitcnt lgkmcnt(8)
	v_mfma_f32_16x16x32_bf16 v[60:63], v[152:155], v[144:147], v[60:63]
	v_mfma_f32_16x16x32_bf16 v[56:59], v[152:155], v[140:143], v[56:59]
	v_mfma_f32_16x16x32_bf16 v[52:55], v[152:155], v[94:97], v[52:55]
	v_mfma_f32_16x16x32_bf16 v[48:51], v[152:155], v[90:93], v[48:51]
	v_mfma_f32_16x16x32_bf16 v[44:47], v[148:151], v[144:147], v[44:47]
	v_mfma_f32_16x16x32_bf16 v[40:43], v[148:151], v[140:143], v[40:43]
	v_mfma_f32_16x16x32_bf16 v[36:39], v[148:151], v[94:97], v[36:39]
	v_mfma_f32_16x16x32_bf16 v[32:35], v[148:151], v[90:93], v[32:35]
	v_mfma_f32_16x16x32_bf16 v[28:31], v[102:105], v[144:147], v[28:31]
	v_mfma_f32_16x16x32_bf16 v[24:27], v[102:105], v[140:143], v[24:27]
	v_mfma_f32_16x16x32_bf16 v[12:15], v[98:101], v[144:147], v[12:15]
	v_mfma_f32_16x16x32_bf16 v[8:11], v[98:101], v[140:143], v[8:11]
	v_mfma_f32_16x16x32_bf16 v[4:7], v[98:101], v[94:97], v[4:7]
	v_mfma_f32_16x16x32_bf16 v[0:3], v[98:101], v[90:93], v[0:3]
	s_waitcnt lgkmcnt(1)
	v_mfma_f32_16x16x32_bf16 v[20:23], v[220:223], v[228:231], v[20:23]
	s_waitcnt lgkmcnt(0)
	v_mfma_f32_16x16x32_bf16 v[16:19], v[220:223], v[232:235], v[16:19]
	v_mfma_f32_16x16x32_bf16 v[60:63], v[204:207], v[212:215], v[60:63]
	v_mfma_f32_16x16x32_bf16 v[56:59], v[204:207], v[216:219], v[56:59]
	v_mfma_f32_16x16x32_bf16 v[52:55], v[204:207], v[228:231], v[52:55]
	v_mfma_f32_16x16x32_bf16 v[48:51], v[204:207], v[232:235], v[48:51]
	v_mfma_f32_16x16x32_bf16 v[44:47], v[208:211], v[212:215], v[44:47]
	v_mfma_f32_16x16x32_bf16 v[40:43], v[208:211], v[216:219], v[40:43]
	v_mfma_f32_16x16x32_bf16 v[36:39], v[208:211], v[228:231], v[36:39]
	v_mfma_f32_16x16x32_bf16 v[32:35], v[208:211], v[232:235], v[32:35]
	v_mfma_f32_16x16x32_bf16 v[28:31], v[220:223], v[212:215], v[28:31]
	v_mfma_f32_16x16x32_bf16 v[24:27], v[220:223], v[216:219], v[24:27]
	v_mfma_f32_16x16x32_bf16 v[12:15], v[224:227], v[212:215], v[12:15]
	v_mfma_f32_16x16x32_bf16 v[8:11], v[224:227], v[216:219], v[8:11]
	v_mfma_f32_16x16x32_bf16 v[4:7], v[224:227], v[228:231], v[4:7]
	v_mfma_f32_16x16x32_bf16 v[0:3], v[224:227], v[232:235], v[0:3]
	s_setprio 0
	s_barrier
	ds_write2_b32 v120, v60, v56 offset1:16
	ds_write2_b32 v120, v61, v57 offset0:132 offset1:148
	v_add_u32_e32 v56, 0x400, v120
	ds_write2_b32 v56, v62, v58 offset0:8 offset1:24
	ds_write2_b32 v56, v63, v59 offset0:140 offset1:156
	ds_write2_b32 v120, v52, v48 offset0:32 offset1:48
	ds_write2_b32 v120, v53, v49 offset0:164 offset1:180
	ds_write2_b32 v56, v54, v50 offset0:40 offset1:56
	ds_write2_b32 v56, v55, v51 offset0:172 offset1:188
	v_add_u32_e32 v48, 0x2000, v120
	ds_write2_b32 v48, v44, v40 offset0:64 offset1:80
	ds_write2_b32 v48, v45, v41 offset0:196 offset1:212
	v_add_u32_e32 v40, 0x2400, v120
	ds_write2_b32 v40, v46, v42 offset0:72 offset1:88
	ds_write2_b32 v40, v47, v43 offset0:204 offset1:220
	ds_write2_b32 v48, v36, v32 offset0:96 offset1:112
	ds_write2_b32 v48, v37, v33 offset0:228 offset1:244
	ds_write2_b32 v40, v38, v34 offset0:104 offset1:120
	ds_write2_b32 v40, v39, v35 offset0:236 offset1:252
	v_add_u32_e32 v32, 0x4000, v120
	ds_write2_b32 v32, v28, v24 offset0:128 offset1:144
	v_add_u32_e32 v24, 0x4400, v120
	ds_write2_b32 v24, v29, v25 offset0:4 offset1:20
	ds_write2_b32 v24, v30, v26 offset0:136 offset1:152
	v_add_u32_e32 v25, 0x4800, v120
	s_cmp_gt_i32 s28, 5
	ds_write2_b32 v25, v31, v27 offset0:12 offset1:28
	ds_write2_b32 v32, v20, v16 offset0:160 offset1:176
	ds_write2_b32 v24, v21, v17 offset0:36 offset1:52
	ds_write2_b32 v24, v22, v18 offset0:168 offset1:184
	ds_write2_b32 v25, v23, v19 offset0:44 offset1:60
	v_add_u32_e32 v16, 0x6000, v120
	v_or_b32_e32 v64, s29, v121
	s_cselect_b64 s[30:31], -1, 0
	s_ashr_i32 s29, s28, 31
	ds_write2_b32 v16, v12, v8 offset0:192 offset1:208
	v_add_u32_e32 v8, 0x6400, v120
	s_cmp_gt_i32 s28, 3
	ds_write2_b32 v8, v13, v9 offset0:68 offset1:84
	ds_write2_b32 v8, v14, v10 offset0:200 offset1:216
	v_add_u32_e32 v9, 0x6800, v120
	s_cselect_b64 s[34:35], -1, 0
	s_lshl_b64 s[28:29], s[28:29], 2
	ds_write2_b32 v9, v15, v11 offset0:76 offset1:92
	ds_write2_b32 v16, v4, v0 offset0:224 offset1:240
	ds_write2_b32 v8, v5, v1 offset0:100 offset1:116
	ds_write2_b32 v8, v6, v2 offset0:232 offset1:248
	ds_write2_b32 v9, v7, v3 offset0:108 offset1:124
	v_ashrrev_i32_e32 v1, 31, v64
	v_mov_b32_e32 v0, v64
	v_lshlrev_b64 v[2:3], 1, v[64:65]
	s_add_u32 s28, s40, s28
	v_cmp_gt_u32_e64 s[8:9], s44, v64
	v_lshl_add_u64 v[16:17], s[16:17], 0, v[2:3]
	s_addc_u32 s29, s41, s29
	v_lshl_add_u64 v[18:19], s[14:15], 0, v[2:3]
	v_lshl_add_u64 v[20:21], v[0:1], 1, s[12:13]
	v_add_u32_e32 v22, s36, v129
	s_mov_b32 s50, 0
	s_waitcnt lgkmcnt(0)
	s_barrier
	s_branch .LBB0_2273

.LBB0_2291:
	s_mul_hi_i32 s8, s34, 0x92492493
	s_add_i32 s8, s8, s34
	s_lshr_b32 s9, s8, 31
	s_ashr_i32 s8, s8, 2
	s_add_i32 s8, s8, s9
	s_mul_i32 s9, s8, 0x1fffff9
	s_add_i32 s9, s9, s34
	v_add_u32_e32 v0, s8, v106
	s_lshl_b32 s22, s9, 7
	v_lshlrev_b32_e32 v2, 7, v0
	v_add_u32_e32 v0, s22, v107
	v_ashrrev_i32_e32 v1, 31, v0
	v_add_u32_e32 v3, 0x4000, v108
	v_lshlrev_b64 v[0:1], 11, v[0:1]
	v_readfirstlane_b32 s9, v3
	v_lshl_add_u64 v[0:1], v[66:67], 0, v[0:1]
	s_mov_b32 m0, s9
	v_readfirstlane_b32 s9, v108
	global_load_lds_dwordx4 v[0:1], off
	v_add_u32_e32 v0, v2, v107
	v_ashrrev_i32_e32 v1, 31, v0
	v_lshlrev_b64 v[0:1], 11, v[0:1]
	v_lshl_add_u64 v[0:1], v[72:73], 0, v[0:1]
	s_mov_b32 m0, s9
	v_readfirstlane_b32 s9, v133
	global_load_lds_dwordx4 v[0:1], off
	v_add_u32_e32 v0, s22, v109
	v_ashrrev_i32_e32 v1, 31, v0
	v_lshlrev_b64 v[0:1], 11, v[0:1]
	v_lshl_add_u64 v[0:1], v[68:69], 0, v[0:1]
	s_mov_b32 m0, s9
	v_add_u32_e32 v3, 0x400, v108
	global_load_lds_dwordx4 v[0:1], off
	v_add_u32_e32 v0, v2, v109
	v_ashrrev_i32_e32 v1, 31, v0
	v_lshlrev_b64 v[0:1], 11, v[0:1]
	v_readfirstlane_b32 s9, v3
	v_lshl_add_u64 v[0:1], v[74:75], 0, v[0:1]
	s_mov_b32 m0, s9
	v_readfirstlane_b32 s9, v134
	global_load_lds_dwordx4 v[0:1], off
	v_add_u32_e32 v0, s22, v111
	v_ashrrev_i32_e32 v1, 31, v0
	v_lshlrev_b64 v[0:1], 11, v[0:1]
	v_lshl_add_u64 v[0:1], v[66:67], 0, v[0:1]
	s_mov_b32 m0, s9
	v_add_u32_e32 v3, 0x800, v108
	global_load_lds_dwordx4 v[0:1], off
	v_add_u32_e32 v0, v2, v111
	v_ashrrev_i32_e32 v1, 31, v0
	v_lshlrev_b64 v[0:1], 11, v[0:1]
	v_readfirstlane_b32 s9, v3
	v_lshl_add_u64 v[0:1], v[72:73], 0, v[0:1]
	s_mov_b32 m0, s9
	v_readfirstlane_b32 s9, v135
	global_load_lds_dwordx4 v[0:1], off
	v_add_u32_e32 v0, s22, v113
	v_ashrrev_i32_e32 v1, 31, v0
	v_lshlrev_b64 v[0:1], 11, v[0:1]
	v_lshl_add_u64 v[0:1], v[70:71], 0, v[0:1]
	s_mov_b32 m0, s9
	s_lshl_b32 s28, s8, 7
	global_load_lds_dwordx4 v[0:1], off
	v_add_u32_e32 v0, v2, v113
	v_ashrrev_i32_e32 v1, 31, v0
	v_add_u32_e32 v2, 0xc00, v108
	v_lshlrev_b64 v[0:1], 11, v[0:1]
	v_readfirstlane_b32 s9, v2
	v_lshl_add_u64 v[0:1], v[76:77], 0, v[0:1]
	s_mov_b32 m0, s9
	s_mul_i32 s9, s8, 0x380
	global_load_lds_dwordx4 v[0:1], off
	v_subrev_u32_e32 v0, s9, v123
	v_ashrrev_i32_e32 v1, 31, v0
	v_lshlrev_b64 v[0:1], 11, v[0:1]
	v_lshl_add_u64 v[90:91], v[78:79], 0, v[0:1]
	v_add_u32_e32 v0, s28, v124
	v_ashrrev_i32_e32 v1, 31, v0
	v_lshlrev_b64 v[0:1], 11, v[0:1]
	v_lshl_add_u64 v[92:93], v[80:81], 0, v[0:1]
	v_subrev_u32_e32 v0, s9, v125
	v_ashrrev_i32_e32 v1, 31, v0
	v_lshlrev_b64 v[0:1], 11, v[0:1]
	v_lshl_add_u64 v[94:95], v[82:83], 0, v[0:1]
	v_add_u32_e32 v0, s28, v126
	v_ashrrev_i32_e32 v1, 31, v0
	v_lshlrev_b64 v[0:1], 11, v[0:1]
	v_lshl_add_u64 v[96:97], v[84:85], 0, v[0:1]
	v_subrev_u32_e32 v0, s9, v127
	v_ashrrev_i32_e32 v1, 31, v0
	v_lshlrev_b64 v[0:1], 11, v[0:1]
	v_lshl_add_u64 v[98:99], v[78:79], 0, v[0:1]
	v_add_u32_e32 v0, s28, v128
	v_ashrrev_i32_e32 v1, 31, v0
	v_lshlrev_b64 v[0:1], 11, v[0:1]
	v_lshl_add_u64 v[100:101], v[80:81], 0, v[0:1]
	v_subrev_u32_e32 v0, s9, v129
	v_ashrrev_i32_e32 v1, 31, v0
	v_lshlrev_b64 v[0:1], 11, v[0:1]
	v_lshl_add_u64 v[102:103], v[86:87], 0, v[0:1]
	v_add_u32_e32 v0, s28, v130
	v_ashrrev_i32_e32 v1, 31, v0
	v_lshlrev_b64 v[0:1], 11, v[0:1]
	v_lshl_add_u64 v[104:105], v[88:89], 0, v[0:1]
	v_mov_b32_e32 v0, 0
	s_mov_b64 s[8:9], 0
	s_mov_b32 s23, 0
	v_mov_b32_e32 v1, v0
	v_mov_b32_e32 v2, v0
	v_mov_b32_e32 v3, v0
	v_mov_b32_e32 v4, v0
	v_mov_b32_e32 v5, v0
	v_mov_b32_e32 v6, v0
	v_mov_b32_e32 v7, v0
	v_mov_b32_e32 v8, v0
	v_mov_b32_e32 v9, v0
	v_mov_b32_e32 v10, v0
	v_mov_b32_e32 v11, v0
	v_mov_b32_e32 v12, v0
	v_mov_b32_e32 v13, v0
	v_mov_b32_e32 v14, v0
	v_mov_b32_e32 v15, v0
	v_mov_b32_e32 v16, v0
	v_mov_b32_e32 v17, v0
	v_mov_b32_e32 v18, v0
	v_mov_b32_e32 v19, v0
	v_mov_b32_e32 v20, v0
	v_mov_b32_e32 v21, v0
	v_mov_b32_e32 v22, v0
	v_mov_b32_e32 v23, v0
	v_mov_b32_e32 v24, v0
	v_mov_b32_e32 v25, v0
	v_mov_b32_e32 v26, v0
	v_mov_b32_e32 v27, v0
	v_mov_b32_e32 v28, v0
	v_mov_b32_e32 v29, v0
	v_mov_b32_e32 v30, v0
	v_mov_b32_e32 v31, v0
	s_waitcnt vmcnt(0)
	v_mov_b32_e32 v32, v0
	v_mov_b32_e32 v33, v0
	v_mov_b32_e32 v34, v0
	v_mov_b32_e32 v35, v0
	v_mov_b32_e32 v36, v0
	v_mov_b32_e32 v37, v0
	v_mov_b32_e32 v38, v0
	v_mov_b32_e32 v39, v0
	v_mov_b32_e32 v40, v0
	v_mov_b32_e32 v41, v0
	v_mov_b32_e32 v42, v0
	v_mov_b32_e32 v43, v0
	v_mov_b32_e32 v44, v0
	v_mov_b32_e32 v45, v0
	v_mov_b32_e32 v46, v0
	v_mov_b32_e32 v47, v0
	v_mov_b32_e32 v48, v0
	v_mov_b32_e32 v49, v0
	v_mov_b32_e32 v50, v0
	v_mov_b32_e32 v51, v0
	v_mov_b32_e32 v52, v0
	v_mov_b32_e32 v53, v0
	v_mov_b32_e32 v54, v0
	v_mov_b32_e32 v55, v0
	v_mov_b32_e32 v56, v0
	v_mov_b32_e32 v57, v0
	v_mov_b32_e32 v58, v0
	v_mov_b32_e32 v59, v0
	v_mov_b32_e32 v60, v0
	v_mov_b32_e32 v61, v0
	v_mov_b32_e32 v62, v0
	v_mov_b32_e32 v63, v0
	s_waitcnt lgkmcnt(0)
	s_barrier
	v_add3_u32 v182, 0, v136, v137
	v_add_u32_e32 v183, 0x4000, v182
	s_nop 0
	v_readfirstlane_b32 s82, v183
	v_lshl_add_u32 v183, v110, 1, 0
	s_nop 0
	v_readfirstlane_b32 s83, v182
	v_add3_u32 v183, v183, v137, s37
	s_nop 0
	v_readfirstlane_b32 s84, v183
	v_add_u32_e32 v183, 0x400, v182
	s_nop 0
	v_readfirstlane_b32 s85, v183
	v_lshl_add_u32 v183, v112, 1, 0
	v_add3_u32 v183, v183, v137, s37
	s_nop 0
	v_readfirstlane_b32 s86, v183
	v_add_u32_e32 v183, 0x800, v182
	s_nop 0
	v_readfirstlane_b32 s87, v183
	v_lshl_add_u32 v183, v114, 1, 0
	v_add3_u32 v183, v183, v137, s37
	s_nop 0
	v_readfirstlane_b32 s88, v183
	v_add_u32_e32 v182, 0xc00, v182
	s_nop 0
	v_readfirstlane_b32 s89, v182
	v_subrev_u32_e32 v184, s52, v90
	v_subrev_u32_e32 v185, s52, v92
	v_subrev_u32_e32 v186, s52, v94
	v_subrev_u32_e32 v187, s52, v96
	v_subrev_u32_e32 v188, s52, v98
	v_subrev_u32_e32 v189, s52, v100
	v_subrev_u32_e32 v190, s52, v102
	v_subrev_u32_e32 v191, s52, v104
	v_subrev_u32_e32 v187, 0x400, v187
	v_subrev_u32_e32 v186, 0x400, v186
	v_subrev_u32_e32 v189, 0x800, v189
	v_subrev_u32_e32 v188, 0x800, v188
	v_subrev_u32_e32 v191, 0xc00, v191
	v_subrev_u32_e32 v190, 0xc00, v190
	s_and_b32 s25, s23, 0x4000
	s_xor_b32 s24, s25, 0x4000
	s_lshl_b32 s24, s24, 1
	s_add_i32 s24, s24, 32
	s_lshl_b32 s25, s25, 1
	s_add_i32 s25, s25, 32
.LBB0_2292:
	s_xor_b32 s24, s24, 0x8000
	s_xor_b32 s25, s25, 0x8000
	s_add_u32 s90, s52, s8
	s_addc_u32 s91, s53, s9
	s_add_i32 m0, s25, s83
	v_lshl_add_u32 v64, v115, 1, s24
	global_load_lds_dwordx4 v185, s[90:91]
	global_load_lds_dwordx4 v187, s[90:91] offset:1024
	global_load_lds_dwordx4 v189, s[90:91] offset:2048
	global_load_lds_dwordx4 v191, s[90:91] offset:3072
	s_add_i32 m0, s25, s82
	v_lshl_add_u32 v141, v116, 1, s24
	global_load_lds_dwordx4 v184, s[90:91]
	global_load_lds_dwordx4 v186, s[90:91] offset:1024
	global_load_lds_dwordx4 v188, s[90:91] offset:2048
	global_load_lds_dwordx4 v190, s[90:91] offset:3072
	v_add_u32_e32 v162, v64, v138
	v_add_u32_e32 v170, v141, v138
	s_add_u32 s8, s8, 0x80
	s_addc_u32 s9, s9, 0
	ds_read_b128 v[142:145], v162
	ds_read_b128 v[150:153], v170 offset:16384
	ds_read_b128 v[154:157], v170 offset:18432
	ds_read_b128 v[166:169], v170 offset:20480
	ds_read_b128 v[170:173], v170 offset:22528
	ds_read_b128 v[146:149], v162 offset:2048
	ds_read_b128 v[158:161], v162 offset:4096
	ds_read_b128 v[162:165], v162 offset:6144
	v_add_u32_e32 v64, v64, v139
	v_add_u32_e32 v141, v141, v139
	ds_read_b128 v[204:207], v64
	ds_read_b128 v[208:211], v141 offset:16384
	ds_read_b128 v[212:215], v141 offset:18432
	ds_read_b128 v[216:219], v141 offset:20480
	ds_read_b128 v[220:223], v141 offset:22528
	ds_read_b128 v[224:227], v64 offset:2048
	ds_read_b128 v[228:231], v64 offset:4096
	ds_read_b128 v[232:235], v64 offset:6144
	s_setprio 1
	s_waitcnt lgkmcnt(11)
	v_mfma_f32_16x16x32_bf16 v[60:63], v[142:145], v[150:153], v[60:63]
	v_mfma_f32_16x16x32_bf16 v[56:59], v[142:145], v[154:157], v[56:59]
	v_mfma_f32_16x16x32_bf16 v[52:55], v[142:145], v[166:169], v[52:55]
	v_mfma_f32_16x16x32_bf16 v[48:51], v[142:145], v[170:173], v[48:51]
	s_waitcnt lgkmcnt(10)
	v_mfma_f32_16x16x32_bf16 v[44:47], v[146:149], v[150:153], v[44:47]
	v_mfma_f32_16x16x32_bf16 v[40:43], v[146:149], v[154:157], v[40:43]
	v_mfma_f32_16x16x32_bf16 v[36:39], v[146:149], v[166:169], v[36:39]
	v_mfma_f32_16x16x32_bf16 v[32:35], v[146:149], v[170:173], v[32:35]
	s_waitcnt lgkmcnt(9)
	v_mfma_f32_16x16x32_bf16 v[28:31], v[158:161], v[150:153], v[28:31]
	v_mfma_f32_16x16x32_bf16 v[24:27], v[158:161], v[154:157], v[24:27]
	v_mfma_f32_16x16x32_bf16 v[20:23], v[158:161], v[166:169], v[20:23]
	v_mfma_f32_16x16x32_bf16 v[16:19], v[158:161], v[170:173], v[16:19]
	s_waitcnt lgkmcnt(8)
	v_mfma_f32_16x16x32_bf16 v[12:15], v[162:165], v[150:153], v[12:15]
	v_mfma_f32_16x16x32_bf16 v[8:11], v[162:165], v[154:157], v[8:11]
	v_mfma_f32_16x16x32_bf16 v[4:7], v[162:165], v[166:169], v[4:7]
	v_mfma_f32_16x16x32_bf16 v[0:3], v[162:165], v[170:173], v[0:3]
	s_waitcnt lgkmcnt(3)
	v_mfma_f32_16x16x32_bf16 v[60:63], v[204:207], v[208:211], v[60:63]
	v_mfma_f32_16x16x32_bf16 v[56:59], v[204:207], v[212:215], v[56:59]
	v_mfma_f32_16x16x32_bf16 v[52:55], v[204:207], v[216:219], v[52:55]
	v_mfma_f32_16x16x32_bf16 v[48:51], v[204:207], v[220:223], v[48:51]
	s_waitcnt lgkmcnt(2)
	v_mfma_f32_16x16x32_bf16 v[44:47], v[224:227], v[208:211], v[44:47]
	v_mfma_f32_16x16x32_bf16 v[40:43], v[224:227], v[212:215], v[40:43]
	v_mfma_f32_16x16x32_bf16 v[36:39], v[224:227], v[216:219], v[36:39]
	v_mfma_f32_16x16x32_bf16 v[32:35], v[224:227], v[220:223], v[32:35]
	s_waitcnt lgkmcnt(1)
	v_mfma_f32_16x16x32_bf16 v[28:31], v[228:231], v[208:211], v[28:31]
	v_mfma_f32_16x16x32_bf16 v[24:27], v[228:231], v[212:215], v[24:27]
	v_mfma_f32_16x16x32_bf16 v[20:23], v[228:231], v[216:219], v[20:23]
	v_mfma_f32_16x16x32_bf16 v[16:19], v[228:231], v[220:223], v[16:19]
	s_waitcnt lgkmcnt(0)
	v_mfma_f32_16x16x32_bf16 v[12:15], v[232:235], v[208:211], v[12:15]
	v_mfma_f32_16x16x32_bf16 v[8:11], v[232:235], v[212:215], v[8:11]
	v_mfma_f32_16x16x32_bf16 v[4:7], v[232:235], v[216:219], v[4:7]
	v_mfma_f32_16x16x32_bf16 v[0:3], v[232:235], v[220:223], v[0:3]
	s_setprio 0
	s_cmpk_eq_i32 s8, 0x780
	s_waitcnt vmcnt(0)
	s_barrier
	s_cbranch_scc0 .LBB0_2292
	ds_read_b128 v[90:93], v117 offset:55296
	ds_read_b128 v[94:97], v117 offset:53248
	ds_read_b128 v[98:101], v118 offset:38912
	ds_read_b128 v[102:105], v118 offset:36864
	ds_read_b128 v[142:145], v117 offset:51200
	ds_read_b128 v[146:149], v117 offset:49152
	ds_read_b128 v[150:153], v118 offset:34816
	ds_read_b128 v[154:157], v118 offset:32768
	ds_read_b128 v[204:207], v119 offset:32768
	ds_read_b128 v[208:211], v119 offset:34816
	ds_read_b128 v[212:215], v120 offset:49152
	ds_read_b128 v[216:219], v120 offset:51200
	ds_read_b128 v[220:223], v119 offset:36864
	ds_read_b128 v[224:227], v119 offset:38912
	ds_read_b128 v[228:231], v120 offset:53248
	ds_read_b128 v[232:235], v120 offset:55296
	s_setprio 1
	s_waitcnt lgkmcnt(12)
	v_mfma_f32_16x16x32_bf16 v[20:23], v[102:105], v[94:97], v[20:23]
	v_mfma_f32_16x16x32_bf16 v[16:19], v[102:105], v[90:93], v[16:19]
	s_waitcnt lgkmcnt(8)
	v_mfma_f32_16x16x32_bf16 v[60:63], v[154:157], v[146:149], v[60:63]
	v_mfma_f32_16x16x32_bf16 v[56:59], v[154:157], v[142:145], v[56:59]
	v_mfma_f32_16x16x32_bf16 v[52:55], v[154:157], v[94:97], v[52:55]
	v_mfma_f32_16x16x32_bf16 v[48:51], v[154:157], v[90:93], v[48:51]
	v_mfma_f32_16x16x32_bf16 v[44:47], v[150:153], v[146:149], v[44:47]
	v_mfma_f32_16x16x32_bf16 v[40:43], v[150:153], v[142:145], v[40:43]
	v_mfma_f32_16x16x32_bf16 v[36:39], v[150:153], v[94:97], v[36:39]
	v_mfma_f32_16x16x32_bf16 v[32:35], v[150:153], v[90:93], v[32:35]
	v_mfma_f32_16x16x32_bf16 v[28:31], v[102:105], v[146:149], v[28:31]
	v_mfma_f32_16x16x32_bf16 v[24:27], v[102:105], v[142:145], v[24:27]
	v_mfma_f32_16x16x32_bf16 v[12:15], v[98:101], v[146:149], v[12:15]
	v_mfma_f32_16x16x32_bf16 v[8:11], v[98:101], v[142:145], v[8:11]
	v_mfma_f32_16x16x32_bf16 v[4:7], v[98:101], v[94:97], v[4:7]
	v_mfma_f32_16x16x32_bf16 v[0:3], v[98:101], v[90:93], v[0:3]
	s_waitcnt lgkmcnt(1)
	v_mfma_f32_16x16x32_bf16 v[20:23], v[220:223], v[228:231], v[20:23]
	s_waitcnt lgkmcnt(0)
	v_mfma_f32_16x16x32_bf16 v[16:19], v[220:223], v[232:235], v[16:19]
	v_mfma_f32_16x16x32_bf16 v[60:63], v[204:207], v[212:215], v[60:63]
	v_mfma_f32_16x16x32_bf16 v[56:59], v[204:207], v[216:219], v[56:59]
	v_mfma_f32_16x16x32_bf16 v[52:55], v[204:207], v[228:231], v[52:55]
	v_mfma_f32_16x16x32_bf16 v[48:51], v[204:207], v[232:235], v[48:51]
	v_mfma_f32_16x16x32_bf16 v[44:47], v[208:211], v[212:215], v[44:47]
	v_mfma_f32_16x16x32_bf16 v[40:43], v[208:211], v[216:219], v[40:43]
	v_mfma_f32_16x16x32_bf16 v[36:39], v[208:211], v[228:231], v[36:39]
	v_mfma_f32_16x16x32_bf16 v[32:35], v[208:211], v[232:235], v[32:35]
	v_mfma_f32_16x16x32_bf16 v[28:31], v[220:223], v[212:215], v[28:31]
	v_mfma_f32_16x16x32_bf16 v[24:27], v[220:223], v[216:219], v[24:27]
	v_mfma_f32_16x16x32_bf16 v[12:15], v[224:227], v[212:215], v[12:15]
	v_mfma_f32_16x16x32_bf16 v[8:11], v[224:227], v[216:219], v[8:11]
	v_mfma_f32_16x16x32_bf16 v[4:7], v[224:227], v[228:231], v[4:7]
	v_mfma_f32_16x16x32_bf16 v[0:3], v[224:227], v[232:235], v[0:3]
	s_setprio 0
	s_barrier
	ds_write2_b32 v121, v60, v56 offset1:16
	ds_write2_b32 v121, v61, v57 offset0:132 offset1:148
	v_add_u32_e32 v56, 0x400, v121
	ds_write2_b32 v56, v62, v58 offset0:8 offset1:24
	ds_write2_b32 v56, v63, v59 offset0:140 offset1:156
	ds_write2_b32 v121, v52, v48 offset0:32 offset1:48
	ds_write2_b32 v121, v53, v49 offset0:164 offset1:180
	ds_write2_b32 v56, v54, v50 offset0:40 offset1:56
	ds_write2_b32 v56, v55, v51 offset0:172 offset1:188
	v_add_u32_e32 v48, 0x2000, v121
	ds_write2_b32 v48, v44, v40 offset0:64 offset1:80
	ds_write2_b32 v48, v45, v41 offset0:196 offset1:212
	v_add_u32_e32 v40, 0x2400, v121
	ds_write2_b32 v40, v46, v42 offset0:72 offset1:88
	ds_write2_b32 v40, v47, v43 offset0:204 offset1:220
	ds_write2_b32 v48, v36, v32 offset0:96 offset1:112
	ds_write2_b32 v48, v37, v33 offset0:228 offset1:244
	ds_write2_b32 v40, v38, v34 offset0:104 offset1:120
	ds_write2_b32 v40, v39, v35 offset0:236 offset1:252
	v_add_u32_e32 v32, 0x4000, v121
	ds_write2_b32 v32, v28, v24 offset0:128 offset1:144
	v_add_u32_e32 v24, 0x4400, v121
	s_ashr_i32 s26, s22, 7
	ds_write2_b32 v24, v29, v25 offset0:4 offset1:20
	ds_write2_b32 v24, v30, v26 offset0:136 offset1:152
	v_add_u32_e32 v25, 0x4800, v121
	s_cmp_gt_i32 s26, 5
	ds_write2_b32 v25, v31, v27 offset0:12 offset1:28
	ds_write2_b32 v32, v20, v16 offset0:160 offset1:176
	ds_write2_b32 v24, v21, v17 offset0:36 offset1:52
	ds_write2_b32 v24, v22, v18 offset0:168 offset1:184
	ds_write2_b32 v25, v23, v19 offset0:44 offset1:60
	v_add_u32_e32 v16, 0x6000, v121
	v_or_b32_e32 v64, s22, v122
	s_cselect_b64 s[22:23], -1, 0
	s_ashr_i32 s27, s26, 31
	ds_write2_b32 v16, v12, v8 offset0:192 offset1:208
	v_add_u32_e32 v8, 0x6400, v121
	s_cmp_gt_i32 s26, 3
	ds_write2_b32 v8, v13, v9 offset0:68 offset1:84
	ds_write2_b32 v8, v14, v10 offset0:200 offset1:216
	v_add_u32_e32 v9, 0x6800, v121
	s_cselect_b64 s[24:25], -1, 0
	s_lshl_b64 s[26:27], s[26:27], 2
	ds_write2_b32 v9, v15, v11 offset0:76 offset1:92
	ds_write2_b32 v16, v4, v0 offset0:224 offset1:240
	ds_write2_b32 v8, v5, v1 offset0:100 offset1:116
	ds_write2_b32 v8, v6, v2 offset0:232 offset1:248
	ds_write2_b32 v9, v7, v3 offset0:108 offset1:124
	v_ashrrev_i32_e32 v1, 31, v64
	v_mov_b32_e32 v0, v64
	v_lshlrev_b64 v[2:3], 1, v[64:65]
	s_add_u32 s26, s40, s26
	v_cmp_gt_u32_e64 s[8:9], s38, v64
	v_lshl_add_u64 v[16:17], s[16:17], 0, v[2:3]
	s_addc_u32 s27, s41, s27
	v_lshl_add_u64 v[18:19], s[14:15], 0, v[2:3]
	v_lshl_add_u64 v[20:21], v[0:1], 1, s[12:13]
	v_add_u32_e32 v22, s28, v131
	s_mov_b32 s43, 0
	s_waitcnt lgkmcnt(0)
	s_barrier
	s_branch .LBB0_2295

.LBB0_2975:
	s_mul_hi_i32 s4, s43, 0x51eb851f
	s_lshr_b32 s5, s4, 31
	s_ashr_i32 s4, s4, 3
	s_add_i32 s4, s4, s5
	s_mul_i32 s5, s4, 0xffffffe7
	s_add_i32 s5, s5, s43
	s_lshl_b32 s6, s5, 7
	v_add_u32_e32 v0, s6, v106
	v_ashrrev_i32_e32 v1, 31, v0
	v_add_u32_e32 v2, 0x4000, v107
	v_lshlrev_b64 v[0:1], 11, v[0:1]
	v_readfirstlane_b32 s5, v2
	s_lshl_b32 s36, s4, 7
	v_lshl_add_u64 v[0:1], v[66:67], 0, v[0:1]
	s_mov_b32 m0, s5
	v_readfirstlane_b32 s5, v107
	global_load_lds_dwordx4 v[0:1], off
	v_add_u32_e32 v0, s36, v106
	v_ashrrev_i32_e32 v1, 31, v0
	v_lshlrev_b64 v[0:1], 11, v[0:1]
	v_lshl_add_u64 v[2:3], v[72:73], 0, v[0:1]
	s_mov_b32 m0, s5
	v_readfirstlane_b32 s5, v131
	global_load_lds_dwordx4 v[2:3], off
	v_add_u32_e32 v2, s6, v108
	v_ashrrev_i32_e32 v3, 31, v2
	v_lshlrev_b64 v[2:3], 11, v[2:3]
	v_lshl_add_u64 v[2:3], v[68:69], 0, v[2:3]
	s_mov_b32 m0, s5
	v_add_u32_e32 v4, 0x400, v107
	global_load_lds_dwordx4 v[2:3], off
	v_add_u32_e32 v2, s36, v108
	v_ashrrev_i32_e32 v3, 31, v2
	v_lshlrev_b64 v[2:3], 11, v[2:3]
	v_readfirstlane_b32 s5, v4
	v_lshl_add_u64 v[2:3], v[74:75], 0, v[2:3]
	s_mov_b32 m0, s5
	v_readfirstlane_b32 s5, v132
	global_load_lds_dwordx4 v[2:3], off
	v_add_u32_e32 v2, s6, v110
	v_ashrrev_i32_e32 v3, 31, v2
	v_lshlrev_b64 v[2:3], 11, v[2:3]
	v_lshl_add_u64 v[2:3], v[66:67], 0, v[2:3]
	s_mov_b32 m0, s5
	v_add_u32_e32 v4, 0x800, v107
	global_load_lds_dwordx4 v[2:3], off
	v_add_u32_e32 v2, s36, v110
	v_ashrrev_i32_e32 v3, 31, v2
	v_lshlrev_b64 v[2:3], 11, v[2:3]
	v_readfirstlane_b32 s5, v4
	v_lshl_add_u64 v[2:3], v[72:73], 0, v[2:3]
	s_mov_b32 m0, s5
	v_readfirstlane_b32 s5, v133
	global_load_lds_dwordx4 v[2:3], off
	v_add_u32_e32 v2, s6, v112
	v_ashrrev_i32_e32 v3, 31, v2
	v_lshlrev_b64 v[2:3], 11, v[2:3]
	v_lshl_add_u64 v[2:3], v[70:71], 0, v[2:3]
	s_mov_b32 m0, s5
	v_add_u32_e32 v4, 0xc00, v107
	global_load_lds_dwordx4 v[2:3], off
	v_add_u32_e32 v2, s36, v112
	v_ashrrev_i32_e32 v3, 31, v2
	v_lshlrev_b64 v[2:3], 11, v[2:3]
	v_readfirstlane_b32 s5, v4
	v_lshl_add_u64 v[2:3], v[76:77], 0, v[2:3]
	s_mov_b32 m0, s5
	s_mulk_i32 s4, 0xc80
	global_load_lds_dwordx4 v[2:3], off
	v_lshl_add_u64 v[92:93], v[80:81], 0, v[0:1]
	v_subrev_u32_e32 v0, s4, v123
	v_ashrrev_i32_e32 v1, 31, v0
	v_lshlrev_b64 v[0:1], 11, v[0:1]
	v_lshl_add_u64 v[94:95], v[82:83], 0, v[0:1]
	v_add_u32_e32 v0, s36, v124
	v_ashrrev_i32_e32 v1, 31, v0
	v_lshlrev_b64 v[0:1], 11, v[0:1]
	v_lshl_add_u64 v[96:97], v[84:85], 0, v[0:1]
	v_subrev_u32_e32 v0, s4, v125
	v_ashrrev_i32_e32 v1, 31, v0
	v_lshlrev_b64 v[0:1], 11, v[0:1]
	v_lshl_add_u64 v[98:99], v[78:79], 0, v[0:1]
	v_add_u32_e32 v0, s36, v126
	v_ashrrev_i32_e32 v1, 31, v0
	v_lshlrev_b64 v[0:1], 11, v[0:1]
	v_lshl_add_u64 v[100:101], v[80:81], 0, v[0:1]
	v_subrev_u32_e32 v0, s4, v127
	v_ashrrev_i32_e32 v1, 31, v0
	v_lshlrev_b64 v[0:1], 11, v[0:1]
	v_subrev_u32_e32 v2, s4, v122
	v_lshl_add_u64 v[102:103], v[86:87], 0, v[0:1]
	v_add_u32_e32 v0, s36, v128
	v_ashrrev_i32_e32 v3, 31, v2
	v_ashrrev_i32_e32 v1, 31, v0
	v_lshlrev_b64 v[2:3], 11, v[2:3]
	v_lshlrev_b64 v[0:1], 11, v[0:1]
	v_lshl_add_u64 v[90:91], v[78:79], 0, v[2:3]
	v_lshl_add_u64 v[104:105], v[88:89], 0, v[0:1]
	s_mov_b32 s7, 0
	s_mov_b64 s[4:5], 0
	v_mov_b32_e32 v0, 0
	v_mov_b32_e32 v1, v65
	v_mov_b32_e32 v2, v65
	v_mov_b32_e32 v3, v65
	v_mov_b32_e32 v4, 0
	v_mov_b32_e32 v5, v65
	v_mov_b32_e32 v6, v65
	v_mov_b32_e32 v7, v65
	v_mov_b32_e32 v8, 0
	v_mov_b32_e32 v9, v65
	v_mov_b32_e32 v10, v65
	v_mov_b32_e32 v11, v65
	v_mov_b32_e32 v12, 0
	v_mov_b32_e32 v13, v65
	v_mov_b32_e32 v14, v65
	v_mov_b32_e32 v15, v65
	v_mov_b32_e32 v16, 0
	v_mov_b32_e32 v17, v65
	v_mov_b32_e32 v18, v65
	v_mov_b32_e32 v19, v65
	v_mov_b32_e32 v20, 0
	v_mov_b32_e32 v21, v65
	v_mov_b32_e32 v22, v65
	v_mov_b32_e32 v23, v65
	v_mov_b32_e32 v24, 0
	v_mov_b32_e32 v25, v65
	v_mov_b32_e32 v26, v65
	v_mov_b32_e32 v27, v65
	v_mov_b32_e32 v28, 0
	v_mov_b32_e32 v29, v65
	v_mov_b32_e32 v30, v65
	v_mov_b32_e32 v31, v65
	v_mov_b32_e32 v32, 0
	v_mov_b32_e32 v33, v65
	v_mov_b32_e32 v34, v65
	v_mov_b32_e32 v35, v65
	v_mov_b32_e32 v36, 0
	v_mov_b32_e32 v37, v65
	v_mov_b32_e32 v38, v65
	v_mov_b32_e32 v39, v65
	v_mov_b32_e32 v40, 0
	v_mov_b32_e32 v41, v65
	v_mov_b32_e32 v42, v65
	v_mov_b32_e32 v43, v65
	v_mov_b32_e32 v44, 0
	v_mov_b32_e32 v45, v65
	v_mov_b32_e32 v46, v65
	v_mov_b32_e32 v47, v65
	v_mov_b32_e32 v48, 0
	v_mov_b32_e32 v49, v65
	v_mov_b32_e32 v50, v65
	v_mov_b32_e32 v51, v65
	v_mov_b32_e32 v52, 0
	v_mov_b32_e32 v53, v65
	v_mov_b32_e32 v54, v65
	v_mov_b32_e32 v55, v65
	v_mov_b32_e32 v56, 0
	v_mov_b32_e32 v57, v65
	v_mov_b32_e32 v58, v65
	v_mov_b32_e32 v59, v65
	v_mov_b32_e32 v60, 0
	v_mov_b32_e32 v61, v65
	v_mov_b32_e32 v62, v65
	v_mov_b32_e32 v63, v65
	s_waitcnt vmcnt(0) lgkmcnt(0)
	s_barrier
	v_add3_u32 v182, 0, v134, v135
	v_add_u32_e32 v183, 0x4000, v182
	s_nop 0
	v_readfirstlane_b32 s82, v183
	v_lshl_add_u32 v183, v109, 1, 0
	s_nop 0
	v_readfirstlane_b32 s83, v182
	v_add3_u32 v183, v183, v135, s40
	s_nop 0
	v_readfirstlane_b32 s84, v183
	v_add_u32_e32 v183, 0x400, v182
	s_nop 0
	v_readfirstlane_b32 s85, v183
	v_lshl_add_u32 v183, v111, 1, 0
	v_add3_u32 v183, v183, v135, s40
	s_nop 0
	v_readfirstlane_b32 s86, v183
	v_add_u32_e32 v183, 0x800, v182
	s_nop 0
	v_readfirstlane_b32 s87, v183
	v_lshl_add_u32 v183, v113, 1, 0
	v_add3_u32 v183, v183, v135, s40
	s_nop 0
	v_readfirstlane_b32 s88, v183
	v_add_u32_e32 v182, 0xc00, v182
	s_nop 0
	v_readfirstlane_b32 s89, v182
	v_subrev_u32_e32 v184, s52, v90
	v_subrev_u32_e32 v185, s52, v92
	v_subrev_u32_e32 v186, s52, v94
	v_subrev_u32_e32 v187, s52, v96
	v_subrev_u32_e32 v188, s52, v98
	v_subrev_u32_e32 v189, s52, v100
	v_subrev_u32_e32 v190, s52, v102
	v_subrev_u32_e32 v191, s52, v104
	v_subrev_u32_e32 v187, 0x400, v187
	v_subrev_u32_e32 v186, 0x400, v186
	v_subrev_u32_e32 v189, 0x800, v189
	v_subrev_u32_e32 v188, 0x800, v188
	v_subrev_u32_e32 v191, 0xc00, v191
	v_subrev_u32_e32 v190, 0xc00, v190
	s_and_b32 s29, s7, 0x4000
	s_xor_b32 s28, s29, 0x4000
	s_lshl_b32 s28, s28, 1
	s_add_i32 s28, s28, 32
	s_lshl_b32 s29, s29, 1
	s_add_i32 s29, s29, 32
.LBB0_2976:
	s_xor_b32 s28, s28, 0x8000
	s_xor_b32 s29, s29, 0x8000
	s_add_u32 s90, s52, s4
	s_addc_u32 s91, s53, s5
	s_add_i32 m0, s29, s83
	v_lshl_add_u32 v64, v114, 1, s28
	global_load_lds_dwordx4 v185, s[90:91]
	global_load_lds_dwordx4 v187, s[90:91] offset:1024
	global_load_lds_dwordx4 v189, s[90:91] offset:2048
	global_load_lds_dwordx4 v191, s[90:91] offset:3072
	s_add_i32 m0, s29, s82
	v_lshl_add_u32 v170, v115, 1, s28
	global_load_lds_dwordx4 v184, s[90:91]
	global_load_lds_dwordx4 v186, s[90:91] offset:1024
	global_load_lds_dwordx4 v188, s[90:91] offset:2048
	global_load_lds_dwordx4 v190, s[90:91] offset:3072
	v_add_u32_e32 v158, v64, v136
	v_add_u32_e32 v166, v170, v136
	s_addk_i32 s7, 0x4000
	s_add_u32 s4, s4, 0x80
	s_addc_u32 s5, s5, 0
	ds_read_b128 v[138:141], v158
	ds_read_b128 v[146:149], v166 offset:16384
	ds_read_b128 v[150:153], v166 offset:18432
	ds_read_b128 v[162:165], v166 offset:20480
	ds_read_b128 v[166:169], v166 offset:22528
	ds_read_b128 v[142:145], v158 offset:2048
	ds_read_b128 v[154:157], v158 offset:4096
	ds_read_b128 v[158:161], v158 offset:6144
	v_add_u32_e32 v64, v64, v137
	v_add_u32_e32 v236, v170, v137
	ds_read_b128 v[204:207], v64
	ds_read_b128 v[208:211], v236 offset:16384
	ds_read_b128 v[212:215], v236 offset:18432
	ds_read_b128 v[216:219], v236 offset:20480
	ds_read_b128 v[220:223], v236 offset:22528
	ds_read_b128 v[224:227], v64 offset:2048
	ds_read_b128 v[228:231], v64 offset:4096
	ds_read_b128 v[232:235], v64 offset:6144
	s_setprio 1
	s_waitcnt lgkmcnt(11)
	v_mfma_f32_16x16x32_bf16 v[60:63], v[138:141], v[146:149], v[60:63]
	v_mfma_f32_16x16x32_bf16 v[56:59], v[138:141], v[150:153], v[56:59]
	v_mfma_f32_16x16x32_bf16 v[52:55], v[138:141], v[162:165], v[52:55]
	v_mfma_f32_16x16x32_bf16 v[48:51], v[138:141], v[166:169], v[48:51]
	s_waitcnt lgkmcnt(10)
	v_mfma_f32_16x16x32_bf16 v[44:47], v[142:145], v[146:149], v[44:47]
	v_mfma_f32_16x16x32_bf16 v[40:43], v[142:145], v[150:153], v[40:43]
	v_mfma_f32_16x16x32_bf16 v[36:39], v[142:145], v[162:165], v[36:39]
	v_mfma_f32_16x16x32_bf16 v[32:35], v[142:145], v[166:169], v[32:35]
	s_waitcnt lgkmcnt(9)
	v_mfma_f32_16x16x32_bf16 v[28:31], v[154:157], v[146:149], v[28:31]
	v_mfma_f32_16x16x32_bf16 v[24:27], v[154:157], v[150:153], v[24:27]
	v_mfma_f32_16x16x32_bf16 v[20:23], v[154:157], v[162:165], v[20:23]
	v_mfma_f32_16x16x32_bf16 v[16:19], v[154:157], v[166:169], v[16:19]
	s_waitcnt lgkmcnt(8)
	v_mfma_f32_16x16x32_bf16 v[12:15], v[158:161], v[146:149], v[12:15]
	v_mfma_f32_16x16x32_bf16 v[8:11], v[158:161], v[150:153], v[8:11]
	v_mfma_f32_16x16x32_bf16 v[4:7], v[158:161], v[162:165], v[4:7]
	v_mfma_f32_16x16x32_bf16 v[0:3], v[158:161], v[166:169], v[0:3]
	s_waitcnt lgkmcnt(3)
	v_mfma_f32_16x16x32_bf16 v[60:63], v[204:207], v[208:211], v[60:63]
	v_mfma_f32_16x16x32_bf16 v[56:59], v[204:207], v[212:215], v[56:59]
	v_mfma_f32_16x16x32_bf16 v[52:55], v[204:207], v[216:219], v[52:55]
	v_mfma_f32_16x16x32_bf16 v[48:51], v[204:207], v[220:223], v[48:51]
	s_waitcnt lgkmcnt(2)
	v_mfma_f32_16x16x32_bf16 v[44:47], v[224:227], v[208:211], v[44:47]
	v_mfma_f32_16x16x32_bf16 v[40:43], v[224:227], v[212:215], v[40:43]
	v_mfma_f32_16x16x32_bf16 v[36:39], v[224:227], v[216:219], v[36:39]
	v_mfma_f32_16x16x32_bf16 v[32:35], v[224:227], v[220:223], v[32:35]
	s_waitcnt lgkmcnt(1)
	v_mfma_f32_16x16x32_bf16 v[28:31], v[228:231], v[208:211], v[28:31]
	v_mfma_f32_16x16x32_bf16 v[24:27], v[228:231], v[212:215], v[24:27]
	v_mfma_f32_16x16x32_bf16 v[20:23], v[228:231], v[216:219], v[20:23]
	v_mfma_f32_16x16x32_bf16 v[16:19], v[228:231], v[220:223], v[16:19]
	s_waitcnt lgkmcnt(0)
	v_mfma_f32_16x16x32_bf16 v[12:15], v[232:235], v[208:211], v[12:15]
	v_mfma_f32_16x16x32_bf16 v[8:11], v[232:235], v[212:215], v[8:11]
	v_mfma_f32_16x16x32_bf16 v[4:7], v[232:235], v[216:219], v[4:7]
	v_mfma_f32_16x16x32_bf16 v[0:3], v[232:235], v[220:223], v[0:3]
	s_setprio 0
	s_cmpk_eq_i32 s4, 0x780
	s_waitcnt vmcnt(0)
	s_barrier
	s_cbranch_scc0 .LBB0_2976
	ds_read_b128 v[90:93], v116 offset:55296
	ds_read_b128 v[94:97], v116 offset:53248
	ds_read_b128 v[98:101], v117 offset:38912
	ds_read_b128 v[102:105], v117 offset:36864
	ds_read_b128 v[138:141], v116 offset:51200
	ds_read_b128 v[142:145], v116 offset:49152
	ds_read_b128 v[146:149], v117 offset:34816
	ds_read_b128 v[150:153], v117 offset:32768
	ds_read_b128 v[204:207], v118 offset:32768
	ds_read_b128 v[208:211], v118 offset:34816
	ds_read_b128 v[212:215], v119 offset:49152
	ds_read_b128 v[216:219], v119 offset:51200
	ds_read_b128 v[220:223], v118 offset:36864
	ds_read_b128 v[224:227], v118 offset:38912
	ds_read_b128 v[228:231], v119 offset:53248
	ds_read_b128 v[232:235], v119 offset:55296
	s_setprio 1
	s_waitcnt lgkmcnt(11)
	v_mfma_f32_16x16x32_bf16 v[24:27], v[102:105], v[138:141], v[24:27]
	v_mfma_f32_16x16x32_bf16 v[20:23], v[102:105], v[94:97], v[20:23]
	v_mfma_f32_16x16x32_bf16 v[16:19], v[102:105], v[90:93], v[16:19]
	s_waitcnt lgkmcnt(8)
	v_mfma_f32_16x16x32_bf16 v[60:63], v[150:153], v[142:145], v[60:63]
	v_mfma_f32_16x16x32_bf16 v[56:59], v[150:153], v[138:141], v[56:59]
	v_mfma_f32_16x16x32_bf16 v[52:55], v[150:153], v[94:97], v[52:55]
	v_mfma_f32_16x16x32_bf16 v[48:51], v[150:153], v[90:93], v[48:51]
	v_mfma_f32_16x16x32_bf16 v[44:47], v[146:149], v[142:145], v[44:47]
	v_mfma_f32_16x16x32_bf16 v[40:43], v[146:149], v[138:141], v[40:43]
	v_mfma_f32_16x16x32_bf16 v[36:39], v[146:149], v[94:97], v[36:39]
	v_mfma_f32_16x16x32_bf16 v[32:35], v[146:149], v[90:93], v[32:35]
	v_mfma_f32_16x16x32_bf16 v[28:31], v[102:105], v[142:145], v[28:31]
	v_mfma_f32_16x16x32_bf16 v[12:15], v[98:101], v[142:145], v[12:15]
	v_mfma_f32_16x16x32_bf16 v[8:11], v[98:101], v[138:141], v[8:11]
	v_mfma_f32_16x16x32_bf16 v[4:7], v[98:101], v[94:97], v[4:7]
	v_mfma_f32_16x16x32_bf16 v[0:3], v[98:101], v[90:93], v[0:3]
	s_waitcnt lgkmcnt(3)
	v_mfma_f32_16x16x32_bf16 v[24:27], v[220:223], v[216:219], v[24:27]
	s_waitcnt lgkmcnt(1)
	v_mfma_f32_16x16x32_bf16 v[20:23], v[220:223], v[228:231], v[20:23]
	s_waitcnt lgkmcnt(0)
	v_mfma_f32_16x16x32_bf16 v[16:19], v[220:223], v[232:235], v[16:19]
	v_mfma_f32_16x16x32_bf16 v[60:63], v[204:207], v[212:215], v[60:63]
	v_mfma_f32_16x16x32_bf16 v[56:59], v[204:207], v[216:219], v[56:59]
	v_mfma_f32_16x16x32_bf16 v[52:55], v[204:207], v[228:231], v[52:55]
	v_mfma_f32_16x16x32_bf16 v[48:51], v[204:207], v[232:235], v[48:51]
	v_mfma_f32_16x16x32_bf16 v[44:47], v[208:211], v[212:215], v[44:47]
	v_mfma_f32_16x16x32_bf16 v[40:43], v[208:211], v[216:219], v[40:43]
	v_mfma_f32_16x16x32_bf16 v[36:39], v[208:211], v[228:231], v[36:39]
	v_mfma_f32_16x16x32_bf16 v[32:35], v[208:211], v[232:235], v[32:35]
	v_mfma_f32_16x16x32_bf16 v[28:31], v[220:223], v[212:215], v[28:31]
	v_mfma_f32_16x16x32_bf16 v[12:15], v[224:227], v[212:215], v[12:15]
	v_mfma_f32_16x16x32_bf16 v[8:11], v[224:227], v[216:219], v[8:11]
	v_mfma_f32_16x16x32_bf16 v[4:7], v[224:227], v[228:231], v[4:7]
	v_mfma_f32_16x16x32_bf16 v[0:3], v[224:227], v[232:235], v[0:3]
	s_setprio 0
	s_barrier
	ds_write2_b32 v120, v60, v56 offset1:16
	ds_write2_b32 v120, v61, v57 offset0:132 offset1:148
	v_add_u32_e32 v56, 0x400, v120
	ds_write2_b32 v56, v62, v58 offset0:8 offset1:24
	ds_write2_b32 v56, v63, v59 offset0:140 offset1:156
	ds_write2_b32 v120, v52, v48 offset0:32 offset1:48
	ds_write2_b32 v120, v53, v49 offset0:164 offset1:180
	ds_write2_b32 v56, v54, v50 offset0:40 offset1:56
	ds_write2_b32 v56, v55, v51 offset0:172 offset1:188
	v_add_u32_e32 v48, 0x2000, v120
	ds_write2_b32 v48, v44, v40 offset0:64 offset1:80
	ds_write2_b32 v48, v45, v41 offset0:196 offset1:212
	v_add_u32_e32 v40, 0x2400, v120
	ds_write2_b32 v40, v46, v42 offset0:72 offset1:88
	ds_write2_b32 v40, v47, v43 offset0:204 offset1:220
	ds_write2_b32 v48, v36, v32 offset0:96 offset1:112
	ds_write2_b32 v48, v37, v33 offset0:228 offset1:244
	ds_write2_b32 v40, v38, v34 offset0:104 offset1:120
	ds_write2_b32 v40, v39, v35 offset0:236 offset1:252
	v_add_u32_e32 v32, 0x4000, v120
	ds_write2_b32 v32, v28, v24 offset0:128 offset1:144
	v_add_u32_e32 v24, 0x4400, v120
	ds_write2_b32 v24, v29, v25 offset0:4 offset1:20
	ds_write2_b32 v24, v30, v26 offset0:136 offset1:152
	v_add_u32_e32 v25, 0x4800, v120
	ds_write2_b32 v25, v31, v27 offset0:12 offset1:28
	ds_write2_b32 v32, v20, v16 offset0:160 offset1:176
	ds_write2_b32 v24, v21, v17 offset0:36 offset1:52
	ds_write2_b32 v24, v22, v18 offset0:168 offset1:184
	ds_write2_b32 v25, v23, v19 offset0:44 offset1:60
	v_add_u32_e32 v16, 0x6000, v120
	ds_write2_b32 v16, v12, v8 offset0:192 offset1:208
	v_add_u32_e32 v8, 0x6400, v120
	s_cmpk_gt_u32 s6, 0x3ff
	ds_write2_b32 v8, v13, v9 offset0:68 offset1:84
	ds_write2_b32 v8, v14, v10 offset0:200 offset1:216
	v_add_u32_e32 v9, 0x6800, v120
	v_or_b32_e32 v64, s6, v121
	s_cselect_b64 s[28:29], -1, 0
	s_cmpk_gt_u32 s6, 0x7ff
	ds_write2_b32 v9, v15, v11 offset0:76 offset1:92
	ds_write2_b32 v16, v4, v0 offset0:224 offset1:240
	ds_write2_b32 v8, v5, v1 offset0:100 offset1:116
	ds_write2_b32 v8, v6, v2 offset0:232 offset1:248
	ds_write2_b32 v9, v7, v3 offset0:108 offset1:124
	s_cselect_b64 s[30:31], -1, 0
	s_cmpk_gt_u32 s6, 0xbff
	v_ashrrev_i32_e32 v1, 31, v64
	v_mov_b32_e32 v0, v64
	v_lshlrev_b64 v[2:3], 1, v[64:65]
	v_cmp_lt_i32_e64 s[4:5], s41, v64
	s_cselect_b64 s[34:35], -1, 0
	v_cmp_gt_u32_e64 s[6:7], s42, v64
	v_lshl_add_u64 v[16:17], v[64:65], 2, s[18:19]
	v_lshl_add_u64 v[18:19], s[16:17], 0, v[2:3]
	v_lshl_add_u64 v[20:21], s[14:15], 0, v[2:3]
	v_lshl_add_u64 v[22:23], s[12:13], 0, v[2:3]
	v_lshl_add_u64 v[24:25], v[0:1], 1, s[10:11]
	v_add_u32_e32 v26, s36, v129
	s_mov_b32 s44, 0
	s_waitcnt lgkmcnt(0)
	s_barrier
	s_branch .LBB0_2979

.LBB0_3007:
	v_cvt_f32_ubyte0_e32 v0, s6
	v_rcp_iflag_f32_e32 v0, v0
	s_sub_i32 s24, 0, s6
	s_abs_i32 s23, s4
	s_ashr_i32 s22, s4, 31
	v_mul_f32_e32 v0, 0x4f7ffffe, v0
	v_cvt_u32_f32_e32 v0, v0
	v_add_u32_e32 v2, 0x4000, v108
	v_add_u32_e32 v4, 0x400, v108
	v_readfirstlane_b32 s25, v0
	s_mul_i32 s24, s24, s25
	s_mul_hi_u32 s24, s25, s24
	s_add_i32 s25, s25, s24
	s_mul_hi_u32 s24, s23, s25
	s_mul_i32 s25, s24, s6
	s_sub_i32 s23, s23, s25
	s_add_i32 s26, s24, 1
	s_sub_i32 s25, s23, s6
	s_cmp_ge_u32 s23, s6
	s_cselect_b32 s24, s26, s24
	s_cselect_b32 s23, s25, s23
	s_add_i32 s25, s24, 1
	s_cmp_ge_u32 s23, s6
	s_cselect_b32 s23, s25, s24
	s_xor_b32 s23, s23, s22
	s_sub_i32 s22, s23, s22
	s_mul_i32 s23, s22, s6
	s_sub_i32 s6, s4, s23
	s_lshl_b32 s6, s6, 7
	v_add_u32_e32 v0, s22, v106
	s_add_i32 s6, s6, s5
	v_lshlrev_b32_e32 v135, 7, v0
	v_add_u32_e32 v0, s6, v107
	v_ashrrev_i32_e32 v1, 31, v0
	v_lshlrev_b64 v[0:1], 11, v[0:1]
	v_readfirstlane_b32 s22, v2
	v_lshl_add_u64 v[0:1], v[66:67], 0, v[0:1]
	s_mov_b32 m0, s22
	v_readfirstlane_b32 s22, v108
	global_load_lds_dwordx4 v[0:1], off
	v_add_u32_e32 v0, v135, v107
	v_ashrrev_i32_e32 v1, 31, v0
	v_lshlrev_b64 v[0:1], 11, v[0:1]
	v_lshl_add_u64 v[2:3], v[72:73], 0, v[0:1]
	s_mov_b32 m0, s22
	v_readfirstlane_b32 s22, v128
	global_load_lds_dwordx4 v[2:3], off
	v_add_u32_e32 v2, s6, v109
	v_ashrrev_i32_e32 v3, 31, v2
	v_lshlrev_b64 v[2:3], 11, v[2:3]
	v_lshl_add_u64 v[2:3], v[68:69], 0, v[2:3]
	s_mov_b32 m0, s22
	v_readfirstlane_b32 s22, v4
	global_load_lds_dwordx4 v[2:3], off
	v_add_u32_e32 v2, v135, v109
	v_ashrrev_i32_e32 v3, 31, v2
	v_lshlrev_b64 v[2:3], 11, v[2:3]
	v_lshl_add_u64 v[2:3], v[74:75], 0, v[2:3]
	s_mov_b32 m0, s22
	v_readfirstlane_b32 s22, v129
	global_load_lds_dwordx4 v[2:3], off
	v_add_u32_e32 v2, s6, v111
	v_ashrrev_i32_e32 v3, 31, v2
	v_lshlrev_b64 v[2:3], 11, v[2:3]
	v_lshl_add_u64 v[2:3], v[66:67], 0, v[2:3]
	s_mov_b32 m0, s22
	v_add_u32_e32 v4, 0x800, v108
	global_load_lds_dwordx4 v[2:3], off
	v_add_u32_e32 v2, v135, v111
	v_ashrrev_i32_e32 v3, 31, v2
	v_lshlrev_b64 v[2:3], 11, v[2:3]
	v_readfirstlane_b32 s22, v4
	v_lshl_add_u64 v[2:3], v[72:73], 0, v[2:3]
	s_mov_b32 m0, s22
	v_readfirstlane_b32 s22, v130
	global_load_lds_dwordx4 v[2:3], off
	v_add_u32_e32 v2, s6, v113
	v_ashrrev_i32_e32 v3, 31, v2
	v_lshlrev_b64 v[2:3], 11, v[2:3]
	v_lshl_add_u64 v[2:3], v[70:71], 0, v[2:3]
	s_mov_b32 m0, s22
	v_add_u32_e32 v4, 0xc00, v108
	global_load_lds_dwordx4 v[2:3], off
	v_add_u32_e32 v2, v135, v113
	v_ashrrev_i32_e32 v3, 31, v2
	v_lshlrev_b64 v[2:3], 11, v[2:3]
	v_readfirstlane_b32 s22, v4
	v_lshl_add_u64 v[2:3], v[76:77], 0, v[2:3]
	s_mov_b32 m0, s22
	s_lshl_b32 s4, s4, 7
	global_load_lds_dwordx4 v[2:3], off
	s_add_i32 s4, s4, s5
	s_lshl_b32 s5, s23, 7
	v_lshl_add_u64 v[92:93], v[80:81], 0, v[0:1]
	v_add_u32_e32 v0, s4, v123
	v_subrev_u32_e32 v0, s5, v0
	v_ashrrev_i32_e32 v1, 31, v0
	v_lshlrev_b64 v[0:1], 11, v[0:1]
	v_lshl_add_u64 v[94:95], v[82:83], 0, v[0:1]
	v_add_u32_e32 v0, v123, v135
	v_ashrrev_i32_e32 v1, 31, v0
	v_lshlrev_b64 v[0:1], 11, v[0:1]
	v_lshl_add_u64 v[96:97], v[84:85], 0, v[0:1]
	v_add_u32_e32 v0, s4, v124
	v_subrev_u32_e32 v0, s5, v0
	v_ashrrev_i32_e32 v1, 31, v0
	v_lshlrev_b64 v[0:1], 11, v[0:1]
	v_lshl_add_u64 v[98:99], v[78:79], 0, v[0:1]
	v_add_u32_e32 v0, v124, v135
	v_ashrrev_i32_e32 v1, 31, v0
	v_lshlrev_b64 v[0:1], 11, v[0:1]
	v_lshl_add_u64 v[100:101], v[80:81], 0, v[0:1]
	v_add_u32_e32 v0, s4, v125
	v_subrev_u32_e32 v0, s5, v0
	v_ashrrev_i32_e32 v1, 31, v0
	v_lshlrev_b64 v[0:1], 11, v[0:1]
	v_add_u32_e32 v2, s4, v107
	v_lshl_add_u64 v[102:103], v[86:87], 0, v[0:1]
	v_add_u32_e32 v0, v125, v135
	v_subrev_u32_e32 v2, s5, v2
	v_ashrrev_i32_e32 v1, 31, v0
	v_ashrrev_i32_e32 v3, 31, v2
	v_lshlrev_b64 v[0:1], 11, v[0:1]
	v_lshlrev_b64 v[2:3], 11, v[2:3]
	v_lshl_add_u64 v[104:105], v[88:89], 0, v[0:1]
	v_mov_b32_e32 v0, 0
	v_lshl_add_u64 v[90:91], v[78:79], 0, v[2:3]
	s_mov_b64 s[4:5], 0
	v_mov_b32_e32 v1, v0
	v_mov_b32_e32 v2, v0
	v_mov_b32_e32 v3, v0
	v_mov_b32_e32 v4, v0
	v_mov_b32_e32 v5, v0
	v_mov_b32_e32 v6, v0
	v_mov_b32_e32 v7, v0
	v_mov_b32_e32 v8, v0
	v_mov_b32_e32 v9, v0
	v_mov_b32_e32 v10, v0
	v_mov_b32_e32 v11, v0
	v_mov_b32_e32 v12, v0
	v_mov_b32_e32 v13, v0
	v_mov_b32_e32 v14, v0
	v_mov_b32_e32 v15, v0
	v_mov_b32_e32 v16, v0
	v_mov_b32_e32 v17, v0
	v_mov_b32_e32 v18, v0
	v_mov_b32_e32 v19, v0
	v_mov_b32_e32 v20, v0
	v_mov_b32_e32 v21, v0
	v_mov_b32_e32 v22, v0
	v_mov_b32_e32 v23, v0
	v_mov_b32_e32 v24, v0
	v_mov_b32_e32 v25, v0
	v_mov_b32_e32 v26, v0
	v_mov_b32_e32 v27, v0
	v_mov_b32_e32 v28, v0
	v_mov_b32_e32 v29, v0
	v_mov_b32_e32 v30, v0
	v_mov_b32_e32 v31, v0
	v_mov_b32_e32 v32, v0
	v_mov_b32_e32 v33, v0
	v_mov_b32_e32 v34, v0
	v_mov_b32_e32 v35, v0
	v_mov_b32_e32 v36, v0
	v_mov_b32_e32 v37, v0
	v_mov_b32_e32 v38, v0
	v_mov_b32_e32 v39, v0
	v_mov_b32_e32 v40, v0
	v_mov_b32_e32 v41, v0
	v_mov_b32_e32 v42, v0
	v_mov_b32_e32 v43, v0
	v_mov_b32_e32 v44, v0
	v_mov_b32_e32 v45, v0
	v_mov_b32_e32 v46, v0
	v_mov_b32_e32 v47, v0
	v_mov_b32_e32 v48, v0
	v_mov_b32_e32 v49, v0
	v_mov_b32_e32 v50, v0
	v_mov_b32_e32 v51, v0
	v_mov_b32_e32 v52, v0
	v_mov_b32_e32 v53, v0
	v_mov_b32_e32 v54, v0
	v_mov_b32_e32 v55, v0
	v_mov_b32_e32 v56, v0
	v_mov_b32_e32 v57, v0
	v_mov_b32_e32 v58, v0
	v_mov_b32_e32 v59, v0
	v_mov_b32_e32 v60, v0
	v_mov_b32_e32 v61, v0
	v_mov_b32_e32 v62, v0
	v_mov_b32_e32 v63, v0
	s_waitcnt vmcnt(0) lgkmcnt(0)
	s_barrier
	v_add3_u32 v182, 0, v131, v132
	v_add_u32_e32 v183, 0x4000, v182
	s_nop 0
	v_readfirstlane_b32 s82, v183
	v_lshl_add_u32 v183, v110, 1, 0
	s_nop 0
	v_readfirstlane_b32 s83, v182
	v_add3_u32 v183, v183, v132, s21
	s_nop 0
	v_readfirstlane_b32 s84, v183
	v_add_u32_e32 v183, 0x400, v182
	s_nop 0
	v_readfirstlane_b32 s85, v183
	v_lshl_add_u32 v183, v112, 1, 0
	v_add3_u32 v183, v183, v132, s21
	s_nop 0
	v_readfirstlane_b32 s86, v183
	v_add_u32_e32 v183, 0x800, v182
	s_nop 0
	v_readfirstlane_b32 s87, v183
	v_lshl_add_u32 v183, v114, 1, 0
	v_add3_u32 v183, v183, v132, s21
	s_nop 0
	v_readfirstlane_b32 s88, v183
	v_add_u32_e32 v182, 0xc00, v182
	s_nop 0
	v_readfirstlane_b32 s89, v182
	v_subrev_u32_e32 v184, s52, v90
	v_subrev_u32_e32 v185, s52, v92
	v_subrev_u32_e32 v186, s52, v94
	v_subrev_u32_e32 v187, s52, v96
	v_subrev_u32_e32 v188, s52, v98
	v_subrev_u32_e32 v189, s52, v100
	v_subrev_u32_e32 v190, s52, v102
	v_subrev_u32_e32 v191, s52, v104
	v_subrev_u32_e32 v187, 0x400, v187
	v_subrev_u32_e32 v186, 0x400, v186
	v_subrev_u32_e32 v189, 0x800, v189
	v_subrev_u32_e32 v188, 0x800, v188
	v_subrev_u32_e32 v191, 0xc00, v191
	v_subrev_u32_e32 v190, 0xc00, v190
	s_and_b32 s23, s7, 0x4000
	s_xor_b32 s22, s23, 0x4000
	s_lshl_b32 s22, s22, 1
	s_add_i32 s22, s22, 32
	s_lshl_b32 s23, s23, 1
	s_add_i32 s23, s23, 32
.LBB0_3008:
	s_xor_b32 s22, s22, 0x8000
	s_xor_b32 s23, s23, 0x8000
	s_add_u32 s90, s52, s4
	s_addc_u32 s91, s53, s5
	s_add_i32 m0, s23, s83
	v_lshl_add_u32 v64, v115, 1, s22
	global_load_lds_dwordx4 v185, s[90:91]
	global_load_lds_dwordx4 v187, s[90:91] offset:1024
	global_load_lds_dwordx4 v189, s[90:91] offset:2048
	global_load_lds_dwordx4 v191, s[90:91] offset:3072
	s_add_i32 m0, s23, s82
	v_lshl_add_u32 v168, v116, 1, s22
	global_load_lds_dwordx4 v184, s[90:91]
	global_load_lds_dwordx4 v186, s[90:91] offset:1024
	global_load_lds_dwordx4 v188, s[90:91] offset:2048
	global_load_lds_dwordx4 v190, s[90:91] offset:3072
	v_add_u32_e32 v156, v64, v133
	v_add_u32_e32 v164, v168, v133
	s_addk_i32 s7, 0x4000
	s_add_u32 s4, s4, 0x80
	s_addc_u32 s5, s5, 0
	ds_read_b128 v[136:139], v156
	ds_read_b128 v[144:147], v164 offset:16384
	ds_read_b128 v[148:151], v164 offset:18432
	ds_read_b128 v[160:163], v164 offset:20480
	ds_read_b128 v[164:167], v164 offset:22528
	ds_read_b128 v[140:143], v156 offset:2048
	ds_read_b128 v[152:155], v156 offset:4096
	ds_read_b128 v[156:159], v156 offset:6144
	v_add_u32_e32 v64, v64, v134
	v_add_u32_e32 v236, v168, v134
	ds_read_b128 v[204:207], v64
	ds_read_b128 v[208:211], v236 offset:16384
	ds_read_b128 v[212:215], v236 offset:18432
	ds_read_b128 v[216:219], v236 offset:20480
	ds_read_b128 v[220:223], v236 offset:22528
	ds_read_b128 v[224:227], v64 offset:2048
	ds_read_b128 v[228:231], v64 offset:4096
	ds_read_b128 v[232:235], v64 offset:6144
	s_setprio 1
	s_waitcnt lgkmcnt(11)
	v_mfma_f32_16x16x32_bf16 v[60:63], v[136:139], v[144:147], v[60:63]
	v_mfma_f32_16x16x32_bf16 v[56:59], v[136:139], v[148:151], v[56:59]
	v_mfma_f32_16x16x32_bf16 v[52:55], v[136:139], v[160:163], v[52:55]
	v_mfma_f32_16x16x32_bf16 v[48:51], v[136:139], v[164:167], v[48:51]
	s_waitcnt lgkmcnt(10)
	v_mfma_f32_16x16x32_bf16 v[44:47], v[140:143], v[144:147], v[44:47]
	v_mfma_f32_16x16x32_bf16 v[40:43], v[140:143], v[148:151], v[40:43]
	v_mfma_f32_16x16x32_bf16 v[36:39], v[140:143], v[160:163], v[36:39]
	v_mfma_f32_16x16x32_bf16 v[32:35], v[140:143], v[164:167], v[32:35]
	s_waitcnt lgkmcnt(9)
	v_mfma_f32_16x16x32_bf16 v[28:31], v[152:155], v[144:147], v[28:31]
	v_mfma_f32_16x16x32_bf16 v[24:27], v[152:155], v[148:151], v[24:27]
	v_mfma_f32_16x16x32_bf16 v[20:23], v[152:155], v[160:163], v[20:23]
	v_mfma_f32_16x16x32_bf16 v[16:19], v[152:155], v[164:167], v[16:19]
	s_waitcnt lgkmcnt(8)
	v_mfma_f32_16x16x32_bf16 v[12:15], v[156:159], v[144:147], v[12:15]
	v_mfma_f32_16x16x32_bf16 v[8:11], v[156:159], v[148:151], v[8:11]
	v_mfma_f32_16x16x32_bf16 v[4:7], v[156:159], v[160:163], v[4:7]
	v_mfma_f32_16x16x32_bf16 v[0:3], v[156:159], v[164:167], v[0:3]
	s_waitcnt lgkmcnt(3)
	v_mfma_f32_16x16x32_bf16 v[60:63], v[204:207], v[208:211], v[60:63]
	v_mfma_f32_16x16x32_bf16 v[56:59], v[204:207], v[212:215], v[56:59]
	v_mfma_f32_16x16x32_bf16 v[52:55], v[204:207], v[216:219], v[52:55]
	v_mfma_f32_16x16x32_bf16 v[48:51], v[204:207], v[220:223], v[48:51]
	s_waitcnt lgkmcnt(2)
	v_mfma_f32_16x16x32_bf16 v[44:47], v[224:227], v[208:211], v[44:47]
	v_mfma_f32_16x16x32_bf16 v[40:43], v[224:227], v[212:215], v[40:43]
	v_mfma_f32_16x16x32_bf16 v[36:39], v[224:227], v[216:219], v[36:39]
	v_mfma_f32_16x16x32_bf16 v[32:35], v[224:227], v[220:223], v[32:35]
	s_waitcnt lgkmcnt(1)
	v_mfma_f32_16x16x32_bf16 v[28:31], v[228:231], v[208:211], v[28:31]
	v_mfma_f32_16x16x32_bf16 v[24:27], v[228:231], v[212:215], v[24:27]
	v_mfma_f32_16x16x32_bf16 v[20:23], v[228:231], v[216:219], v[20:23]
	v_mfma_f32_16x16x32_bf16 v[16:19], v[228:231], v[220:223], v[16:19]
	s_waitcnt lgkmcnt(0)
	v_mfma_f32_16x16x32_bf16 v[12:15], v[232:235], v[208:211], v[12:15]
	v_mfma_f32_16x16x32_bf16 v[8:11], v[232:235], v[212:215], v[8:11]
	v_mfma_f32_16x16x32_bf16 v[4:7], v[232:235], v[216:219], v[4:7]
	v_mfma_f32_16x16x32_bf16 v[0:3], v[232:235], v[220:223], v[0:3]
	s_setprio 0
	s_cmpk_eq_i32 s4, 0x780
	s_waitcnt vmcnt(0)
	s_barrier
	s_cbranch_scc0 .LBB0_3008
	ds_read_b128 v[90:93], v117 offset:55296
	ds_read_b128 v[94:97], v117 offset:53248
	ds_read_b128 v[98:101], v118 offset:38912
	ds_read_b128 v[102:105], v118 offset:36864
	ds_read_b128 v[136:139], v117 offset:51200
	ds_read_b128 v[140:143], v117 offset:49152
	ds_read_b128 v[144:147], v118 offset:34816
	ds_read_b128 v[148:151], v118 offset:32768
	ds_read_b128 v[204:207], v119 offset:32768
	ds_read_b128 v[208:211], v119 offset:34816
	ds_read_b128 v[212:215], v120 offset:49152
	ds_read_b128 v[216:219], v120 offset:51200
	ds_read_b128 v[220:223], v119 offset:36864
	ds_read_b128 v[224:227], v119 offset:38912
	ds_read_b128 v[228:231], v120 offset:53248
	ds_read_b128 v[232:235], v120 offset:55296
	s_setprio 1
	s_waitcnt lgkmcnt(11)
	v_mfma_f32_16x16x32_bf16 v[24:27], v[102:105], v[136:139], v[24:27]
	v_mfma_f32_16x16x32_bf16 v[20:23], v[102:105], v[94:97], v[20:23]
	v_mfma_f32_16x16x32_bf16 v[16:19], v[102:105], v[90:93], v[16:19]
	s_waitcnt lgkmcnt(8)
	v_mfma_f32_16x16x32_bf16 v[60:63], v[148:151], v[140:143], v[60:63]
	v_mfma_f32_16x16x32_bf16 v[56:59], v[148:151], v[136:139], v[56:59]
	v_mfma_f32_16x16x32_bf16 v[52:55], v[148:151], v[94:97], v[52:55]
	v_mfma_f32_16x16x32_bf16 v[48:51], v[148:151], v[90:93], v[48:51]
	v_mfma_f32_16x16x32_bf16 v[44:47], v[144:147], v[140:143], v[44:47]
	v_mfma_f32_16x16x32_bf16 v[40:43], v[144:147], v[136:139], v[40:43]
	v_mfma_f32_16x16x32_bf16 v[36:39], v[144:147], v[94:97], v[36:39]
	v_mfma_f32_16x16x32_bf16 v[32:35], v[144:147], v[90:93], v[32:35]
	v_mfma_f32_16x16x32_bf16 v[28:31], v[102:105], v[140:143], v[28:31]
	v_mfma_f32_16x16x32_bf16 v[12:15], v[98:101], v[140:143], v[12:15]
	v_mfma_f32_16x16x32_bf16 v[8:11], v[98:101], v[136:139], v[8:11]
	v_mfma_f32_16x16x32_bf16 v[4:7], v[98:101], v[94:97], v[4:7]
	v_mfma_f32_16x16x32_bf16 v[0:3], v[98:101], v[90:93], v[0:3]
	s_waitcnt lgkmcnt(3)
	v_mfma_f32_16x16x32_bf16 v[24:27], v[220:223], v[216:219], v[24:27]
	s_waitcnt lgkmcnt(1)
	v_mfma_f32_16x16x32_bf16 v[20:23], v[220:223], v[228:231], v[20:23]
	s_waitcnt lgkmcnt(0)
	v_mfma_f32_16x16x32_bf16 v[16:19], v[220:223], v[232:235], v[16:19]
	v_mfma_f32_16x16x32_bf16 v[60:63], v[204:207], v[212:215], v[60:63]
	v_mfma_f32_16x16x32_bf16 v[56:59], v[204:207], v[216:219], v[56:59]
	v_mfma_f32_16x16x32_bf16 v[52:55], v[204:207], v[228:231], v[52:55]
	v_mfma_f32_16x16x32_bf16 v[48:51], v[204:207], v[232:235], v[48:51]
	v_mfma_f32_16x16x32_bf16 v[44:47], v[208:211], v[212:215], v[44:47]
	v_mfma_f32_16x16x32_bf16 v[40:43], v[208:211], v[216:219], v[40:43]
	v_mfma_f32_16x16x32_bf16 v[36:39], v[208:211], v[228:231], v[36:39]
	v_mfma_f32_16x16x32_bf16 v[32:35], v[208:211], v[232:235], v[32:35]
	v_mfma_f32_16x16x32_bf16 v[28:31], v[220:223], v[212:215], v[28:31]
	v_mfma_f32_16x16x32_bf16 v[12:15], v[224:227], v[212:215], v[12:15]
	v_mfma_f32_16x16x32_bf16 v[8:11], v[224:227], v[216:219], v[8:11]
	v_mfma_f32_16x16x32_bf16 v[4:7], v[224:227], v[228:231], v[4:7]
	v_mfma_f32_16x16x32_bf16 v[0:3], v[224:227], v[232:235], v[0:3]
	s_setprio 0
	s_barrier
	ds_write2_b32 v121, v60, v56 offset1:16
	ds_write2_b32 v121, v61, v57 offset0:132 offset1:148
	v_add_u32_e32 v56, 0x400, v121
	ds_write2_b32 v56, v62, v58 offset0:8 offset1:24
	ds_write2_b32 v56, v63, v59 offset0:140 offset1:156
	ds_write2_b32 v121, v52, v48 offset0:32 offset1:48
	ds_write2_b32 v121, v53, v49 offset0:164 offset1:180
	ds_write2_b32 v56, v54, v50 offset0:40 offset1:56
	ds_write2_b32 v56, v55, v51 offset0:172 offset1:188
	v_add_u32_e32 v48, 0x2000, v121
	ds_write2_b32 v48, v44, v40 offset0:64 offset1:80
	ds_write2_b32 v48, v45, v41 offset0:196 offset1:212
	v_add_u32_e32 v40, 0x2400, v121
	ds_write2_b32 v40, v46, v42 offset0:72 offset1:88
	ds_write2_b32 v40, v47, v43 offset0:204 offset1:220
	ds_write2_b32 v48, v36, v32 offset0:96 offset1:112
	ds_write2_b32 v48, v37, v33 offset0:228 offset1:244
	ds_write2_b32 v40, v38, v34 offset0:104 offset1:120
	ds_write2_b32 v40, v39, v35 offset0:236 offset1:252
	v_add_u32_e32 v32, 0x4000, v121
	ds_write2_b32 v32, v28, v24 offset0:128 offset1:144
	v_add_u32_e32 v24, 0x4400, v121
	ds_write2_b32 v24, v29, v25 offset0:4 offset1:20
	ds_write2_b32 v24, v30, v26 offset0:136 offset1:152
	v_add_u32_e32 v25, 0x4800, v121
	ds_write2_b32 v25, v31, v27 offset0:12 offset1:28
	ds_write2_b32 v32, v20, v16 offset0:160 offset1:176
	ds_write2_b32 v24, v21, v17 offset0:36 offset1:52
	ds_write2_b32 v24, v22, v18 offset0:168 offset1:184
	ds_write2_b32 v25, v23, v19 offset0:44 offset1:60
	v_add_u32_e32 v16, 0x6000, v121
	ds_write2_b32 v16, v12, v8 offset0:192 offset1:208
	v_add_u32_e32 v8, 0x6400, v121
	s_cmpk_gt_u32 s6, 0x3ff
	ds_write2_b32 v8, v13, v9 offset0:68 offset1:84
	ds_write2_b32 v8, v14, v10 offset0:200 offset1:216
	v_add_u32_e32 v9, 0x6800, v121
	v_or_b32_e32 v64, s6, v122
	s_cselect_b64 s[22:23], -1, 0
	s_cmpk_gt_u32 s6, 0x7ff
	ds_write2_b32 v9, v15, v11 offset0:76 offset1:92
	ds_write2_b32 v16, v4, v0 offset0:224 offset1:240
	ds_write2_b32 v8, v5, v1 offset0:100 offset1:116
	ds_write2_b32 v8, v6, v2 offset0:232 offset1:248
	ds_write2_b32 v9, v7, v3 offset0:108 offset1:124
	s_cselect_b64 s[24:25], -1, 0
	s_cmpk_gt_u32 s6, 0xbff
	v_ashrrev_i32_e32 v1, 31, v64
	v_mov_b32_e32 v0, v64
	v_lshlrev_b64 v[2:3], 1, v[64:65]
	v_cmp_lt_i32_e64 s[4:5], s36, v64
	s_cselect_b64 s[26:27], -1, 0
	v_cmp_gt_u32_e64 s[6:7], s37, v64
	v_lshl_add_u64 v[16:17], v[64:65], 2, s[18:19]
	v_lshl_add_u64 v[18:19], s[16:17], 0, v[2:3]
	v_lshl_add_u64 v[20:21], s[14:15], 0, v[2:3]
	v_lshl_add_u64 v[22:23], s[12:13], 0, v[2:3]
	v_lshl_add_u64 v[24:25], v[0:1], 1, s[10:11]
	v_add_u32_e32 v26, v126, v135
	s_mov_b32 s38, 0
	s_waitcnt lgkmcnt(0)
	s_barrier
	s_branch .LBB0_3011

.LBB0_3221:
	s_ashr_i32 s16, s23, 31
	s_lshr_b32 s16, s16, 29
	s_add_i32 s16, s23, s16
	s_ashr_i32 s16, s16, 3
	s_lshr_b32 s17, s16, 4
	s_lshl_b32 s24, s16, 7
	s_lshl_b32 s16, s16, 10
	s_lshl_b32 s25, s23, 7
	s_sub_i32 s25, s25, s16
	v_add_u32_e32 v0, s25, v106
	s_mulk_i32 s17, 0x900
	s_and_b32 s24, s24, 0x780
	v_ashrrev_i32_e32 v1, 31, v0
	v_add_u32_e32 v2, 0x4000, v107
	s_add_i32 s24, s24, s17
	v_lshlrev_b64 v[0:1], 11, v[0:1]
	v_readfirstlane_b32 s26, v2
	s_add_i32 s17, s24, 0x100
	v_lshl_add_u64 v[0:1], v[66:67], 0, v[0:1]
	s_mov_b32 m0, s26
	v_readfirstlane_b32 s26, v107
	global_load_lds_dwordx4 v[0:1], off
	v_add_u32_e32 v0, s17, v106
	v_ashrrev_i32_e32 v1, 31, v0
	v_lshlrev_b64 v[0:1], 11, v[0:1]
	v_lshl_add_u64 v[0:1], v[72:73], 0, v[0:1]
	s_mov_b32 m0, s26
	v_readfirstlane_b32 s26, v131
	global_load_lds_dwordx4 v[0:1], off
	v_add_u32_e32 v0, s25, v108
	v_ashrrev_i32_e32 v1, 31, v0
	v_lshlrev_b64 v[0:1], 11, v[0:1]
	v_lshl_add_u64 v[0:1], v[68:69], 0, v[0:1]
	s_mov_b32 m0, s26
	v_add_u32_e32 v2, 0x400, v107
	global_load_lds_dwordx4 v[0:1], off
	v_add_u32_e32 v0, s17, v108
	v_ashrrev_i32_e32 v1, 31, v0
	v_lshlrev_b64 v[0:1], 11, v[0:1]
	v_readfirstlane_b32 s26, v2
	v_lshl_add_u64 v[0:1], v[74:75], 0, v[0:1]
	s_mov_b32 m0, s26
	v_readfirstlane_b32 s26, v132
	global_load_lds_dwordx4 v[0:1], off
	v_add_u32_e32 v0, s25, v110
	v_ashrrev_i32_e32 v1, 31, v0
	v_lshlrev_b64 v[0:1], 11, v[0:1]
	v_lshl_add_u64 v[0:1], v[66:67], 0, v[0:1]
	s_mov_b32 m0, s26
	v_add_u32_e32 v2, 0x800, v107
	global_load_lds_dwordx4 v[0:1], off
	v_add_u32_e32 v0, s17, v110
	v_ashrrev_i32_e32 v1, 31, v0
	v_lshlrev_b64 v[0:1], 11, v[0:1]
	v_readfirstlane_b32 s26, v2
	v_lshl_add_u64 v[0:1], v[72:73], 0, v[0:1]
	s_mov_b32 m0, s26
	v_readfirstlane_b32 s26, v133
	global_load_lds_dwordx4 v[0:1], off
	v_add_u32_e32 v0, s25, v112
	v_ashrrev_i32_e32 v1, 31, v0
	v_lshlrev_b64 v[0:1], 11, v[0:1]
	v_lshl_add_u64 v[0:1], v[70:71], 0, v[0:1]
	s_mov_b32 m0, s26
	v_add_u32_e32 v2, 0xc00, v107
	global_load_lds_dwordx4 v[0:1], off
	v_add_u32_e32 v0, s17, v112
	v_ashrrev_i32_e32 v1, 31, v0
	v_lshlrev_b64 v[0:1], 11, v[0:1]
	v_readfirstlane_b32 s17, v2
	v_lshl_add_u64 v[0:1], v[76:77], 0, v[0:1]
	s_mov_b32 m0, s17
	s_mov_b32 s26, 0
	global_load_lds_dwordx4 v[0:1], off
	v_subrev_u32_e32 v0, s16, v122
	v_ashrrev_i32_e32 v1, 31, v0
	v_lshlrev_b64 v[0:1], 11, v[0:1]
	v_lshl_add_u64 v[90:91], v[78:79], 0, v[0:1]
	v_add_u32_e32 v0, s24, v123
	v_ashrrev_i32_e32 v1, 31, v0
	v_lshlrev_b64 v[0:1], 11, v[0:1]
	v_lshl_add_u64 v[92:93], v[80:81], 0, v[0:1]
	v_subrev_u32_e32 v0, s16, v124
	v_ashrrev_i32_e32 v1, 31, v0
	v_lshlrev_b64 v[0:1], 11, v[0:1]
	v_lshl_add_u64 v[94:95], v[82:83], 0, v[0:1]
	v_add_u32_e32 v0, s24, v125
	v_ashrrev_i32_e32 v1, 31, v0
	v_lshlrev_b64 v[0:1], 11, v[0:1]
	v_lshl_add_u64 v[96:97], v[84:85], 0, v[0:1]
	v_subrev_u32_e32 v0, s16, v126
	v_ashrrev_i32_e32 v1, 31, v0
	v_lshlrev_b64 v[0:1], 11, v[0:1]
	v_lshl_add_u64 v[98:99], v[78:79], 0, v[0:1]
	v_add_u32_e32 v0, s24, v127
	v_ashrrev_i32_e32 v1, 31, v0
	v_lshlrev_b64 v[0:1], 11, v[0:1]
	v_lshl_add_u64 v[100:101], v[80:81], 0, v[0:1]
	v_subrev_u32_e32 v0, s16, v64
	v_ashrrev_i32_e32 v1, 31, v0
	v_lshlrev_b64 v[0:1], 11, v[0:1]
	v_lshl_add_u64 v[102:103], v[86:87], 0, v[0:1]
	v_add_u32_e32 v0, s24, v128
	v_ashrrev_i32_e32 v1, 31, v0
	v_lshlrev_b64 v[0:1], 11, v[0:1]
	v_lshl_add_u64 v[104:105], v[88:89], 0, v[0:1]
	s_mov_b64 s[16:17], 0
	v_mov_b32_e32 v0, 0
	v_mov_b32_e32 v1, v65
	v_mov_b32_e32 v2, v65
	v_mov_b32_e32 v3, v65
	v_mov_b32_e32 v4, 0
	v_mov_b32_e32 v5, v65
	v_mov_b32_e32 v6, v65
	v_mov_b32_e32 v7, v65
	v_mov_b32_e32 v8, 0
	v_mov_b32_e32 v9, v65
	v_mov_b32_e32 v10, v65
	v_mov_b32_e32 v11, v65
	v_mov_b32_e32 v12, 0
	v_mov_b32_e32 v13, v65
	v_mov_b32_e32 v14, v65
	v_mov_b32_e32 v15, v65
	v_mov_b32_e32 v16, 0
	v_mov_b32_e32 v17, v65
	v_mov_b32_e32 v18, v65
	v_mov_b32_e32 v19, v65
	v_mov_b32_e32 v20, 0
	v_mov_b32_e32 v21, v65
	v_mov_b32_e32 v22, v65
	v_mov_b32_e32 v23, v65
	s_waitcnt vmcnt(0)
	v_mov_b32_e32 v24, 0
	v_mov_b32_e32 v25, v65
	v_mov_b32_e32 v26, v65
	v_mov_b32_e32 v27, v65
	v_mov_b32_e32 v28, 0
	v_mov_b32_e32 v29, v65
	v_mov_b32_e32 v30, v65
	v_mov_b32_e32 v31, v65
	v_mov_b32_e32 v32, 0
	v_mov_b32_e32 v33, v65
	v_mov_b32_e32 v34, v65
	v_mov_b32_e32 v35, v65
	v_mov_b32_e32 v36, 0
	v_mov_b32_e32 v37, v65
	v_mov_b32_e32 v38, v65
	v_mov_b32_e32 v39, v65
	v_mov_b32_e32 v40, 0
	v_mov_b32_e32 v41, v65
	v_mov_b32_e32 v42, v65
	v_mov_b32_e32 v43, v65
	v_mov_b32_e32 v44, 0
	v_mov_b32_e32 v45, v65
	v_mov_b32_e32 v46, v65
	v_mov_b32_e32 v47, v65
	v_mov_b32_e32 v48, 0
	v_mov_b32_e32 v49, v65
	v_mov_b32_e32 v50, v65
	v_mov_b32_e32 v51, v65
	v_mov_b32_e32 v52, 0
	v_mov_b32_e32 v53, v65
	v_mov_b32_e32 v54, v65
	v_mov_b32_e32 v55, v65
	v_mov_b32_e32 v56, 0
	v_mov_b32_e32 v57, v65
	v_mov_b32_e32 v58, v65
	v_mov_b32_e32 v59, v65
	v_mov_b32_e32 v60, 0
	v_mov_b32_e32 v61, v65
	v_mov_b32_e32 v62, v65
	v_mov_b32_e32 v63, v65
	s_waitcnt lgkmcnt(0)
	s_barrier
	v_add3_u32 v182, 0, v134, v135
	v_add_u32_e32 v183, 0x4000, v182
	s_nop 0
	v_readfirstlane_b32 s82, v183
	v_lshl_add_u32 v183, v109, 1, 0
	s_nop 0
	v_readfirstlane_b32 s83, v182
	v_add3_u32 v183, v183, v135, s19
	s_nop 0
	v_readfirstlane_b32 s84, v183
	v_add_u32_e32 v183, 0x400, v182
	s_nop 0
	v_readfirstlane_b32 s85, v183
	v_lshl_add_u32 v183, v111, 1, 0
	v_add3_u32 v183, v183, v135, s19
	s_nop 0
	v_readfirstlane_b32 s86, v183
	v_add_u32_e32 v183, 0x800, v182
	s_nop 0
	v_readfirstlane_b32 s87, v183
	v_lshl_add_u32 v183, v113, 1, 0
	v_add3_u32 v183, v183, v135, s19
	s_nop 0
	v_readfirstlane_b32 s88, v183
	v_add_u32_e32 v182, 0xc00, v182
	s_nop 0
	v_readfirstlane_b32 s89, v182
	v_subrev_u32_e32 v184, s52, v90
	v_subrev_u32_e32 v185, s52, v92
	v_subrev_u32_e32 v186, s52, v94
	v_subrev_u32_e32 v187, s52, v96
	v_subrev_u32_e32 v188, s52, v98
	v_subrev_u32_e32 v189, s52, v100
	v_subrev_u32_e32 v190, s52, v102
	v_subrev_u32_e32 v191, s52, v104
	v_subrev_u32_e32 v187, 0x400, v187
	v_subrev_u32_e32 v186, 0x400, v186
	v_subrev_u32_e32 v189, 0x800, v189
	v_subrev_u32_e32 v188, 0x800, v188
	v_subrev_u32_e32 v191, 0xc00, v191
	v_subrev_u32_e32 v190, 0xc00, v190
	s_and_b32 s28, s26, 0x4000
	s_xor_b32 s27, s28, 0x4000
	s_lshl_b32 s27, s27, 1
	s_add_i32 s27, s27, 32
	s_lshl_b32 s28, s28, 1
	s_add_i32 s28, s28, 32
.LBB0_3222:
	s_xor_b32 s27, s27, 0x8000
	s_xor_b32 s28, s28, 0x8000
	s_add_u32 s90, s52, s16
	s_addc_u32 s91, s53, s17
	s_add_i32 m0, s28, s83
	v_add3_u32 v139, s27, v114, v136
	global_load_lds_dwordx4 v185, s[90:91]
	global_load_lds_dwordx4 v187, s[90:91] offset:1024
	global_load_lds_dwordx4 v189, s[90:91] offset:2048
	global_load_lds_dwordx4 v191, s[90:91] offset:3072
	s_add_i32 m0, s28, s82
	v_add3_u32 v172, s27, v115, v136
	global_load_lds_dwordx4 v184, s[90:91]
	global_load_lds_dwordx4 v186, s[90:91] offset:1024
	global_load_lds_dwordx4 v188, s[90:91] offset:2048
	global_load_lds_dwordx4 v190, s[90:91] offset:3072
	v_add_u32_e32 v160, v139, v137
	v_add_u32_e32 v168, v172, v137
	s_add_u32 s16, s16, 0x80
	s_addc_u32 s17, s17, 0
	ds_read_b128 v[140:143], v160
	ds_read_b128 v[148:151], v168 offset:16384
	ds_read_b128 v[152:155], v168 offset:18432
	ds_read_b128 v[164:167], v168 offset:20480
	ds_read_b128 v[168:171], v168 offset:22528
	ds_read_b128 v[144:147], v160 offset:2048
	ds_read_b128 v[156:159], v160 offset:4096
	ds_read_b128 v[160:163], v160 offset:6144
	v_add_u32_e32 v139, v139, v138
	v_add_u32_e32 v236, v172, v138
	ds_read_b128 v[204:207], v139
	ds_read_b128 v[208:211], v236 offset:16384
	ds_read_b128 v[212:215], v236 offset:18432
	ds_read_b128 v[216:219], v236 offset:20480
	ds_read_b128 v[220:223], v236 offset:22528
	ds_read_b128 v[224:227], v139 offset:2048
	ds_read_b128 v[228:231], v139 offset:4096
	ds_read_b128 v[232:235], v139 offset:6144
	s_setprio 1
	s_waitcnt lgkmcnt(11)
	v_mfma_f32_16x16x32_bf16 v[60:63], v[140:143], v[148:151], v[60:63]
	v_mfma_f32_16x16x32_bf16 v[56:59], v[140:143], v[152:155], v[56:59]
	v_mfma_f32_16x16x32_bf16 v[52:55], v[140:143], v[164:167], v[52:55]
	v_mfma_f32_16x16x32_bf16 v[48:51], v[140:143], v[168:171], v[48:51]
	s_waitcnt lgkmcnt(10)
	v_mfma_f32_16x16x32_bf16 v[44:47], v[144:147], v[148:151], v[44:47]
	v_mfma_f32_16x16x32_bf16 v[40:43], v[144:147], v[152:155], v[40:43]
	v_mfma_f32_16x16x32_bf16 v[36:39], v[144:147], v[164:167], v[36:39]
	v_mfma_f32_16x16x32_bf16 v[32:35], v[144:147], v[168:171], v[32:35]
	s_waitcnt lgkmcnt(9)
	v_mfma_f32_16x16x32_bf16 v[28:31], v[156:159], v[148:151], v[28:31]
	v_mfma_f32_16x16x32_bf16 v[24:27], v[156:159], v[152:155], v[24:27]
	v_mfma_f32_16x16x32_bf16 v[20:23], v[156:159], v[164:167], v[20:23]
	v_mfma_f32_16x16x32_bf16 v[16:19], v[156:159], v[168:171], v[16:19]
	s_waitcnt lgkmcnt(8)
	v_mfma_f32_16x16x32_bf16 v[12:15], v[160:163], v[148:151], v[12:15]
	v_mfma_f32_16x16x32_bf16 v[8:11], v[160:163], v[152:155], v[8:11]
	v_mfma_f32_16x16x32_bf16 v[4:7], v[160:163], v[164:167], v[4:7]
	v_mfma_f32_16x16x32_bf16 v[0:3], v[160:163], v[168:171], v[0:3]
	s_waitcnt lgkmcnt(3)
	v_mfma_f32_16x16x32_bf16 v[60:63], v[204:207], v[208:211], v[60:63]
	v_mfma_f32_16x16x32_bf16 v[56:59], v[204:207], v[212:215], v[56:59]
	v_mfma_f32_16x16x32_bf16 v[52:55], v[204:207], v[216:219], v[52:55]
	v_mfma_f32_16x16x32_bf16 v[48:51], v[204:207], v[220:223], v[48:51]
	s_waitcnt lgkmcnt(2)
	v_mfma_f32_16x16x32_bf16 v[44:47], v[224:227], v[208:211], v[44:47]
	v_mfma_f32_16x16x32_bf16 v[40:43], v[224:227], v[212:215], v[40:43]
	v_mfma_f32_16x16x32_bf16 v[36:39], v[224:227], v[216:219], v[36:39]
	v_mfma_f32_16x16x32_bf16 v[32:35], v[224:227], v[220:223], v[32:35]
	s_waitcnt lgkmcnt(1)
	v_mfma_f32_16x16x32_bf16 v[28:31], v[228:231], v[208:211], v[28:31]
	v_mfma_f32_16x16x32_bf16 v[24:27], v[228:231], v[212:215], v[24:27]
	v_mfma_f32_16x16x32_bf16 v[20:23], v[228:231], v[216:219], v[20:23]
	v_mfma_f32_16x16x32_bf16 v[16:19], v[228:231], v[220:223], v[16:19]
	s_waitcnt lgkmcnt(0)
	v_mfma_f32_16x16x32_bf16 v[12:15], v[232:235], v[208:211], v[12:15]
	v_mfma_f32_16x16x32_bf16 v[8:11], v[232:235], v[212:215], v[8:11]
	v_mfma_f32_16x16x32_bf16 v[4:7], v[232:235], v[216:219], v[4:7]
	v_mfma_f32_16x16x32_bf16 v[0:3], v[232:235], v[220:223], v[0:3]
	s_setprio 0
	s_cmpk_eq_i32 s16, 0x780
	s_waitcnt vmcnt(0)
	s_barrier
	s_cbranch_scc0 .LBB0_3222
	ds_read_b128 v[90:93], v118 offset:55296
	ds_read_b128 v[94:97], v118 offset:53248
	ds_read_b128 v[98:101], v119 offset:38912
	ds_read_b128 v[102:105], v119 offset:36864
	ds_read_b128 v[140:143], v118 offset:51200
	ds_read_b128 v[144:147], v118 offset:49152
	ds_read_b128 v[148:151], v119 offset:34816
	ds_read_b128 v[152:155], v119 offset:32768
	ds_read_b128 v[204:207], v120 offset:32768
	ds_read_b128 v[208:211], v120 offset:34816
	ds_read_b128 v[212:215], v121 offset:49152
	ds_read_b128 v[216:219], v121 offset:51200
	ds_read_b128 v[220:223], v120 offset:36864
	ds_read_b128 v[224:227], v120 offset:38912
	ds_read_b128 v[228:231], v121 offset:53248
	ds_read_b128 v[232:235], v121 offset:55296
	s_setprio 1
	s_waitcnt lgkmcnt(13)
	v_mfma_f32_16x16x32_bf16 v[4:7], v[98:101], v[94:97], v[4:7]
	v_mfma_f32_16x16x32_bf16 v[0:3], v[98:101], v[90:93], v[0:3]
	s_waitcnt lgkmcnt(8)
	v_mfma_f32_16x16x32_bf16 v[60:63], v[152:155], v[144:147], v[60:63]
	v_mfma_f32_16x16x32_bf16 v[56:59], v[152:155], v[140:143], v[56:59]
	v_mfma_f32_16x16x32_bf16 v[52:55], v[152:155], v[94:97], v[52:55]
	v_mfma_f32_16x16x32_bf16 v[48:51], v[152:155], v[90:93], v[48:51]
	v_mfma_f32_16x16x32_bf16 v[44:47], v[148:151], v[144:147], v[44:47]
	v_mfma_f32_16x16x32_bf16 v[40:43], v[148:151], v[140:143], v[40:43]
	v_mfma_f32_16x16x32_bf16 v[36:39], v[148:151], v[94:97], v[36:39]
	v_mfma_f32_16x16x32_bf16 v[32:35], v[148:151], v[90:93], v[32:35]
	v_mfma_f32_16x16x32_bf16 v[28:31], v[102:105], v[144:147], v[28:31]
	v_mfma_f32_16x16x32_bf16 v[24:27], v[102:105], v[140:143], v[24:27]
	v_mfma_f32_16x16x32_bf16 v[20:23], v[102:105], v[94:97], v[20:23]
	v_mfma_f32_16x16x32_bf16 v[16:19], v[102:105], v[90:93], v[16:19]
	v_mfma_f32_16x16x32_bf16 v[12:15], v[98:101], v[144:147], v[12:15]
	v_mfma_f32_16x16x32_bf16 v[8:11], v[98:101], v[140:143], v[8:11]
	s_waitcnt lgkmcnt(1)
	v_mfma_f32_16x16x32_bf16 v[4:7], v[224:227], v[228:231], v[4:7]
	s_waitcnt lgkmcnt(0)
	v_mfma_f32_16x16x32_bf16 v[0:3], v[224:227], v[232:235], v[0:3]
	v_mfma_f32_16x16x32_bf16 v[60:63], v[204:207], v[212:215], v[60:63]
	v_mfma_f32_16x16x32_bf16 v[56:59], v[204:207], v[216:219], v[56:59]
	v_mfma_f32_16x16x32_bf16 v[52:55], v[204:207], v[228:231], v[52:55]
	v_mfma_f32_16x16x32_bf16 v[48:51], v[204:207], v[232:235], v[48:51]
	v_mfma_f32_16x16x32_bf16 v[44:47], v[208:211], v[212:215], v[44:47]
	v_mfma_f32_16x16x32_bf16 v[40:43], v[208:211], v[216:219], v[40:43]
	v_mfma_f32_16x16x32_bf16 v[36:39], v[208:211], v[228:231], v[36:39]
	v_mfma_f32_16x16x32_bf16 v[32:35], v[208:211], v[232:235], v[32:35]
	v_mfma_f32_16x16x32_bf16 v[28:31], v[220:223], v[212:215], v[28:31]
	v_mfma_f32_16x16x32_bf16 v[24:27], v[220:223], v[216:219], v[24:27]
	v_mfma_f32_16x16x32_bf16 v[20:23], v[220:223], v[228:231], v[20:23]
	v_mfma_f32_16x16x32_bf16 v[16:19], v[220:223], v[232:235], v[16:19]
	v_mfma_f32_16x16x32_bf16 v[12:15], v[224:227], v[212:215], v[12:15]
	v_mfma_f32_16x16x32_bf16 v[8:11], v[224:227], v[216:219], v[8:11]
	s_setprio 0
	s_barrier
	ds_write2_b32 v116, v60, v56 offset1:16
	ds_write2_b32 v116, v61, v57 offset0:132 offset1:148
	v_add_u32_e32 v56, 0x400, v116
	ds_write2_b32 v56, v62, v58 offset0:8 offset1:24
	ds_write2_b32 v56, v63, v59 offset0:140 offset1:156
	ds_write2_b32 v116, v52, v48 offset0:32 offset1:48
	ds_write2_b32 v116, v53, v49 offset0:164 offset1:180
	ds_write2_b32 v56, v54, v50 offset0:40 offset1:56
	ds_write2_b32 v56, v55, v51 offset0:172 offset1:188
	v_add_u32_e32 v48, 0x2000, v116
	ds_write2_b32 v48, v44, v40 offset0:64 offset1:80
	ds_write2_b32 v48, v45, v41 offset0:196 offset1:212
	v_add_u32_e32 v40, 0x2400, v116
	ds_write2_b32 v40, v46, v42 offset0:72 offset1:88
	ds_write2_b32 v40, v47, v43 offset0:204 offset1:220
	ds_write2_b32 v48, v36, v32 offset0:96 offset1:112
	ds_write2_b32 v48, v37, v33 offset0:228 offset1:244
	ds_write2_b32 v40, v38, v34 offset0:104 offset1:120
	ds_write2_b32 v40, v39, v35 offset0:236 offset1:252
	v_add_u32_e32 v32, 0x4000, v116
	ds_write2_b32 v32, v28, v24 offset0:128 offset1:144
	v_add_u32_e32 v24, 0x4400, v116
	ds_write2_b32 v24, v29, v25 offset0:4 offset1:20
	ds_write2_b32 v24, v30, v26 offset0:136 offset1:152
	v_add_u32_e32 v25, 0x4800, v116
	ds_write2_b32 v25, v31, v27 offset0:12 offset1:28
	ds_write2_b32 v32, v20, v16 offset0:160 offset1:176
	ds_write2_b32 v24, v21, v17 offset0:36 offset1:52
	ds_write2_b32 v24, v22, v18 offset0:168 offset1:184
	ds_write2_b32 v25, v23, v19 offset0:44 offset1:60
	v_add_u32_e32 v16, 0x6000, v116
	ds_write2_b32 v16, v12, v8 offset0:192 offset1:208
	v_add_u32_e32 v8, 0x6400, v116
	ds_write2_b32 v8, v13, v9 offset0:68 offset1:84
	ds_write2_b32 v8, v14, v10 offset0:200 offset1:216
	v_add_u32_e32 v9, 0x6800, v116
	ds_write2_b32 v9, v15, v11 offset0:76 offset1:92
	ds_write2_b32 v16, v4, v0 offset0:224 offset1:240
	ds_write2_b32 v8, v5, v1 offset0:100 offset1:116
	ds_write2_b32 v8, v6, v2 offset0:232 offset1:248
	ds_write2_b32 v9, v7, v3 offset0:108 offset1:124
	v_or_b32_e32 v0, s25, v117
	v_ashrrev_i32_e32 v1, 31, v0
	v_lshlrev_b64 v[2:3], 2, v[0:1]
	v_lshl_add_u64 v[0:1], s[14:15], 0, v[2:3]
	v_lshl_add_u64 v[2:3], s[6:7], 0, v[2:3]
	v_add_u32_e32 v4, s24, v129
	s_mov_b32 s16, 0
	s_waitcnt lgkmcnt(0)
	s_barrier

.LBB0_3230:
	s_ashr_i32 s8, s14, 31
	s_lshr_b32 s8, s8, 29
	s_add_i32 s8, s14, s8
	s_ashr_i32 s8, s8, 3
	s_add_i32 s9, s8, s16
	s_lshl_b32 s20, s8, 7
	s_lshl_b32 s8, s8, 10
	s_lshl_b32 s21, s14, 7
	s_sub_i32 s21, s21, s8
	s_lshr_b32 s9, s9, 4
	v_add_u32_e32 v0, s21, v104
	s_mulk_i32 s9, 0x900
	s_and_b32 s20, s20, 0x780
	v_ashrrev_i32_e32 v1, 31, v0
	v_add_u32_e32 v2, 0x4000, v105
	s_add_i32 s20, s20, s9
	v_lshlrev_b64 v[0:1], 11, v[0:1]
	v_readfirstlane_b32 s22, v2
	s_add_i32 s9, s20, 0x100
	v_lshl_add_u64 v[0:1], v[64:65], 0, v[0:1]
	s_mov_b32 m0, s22
	v_readfirstlane_b32 s22, v105
	global_load_lds_dwordx4 v[0:1], off
	v_add_u32_e32 v0, s9, v104
	v_ashrrev_i32_e32 v1, 31, v0
	v_lshlrev_b64 v[0:1], 11, v[0:1]
	v_lshl_add_u64 v[0:1], v[70:71], 0, v[0:1]
	s_mov_b32 m0, s22
	v_readfirstlane_b32 s22, v130
	global_load_lds_dwordx4 v[0:1], off
	v_add_u32_e32 v0, s21, v106
	v_ashrrev_i32_e32 v1, 31, v0
	v_lshlrev_b64 v[0:1], 11, v[0:1]
	v_lshl_add_u64 v[0:1], v[66:67], 0, v[0:1]
	s_mov_b32 m0, s22
	v_add_u32_e32 v2, 0x400, v105
	global_load_lds_dwordx4 v[0:1], off
	v_add_u32_e32 v0, s9, v106
	v_ashrrev_i32_e32 v1, 31, v0
	v_lshlrev_b64 v[0:1], 11, v[0:1]
	v_readfirstlane_b32 s22, v2
	v_lshl_add_u64 v[0:1], v[72:73], 0, v[0:1]
	s_mov_b32 m0, s22
	v_readfirstlane_b32 s22, v131
	global_load_lds_dwordx4 v[0:1], off
	v_add_u32_e32 v0, s21, v108
	v_ashrrev_i32_e32 v1, 31, v0
	v_lshlrev_b64 v[0:1], 11, v[0:1]
	v_lshl_add_u64 v[0:1], v[64:65], 0, v[0:1]
	s_mov_b32 m0, s22
	v_add_u32_e32 v2, 0x800, v105
	global_load_lds_dwordx4 v[0:1], off
	v_add_u32_e32 v0, s9, v108
	v_ashrrev_i32_e32 v1, 31, v0
	v_lshlrev_b64 v[0:1], 11, v[0:1]
	v_readfirstlane_b32 s22, v2
	v_lshl_add_u64 v[0:1], v[70:71], 0, v[0:1]
	s_mov_b32 m0, s22
	v_readfirstlane_b32 s22, v132
	global_load_lds_dwordx4 v[0:1], off
	v_add_u32_e32 v0, s21, v110
	v_ashrrev_i32_e32 v1, 31, v0
	v_lshlrev_b64 v[0:1], 11, v[0:1]
	v_lshl_add_u64 v[0:1], v[68:69], 0, v[0:1]
	s_mov_b32 m0, s22
	v_add_u32_e32 v2, 0xc00, v105
	global_load_lds_dwordx4 v[0:1], off
	v_add_u32_e32 v0, s9, v110
	v_ashrrev_i32_e32 v1, 31, v0
	v_lshlrev_b64 v[0:1], 11, v[0:1]
	v_readfirstlane_b32 s9, v2
	v_lshl_add_u64 v[0:1], v[74:75], 0, v[0:1]
	s_mov_b32 m0, s9
	s_mov_b32 s22, 0
	global_load_lds_dwordx4 v[0:1], off
	v_subrev_u32_e32 v0, s8, v120
	v_ashrrev_i32_e32 v1, 31, v0
	v_lshlrev_b64 v[0:1], 11, v[0:1]
	v_lshl_add_u64 v[88:89], v[76:77], 0, v[0:1]
	v_add_u32_e32 v0, s20, v121
	v_ashrrev_i32_e32 v1, 31, v0
	v_lshlrev_b64 v[0:1], 11, v[0:1]
	v_lshl_add_u64 v[90:91], v[78:79], 0, v[0:1]
	v_subrev_u32_e32 v0, s8, v122
	v_ashrrev_i32_e32 v1, 31, v0
	v_lshlrev_b64 v[0:1], 11, v[0:1]
	v_lshl_add_u64 v[92:93], v[80:81], 0, v[0:1]
	v_add_u32_e32 v0, s20, v123
	v_ashrrev_i32_e32 v1, 31, v0
	v_lshlrev_b64 v[0:1], 11, v[0:1]
	v_lshl_add_u64 v[94:95], v[82:83], 0, v[0:1]
	v_subrev_u32_e32 v0, s8, v124
	v_ashrrev_i32_e32 v1, 31, v0
	v_lshlrev_b64 v[0:1], 11, v[0:1]
	v_lshl_add_u64 v[96:97], v[76:77], 0, v[0:1]
	v_add_u32_e32 v0, s20, v125
	v_ashrrev_i32_e32 v1, 31, v0
	v_lshlrev_b64 v[0:1], 11, v[0:1]
	v_lshl_add_u64 v[98:99], v[78:79], 0, v[0:1]
	v_subrev_u32_e32 v0, s8, v126
	v_ashrrev_i32_e32 v1, 31, v0
	v_lshlrev_b64 v[0:1], 11, v[0:1]
	v_lshl_add_u64 v[100:101], v[84:85], 0, v[0:1]
	v_add_u32_e32 v0, s20, v127
	v_ashrrev_i32_e32 v1, 31, v0
	v_lshlrev_b64 v[0:1], 11, v[0:1]
	v_lshl_add_u64 v[102:103], v[86:87], 0, v[0:1]
	v_mov_b32_e32 v0, 0
	s_mov_b64 s[8:9], 0
	v_mov_b32_e32 v1, v0
	v_mov_b32_e32 v2, v0
	v_mov_b32_e32 v3, v0
	v_mov_b32_e32 v4, v0
	v_mov_b32_e32 v5, v0
	v_mov_b32_e32 v6, v0
	v_mov_b32_e32 v7, v0
	v_mov_b32_e32 v8, v0
	v_mov_b32_e32 v9, v0
	v_mov_b32_e32 v10, v0
	v_mov_b32_e32 v11, v0
	v_mov_b32_e32 v12, v0
	v_mov_b32_e32 v13, v0
	v_mov_b32_e32 v14, v0
	v_mov_b32_e32 v15, v0
	v_mov_b32_e32 v16, v0
	v_mov_b32_e32 v17, v0
	v_mov_b32_e32 v18, v0
	v_mov_b32_e32 v19, v0
	v_mov_b32_e32 v20, v0
	v_mov_b32_e32 v21, v0
	v_mov_b32_e32 v22, v0
	v_mov_b32_e32 v23, v0
	v_mov_b32_e32 v24, v0
	v_mov_b32_e32 v25, v0
	v_mov_b32_e32 v26, v0
	v_mov_b32_e32 v27, v0
	s_waitcnt vmcnt(0)
	v_mov_b32_e32 v28, v0
	v_mov_b32_e32 v29, v0
	v_mov_b32_e32 v30, v0
	v_mov_b32_e32 v31, v0
	v_mov_b32_e32 v32, v0
	v_mov_b32_e32 v33, v0
	v_mov_b32_e32 v34, v0
	v_mov_b32_e32 v35, v0
	v_mov_b32_e32 v36, v0
	v_mov_b32_e32 v37, v0
	v_mov_b32_e32 v38, v0
	v_mov_b32_e32 v39, v0
	v_mov_b32_e32 v40, v0
	v_mov_b32_e32 v41, v0
	v_mov_b32_e32 v42, v0
	v_mov_b32_e32 v43, v0
	v_mov_b32_e32 v44, v0
	v_mov_b32_e32 v45, v0
	v_mov_b32_e32 v46, v0
	v_mov_b32_e32 v47, v0
	v_mov_b32_e32 v48, v0
	v_mov_b32_e32 v49, v0
	v_mov_b32_e32 v50, v0
	v_mov_b32_e32 v51, v0
	v_mov_b32_e32 v52, v0
	v_mov_b32_e32 v53, v0
	v_mov_b32_e32 v54, v0
	v_mov_b32_e32 v55, v0
	v_mov_b32_e32 v56, v0
	v_mov_b32_e32 v57, v0
	v_mov_b32_e32 v58, v0
	v_mov_b32_e32 v59, v0
	v_mov_b32_e32 v60, v0
	v_mov_b32_e32 v61, v0
	v_mov_b32_e32 v62, v0
	v_mov_b32_e32 v63, v0
	s_waitcnt lgkmcnt(0)
	s_barrier
	v_add3_u32 v182, 0, v133, v134
	v_add_u32_e32 v183, 0x4000, v182
	s_nop 0
	v_readfirstlane_b32 s82, v183
	v_lshl_add_u32 v183, v107, 1, 0
	s_nop 0
	v_readfirstlane_b32 s83, v182
	v_add3_u32 v183, v183, v134, s13
	s_nop 0
	v_readfirstlane_b32 s84, v183
	v_add_u32_e32 v183, 0x400, v182
	s_nop 0
	v_readfirstlane_b32 s85, v183
	v_lshl_add_u32 v183, v109, 1, 0
	v_add3_u32 v183, v183, v134, s13
	s_nop 0
	v_readfirstlane_b32 s86, v183
	v_add_u32_e32 v183, 0x800, v182
	s_nop 0
	v_readfirstlane_b32 s87, v183
	v_lshl_add_u32 v183, v111, 1, 0
	v_add3_u32 v183, v183, v134, s13
	s_nop 0
	v_readfirstlane_b32 s88, v183
	v_add_u32_e32 v182, 0xc00, v182
	s_nop 0
	v_readfirstlane_b32 s89, v182
	v_subrev_u32_e32 v184, s52, v88
	v_subrev_u32_e32 v185, s52, v90
	v_subrev_u32_e32 v186, s52, v92
	v_subrev_u32_e32 v187, s52, v94
	v_subrev_u32_e32 v188, s52, v96
	v_subrev_u32_e32 v189, s52, v98
	v_subrev_u32_e32 v190, s52, v100
	v_subrev_u32_e32 v191, s52, v102
	v_subrev_u32_e32 v187, 0x400, v187
	v_subrev_u32_e32 v186, 0x400, v186
	v_subrev_u32_e32 v189, 0x800, v189
	v_subrev_u32_e32 v188, 0x800, v188
	v_subrev_u32_e32 v191, 0xc00, v191
	v_subrev_u32_e32 v190, 0xc00, v190
	s_and_b32 s24, s22, 0x4000
	s_xor_b32 s23, s24, 0x4000
	s_lshl_b32 s23, s23, 1
	s_add_i32 s23, s23, 32
	s_lshl_b32 s24, s24, 1
	s_add_i32 s24, s24, 32
.LBB0_3231:
	s_xor_b32 s23, s23, 0x8000
	s_xor_b32 s24, s24, 0x8000
	s_add_u32 s90, s52, s8
	s_addc_u32 s91, s53, s9
	s_add_i32 m0, s24, s83
	v_add3_u32 v170, s23, v112, v135
	global_load_lds_dwordx4 v185, s[90:91]
	global_load_lds_dwordx4 v187, s[90:91] offset:1024
	global_load_lds_dwordx4 v189, s[90:91] offset:2048
	global_load_lds_dwordx4 v191, s[90:91] offset:3072
	s_add_i32 m0, s24, s82
	v_add3_u32 v171, s23, v113, v135
	global_load_lds_dwordx4 v184, s[90:91]
	global_load_lds_dwordx4 v186, s[90:91] offset:1024
	global_load_lds_dwordx4 v188, s[90:91] offset:2048
	global_load_lds_dwordx4 v190, s[90:91] offset:3072
	v_add_u32_e32 v158, v170, v136
	v_add_u32_e32 v166, v171, v136
	s_add_u32 s8, s8, 0x80
	s_addc_u32 s9, s9, 0
	ds_read_b128 v[138:141], v158
	ds_read_b128 v[146:149], v166 offset:16384
	ds_read_b128 v[150:153], v166 offset:18432
	ds_read_b128 v[162:165], v166 offset:20480
	ds_read_b128 v[166:169], v166 offset:22528
	ds_read_b128 v[142:145], v158 offset:2048
	ds_read_b128 v[154:157], v158 offset:4096
	ds_read_b128 v[158:161], v158 offset:6144
	v_add_u32_e32 v236, v170, v137
	v_add_u32_e32 v237, v171, v137
	ds_read_b128 v[204:207], v236
	ds_read_b128 v[208:211], v237 offset:16384
	ds_read_b128 v[212:215], v237 offset:18432
	ds_read_b128 v[216:219], v237 offset:20480
	ds_read_b128 v[220:223], v237 offset:22528
	ds_read_b128 v[224:227], v236 offset:2048
	ds_read_b128 v[228:231], v236 offset:4096
	ds_read_b128 v[232:235], v236 offset:6144
	s_setprio 1
	s_waitcnt lgkmcnt(11)
	v_mfma_f32_16x16x32_bf16 v[60:63], v[138:141], v[146:149], v[60:63]
	v_mfma_f32_16x16x32_bf16 v[56:59], v[138:141], v[150:153], v[56:59]
	v_mfma_f32_16x16x32_bf16 v[52:55], v[138:141], v[162:165], v[52:55]
	v_mfma_f32_16x16x32_bf16 v[48:51], v[138:141], v[166:169], v[48:51]
	s_waitcnt lgkmcnt(10)
	v_mfma_f32_16x16x32_bf16 v[44:47], v[142:145], v[146:149], v[44:47]
	v_mfma_f32_16x16x32_bf16 v[40:43], v[142:145], v[150:153], v[40:43]
	v_mfma_f32_16x16x32_bf16 v[36:39], v[142:145], v[162:165], v[36:39]
	v_mfma_f32_16x16x32_bf16 v[32:35], v[142:145], v[166:169], v[32:35]
	s_waitcnt lgkmcnt(9)
	v_mfma_f32_16x16x32_bf16 v[28:31], v[154:157], v[146:149], v[28:31]
	v_mfma_f32_16x16x32_bf16 v[24:27], v[154:157], v[150:153], v[24:27]
	v_mfma_f32_16x16x32_bf16 v[20:23], v[154:157], v[162:165], v[20:23]
	v_mfma_f32_16x16x32_bf16 v[16:19], v[154:157], v[166:169], v[16:19]
	s_waitcnt lgkmcnt(8)
	v_mfma_f32_16x16x32_bf16 v[12:15], v[158:161], v[146:149], v[12:15]
	v_mfma_f32_16x16x32_bf16 v[8:11], v[158:161], v[150:153], v[8:11]
	v_mfma_f32_16x16x32_bf16 v[4:7], v[158:161], v[162:165], v[4:7]
	v_mfma_f32_16x16x32_bf16 v[0:3], v[158:161], v[166:169], v[0:3]
	s_waitcnt lgkmcnt(3)
	v_mfma_f32_16x16x32_bf16 v[60:63], v[204:207], v[208:211], v[60:63]
	v_mfma_f32_16x16x32_bf16 v[56:59], v[204:207], v[212:215], v[56:59]
	v_mfma_f32_16x16x32_bf16 v[52:55], v[204:207], v[216:219], v[52:55]
	v_mfma_f32_16x16x32_bf16 v[48:51], v[204:207], v[220:223], v[48:51]
	s_waitcnt lgkmcnt(2)
	v_mfma_f32_16x16x32_bf16 v[44:47], v[224:227], v[208:211], v[44:47]
	v_mfma_f32_16x16x32_bf16 v[40:43], v[224:227], v[212:215], v[40:43]
	v_mfma_f32_16x16x32_bf16 v[36:39], v[224:227], v[216:219], v[36:39]
	v_mfma_f32_16x16x32_bf16 v[32:35], v[224:227], v[220:223], v[32:35]
	s_waitcnt lgkmcnt(1)
	v_mfma_f32_16x16x32_bf16 v[28:31], v[228:231], v[208:211], v[28:31]
	v_mfma_f32_16x16x32_bf16 v[24:27], v[228:231], v[212:215], v[24:27]
	v_mfma_f32_16x16x32_bf16 v[20:23], v[228:231], v[216:219], v[20:23]
	v_mfma_f32_16x16x32_bf16 v[16:19], v[228:231], v[220:223], v[16:19]
	s_waitcnt lgkmcnt(0)
	v_mfma_f32_16x16x32_bf16 v[12:15], v[232:235], v[208:211], v[12:15]
	v_mfma_f32_16x16x32_bf16 v[8:11], v[232:235], v[212:215], v[8:11]
	v_mfma_f32_16x16x32_bf16 v[4:7], v[232:235], v[216:219], v[4:7]
	v_mfma_f32_16x16x32_bf16 v[0:3], v[232:235], v[220:223], v[0:3]
	s_setprio 0
	s_cmpk_eq_i32 s8, 0x780
	s_waitcnt vmcnt(0)
	s_barrier
	s_cbranch_scc0 .LBB0_3231
	ds_read_b128 v[88:91], v116 offset:55296
	ds_read_b128 v[92:95], v116 offset:53248
	ds_read_b128 v[96:99], v117 offset:38912
	ds_read_b128 v[100:103], v117 offset:36864
	ds_read_b128 v[138:141], v116 offset:51200
	ds_read_b128 v[142:145], v116 offset:49152
	ds_read_b128 v[146:149], v117 offset:34816
	ds_read_b128 v[150:153], v117 offset:32768
	ds_read_b128 v[204:207], v118 offset:32768
	ds_read_b128 v[208:211], v118 offset:34816
	ds_read_b128 v[212:215], v119 offset:49152
	ds_read_b128 v[216:219], v119 offset:51200
	ds_read_b128 v[220:223], v118 offset:36864
	ds_read_b128 v[224:227], v118 offset:38912
	ds_read_b128 v[228:231], v119 offset:53248
	ds_read_b128 v[232:235], v119 offset:55296
	s_setprio 1
	s_waitcnt lgkmcnt(13)
	v_mfma_f32_16x16x32_bf16 v[4:7], v[96:99], v[92:95], v[4:7]
	v_mfma_f32_16x16x32_bf16 v[0:3], v[96:99], v[88:91], v[0:3]
	s_waitcnt lgkmcnt(8)
	v_mfma_f32_16x16x32_bf16 v[60:63], v[150:153], v[142:145], v[60:63]
	v_mfma_f32_16x16x32_bf16 v[56:59], v[150:153], v[138:141], v[56:59]
	v_mfma_f32_16x16x32_bf16 v[52:55], v[150:153], v[92:95], v[52:55]
	v_mfma_f32_16x16x32_bf16 v[48:51], v[150:153], v[88:91], v[48:51]
	v_mfma_f32_16x16x32_bf16 v[44:47], v[146:149], v[142:145], v[44:47]
	v_mfma_f32_16x16x32_bf16 v[40:43], v[146:149], v[138:141], v[40:43]
	v_mfma_f32_16x16x32_bf16 v[36:39], v[146:149], v[92:95], v[36:39]
	v_mfma_f32_16x16x32_bf16 v[32:35], v[146:149], v[88:91], v[32:35]
	v_mfma_f32_16x16x32_bf16 v[28:31], v[100:103], v[142:145], v[28:31]
	v_mfma_f32_16x16x32_bf16 v[24:27], v[100:103], v[138:141], v[24:27]
	v_mfma_f32_16x16x32_bf16 v[20:23], v[100:103], v[92:95], v[20:23]
	v_mfma_f32_16x16x32_bf16 v[16:19], v[100:103], v[88:91], v[16:19]
	v_mfma_f32_16x16x32_bf16 v[12:15], v[96:99], v[142:145], v[12:15]
	v_mfma_f32_16x16x32_bf16 v[8:11], v[96:99], v[138:141], v[8:11]
	s_waitcnt lgkmcnt(1)
	v_mfma_f32_16x16x32_bf16 v[4:7], v[224:227], v[228:231], v[4:7]
	s_waitcnt lgkmcnt(0)
	v_mfma_f32_16x16x32_bf16 v[0:3], v[224:227], v[232:235], v[0:3]
	v_mfma_f32_16x16x32_bf16 v[60:63], v[204:207], v[212:215], v[60:63]
	v_mfma_f32_16x16x32_bf16 v[56:59], v[204:207], v[216:219], v[56:59]
	v_mfma_f32_16x16x32_bf16 v[52:55], v[204:207], v[228:231], v[52:55]
	v_mfma_f32_16x16x32_bf16 v[48:51], v[204:207], v[232:235], v[48:51]
	v_mfma_f32_16x16x32_bf16 v[44:47], v[208:211], v[212:215], v[44:47]
	v_mfma_f32_16x16x32_bf16 v[40:43], v[208:211], v[216:219], v[40:43]
	v_mfma_f32_16x16x32_bf16 v[36:39], v[208:211], v[228:231], v[36:39]
	v_mfma_f32_16x16x32_bf16 v[32:35], v[208:211], v[232:235], v[32:35]
	v_mfma_f32_16x16x32_bf16 v[28:31], v[220:223], v[212:215], v[28:31]
	v_mfma_f32_16x16x32_bf16 v[24:27], v[220:223], v[216:219], v[24:27]
	v_mfma_f32_16x16x32_bf16 v[20:23], v[220:223], v[228:231], v[20:23]
	v_mfma_f32_16x16x32_bf16 v[16:19], v[220:223], v[232:235], v[16:19]
	v_mfma_f32_16x16x32_bf16 v[12:15], v[224:227], v[212:215], v[12:15]
	v_mfma_f32_16x16x32_bf16 v[8:11], v[224:227], v[216:219], v[8:11]
	s_setprio 0
	s_barrier
	ds_write2_b32 v114, v60, v56 offset1:16
	ds_write2_b32 v114, v61, v57 offset0:132 offset1:148
	v_add_u32_e32 v56, 0x400, v114
	ds_write2_b32 v56, v62, v58 offset0:8 offset1:24
	ds_write2_b32 v56, v63, v59 offset0:140 offset1:156
	ds_write2_b32 v114, v52, v48 offset0:32 offset1:48
	ds_write2_b32 v114, v53, v49 offset0:164 offset1:180
	ds_write2_b32 v56, v54, v50 offset0:40 offset1:56
	ds_write2_b32 v56, v55, v51 offset0:172 offset1:188
	v_add_u32_e32 v48, 0x2000, v114
	ds_write2_b32 v48, v44, v40 offset0:64 offset1:80
	ds_write2_b32 v48, v45, v41 offset0:196 offset1:212
	v_add_u32_e32 v40, 0x2400, v114
	ds_write2_b32 v40, v46, v42 offset0:72 offset1:88
	ds_write2_b32 v40, v47, v43 offset0:204 offset1:220
	ds_write2_b32 v48, v36, v32 offset0:96 offset1:112
	ds_write2_b32 v48, v37, v33 offset0:228 offset1:244
	ds_write2_b32 v40, v38, v34 offset0:104 offset1:120
	ds_write2_b32 v40, v39, v35 offset0:236 offset1:252
	v_add_u32_e32 v32, 0x4000, v114
	ds_write2_b32 v32, v28, v24 offset0:128 offset1:144
	v_add_u32_e32 v24, 0x4400, v114
	ds_write2_b32 v24, v29, v25 offset0:4 offset1:20
	ds_write2_b32 v24, v30, v26 offset0:136 offset1:152
	v_add_u32_e32 v25, 0x4800, v114
	ds_write2_b32 v25, v31, v27 offset0:12 offset1:28
	ds_write2_b32 v32, v20, v16 offset0:160 offset1:176
	ds_write2_b32 v24, v21, v17 offset0:36 offset1:52
	ds_write2_b32 v24, v22, v18 offset0:168 offset1:184
	ds_write2_b32 v25, v23, v19 offset0:44 offset1:60
	v_add_u32_e32 v16, 0x6000, v114
	ds_write2_b32 v16, v12, v8 offset0:192 offset1:208
	v_add_u32_e32 v8, 0x6400, v114
	ds_write2_b32 v8, v13, v9 offset0:68 offset1:84
	ds_write2_b32 v8, v14, v10 offset0:200 offset1:216
	v_add_u32_e32 v9, 0x6800, v114
	ds_write2_b32 v9, v15, v11 offset0:76 offset1:92
	ds_write2_b32 v16, v4, v0 offset0:224 offset1:240
	ds_write2_b32 v8, v5, v1 offset0:100 offset1:116
	ds_write2_b32 v8, v6, v2 offset0:232 offset1:248
	ds_write2_b32 v9, v7, v3 offset0:108 offset1:124
	v_or_b32_e32 v0, s21, v115
	v_ashrrev_i32_e32 v1, 31, v0
	v_lshlrev_b64 v[2:3], 2, v[0:1]
	v_lshl_add_u64 v[0:1], s[10:11], 0, v[2:3]
	v_lshl_add_u64 v[2:3], s[6:7], 0, v[2:3]
	v_add_u32_e32 v4, s20, v128
	s_mov_b32 s8, 0
	s_waitcnt lgkmcnt(0)
	s_barrier

.LBB0_3387:
	s_ashr_i32 s12, s16, 31
	s_lshr_b32 s12, s12, 27
	s_add_i32 s12, s16, s12
	s_ashr_i32 s12, s12, 5
	s_lshr_b32 s13, s12, 4
	s_lshl_b32 s17, s12, 7
	s_lshl_b32 s12, s12, 12
	s_lshl_b32 s18, s16, 7
	s_sub_i32 s18, s18, s12
	v_add_u32_e32 v0, s18, v106
	s_mulk_i32 s13, 0x900
	s_and_b32 s17, s17, 0x780
	v_ashrrev_i32_e32 v1, 31, v0
	v_add_u32_e32 v2, 0x4000, v107
	s_add_i32 s17, s17, s13
	v_lshlrev_b64 v[0:1], 11, v[0:1]
	v_readfirstlane_b32 s19, v2
	s_add_i32 s13, s17, 0x100
	v_lshl_add_u64 v[0:1], v[66:67], 0, v[0:1]
	s_mov_b32 m0, s19
	v_readfirstlane_b32 s19, v107
	global_load_lds_dwordx4 v[0:1], off
	v_add_u32_e32 v0, s13, v106
	v_ashrrev_i32_e32 v1, 31, v0
	v_lshlrev_b64 v[0:1], 11, v[0:1]
	v_lshl_add_u64 v[0:1], v[72:73], 0, v[0:1]
	s_mov_b32 m0, s19
	v_readfirstlane_b32 s19, v131
	global_load_lds_dwordx4 v[0:1], off
	v_add_u32_e32 v0, s18, v108
	v_ashrrev_i32_e32 v1, 31, v0
	v_lshlrev_b64 v[0:1], 11, v[0:1]
	v_lshl_add_u64 v[0:1], v[68:69], 0, v[0:1]
	s_mov_b32 m0, s19
	v_add_u32_e32 v2, 0x400, v107
	global_load_lds_dwordx4 v[0:1], off
	v_add_u32_e32 v0, s13, v108
	v_ashrrev_i32_e32 v1, 31, v0
	v_lshlrev_b64 v[0:1], 11, v[0:1]
	v_readfirstlane_b32 s19, v2
	v_lshl_add_u64 v[0:1], v[74:75], 0, v[0:1]
	s_mov_b32 m0, s19
	v_readfirstlane_b32 s19, v132
	global_load_lds_dwordx4 v[0:1], off
	v_add_u32_e32 v0, s18, v110
	v_ashrrev_i32_e32 v1, 31, v0
	v_lshlrev_b64 v[0:1], 11, v[0:1]
	v_lshl_add_u64 v[0:1], v[66:67], 0, v[0:1]
	s_mov_b32 m0, s19
	v_add_u32_e32 v2, 0x800, v107
	global_load_lds_dwordx4 v[0:1], off
	v_add_u32_e32 v0, s13, v110
	v_ashrrev_i32_e32 v1, 31, v0
	v_lshlrev_b64 v[0:1], 11, v[0:1]
	v_readfirstlane_b32 s19, v2
	v_lshl_add_u64 v[0:1], v[72:73], 0, v[0:1]
	s_mov_b32 m0, s19
	v_readfirstlane_b32 s19, v133
	global_load_lds_dwordx4 v[0:1], off
	v_add_u32_e32 v0, s18, v112
	v_ashrrev_i32_e32 v1, 31, v0
	v_lshlrev_b64 v[0:1], 11, v[0:1]
	v_lshl_add_u64 v[0:1], v[70:71], 0, v[0:1]
	s_mov_b32 m0, s19
	v_add_u32_e32 v2, 0xc00, v107
	global_load_lds_dwordx4 v[0:1], off
	v_add_u32_e32 v0, s13, v112
	v_ashrrev_i32_e32 v1, 31, v0
	v_lshlrev_b64 v[0:1], 11, v[0:1]
	v_readfirstlane_b32 s13, v2
	v_lshl_add_u64 v[0:1], v[76:77], 0, v[0:1]
	s_mov_b32 m0, s13
	s_mov_b32 s19, 0
	global_load_lds_dwordx4 v[0:1], off
	v_subrev_u32_e32 v0, s12, v122
	v_ashrrev_i32_e32 v1, 31, v0
	v_lshlrev_b64 v[0:1], 11, v[0:1]
	v_lshl_add_u64 v[90:91], v[78:79], 0, v[0:1]
	v_add_u32_e32 v0, s17, v123
	v_ashrrev_i32_e32 v1, 31, v0
	v_lshlrev_b64 v[0:1], 11, v[0:1]
	v_lshl_add_u64 v[92:93], v[80:81], 0, v[0:1]
	v_subrev_u32_e32 v0, s12, v124
	v_ashrrev_i32_e32 v1, 31, v0
	v_lshlrev_b64 v[0:1], 11, v[0:1]
	v_lshl_add_u64 v[94:95], v[82:83], 0, v[0:1]
	v_add_u32_e32 v0, s17, v125
	v_ashrrev_i32_e32 v1, 31, v0
	v_lshlrev_b64 v[0:1], 11, v[0:1]
	v_lshl_add_u64 v[96:97], v[84:85], 0, v[0:1]
	v_subrev_u32_e32 v0, s12, v126
	v_ashrrev_i32_e32 v1, 31, v0
	v_lshlrev_b64 v[0:1], 11, v[0:1]
	v_lshl_add_u64 v[98:99], v[78:79], 0, v[0:1]
	v_add_u32_e32 v0, s17, v127
	v_ashrrev_i32_e32 v1, 31, v0
	v_lshlrev_b64 v[0:1], 11, v[0:1]
	v_lshl_add_u64 v[100:101], v[80:81], 0, v[0:1]
	v_subrev_u32_e32 v0, s12, v64
	v_ashrrev_i32_e32 v1, 31, v0
	v_lshlrev_b64 v[0:1], 11, v[0:1]
	v_lshl_add_u64 v[102:103], v[86:87], 0, v[0:1]
	v_add_u32_e32 v0, s17, v128
	v_ashrrev_i32_e32 v1, 31, v0
	v_lshlrev_b64 v[0:1], 11, v[0:1]
	v_lshl_add_u64 v[104:105], v[88:89], 0, v[0:1]
	s_mov_b64 s[12:13], 0
	v_mov_b32_e32 v0, 0
	v_mov_b32_e32 v1, v65
	v_mov_b32_e32 v2, v65
	v_mov_b32_e32 v3, v65
	v_mov_b32_e32 v4, 0
	v_mov_b32_e32 v5, v65
	v_mov_b32_e32 v6, v65
	v_mov_b32_e32 v7, v65
	v_mov_b32_e32 v8, 0
	v_mov_b32_e32 v9, v65
	v_mov_b32_e32 v10, v65
	v_mov_b32_e32 v11, v65
	v_mov_b32_e32 v12, 0
	v_mov_b32_e32 v13, v65
	v_mov_b32_e32 v14, v65
	v_mov_b32_e32 v15, v65
	v_mov_b32_e32 v16, 0
	v_mov_b32_e32 v17, v65
	v_mov_b32_e32 v18, v65
	v_mov_b32_e32 v19, v65
	v_mov_b32_e32 v20, 0
	v_mov_b32_e32 v21, v65
	v_mov_b32_e32 v22, v65
	v_mov_b32_e32 v23, v65
	v_mov_b32_e32 v24, 0
	v_mov_b32_e32 v25, v65
	v_mov_b32_e32 v26, v65
	v_mov_b32_e32 v27, v65
	v_mov_b32_e32 v28, 0
	v_mov_b32_e32 v29, v65
	v_mov_b32_e32 v30, v65
	v_mov_b32_e32 v31, v65
	v_mov_b32_e32 v32, 0
	v_mov_b32_e32 v33, v65
	v_mov_b32_e32 v34, v65
	v_mov_b32_e32 v35, v65
	v_mov_b32_e32 v36, 0
	v_mov_b32_e32 v37, v65
	v_mov_b32_e32 v38, v65
	v_mov_b32_e32 v39, v65
	v_mov_b32_e32 v40, 0
	v_mov_b32_e32 v41, v65
	v_mov_b32_e32 v42, v65
	v_mov_b32_e32 v43, v65
	v_mov_b32_e32 v44, 0
	v_mov_b32_e32 v45, v65
	v_mov_b32_e32 v46, v65
	v_mov_b32_e32 v47, v65
	v_mov_b32_e32 v48, 0
	v_mov_b32_e32 v49, v65
	v_mov_b32_e32 v50, v65
	v_mov_b32_e32 v51, v65
	v_mov_b32_e32 v52, 0
	v_mov_b32_e32 v53, v65
	v_mov_b32_e32 v54, v65
	v_mov_b32_e32 v55, v65
	v_mov_b32_e32 v56, 0
	v_mov_b32_e32 v57, v65
	v_mov_b32_e32 v58, v65
	v_mov_b32_e32 v59, v65
	v_mov_b32_e32 v60, 0
	v_mov_b32_e32 v61, v65
	v_mov_b32_e32 v62, v65
	v_mov_b32_e32 v63, v65
	s_waitcnt vmcnt(0) lgkmcnt(0)
	s_barrier
	v_add3_u32 v182, 0, v134, v135
	v_add_u32_e32 v183, 0x4000, v182
	s_nop 0
	v_readfirstlane_b32 s82, v183
	v_lshl_add_u32 v183, v109, 1, 0
	s_nop 0
	v_readfirstlane_b32 s83, v182
	v_add3_u32 v183, v183, v135, s15
	s_nop 0
	v_readfirstlane_b32 s84, v183
	v_add_u32_e32 v183, 0x400, v182
	s_nop 0
	v_readfirstlane_b32 s85, v183
	v_lshl_add_u32 v183, v111, 1, 0
	v_add3_u32 v183, v183, v135, s15
	s_nop 0
	v_readfirstlane_b32 s86, v183
	v_add_u32_e32 v183, 0x800, v182
	s_nop 0
	v_readfirstlane_b32 s87, v183
	v_lshl_add_u32 v183, v113, 1, 0
	v_add3_u32 v183, v183, v135, s15
	s_nop 0
	v_readfirstlane_b32 s88, v183
	v_add_u32_e32 v182, 0xc00, v182
	s_nop 0
	v_readfirstlane_b32 s89, v182
	v_subrev_u32_e32 v184, s52, v90
	v_subrev_u32_e32 v185, s52, v92
	v_subrev_u32_e32 v186, s52, v94
	v_subrev_u32_e32 v187, s52, v96
	v_subrev_u32_e32 v188, s52, v98
	v_subrev_u32_e32 v189, s52, v100
	v_subrev_u32_e32 v190, s52, v102
	v_subrev_u32_e32 v191, s52, v104
	v_subrev_u32_e32 v187, 0x400, v187
	v_subrev_u32_e32 v186, 0x400, v186
	v_subrev_u32_e32 v189, 0x800, v189
	v_subrev_u32_e32 v188, 0x800, v188
	v_subrev_u32_e32 v191, 0xc00, v191
	v_subrev_u32_e32 v190, 0xc00, v190
	s_and_b32 s21, s19, 0x4000
	s_xor_b32 s20, s21, 0x4000
	s_lshl_b32 s20, s20, 1
	s_add_i32 s20, s20, 32
	s_lshl_b32 s21, s21, 1
	s_add_i32 s21, s21, 32
.LBB0_3388:
	s_xor_b32 s20, s20, 0x8000
	s_xor_b32 s21, s21, 0x8000
	s_add_u32 s90, s52, s12
	s_addc_u32 s91, s53, s13
	s_add_i32 m0, s21, s83
	v_lshl_add_u32 v170, v114, 1, s20
	global_load_lds_dwordx4 v185, s[90:91]
	global_load_lds_dwordx4 v187, s[90:91] offset:1024
	global_load_lds_dwordx4 v189, s[90:91] offset:2048
	global_load_lds_dwordx4 v191, s[90:91] offset:3072
	s_add_i32 m0, s21, s82
	v_lshl_add_u32 v171, v115, 1, s20
	global_load_lds_dwordx4 v184, s[90:91]
	global_load_lds_dwordx4 v186, s[90:91] offset:1024
	global_load_lds_dwordx4 v188, s[90:91] offset:2048
	global_load_lds_dwordx4 v190, s[90:91] offset:3072
	v_add_u32_e32 v158, v170, v136
	v_add_u32_e32 v166, v171, v136
	s_addk_i32 s19, 0x4000
	s_add_u32 s12, s12, 0x80
	s_addc_u32 s13, s13, 0
	ds_read_b128 v[138:141], v158
	ds_read_b128 v[146:149], v166 offset:16384
	ds_read_b128 v[150:153], v166 offset:18432
	ds_read_b128 v[162:165], v166 offset:20480
	ds_read_b128 v[166:169], v166 offset:22528
	ds_read_b128 v[142:145], v158 offset:2048
	ds_read_b128 v[154:157], v158 offset:4096
	ds_read_b128 v[158:161], v158 offset:6144
	v_add_u32_e32 v236, v170, v137
	v_add_u32_e32 v237, v171, v137
	ds_read_b128 v[204:207], v236
	ds_read_b128 v[208:211], v237 offset:16384
	ds_read_b128 v[212:215], v237 offset:18432
	ds_read_b128 v[216:219], v237 offset:20480
	ds_read_b128 v[220:223], v237 offset:22528
	ds_read_b128 v[224:227], v236 offset:2048
	ds_read_b128 v[228:231], v236 offset:4096
	ds_read_b128 v[232:235], v236 offset:6144
	s_setprio 1
	s_waitcnt lgkmcnt(11)
	v_mfma_f32_16x16x32_bf16 v[60:63], v[138:141], v[146:149], v[60:63]
	v_mfma_f32_16x16x32_bf16 v[56:59], v[138:141], v[150:153], v[56:59]
	v_mfma_f32_16x16x32_bf16 v[52:55], v[138:141], v[162:165], v[52:55]
	v_mfma_f32_16x16x32_bf16 v[48:51], v[138:141], v[166:169], v[48:51]
	s_waitcnt lgkmcnt(10)
	v_mfma_f32_16x16x32_bf16 v[44:47], v[142:145], v[146:149], v[44:47]
	v_mfma_f32_16x16x32_bf16 v[40:43], v[142:145], v[150:153], v[40:43]
	v_mfma_f32_16x16x32_bf16 v[36:39], v[142:145], v[162:165], v[36:39]
	v_mfma_f32_16x16x32_bf16 v[32:35], v[142:145], v[166:169], v[32:35]
	s_waitcnt lgkmcnt(9)
	v_mfma_f32_16x16x32_bf16 v[28:31], v[154:157], v[146:149], v[28:31]
	v_mfma_f32_16x16x32_bf16 v[24:27], v[154:157], v[150:153], v[24:27]
	v_mfma_f32_16x16x32_bf16 v[20:23], v[154:157], v[162:165], v[20:23]
	v_mfma_f32_16x16x32_bf16 v[16:19], v[154:157], v[166:169], v[16:19]
	s_waitcnt lgkmcnt(8)
	v_mfma_f32_16x16x32_bf16 v[12:15], v[158:161], v[146:149], v[12:15]
	v_mfma_f32_16x16x32_bf16 v[8:11], v[158:161], v[150:153], v[8:11]
	v_mfma_f32_16x16x32_bf16 v[4:7], v[158:161], v[162:165], v[4:7]
	v_mfma_f32_16x16x32_bf16 v[0:3], v[158:161], v[166:169], v[0:3]
	s_waitcnt lgkmcnt(3)
	v_mfma_f32_16x16x32_bf16 v[60:63], v[204:207], v[208:211], v[60:63]
	v_mfma_f32_16x16x32_bf16 v[56:59], v[204:207], v[212:215], v[56:59]
	v_mfma_f32_16x16x32_bf16 v[52:55], v[204:207], v[216:219], v[52:55]
	v_mfma_f32_16x16x32_bf16 v[48:51], v[204:207], v[220:223], v[48:51]
	s_waitcnt lgkmcnt(2)
	v_mfma_f32_16x16x32_bf16 v[44:47], v[224:227], v[208:211], v[44:47]
	v_mfma_f32_16x16x32_bf16 v[40:43], v[224:227], v[212:215], v[40:43]
	v_mfma_f32_16x16x32_bf16 v[36:39], v[224:227], v[216:219], v[36:39]
	v_mfma_f32_16x16x32_bf16 v[32:35], v[224:227], v[220:223], v[32:35]
	s_waitcnt lgkmcnt(1)
	v_mfma_f32_16x16x32_bf16 v[28:31], v[228:231], v[208:211], v[28:31]
	v_mfma_f32_16x16x32_bf16 v[24:27], v[228:231], v[212:215], v[24:27]
	v_mfma_f32_16x16x32_bf16 v[20:23], v[228:231], v[216:219], v[20:23]
	v_mfma_f32_16x16x32_bf16 v[16:19], v[228:231], v[220:223], v[16:19]
	s_waitcnt lgkmcnt(0)
	v_mfma_f32_16x16x32_bf16 v[12:15], v[232:235], v[208:211], v[12:15]
	v_mfma_f32_16x16x32_bf16 v[8:11], v[232:235], v[212:215], v[8:11]
	v_mfma_f32_16x16x32_bf16 v[4:7], v[232:235], v[216:219], v[4:7]
	v_mfma_f32_16x16x32_bf16 v[0:3], v[232:235], v[220:223], v[0:3]
	s_setprio 0
	s_cmpk_eq_i32 s12, 0x780
	s_waitcnt vmcnt(0)
	s_barrier
	s_cbranch_scc0 .LBB0_3388
	ds_read_b128 v[90:93], v116 offset:55296
	ds_read_b128 v[94:97], v116 offset:53248
	ds_read_b128 v[98:101], v117 offset:38912
	ds_read_b128 v[102:105], v117 offset:36864
	ds_read_b128 v[138:141], v116 offset:51200
	ds_read_b128 v[142:145], v116 offset:49152
	ds_read_b128 v[146:149], v117 offset:34816
	ds_read_b128 v[150:153], v117 offset:32768
	ds_read_b128 v[204:207], v118 offset:32768
	ds_read_b128 v[208:211], v118 offset:34816
	ds_read_b128 v[212:215], v119 offset:49152
	ds_read_b128 v[216:219], v119 offset:51200
	ds_read_b128 v[220:223], v118 offset:36864
	ds_read_b128 v[224:227], v118 offset:38912
	ds_read_b128 v[228:231], v119 offset:53248
	ds_read_b128 v[232:235], v119 offset:55296
	s_setprio 1
	s_waitcnt lgkmcnt(13)
	v_mfma_f32_16x16x32_bf16 v[0:3], v[98:101], v[90:93], v[0:3]
	s_waitcnt lgkmcnt(8)
	v_mfma_f32_16x16x32_bf16 v[60:63], v[150:153], v[142:145], v[60:63]
	v_mfma_f32_16x16x32_bf16 v[56:59], v[150:153], v[138:141], v[56:59]
	v_mfma_f32_16x16x32_bf16 v[52:55], v[150:153], v[94:97], v[52:55]
	v_mfma_f32_16x16x32_bf16 v[48:51], v[150:153], v[90:93], v[48:51]
	v_mfma_f32_16x16x32_bf16 v[44:47], v[146:149], v[142:145], v[44:47]
	v_mfma_f32_16x16x32_bf16 v[40:43], v[146:149], v[138:141], v[40:43]
	v_mfma_f32_16x16x32_bf16 v[36:39], v[146:149], v[94:97], v[36:39]
	v_mfma_f32_16x16x32_bf16 v[32:35], v[146:149], v[90:93], v[32:35]
	v_mfma_f32_16x16x32_bf16 v[28:31], v[102:105], v[142:145], v[28:31]
	v_mfma_f32_16x16x32_bf16 v[24:27], v[102:105], v[138:141], v[24:27]
	v_mfma_f32_16x16x32_bf16 v[20:23], v[102:105], v[94:97], v[20:23]
	v_mfma_f32_16x16x32_bf16 v[16:19], v[102:105], v[90:93], v[16:19]
	v_mfma_f32_16x16x32_bf16 v[12:15], v[98:101], v[142:145], v[12:15]
	v_mfma_f32_16x16x32_bf16 v[8:11], v[98:101], v[138:141], v[8:11]
	v_mfma_f32_16x16x32_bf16 v[4:7], v[98:101], v[94:97], v[4:7]
	s_waitcnt lgkmcnt(0)
	v_mfma_f32_16x16x32_bf16 v[0:3], v[224:227], v[232:235], v[0:3]
	v_mfma_f32_16x16x32_bf16 v[60:63], v[204:207], v[212:215], v[60:63]
	v_mfma_f32_16x16x32_bf16 v[56:59], v[204:207], v[216:219], v[56:59]
	v_mfma_f32_16x16x32_bf16 v[52:55], v[204:207], v[228:231], v[52:55]
	v_mfma_f32_16x16x32_bf16 v[48:51], v[204:207], v[232:235], v[48:51]
	v_mfma_f32_16x16x32_bf16 v[44:47], v[208:211], v[212:215], v[44:47]
	v_mfma_f32_16x16x32_bf16 v[40:43], v[208:211], v[216:219], v[40:43]
	v_mfma_f32_16x16x32_bf16 v[36:39], v[208:211], v[228:231], v[36:39]
	v_mfma_f32_16x16x32_bf16 v[32:35], v[208:211], v[232:235], v[32:35]
	v_mfma_f32_16x16x32_bf16 v[28:31], v[220:223], v[212:215], v[28:31]
	v_mfma_f32_16x16x32_bf16 v[24:27], v[220:223], v[216:219], v[24:27]
	v_mfma_f32_16x16x32_bf16 v[20:23], v[220:223], v[228:231], v[20:23]
	v_mfma_f32_16x16x32_bf16 v[16:19], v[220:223], v[232:235], v[16:19]
	v_mfma_f32_16x16x32_bf16 v[12:15], v[224:227], v[212:215], v[12:15]
	v_mfma_f32_16x16x32_bf16 v[8:11], v[224:227], v[216:219], v[8:11]
	v_mfma_f32_16x16x32_bf16 v[4:7], v[224:227], v[228:231], v[4:7]
	s_setprio 0
	s_barrier
	ds_write2_b32 v120, v60, v56 offset1:16
	ds_write2_b32 v120, v61, v57 offset0:132 offset1:148
	v_add_u32_e32 v56, 0x400, v120
	ds_write2_b32 v56, v62, v58 offset0:8 offset1:24
	ds_write2_b32 v56, v63, v59 offset0:140 offset1:156
	ds_write2_b32 v120, v52, v48 offset0:32 offset1:48
	ds_write2_b32 v120, v53, v49 offset0:164 offset1:180
	ds_write2_b32 v56, v54, v50 offset0:40 offset1:56
	ds_write2_b32 v56, v55, v51 offset0:172 offset1:188
	v_add_u32_e32 v48, 0x2000, v120
	ds_write2_b32 v48, v44, v40 offset0:64 offset1:80
	ds_write2_b32 v48, v45, v41 offset0:196 offset1:212
	v_add_u32_e32 v40, 0x2400, v120
	ds_write2_b32 v40, v46, v42 offset0:72 offset1:88
	ds_write2_b32 v40, v47, v43 offset0:204 offset1:220
	ds_write2_b32 v48, v36, v32 offset0:96 offset1:112
	ds_write2_b32 v48, v37, v33 offset0:228 offset1:244
	ds_write2_b32 v40, v38, v34 offset0:104 offset1:120
	ds_write2_b32 v40, v39, v35 offset0:236 offset1:252
	v_add_u32_e32 v32, 0x4000, v120
	ds_write2_b32 v32, v28, v24 offset0:128 offset1:144
	v_add_u32_e32 v24, 0x4400, v120
	ds_write2_b32 v24, v29, v25 offset0:4 offset1:20
	ds_write2_b32 v24, v30, v26 offset0:136 offset1:152
	v_add_u32_e32 v25, 0x4800, v120
	ds_write2_b32 v25, v31, v27 offset0:12 offset1:28
	ds_write2_b32 v32, v20, v16 offset0:160 offset1:176
	ds_write2_b32 v24, v21, v17 offset0:36 offset1:52
	ds_write2_b32 v24, v22, v18 offset0:168 offset1:184
	ds_write2_b32 v25, v23, v19 offset0:44 offset1:60
	v_add_u32_e32 v16, 0x6000, v120
	ds_write2_b32 v16, v12, v8 offset0:192 offset1:208
	v_add_u32_e32 v8, 0x6400, v120
	ds_write2_b32 v8, v13, v9 offset0:68 offset1:84
	ds_write2_b32 v8, v14, v10 offset0:200 offset1:216
	v_add_u32_e32 v9, 0x6800, v120
	ds_write2_b32 v9, v15, v11 offset0:76 offset1:92
	ds_write2_b32 v16, v4, v0 offset0:224 offset1:240
	ds_write2_b32 v8, v5, v1 offset0:100 offset1:116
	ds_write2_b32 v8, v6, v2 offset0:232 offset1:248
	ds_write2_b32 v9, v7, v3 offset0:108 offset1:124
	v_or_b32_e32 v0, s18, v121
	v_ashrrev_i32_e32 v1, 31, v0
	v_lshl_add_u64 v[0:1], v[0:1], 1, s[6:7]
	v_add_u32_e32 v2, s17, v129
	s_mov_b32 s12, 0
	s_waitcnt lgkmcnt(0)
	s_barrier

.LBB0_3398:
	s_ashr_i32 s15, s9, 31
	s_lshr_b32 s15, s15, 29
	s_add_i32 s15, s9, s15
	s_ashr_i32 s16, s15, 3
	s_lshl_b32 s18, s16, 10
	s_lshl_b32 s9, s9, 7
	s_add_i32 s15, s16, s14
	s_lshl_b32 s17, s16, 7
	s_sub_i32 s16, s9, s18
	s_add_i32 s16, s16, s8
	s_lshr_b32 s15, s15, 4
	v_add_u32_e32 v0, s16, v104
	s_mulk_i32 s15, 0x900
	s_and_b32 s17, s17, 0x780
	v_ashrrev_i32_e32 v1, 31, v0
	v_add_u32_e32 v2, 0x4000, v105
	s_add_i32 s15, s17, s15
	v_lshlrev_b64 v[0:1], 11, v[0:1]
	v_readfirstlane_b32 s19, v2
	s_add_i32 s17, s15, 0x100
	v_lshl_add_u64 v[0:1], v[64:65], 0, v[0:1]
	s_mov_b32 m0, s19
	v_readfirstlane_b32 s19, v105
	global_load_lds_dwordx4 v[0:1], off
	v_add_u32_e32 v0, s17, v104
	v_ashrrev_i32_e32 v1, 31, v0
	v_lshlrev_b64 v[0:1], 11, v[0:1]
	v_lshl_add_u64 v[0:1], v[70:71], 0, v[0:1]
	s_mov_b32 m0, s19
	v_readfirstlane_b32 s19, v129
	global_load_lds_dwordx4 v[0:1], off
	v_add_u32_e32 v0, s16, v106
	v_ashrrev_i32_e32 v1, 31, v0
	v_lshlrev_b64 v[0:1], 11, v[0:1]
	v_lshl_add_u64 v[0:1], v[66:67], 0, v[0:1]
	s_mov_b32 m0, s19
	v_add_u32_e32 v2, 0x400, v105
	global_load_lds_dwordx4 v[0:1], off
	v_add_u32_e32 v0, s17, v106
	v_ashrrev_i32_e32 v1, 31, v0
	v_lshlrev_b64 v[0:1], 11, v[0:1]
	v_readfirstlane_b32 s19, v2
	v_lshl_add_u64 v[0:1], v[72:73], 0, v[0:1]
	s_mov_b32 m0, s19
	v_readfirstlane_b32 s19, v130
	global_load_lds_dwordx4 v[0:1], off
	v_add_u32_e32 v0, s16, v108
	v_ashrrev_i32_e32 v1, 31, v0
	v_lshlrev_b64 v[0:1], 11, v[0:1]
	v_lshl_add_u64 v[0:1], v[64:65], 0, v[0:1]
	s_mov_b32 m0, s19
	v_add_u32_e32 v2, 0x800, v105
	global_load_lds_dwordx4 v[0:1], off
	v_add_u32_e32 v0, s17, v108
	v_ashrrev_i32_e32 v1, 31, v0
	v_lshlrev_b64 v[0:1], 11, v[0:1]
	v_readfirstlane_b32 s19, v2
	v_lshl_add_u64 v[0:1], v[70:71], 0, v[0:1]
	s_mov_b32 m0, s19
	v_readfirstlane_b32 s19, v131
	global_load_lds_dwordx4 v[0:1], off
	v_add_u32_e32 v0, s16, v110
	v_ashrrev_i32_e32 v1, 31, v0
	v_lshlrev_b64 v[0:1], 11, v[0:1]
	v_lshl_add_u64 v[0:1], v[68:69], 0, v[0:1]
	s_mov_b32 m0, s19
	v_add_u32_e32 v2, 0xc00, v105
	global_load_lds_dwordx4 v[0:1], off
	v_add_u32_e32 v0, s17, v110
	v_ashrrev_i32_e32 v1, 31, v0
	v_lshlrev_b64 v[0:1], 11, v[0:1]
	v_readfirstlane_b32 s17, v2
	v_lshl_add_u64 v[0:1], v[74:75], 0, v[0:1]
	s_mov_b32 m0, s17
	s_add_i32 s9, s9, s8
	global_load_lds_dwordx4 v[0:1], off
	v_add_u32_e32 v0, s9, v104
	v_subrev_u32_e32 v0, s18, v0
	v_ashrrev_i32_e32 v1, 31, v0
	v_lshlrev_b64 v[0:1], 11, v[0:1]
	v_lshl_add_u64 v[88:89], v[76:77], 0, v[0:1]
	v_add_u32_e32 v0, s15, v120
	v_ashrrev_i32_e32 v1, 31, v0
	v_lshlrev_b64 v[0:1], 11, v[0:1]
	v_lshl_add_u64 v[90:91], v[78:79], 0, v[0:1]
	v_add_u32_e32 v0, s9, v121
	v_subrev_u32_e32 v0, s18, v0
	v_ashrrev_i32_e32 v1, 31, v0
	v_lshlrev_b64 v[0:1], 11, v[0:1]
	v_lshl_add_u64 v[92:93], v[80:81], 0, v[0:1]
	v_add_u32_e32 v0, s15, v122
	v_ashrrev_i32_e32 v1, 31, v0
	v_lshlrev_b64 v[0:1], 11, v[0:1]
	v_lshl_add_u64 v[94:95], v[82:83], 0, v[0:1]
	v_add_u32_e32 v0, s9, v123
	v_subrev_u32_e32 v0, s18, v0
	v_ashrrev_i32_e32 v1, 31, v0
	v_lshlrev_b64 v[0:1], 11, v[0:1]
	v_lshl_add_u64 v[96:97], v[76:77], 0, v[0:1]
	v_add_u32_e32 v0, s15, v124
	v_ashrrev_i32_e32 v1, 31, v0
	v_lshlrev_b64 v[0:1], 11, v[0:1]
	v_lshl_add_u64 v[98:99], v[78:79], 0, v[0:1]
	v_add_u32_e32 v0, s9, v125
	v_subrev_u32_e32 v0, s18, v0
	v_ashrrev_i32_e32 v1, 31, v0
	v_lshlrev_b64 v[0:1], 11, v[0:1]
	v_lshl_add_u64 v[100:101], v[84:85], 0, v[0:1]
	v_add_u32_e32 v0, s15, v126
	v_ashrrev_i32_e32 v1, 31, v0
	v_lshlrev_b64 v[0:1], 11, v[0:1]
	v_lshl_add_u64 v[102:103], v[86:87], 0, v[0:1]
	v_mov_b32_e32 v0, 0
	s_mov_b32 s17, 0
	s_mov_b64 s[8:9], 0
	v_mov_b32_e32 v1, v0
	v_mov_b32_e32 v2, v0
	v_mov_b32_e32 v3, v0
	v_mov_b32_e32 v4, v0
	v_mov_b32_e32 v5, v0
	v_mov_b32_e32 v6, v0
	v_mov_b32_e32 v7, v0
	v_mov_b32_e32 v8, v0
	v_mov_b32_e32 v9, v0
	v_mov_b32_e32 v10, v0
	v_mov_b32_e32 v11, v0
	v_mov_b32_e32 v12, v0
	v_mov_b32_e32 v13, v0
	v_mov_b32_e32 v14, v0
	v_mov_b32_e32 v15, v0
	v_mov_b32_e32 v16, v0
	v_mov_b32_e32 v17, v0
	v_mov_b32_e32 v18, v0
	v_mov_b32_e32 v19, v0
	v_mov_b32_e32 v20, v0
	v_mov_b32_e32 v21, v0
	v_mov_b32_e32 v22, v0
	v_mov_b32_e32 v23, v0
	v_mov_b32_e32 v24, v0
	v_mov_b32_e32 v25, v0
	v_mov_b32_e32 v26, v0
	v_mov_b32_e32 v27, v0
	v_mov_b32_e32 v28, v0
	v_mov_b32_e32 v29, v0
	v_mov_b32_e32 v30, v0
	v_mov_b32_e32 v31, v0
	v_mov_b32_e32 v32, v0
	v_mov_b32_e32 v33, v0
	v_mov_b32_e32 v34, v0
	v_mov_b32_e32 v35, v0
	v_mov_b32_e32 v36, v0
	v_mov_b32_e32 v37, v0
	v_mov_b32_e32 v38, v0
	v_mov_b32_e32 v39, v0
	v_mov_b32_e32 v40, v0
	v_mov_b32_e32 v41, v0
	v_mov_b32_e32 v42, v0
	v_mov_b32_e32 v43, v0
	v_mov_b32_e32 v44, v0
	v_mov_b32_e32 v45, v0
	v_mov_b32_e32 v46, v0
	v_mov_b32_e32 v47, v0
	v_mov_b32_e32 v48, v0
	v_mov_b32_e32 v49, v0
	v_mov_b32_e32 v50, v0
	v_mov_b32_e32 v51, v0
	v_mov_b32_e32 v52, v0
	v_mov_b32_e32 v53, v0
	v_mov_b32_e32 v54, v0
	v_mov_b32_e32 v55, v0
	v_mov_b32_e32 v56, v0
	v_mov_b32_e32 v57, v0
	v_mov_b32_e32 v58, v0
	v_mov_b32_e32 v59, v0
	v_mov_b32_e32 v60, v0
	v_mov_b32_e32 v61, v0
	v_mov_b32_e32 v62, v0
	v_mov_b32_e32 v63, v0
	s_waitcnt vmcnt(0) lgkmcnt(0)
	s_barrier
	v_add3_u32 v182, 0, v132, v133
	v_add_u32_e32 v183, 0x4000, v182
	s_nop 0
	v_readfirstlane_b32 s82, v183
	v_lshl_add_u32 v183, v107, 1, 0
	s_nop 0
	v_readfirstlane_b32 s83, v182
	v_add3_u32 v183, v183, v133, s11
	s_nop 0
	v_readfirstlane_b32 s84, v183
	v_add_u32_e32 v183, 0x400, v182
	s_nop 0
	v_readfirstlane_b32 s85, v183
	v_lshl_add_u32 v183, v109, 1, 0
	v_add3_u32 v183, v183, v133, s11
	s_nop 0
	v_readfirstlane_b32 s86, v183
	v_add_u32_e32 v183, 0x800, v182
	s_nop 0
	v_readfirstlane_b32 s87, v183
	v_lshl_add_u32 v183, v111, 1, 0
	v_add3_u32 v183, v183, v133, s11
	s_nop 0
	v_readfirstlane_b32 s88, v183
	v_add_u32_e32 v182, 0xc00, v182
	s_nop 0
	v_readfirstlane_b32 s89, v182
	v_subrev_u32_e32 v184, s52, v88
	v_subrev_u32_e32 v185, s52, v90
	v_subrev_u32_e32 v186, s52, v92
	v_subrev_u32_e32 v187, s52, v94
	v_subrev_u32_e32 v188, s52, v96
	v_subrev_u32_e32 v189, s52, v98
	v_subrev_u32_e32 v190, s52, v100
	v_subrev_u32_e32 v191, s52, v102
	v_subrev_u32_e32 v187, 0x400, v187
	v_subrev_u32_e32 v186, 0x400, v186
	v_subrev_u32_e32 v189, 0x800, v189
	v_subrev_u32_e32 v188, 0x800, v188
	v_subrev_u32_e32 v191, 0xc00, v191
	v_subrev_u32_e32 v190, 0xc00, v190
	s_and_b32 s19, s17, 0x4000
	s_xor_b32 s18, s19, 0x4000
	s_lshl_b32 s18, s18, 1
	s_add_i32 s18, s18, 32
	s_lshl_b32 s19, s19, 1
	s_add_i32 s19, s19, 32
.LBB0_3399:
	s_xor_b32 s18, s18, 0x8000
	s_xor_b32 s19, s19, 0x8000
	s_add_u32 s90, s52, s8
	s_addc_u32 s91, s53, s9
	s_add_i32 m0, s19, s83
	v_lshl_add_u32 v168, v112, 1, s18
	global_load_lds_dwordx4 v185, s[90:91]
	global_load_lds_dwordx4 v187, s[90:91] offset:1024
	global_load_lds_dwordx4 v189, s[90:91] offset:2048
	global_load_lds_dwordx4 v191, s[90:91] offset:3072
	s_add_i32 m0, s19, s82
	v_lshl_add_u32 v169, v113, 1, s18
	global_load_lds_dwordx4 v184, s[90:91]
	global_load_lds_dwordx4 v186, s[90:91] offset:1024
	global_load_lds_dwordx4 v188, s[90:91] offset:2048
	global_load_lds_dwordx4 v190, s[90:91] offset:3072
	v_add_u32_e32 v156, v168, v134
	v_add_u32_e32 v164, v169, v134
	s_add_u32 s8, s8, 0x80
	s_addc_u32 s9, s9, 0
	ds_read_b128 v[136:139], v156
	ds_read_b128 v[144:147], v164 offset:16384
	ds_read_b128 v[148:151], v164 offset:18432
	ds_read_b128 v[160:163], v164 offset:20480
	ds_read_b128 v[164:167], v164 offset:22528
	ds_read_b128 v[140:143], v156 offset:2048
	ds_read_b128 v[152:155], v156 offset:4096
	ds_read_b128 v[156:159], v156 offset:6144
	v_add_u32_e32 v236, v168, v135
	v_add_u32_e32 v237, v169, v135
	ds_read_b128 v[204:207], v236
	ds_read_b128 v[208:211], v237 offset:16384
	ds_read_b128 v[212:215], v237 offset:18432
	ds_read_b128 v[216:219], v237 offset:20480
	ds_read_b128 v[220:223], v237 offset:22528
	ds_read_b128 v[224:227], v236 offset:2048
	ds_read_b128 v[228:231], v236 offset:4096
	ds_read_b128 v[232:235], v236 offset:6144
	s_setprio 1
	s_waitcnt lgkmcnt(11)
	v_mfma_f32_16x16x32_bf16 v[60:63], v[136:139], v[144:147], v[60:63]
	v_mfma_f32_16x16x32_bf16 v[56:59], v[136:139], v[148:151], v[56:59]
	v_mfma_f32_16x16x32_bf16 v[52:55], v[136:139], v[160:163], v[52:55]
	v_mfma_f32_16x16x32_bf16 v[48:51], v[136:139], v[164:167], v[48:51]
	s_waitcnt lgkmcnt(10)
	v_mfma_f32_16x16x32_bf16 v[44:47], v[140:143], v[144:147], v[44:47]
	v_mfma_f32_16x16x32_bf16 v[40:43], v[140:143], v[148:151], v[40:43]
	v_mfma_f32_16x16x32_bf16 v[36:39], v[140:143], v[160:163], v[36:39]
	v_mfma_f32_16x16x32_bf16 v[32:35], v[140:143], v[164:167], v[32:35]
	s_waitcnt lgkmcnt(9)
	v_mfma_f32_16x16x32_bf16 v[28:31], v[152:155], v[144:147], v[28:31]
	v_mfma_f32_16x16x32_bf16 v[24:27], v[152:155], v[148:151], v[24:27]
	v_mfma_f32_16x16x32_bf16 v[20:23], v[152:155], v[160:163], v[20:23]
	v_mfma_f32_16x16x32_bf16 v[16:19], v[152:155], v[164:167], v[16:19]
	s_waitcnt lgkmcnt(8)
	v_mfma_f32_16x16x32_bf16 v[12:15], v[156:159], v[144:147], v[12:15]
	v_mfma_f32_16x16x32_bf16 v[8:11], v[156:159], v[148:151], v[8:11]
	v_mfma_f32_16x16x32_bf16 v[4:7], v[156:159], v[160:163], v[4:7]
	v_mfma_f32_16x16x32_bf16 v[0:3], v[156:159], v[164:167], v[0:3]
	s_waitcnt lgkmcnt(3)
	v_mfma_f32_16x16x32_bf16 v[60:63], v[204:207], v[208:211], v[60:63]
	v_mfma_f32_16x16x32_bf16 v[56:59], v[204:207], v[212:215], v[56:59]
	v_mfma_f32_16x16x32_bf16 v[52:55], v[204:207], v[216:219], v[52:55]
	v_mfma_f32_16x16x32_bf16 v[48:51], v[204:207], v[220:223], v[48:51]
	s_waitcnt lgkmcnt(2)
	v_mfma_f32_16x16x32_bf16 v[44:47], v[224:227], v[208:211], v[44:47]
	v_mfma_f32_16x16x32_bf16 v[40:43], v[224:227], v[212:215], v[40:43]
	v_mfma_f32_16x16x32_bf16 v[36:39], v[224:227], v[216:219], v[36:39]
	v_mfma_f32_16x16x32_bf16 v[32:35], v[224:227], v[220:223], v[32:35]
	s_waitcnt lgkmcnt(1)
	v_mfma_f32_16x16x32_bf16 v[28:31], v[228:231], v[208:211], v[28:31]
	v_mfma_f32_16x16x32_bf16 v[24:27], v[228:231], v[212:215], v[24:27]
	v_mfma_f32_16x16x32_bf16 v[20:23], v[228:231], v[216:219], v[20:23]
	v_mfma_f32_16x16x32_bf16 v[16:19], v[228:231], v[220:223], v[16:19]
	s_waitcnt lgkmcnt(0)
	v_mfma_f32_16x16x32_bf16 v[12:15], v[232:235], v[208:211], v[12:15]
	v_mfma_f32_16x16x32_bf16 v[8:11], v[232:235], v[212:215], v[8:11]
	v_mfma_f32_16x16x32_bf16 v[4:7], v[232:235], v[216:219], v[4:7]
	v_mfma_f32_16x16x32_bf16 v[0:3], v[232:235], v[220:223], v[0:3]
	s_setprio 0
	s_cmpk_eq_i32 s8, 0x780
	s_waitcnt vmcnt(0)
	s_barrier
	s_cbranch_scc0 .LBB0_3399
	ds_read_b128 v[88:91], v114 offset:55296
	ds_read_b128 v[92:95], v114 offset:53248
	ds_read_b128 v[96:99], v115 offset:38912
	ds_read_b128 v[100:103], v115 offset:36864
	ds_read_b128 v[136:139], v114 offset:51200
	ds_read_b128 v[140:143], v114 offset:49152
	ds_read_b128 v[144:147], v115 offset:34816
	ds_read_b128 v[148:151], v115 offset:32768
	ds_read_b128 v[204:207], v116 offset:32768
	ds_read_b128 v[208:211], v116 offset:34816
	ds_read_b128 v[212:215], v117 offset:49152
	ds_read_b128 v[216:219], v117 offset:51200
	ds_read_b128 v[220:223], v116 offset:36864
	ds_read_b128 v[224:227], v116 offset:38912
	ds_read_b128 v[228:231], v117 offset:53248
	ds_read_b128 v[232:235], v117 offset:55296
	s_setprio 1
	s_waitcnt lgkmcnt(13)
	v_mfma_f32_16x16x32_bf16 v[0:3], v[96:99], v[88:91], v[0:3]
	s_waitcnt lgkmcnt(8)
	v_mfma_f32_16x16x32_bf16 v[60:63], v[148:151], v[140:143], v[60:63]
	v_mfma_f32_16x16x32_bf16 v[56:59], v[148:151], v[136:139], v[56:59]
	v_mfma_f32_16x16x32_bf16 v[52:55], v[148:151], v[92:95], v[52:55]
	v_mfma_f32_16x16x32_bf16 v[48:51], v[148:151], v[88:91], v[48:51]
	v_mfma_f32_16x16x32_bf16 v[44:47], v[144:147], v[140:143], v[44:47]
	v_mfma_f32_16x16x32_bf16 v[40:43], v[144:147], v[136:139], v[40:43]
	v_mfma_f32_16x16x32_bf16 v[36:39], v[144:147], v[92:95], v[36:39]
	v_mfma_f32_16x16x32_bf16 v[32:35], v[144:147], v[88:91], v[32:35]
	v_mfma_f32_16x16x32_bf16 v[28:31], v[100:103], v[140:143], v[28:31]
	v_mfma_f32_16x16x32_bf16 v[24:27], v[100:103], v[136:139], v[24:27]
	v_mfma_f32_16x16x32_bf16 v[20:23], v[100:103], v[92:95], v[20:23]
	v_mfma_f32_16x16x32_bf16 v[16:19], v[100:103], v[88:91], v[16:19]
	v_mfma_f32_16x16x32_bf16 v[12:15], v[96:99], v[140:143], v[12:15]
	v_mfma_f32_16x16x32_bf16 v[8:11], v[96:99], v[136:139], v[8:11]
	v_mfma_f32_16x16x32_bf16 v[4:7], v[96:99], v[92:95], v[4:7]
	s_waitcnt lgkmcnt(0)
	v_mfma_f32_16x16x32_bf16 v[0:3], v[224:227], v[232:235], v[0:3]
	v_mfma_f32_16x16x32_bf16 v[60:63], v[204:207], v[212:215], v[60:63]
	v_mfma_f32_16x16x32_bf16 v[56:59], v[204:207], v[216:219], v[56:59]
	v_mfma_f32_16x16x32_bf16 v[52:55], v[204:207], v[228:231], v[52:55]
	v_mfma_f32_16x16x32_bf16 v[48:51], v[204:207], v[232:235], v[48:51]
	v_mfma_f32_16x16x32_bf16 v[44:47], v[208:211], v[212:215], v[44:47]
	v_mfma_f32_16x16x32_bf16 v[40:43], v[208:211], v[216:219], v[40:43]
	v_mfma_f32_16x16x32_bf16 v[36:39], v[208:211], v[228:231], v[36:39]
	v_mfma_f32_16x16x32_bf16 v[32:35], v[208:211], v[232:235], v[32:35]
	v_mfma_f32_16x16x32_bf16 v[28:31], v[220:223], v[212:215], v[28:31]
	v_mfma_f32_16x16x32_bf16 v[24:27], v[220:223], v[216:219], v[24:27]
	v_mfma_f32_16x16x32_bf16 v[20:23], v[220:223], v[228:231], v[20:23]
	v_mfma_f32_16x16x32_bf16 v[16:19], v[220:223], v[232:235], v[16:19]
	v_mfma_f32_16x16x32_bf16 v[12:15], v[224:227], v[212:215], v[12:15]
	v_mfma_f32_16x16x32_bf16 v[8:11], v[224:227], v[216:219], v[8:11]
	v_mfma_f32_16x16x32_bf16 v[4:7], v[224:227], v[228:231], v[4:7]
	s_setprio 0
	s_barrier
	ds_write2_b32 v118, v60, v56 offset1:16
	ds_write2_b32 v118, v61, v57 offset0:132 offset1:148
	v_add_u32_e32 v56, 0x400, v118
	ds_write2_b32 v56, v62, v58 offset0:8 offset1:24
	ds_write2_b32 v56, v63, v59 offset0:140 offset1:156
	ds_write2_b32 v118, v52, v48 offset0:32 offset1:48
	ds_write2_b32 v118, v53, v49 offset0:164 offset1:180
	ds_write2_b32 v56, v54, v50 offset0:40 offset1:56
	ds_write2_b32 v56, v55, v51 offset0:172 offset1:188
	v_add_u32_e32 v48, 0x2000, v118
	ds_write2_b32 v48, v44, v40 offset0:64 offset1:80
	ds_write2_b32 v48, v45, v41 offset0:196 offset1:212
	v_add_u32_e32 v40, 0x2400, v118
	ds_write2_b32 v40, v46, v42 offset0:72 offset1:88
	ds_write2_b32 v40, v47, v43 offset0:204 offset1:220
	ds_write2_b32 v48, v36, v32 offset0:96 offset1:112
	ds_write2_b32 v48, v37, v33 offset0:228 offset1:244
	ds_write2_b32 v40, v38, v34 offset0:104 offset1:120
	ds_write2_b32 v40, v39, v35 offset0:236 offset1:252
	v_add_u32_e32 v32, 0x4000, v118
	ds_write2_b32 v32, v28, v24 offset0:128 offset1:144
	v_add_u32_e32 v24, 0x4400, v118
	ds_write2_b32 v24, v29, v25 offset0:4 offset1:20
	ds_write2_b32 v24, v30, v26 offset0:136 offset1:152
	v_add_u32_e32 v25, 0x4800, v118
	ds_write2_b32 v25, v31, v27 offset0:12 offset1:28
	ds_write2_b32 v32, v20, v16 offset0:160 offset1:176
	ds_write2_b32 v24, v21, v17 offset0:36 offset1:52
	ds_write2_b32 v24, v22, v18 offset0:168 offset1:184
	ds_write2_b32 v25, v23, v19 offset0:44 offset1:60
	v_add_u32_e32 v16, 0x6000, v118
	ds_write2_b32 v16, v12, v8 offset0:192 offset1:208
	v_add_u32_e32 v8, 0x6400, v118
	ds_write2_b32 v8, v13, v9 offset0:68 offset1:84
	ds_write2_b32 v8, v14, v10 offset0:200 offset1:216
	v_add_u32_e32 v9, 0x6800, v118
	ds_write2_b32 v9, v15, v11 offset0:76 offset1:92
	ds_write2_b32 v16, v4, v0 offset0:224 offset1:240
	ds_write2_b32 v8, v5, v1 offset0:100 offset1:116
	ds_write2_b32 v8, v6, v2 offset0:232 offset1:248
	ds_write2_b32 v9, v7, v3 offset0:108 offset1:124
	v_or_b32_e32 v0, s16, v119
	v_ashrrev_i32_e32 v1, 31, v0
	v_lshl_add_u64 v[0:1], v[0:1], 1, s[6:7]
	v_add_u32_e32 v2, s15, v127
	s_mov_b32 s8, 0
	s_waitcnt lgkmcnt(0)
	s_barrier

.LBB0_3462:
	s_ashr_i32 s16, s23, 31
	s_lshr_b32 s16, s16, 29
	s_add_i32 s16, s23, s16
	s_ashr_i32 s16, s16, 3
	s_lshr_b32 s17, s16, 4
	s_lshl_b32 s24, s16, 7
	s_lshl_b32 s16, s16, 10
	s_lshl_b32 s25, s23, 7
	s_sub_i32 s25, s25, s16
	v_add_u32_e32 v0, s25, v106
	s_mulk_i32 s17, 0x900
	s_and_b32 s24, s24, 0x780
	v_ashrrev_i32_e32 v1, 31, v0
	v_add_u32_e32 v2, 0x4000, v107
	s_add_i32 s24, s24, s17
	v_lshlrev_b64 v[0:1], 13, v[0:1]
	v_readfirstlane_b32 s26, v2
	s_add_i32 s17, s24, 0x100
	v_lshl_add_u64 v[0:1], v[66:67], 0, v[0:1]
	s_mov_b32 m0, s26
	v_readfirstlane_b32 s26, v107
	global_load_lds_dwordx4 v[0:1], off
	v_add_u32_e32 v0, s17, v106
	v_ashrrev_i32_e32 v1, 31, v0
	v_lshlrev_b64 v[0:1], 13, v[0:1]
	v_lshl_add_u64 v[0:1], v[72:73], 0, v[0:1]
	s_mov_b32 m0, s26
	v_readfirstlane_b32 s26, v131
	global_load_lds_dwordx4 v[0:1], off
	v_add_u32_e32 v0, s25, v108
	v_ashrrev_i32_e32 v1, 31, v0
	v_lshlrev_b64 v[0:1], 13, v[0:1]
	v_lshl_add_u64 v[0:1], v[68:69], 0, v[0:1]
	s_mov_b32 m0, s26
	v_add_u32_e32 v2, 0x400, v107
	global_load_lds_dwordx4 v[0:1], off
	v_add_u32_e32 v0, s17, v108
	v_ashrrev_i32_e32 v1, 31, v0
	v_lshlrev_b64 v[0:1], 13, v[0:1]
	v_readfirstlane_b32 s26, v2
	v_lshl_add_u64 v[0:1], v[74:75], 0, v[0:1]
	s_mov_b32 m0, s26
	v_readfirstlane_b32 s26, v132
	global_load_lds_dwordx4 v[0:1], off
	v_add_u32_e32 v0, s25, v110
	v_ashrrev_i32_e32 v1, 31, v0
	v_lshlrev_b64 v[0:1], 13, v[0:1]
	v_lshl_add_u64 v[0:1], v[66:67], 0, v[0:1]
	s_mov_b32 m0, s26
	v_add_u32_e32 v2, 0x800, v107
	global_load_lds_dwordx4 v[0:1], off
	v_add_u32_e32 v0, s17, v110
	v_ashrrev_i32_e32 v1, 31, v0
	v_lshlrev_b64 v[0:1], 13, v[0:1]
	v_readfirstlane_b32 s26, v2
	v_lshl_add_u64 v[0:1], v[72:73], 0, v[0:1]
	s_mov_b32 m0, s26
	v_readfirstlane_b32 s26, v133
	global_load_lds_dwordx4 v[0:1], off
	v_add_u32_e32 v0, s25, v112
	v_ashrrev_i32_e32 v1, 31, v0
	v_lshlrev_b64 v[0:1], 13, v[0:1]
	v_lshl_add_u64 v[0:1], v[70:71], 0, v[0:1]
	s_mov_b32 m0, s26
	v_add_u32_e32 v2, 0xc00, v107
	global_load_lds_dwordx4 v[0:1], off
	v_add_u32_e32 v0, s17, v112
	v_ashrrev_i32_e32 v1, 31, v0
	v_lshlrev_b64 v[0:1], 13, v[0:1]
	v_readfirstlane_b32 s17, v2
	v_lshl_add_u64 v[0:1], v[76:77], 0, v[0:1]
	s_mov_b32 m0, s17
	s_mov_b32 s26, 0
	global_load_lds_dwordx4 v[0:1], off
	v_subrev_u32_e32 v0, s16, v122
	v_ashrrev_i32_e32 v1, 31, v0
	v_lshlrev_b64 v[0:1], 13, v[0:1]
	v_lshl_add_u64 v[90:91], v[78:79], 0, v[0:1]
	v_add_u32_e32 v0, s24, v123
	v_ashrrev_i32_e32 v1, 31, v0
	v_lshlrev_b64 v[0:1], 13, v[0:1]
	v_lshl_add_u64 v[92:93], v[80:81], 0, v[0:1]
	v_subrev_u32_e32 v0, s16, v124
	v_ashrrev_i32_e32 v1, 31, v0
	v_lshlrev_b64 v[0:1], 13, v[0:1]
	v_lshl_add_u64 v[94:95], v[82:83], 0, v[0:1]
	v_add_u32_e32 v0, s24, v125
	v_ashrrev_i32_e32 v1, 31, v0
	v_lshlrev_b64 v[0:1], 13, v[0:1]
	v_lshl_add_u64 v[96:97], v[84:85], 0, v[0:1]
	v_subrev_u32_e32 v0, s16, v126
	v_ashrrev_i32_e32 v1, 31, v0
	v_lshlrev_b64 v[0:1], 13, v[0:1]
	v_lshl_add_u64 v[98:99], v[78:79], 0, v[0:1]
	v_add_u32_e32 v0, s24, v127
	v_ashrrev_i32_e32 v1, 31, v0
	v_lshlrev_b64 v[0:1], 13, v[0:1]
	v_lshl_add_u64 v[100:101], v[80:81], 0, v[0:1]
	v_subrev_u32_e32 v0, s16, v64
	v_ashrrev_i32_e32 v1, 31, v0
	v_lshlrev_b64 v[0:1], 13, v[0:1]
	v_lshl_add_u64 v[102:103], v[86:87], 0, v[0:1]
	v_add_u32_e32 v0, s24, v128
	v_ashrrev_i32_e32 v1, 31, v0
	v_lshlrev_b64 v[0:1], 13, v[0:1]
	v_lshl_add_u64 v[104:105], v[88:89], 0, v[0:1]
	s_mov_b64 s[16:17], 0
	v_mov_b32_e32 v0, 0
	v_mov_b32_e32 v1, v65
	v_mov_b32_e32 v2, v65
	v_mov_b32_e32 v3, v65
	v_mov_b32_e32 v4, 0
	v_mov_b32_e32 v5, v65
	v_mov_b32_e32 v6, v65
	v_mov_b32_e32 v7, v65
	v_mov_b32_e32 v8, 0
	v_mov_b32_e32 v9, v65
	v_mov_b32_e32 v10, v65
	v_mov_b32_e32 v11, v65
	v_mov_b32_e32 v12, 0
	v_mov_b32_e32 v13, v65
	v_mov_b32_e32 v14, v65
	v_mov_b32_e32 v15, v65
	v_mov_b32_e32 v16, 0
	v_mov_b32_e32 v17, v65
	v_mov_b32_e32 v18, v65
	v_mov_b32_e32 v19, v65
	v_mov_b32_e32 v20, 0
	v_mov_b32_e32 v21, v65
	v_mov_b32_e32 v22, v65
	v_mov_b32_e32 v23, v65
	s_waitcnt vmcnt(0)
	v_mov_b32_e32 v24, 0
	v_mov_b32_e32 v25, v65
	v_mov_b32_e32 v26, v65
	v_mov_b32_e32 v27, v65
	v_mov_b32_e32 v28, 0
	v_mov_b32_e32 v29, v65
	v_mov_b32_e32 v30, v65
	v_mov_b32_e32 v31, v65
	v_mov_b32_e32 v32, 0
	v_mov_b32_e32 v33, v65
	v_mov_b32_e32 v34, v65
	v_mov_b32_e32 v35, v65
	v_mov_b32_e32 v36, 0
	v_mov_b32_e32 v37, v65
	v_mov_b32_e32 v38, v65
	v_mov_b32_e32 v39, v65
	v_mov_b32_e32 v40, 0
	v_mov_b32_e32 v41, v65
	v_mov_b32_e32 v42, v65
	v_mov_b32_e32 v43, v65
	v_mov_b32_e32 v44, 0
	v_mov_b32_e32 v45, v65
	v_mov_b32_e32 v46, v65
	v_mov_b32_e32 v47, v65
	v_mov_b32_e32 v48, 0
	v_mov_b32_e32 v49, v65
	v_mov_b32_e32 v50, v65
	v_mov_b32_e32 v51, v65
	v_mov_b32_e32 v52, 0
	v_mov_b32_e32 v53, v65
	v_mov_b32_e32 v54, v65
	v_mov_b32_e32 v55, v65
	v_mov_b32_e32 v56, 0
	v_mov_b32_e32 v57, v65
	v_mov_b32_e32 v58, v65
	v_mov_b32_e32 v59, v65
	v_mov_b32_e32 v60, 0
	v_mov_b32_e32 v61, v65
	v_mov_b32_e32 v62, v65
	v_mov_b32_e32 v63, v65
	s_waitcnt lgkmcnt(0)
	s_barrier
	v_add3_u32 v182, 0, v134, v135
	v_add_u32_e32 v183, 0x4000, v182
	s_nop 0
	v_readfirstlane_b32 s82, v183
	v_lshl_add_u32 v183, v109, 1, 0
	s_nop 0
	v_readfirstlane_b32 s83, v182
	v_add3_u32 v183, v183, v135, s19
	s_nop 0
	v_readfirstlane_b32 s84, v183
	v_add_u32_e32 v183, 0x400, v182
	s_nop 0
	v_readfirstlane_b32 s85, v183
	v_lshl_add_u32 v183, v111, 1, 0
	v_add3_u32 v183, v183, v135, s19
	s_nop 0
	v_readfirstlane_b32 s86, v183
	v_add_u32_e32 v183, 0x800, v182
	s_nop 0
	v_readfirstlane_b32 s87, v183
	v_lshl_add_u32 v183, v113, 1, 0
	v_add3_u32 v183, v183, v135, s19
	s_nop 0
	v_readfirstlane_b32 s88, v183
	v_add_u32_e32 v182, 0xc00, v182
	s_nop 0
	v_readfirstlane_b32 s89, v182
	v_subrev_u32_e32 v184, s52, v90
	v_subrev_u32_e32 v185, s52, v92
	v_subrev_u32_e32 v186, s52, v94
	v_subrev_u32_e32 v187, s52, v96
	v_subrev_u32_e32 v188, s52, v98
	v_subrev_u32_e32 v189, s52, v100
	v_subrev_u32_e32 v190, s52, v102
	v_subrev_u32_e32 v191, s52, v104
	v_subrev_u32_e32 v187, 0x400, v187
	v_subrev_u32_e32 v186, 0x400, v186
	v_subrev_u32_e32 v189, 0x800, v189
	v_subrev_u32_e32 v188, 0x800, v188
	v_subrev_u32_e32 v191, 0xc00, v191
	v_subrev_u32_e32 v190, 0xc00, v190
	s_and_b32 s28, s26, 0x4000
	s_xor_b32 s27, s28, 0x4000
	s_lshl_b32 s27, s27, 1
	s_add_i32 s27, s27, 32
	s_lshl_b32 s28, s28, 1
	s_add_i32 s28, s28, 32
.LBB0_3463:
	s_xor_b32 s27, s27, 0x8000
	s_xor_b32 s28, s28, 0x8000
	s_add_u32 s90, s52, s16
	s_addc_u32 s91, s53, s17
	s_add_i32 m0, s28, s83
	v_add3_u32 v139, s27, v114, v136
	global_load_lds_dwordx4 v185, s[90:91]
	global_load_lds_dwordx4 v187, s[90:91] offset:1024
	global_load_lds_dwordx4 v189, s[90:91] offset:2048
	global_load_lds_dwordx4 v191, s[90:91] offset:3072
	s_add_i32 m0, s28, s82
	v_add3_u32 v172, s27, v115, v136
	global_load_lds_dwordx4 v184, s[90:91]
	global_load_lds_dwordx4 v186, s[90:91] offset:1024
	global_load_lds_dwordx4 v188, s[90:91] offset:2048
	global_load_lds_dwordx4 v190, s[90:91] offset:3072
	v_add_u32_e32 v160, v139, v137
	v_add_u32_e32 v168, v172, v137
	s_add_u32 s16, s16, 0x80
	s_addc_u32 s17, s17, 0
	ds_read_b128 v[140:143], v160
	ds_read_b128 v[148:151], v168 offset:16384
	ds_read_b128 v[152:155], v168 offset:18432
	ds_read_b128 v[164:167], v168 offset:20480
	ds_read_b128 v[168:171], v168 offset:22528
	ds_read_b128 v[144:147], v160 offset:2048
	ds_read_b128 v[156:159], v160 offset:4096
	ds_read_b128 v[160:163], v160 offset:6144
	v_add_u32_e32 v139, v139, v138
	v_add_u32_e32 v236, v172, v138
	ds_read_b128 v[204:207], v139
	ds_read_b128 v[208:211], v236 offset:16384
	ds_read_b128 v[212:215], v236 offset:18432
	ds_read_b128 v[216:219], v236 offset:20480
	ds_read_b128 v[220:223], v236 offset:22528
	ds_read_b128 v[224:227], v139 offset:2048
	ds_read_b128 v[228:231], v139 offset:4096
	ds_read_b128 v[232:235], v139 offset:6144
	s_setprio 1
	s_waitcnt lgkmcnt(11)
	v_mfma_f32_16x16x32_bf16 v[60:63], v[140:143], v[148:151], v[60:63]
	v_mfma_f32_16x16x32_bf16 v[56:59], v[140:143], v[152:155], v[56:59]
	v_mfma_f32_16x16x32_bf16 v[52:55], v[140:143], v[164:167], v[52:55]
	v_mfma_f32_16x16x32_bf16 v[48:51], v[140:143], v[168:171], v[48:51]
	s_waitcnt lgkmcnt(10)
	v_mfma_f32_16x16x32_bf16 v[44:47], v[144:147], v[148:151], v[44:47]
	v_mfma_f32_16x16x32_bf16 v[40:43], v[144:147], v[152:155], v[40:43]
	v_mfma_f32_16x16x32_bf16 v[36:39], v[144:147], v[164:167], v[36:39]
	v_mfma_f32_16x16x32_bf16 v[32:35], v[144:147], v[168:171], v[32:35]
	s_waitcnt lgkmcnt(9)
	v_mfma_f32_16x16x32_bf16 v[28:31], v[156:159], v[148:151], v[28:31]
	v_mfma_f32_16x16x32_bf16 v[24:27], v[156:159], v[152:155], v[24:27]
	v_mfma_f32_16x16x32_bf16 v[20:23], v[156:159], v[164:167], v[20:23]
	v_mfma_f32_16x16x32_bf16 v[16:19], v[156:159], v[168:171], v[16:19]
	s_waitcnt lgkmcnt(8)
	v_mfma_f32_16x16x32_bf16 v[12:15], v[160:163], v[148:151], v[12:15]
	v_mfma_f32_16x16x32_bf16 v[8:11], v[160:163], v[152:155], v[8:11]
	v_mfma_f32_16x16x32_bf16 v[4:7], v[160:163], v[164:167], v[4:7]
	v_mfma_f32_16x16x32_bf16 v[0:3], v[160:163], v[168:171], v[0:3]
	s_waitcnt lgkmcnt(3)
	v_mfma_f32_16x16x32_bf16 v[60:63], v[204:207], v[208:211], v[60:63]
	v_mfma_f32_16x16x32_bf16 v[56:59], v[204:207], v[212:215], v[56:59]
	v_mfma_f32_16x16x32_bf16 v[52:55], v[204:207], v[216:219], v[52:55]
	v_mfma_f32_16x16x32_bf16 v[48:51], v[204:207], v[220:223], v[48:51]
	s_waitcnt lgkmcnt(2)
	v_mfma_f32_16x16x32_bf16 v[44:47], v[224:227], v[208:211], v[44:47]
	v_mfma_f32_16x16x32_bf16 v[40:43], v[224:227], v[212:215], v[40:43]
	v_mfma_f32_16x16x32_bf16 v[36:39], v[224:227], v[216:219], v[36:39]
	v_mfma_f32_16x16x32_bf16 v[32:35], v[224:227], v[220:223], v[32:35]
	s_waitcnt lgkmcnt(1)
	v_mfma_f32_16x16x32_bf16 v[28:31], v[228:231], v[208:211], v[28:31]
	v_mfma_f32_16x16x32_bf16 v[24:27], v[228:231], v[212:215], v[24:27]
	v_mfma_f32_16x16x32_bf16 v[20:23], v[228:231], v[216:219], v[20:23]
	v_mfma_f32_16x16x32_bf16 v[16:19], v[228:231], v[220:223], v[16:19]
	s_waitcnt lgkmcnt(0)
	v_mfma_f32_16x16x32_bf16 v[12:15], v[232:235], v[208:211], v[12:15]
	v_mfma_f32_16x16x32_bf16 v[8:11], v[232:235], v[212:215], v[8:11]
	v_mfma_f32_16x16x32_bf16 v[4:7], v[232:235], v[216:219], v[4:7]
	v_mfma_f32_16x16x32_bf16 v[0:3], v[232:235], v[220:223], v[0:3]
	s_setprio 0
	s_cmpk_eq_i32 s16, 0x1f80
	s_waitcnt vmcnt(0)
	s_barrier
	s_cbranch_scc0 .LBB0_3463
	ds_read_b128 v[90:93], v118 offset:55296
	ds_read_b128 v[94:97], v118 offset:53248
	ds_read_b128 v[98:101], v119 offset:38912
	ds_read_b128 v[102:105], v119 offset:36864
	ds_read_b128 v[140:143], v118 offset:51200
	ds_read_b128 v[144:147], v118 offset:49152
	ds_read_b128 v[148:151], v119 offset:34816
	ds_read_b128 v[152:155], v119 offset:32768
	ds_read_b128 v[204:207], v120 offset:32768
	ds_read_b128 v[208:211], v120 offset:34816
	ds_read_b128 v[212:215], v121 offset:49152
	ds_read_b128 v[216:219], v121 offset:51200
	ds_read_b128 v[220:223], v120 offset:36864
	ds_read_b128 v[224:227], v120 offset:38912
	ds_read_b128 v[228:231], v121 offset:53248
	ds_read_b128 v[232:235], v121 offset:55296
	s_setprio 1
	s_waitcnt lgkmcnt(13)
	v_mfma_f32_16x16x32_bf16 v[4:7], v[98:101], v[94:97], v[4:7]
	v_mfma_f32_16x16x32_bf16 v[0:3], v[98:101], v[90:93], v[0:3]
	s_waitcnt lgkmcnt(8)
	v_mfma_f32_16x16x32_bf16 v[60:63], v[152:155], v[144:147], v[60:63]
	v_mfma_f32_16x16x32_bf16 v[56:59], v[152:155], v[140:143], v[56:59]
	v_mfma_f32_16x16x32_bf16 v[52:55], v[152:155], v[94:97], v[52:55]
	v_mfma_f32_16x16x32_bf16 v[48:51], v[152:155], v[90:93], v[48:51]
	v_mfma_f32_16x16x32_bf16 v[44:47], v[148:151], v[144:147], v[44:47]
	v_mfma_f32_16x16x32_bf16 v[40:43], v[148:151], v[140:143], v[40:43]
	v_mfma_f32_16x16x32_bf16 v[36:39], v[148:151], v[94:97], v[36:39]
	v_mfma_f32_16x16x32_bf16 v[32:35], v[148:151], v[90:93], v[32:35]
	v_mfma_f32_16x16x32_bf16 v[28:31], v[102:105], v[144:147], v[28:31]
	v_mfma_f32_16x16x32_bf16 v[24:27], v[102:105], v[140:143], v[24:27]
	v_mfma_f32_16x16x32_bf16 v[20:23], v[102:105], v[94:97], v[20:23]
	v_mfma_f32_16x16x32_bf16 v[16:19], v[102:105], v[90:93], v[16:19]
	v_mfma_f32_16x16x32_bf16 v[12:15], v[98:101], v[144:147], v[12:15]
	v_mfma_f32_16x16x32_bf16 v[8:11], v[98:101], v[140:143], v[8:11]
	s_waitcnt lgkmcnt(1)
	v_mfma_f32_16x16x32_bf16 v[4:7], v[224:227], v[228:231], v[4:7]
	s_waitcnt lgkmcnt(0)
	v_mfma_f32_16x16x32_bf16 v[0:3], v[224:227], v[232:235], v[0:3]
	v_mfma_f32_16x16x32_bf16 v[60:63], v[204:207], v[212:215], v[60:63]
	v_mfma_f32_16x16x32_bf16 v[56:59], v[204:207], v[216:219], v[56:59]
	v_mfma_f32_16x16x32_bf16 v[52:55], v[204:207], v[228:231], v[52:55]
	v_mfma_f32_16x16x32_bf16 v[48:51], v[204:207], v[232:235], v[48:51]
	v_mfma_f32_16x16x32_bf16 v[44:47], v[208:211], v[212:215], v[44:47]
	v_mfma_f32_16x16x32_bf16 v[40:43], v[208:211], v[216:219], v[40:43]
	v_mfma_f32_16x16x32_bf16 v[36:39], v[208:211], v[228:231], v[36:39]
	v_mfma_f32_16x16x32_bf16 v[32:35], v[208:211], v[232:235], v[32:35]
	v_mfma_f32_16x16x32_bf16 v[28:31], v[220:223], v[212:215], v[28:31]
	v_mfma_f32_16x16x32_bf16 v[24:27], v[220:223], v[216:219], v[24:27]
	v_mfma_f32_16x16x32_bf16 v[20:23], v[220:223], v[228:231], v[20:23]
	v_mfma_f32_16x16x32_bf16 v[16:19], v[220:223], v[232:235], v[16:19]
	v_mfma_f32_16x16x32_bf16 v[12:15], v[224:227], v[212:215], v[12:15]
	v_mfma_f32_16x16x32_bf16 v[8:11], v[224:227], v[216:219], v[8:11]
	s_setprio 0
	s_barrier
	ds_write2_b32 v116, v60, v56 offset1:16
	ds_write2_b32 v116, v61, v57 offset0:132 offset1:148
	v_add_u32_e32 v56, 0x400, v116
	ds_write2_b32 v56, v62, v58 offset0:8 offset1:24
	ds_write2_b32 v56, v63, v59 offset0:140 offset1:156
	ds_write2_b32 v116, v52, v48 offset0:32 offset1:48
	ds_write2_b32 v116, v53, v49 offset0:164 offset1:180
	ds_write2_b32 v56, v54, v50 offset0:40 offset1:56
	ds_write2_b32 v56, v55, v51 offset0:172 offset1:188
	v_add_u32_e32 v48, 0x2000, v116
	ds_write2_b32 v48, v44, v40 offset0:64 offset1:80
	ds_write2_b32 v48, v45, v41 offset0:196 offset1:212
	v_add_u32_e32 v40, 0x2400, v116
	ds_write2_b32 v40, v46, v42 offset0:72 offset1:88
	ds_write2_b32 v40, v47, v43 offset0:204 offset1:220
	ds_write2_b32 v48, v36, v32 offset0:96 offset1:112
	ds_write2_b32 v48, v37, v33 offset0:228 offset1:244
	ds_write2_b32 v40, v38, v34 offset0:104 offset1:120
	ds_write2_b32 v40, v39, v35 offset0:236 offset1:252
	v_add_u32_e32 v32, 0x4000, v116
	ds_write2_b32 v32, v28, v24 offset0:128 offset1:144
	v_add_u32_e32 v24, 0x4400, v116
	ds_write2_b32 v24, v29, v25 offset0:4 offset1:20
	ds_write2_b32 v24, v30, v26 offset0:136 offset1:152
	v_add_u32_e32 v25, 0x4800, v116
	ds_write2_b32 v25, v31, v27 offset0:12 offset1:28
	ds_write2_b32 v32, v20, v16 offset0:160 offset1:176
	ds_write2_b32 v24, v21, v17 offset0:36 offset1:52
	ds_write2_b32 v24, v22, v18 offset0:168 offset1:184
	ds_write2_b32 v25, v23, v19 offset0:44 offset1:60
	v_add_u32_e32 v16, 0x6000, v116
	ds_write2_b32 v16, v12, v8 offset0:192 offset1:208
	v_add_u32_e32 v8, 0x6400, v116
	ds_write2_b32 v8, v13, v9 offset0:68 offset1:84
	ds_write2_b32 v8, v14, v10 offset0:200 offset1:216
	v_add_u32_e32 v9, 0x6800, v116
	ds_write2_b32 v9, v15, v11 offset0:76 offset1:92
	ds_write2_b32 v16, v4, v0 offset0:224 offset1:240
	ds_write2_b32 v8, v5, v1 offset0:100 offset1:116
	ds_write2_b32 v8, v6, v2 offset0:232 offset1:248
	ds_write2_b32 v9, v7, v3 offset0:108 offset1:124
	v_or_b32_e32 v0, s25, v117
	v_ashrrev_i32_e32 v1, 31, v0
	v_lshlrev_b64 v[2:3], 2, v[0:1]
	v_lshl_add_u64 v[0:1], s[14:15], 0, v[2:3]
	v_lshl_add_u64 v[2:3], s[6:7], 0, v[2:3]
	v_add_u32_e32 v4, s24, v129
	s_mov_b32 s16, 0
	s_waitcnt lgkmcnt(0)
	s_barrier

.LBB0_3471:
	s_ashr_i32 s8, s14, 31
	s_lshr_b32 s8, s8, 29
	s_add_i32 s8, s14, s8
	s_ashr_i32 s8, s8, 3
	s_add_i32 s9, s8, s16
	s_lshl_b32 s20, s8, 7
	s_lshl_b32 s8, s8, 10
	s_lshl_b32 s21, s14, 7
	s_sub_i32 s21, s21, s8
	s_lshr_b32 s9, s9, 4
	v_add_u32_e32 v0, s21, v104
	s_mulk_i32 s9, 0x900
	s_and_b32 s20, s20, 0x780
	v_ashrrev_i32_e32 v1, 31, v0
	v_add_u32_e32 v2, 0x4000, v105
	s_add_i32 s20, s20, s9
	v_lshlrev_b64 v[0:1], 13, v[0:1]
	v_readfirstlane_b32 s22, v2
	s_add_i32 s9, s20, 0x100
	v_lshl_add_u64 v[0:1], v[64:65], 0, v[0:1]
	s_mov_b32 m0, s22
	v_readfirstlane_b32 s22, v105
	global_load_lds_dwordx4 v[0:1], off
	v_add_u32_e32 v0, s9, v104
	v_ashrrev_i32_e32 v1, 31, v0
	v_lshlrev_b64 v[0:1], 13, v[0:1]
	v_lshl_add_u64 v[0:1], v[70:71], 0, v[0:1]
	s_mov_b32 m0, s22
	v_readfirstlane_b32 s22, v130
	global_load_lds_dwordx4 v[0:1], off
	v_add_u32_e32 v0, s21, v106
	v_ashrrev_i32_e32 v1, 31, v0
	v_lshlrev_b64 v[0:1], 13, v[0:1]
	v_lshl_add_u64 v[0:1], v[66:67], 0, v[0:1]
	s_mov_b32 m0, s22
	v_add_u32_e32 v2, 0x400, v105
	global_load_lds_dwordx4 v[0:1], off
	v_add_u32_e32 v0, s9, v106
	v_ashrrev_i32_e32 v1, 31, v0
	v_lshlrev_b64 v[0:1], 13, v[0:1]
	v_readfirstlane_b32 s22, v2
	v_lshl_add_u64 v[0:1], v[72:73], 0, v[0:1]
	s_mov_b32 m0, s22
	v_readfirstlane_b32 s22, v131
	global_load_lds_dwordx4 v[0:1], off
	v_add_u32_e32 v0, s21, v108
	v_ashrrev_i32_e32 v1, 31, v0
	v_lshlrev_b64 v[0:1], 13, v[0:1]
	v_lshl_add_u64 v[0:1], v[64:65], 0, v[0:1]
	s_mov_b32 m0, s22
	v_add_u32_e32 v2, 0x800, v105
	global_load_lds_dwordx4 v[0:1], off
	v_add_u32_e32 v0, s9, v108
	v_ashrrev_i32_e32 v1, 31, v0
	v_lshlrev_b64 v[0:1], 13, v[0:1]
	v_readfirstlane_b32 s22, v2
	v_lshl_add_u64 v[0:1], v[70:71], 0, v[0:1]
	s_mov_b32 m0, s22
	v_readfirstlane_b32 s22, v132
	global_load_lds_dwordx4 v[0:1], off
	v_add_u32_e32 v0, s21, v110
	v_ashrrev_i32_e32 v1, 31, v0
	v_lshlrev_b64 v[0:1], 13, v[0:1]
	v_lshl_add_u64 v[0:1], v[68:69], 0, v[0:1]
	s_mov_b32 m0, s22
	v_add_u32_e32 v2, 0xc00, v105
	global_load_lds_dwordx4 v[0:1], off
	v_add_u32_e32 v0, s9, v110
	v_ashrrev_i32_e32 v1, 31, v0
	v_lshlrev_b64 v[0:1], 13, v[0:1]
	v_readfirstlane_b32 s9, v2
	v_lshl_add_u64 v[0:1], v[74:75], 0, v[0:1]
	s_mov_b32 m0, s9
	s_mov_b32 s22, 0
	global_load_lds_dwordx4 v[0:1], off
	v_subrev_u32_e32 v0, s8, v120
	v_ashrrev_i32_e32 v1, 31, v0
	v_lshlrev_b64 v[0:1], 13, v[0:1]
	v_lshl_add_u64 v[88:89], v[76:77], 0, v[0:1]
	v_add_u32_e32 v0, s20, v121
	v_ashrrev_i32_e32 v1, 31, v0
	v_lshlrev_b64 v[0:1], 13, v[0:1]
	v_lshl_add_u64 v[90:91], v[78:79], 0, v[0:1]
	v_subrev_u32_e32 v0, s8, v122
	v_ashrrev_i32_e32 v1, 31, v0
	v_lshlrev_b64 v[0:1], 13, v[0:1]
	v_lshl_add_u64 v[92:93], v[80:81], 0, v[0:1]
	v_add_u32_e32 v0, s20, v123
	v_ashrrev_i32_e32 v1, 31, v0
	v_lshlrev_b64 v[0:1], 13, v[0:1]
	v_lshl_add_u64 v[94:95], v[82:83], 0, v[0:1]
	v_subrev_u32_e32 v0, s8, v124
	v_ashrrev_i32_e32 v1, 31, v0
	v_lshlrev_b64 v[0:1], 13, v[0:1]
	v_lshl_add_u64 v[96:97], v[76:77], 0, v[0:1]
	v_add_u32_e32 v0, s20, v125
	v_ashrrev_i32_e32 v1, 31, v0
	v_lshlrev_b64 v[0:1], 13, v[0:1]
	v_lshl_add_u64 v[98:99], v[78:79], 0, v[0:1]
	v_subrev_u32_e32 v0, s8, v126
	v_ashrrev_i32_e32 v1, 31, v0
	v_lshlrev_b64 v[0:1], 13, v[0:1]
	v_lshl_add_u64 v[100:101], v[84:85], 0, v[0:1]
	v_add_u32_e32 v0, s20, v127
	v_ashrrev_i32_e32 v1, 31, v0
	v_lshlrev_b64 v[0:1], 13, v[0:1]
	v_lshl_add_u64 v[102:103], v[86:87], 0, v[0:1]
	v_mov_b32_e32 v0, 0
	s_mov_b64 s[8:9], 0
	v_mov_b32_e32 v1, v0
	v_mov_b32_e32 v2, v0
	v_mov_b32_e32 v3, v0
	v_mov_b32_e32 v4, v0
	v_mov_b32_e32 v5, v0
	v_mov_b32_e32 v6, v0
	v_mov_b32_e32 v7, v0
	v_mov_b32_e32 v8, v0
	v_mov_b32_e32 v9, v0
	v_mov_b32_e32 v10, v0
	v_mov_b32_e32 v11, v0
	v_mov_b32_e32 v12, v0
	v_mov_b32_e32 v13, v0
	v_mov_b32_e32 v14, v0
	v_mov_b32_e32 v15, v0
	v_mov_b32_e32 v16, v0
	v_mov_b32_e32 v17, v0
	v_mov_b32_e32 v18, v0
	v_mov_b32_e32 v19, v0
	v_mov_b32_e32 v20, v0
	v_mov_b32_e32 v21, v0
	v_mov_b32_e32 v22, v0
	v_mov_b32_e32 v23, v0
	v_mov_b32_e32 v24, v0
	v_mov_b32_e32 v25, v0
	v_mov_b32_e32 v26, v0
	v_mov_b32_e32 v27, v0
	s_waitcnt vmcnt(0)
	v_mov_b32_e32 v28, v0
	v_mov_b32_e32 v29, v0
	v_mov_b32_e32 v30, v0
	v_mov_b32_e32 v31, v0
	v_mov_b32_e32 v32, v0
	v_mov_b32_e32 v33, v0
	v_mov_b32_e32 v34, v0
	v_mov_b32_e32 v35, v0
	v_mov_b32_e32 v36, v0
	v_mov_b32_e32 v37, v0
	v_mov_b32_e32 v38, v0
	v_mov_b32_e32 v39, v0
	v_mov_b32_e32 v40, v0
	v_mov_b32_e32 v41, v0
	v_mov_b32_e32 v42, v0
	v_mov_b32_e32 v43, v0
	v_mov_b32_e32 v44, v0
	v_mov_b32_e32 v45, v0
	v_mov_b32_e32 v46, v0
	v_mov_b32_e32 v47, v0
	v_mov_b32_e32 v48, v0
	v_mov_b32_e32 v49, v0
	v_mov_b32_e32 v50, v0
	v_mov_b32_e32 v51, v0
	v_mov_b32_e32 v52, v0
	v_mov_b32_e32 v53, v0
	v_mov_b32_e32 v54, v0
	v_mov_b32_e32 v55, v0
	v_mov_b32_e32 v56, v0
	v_mov_b32_e32 v57, v0
	v_mov_b32_e32 v58, v0
	v_mov_b32_e32 v59, v0
	v_mov_b32_e32 v60, v0
	v_mov_b32_e32 v61, v0
	v_mov_b32_e32 v62, v0
	v_mov_b32_e32 v63, v0
	s_waitcnt lgkmcnt(0)
	s_barrier
	v_add3_u32 v182, 0, v133, v134
	v_add_u32_e32 v183, 0x4000, v182
	s_nop 0
	v_readfirstlane_b32 s82, v183
	v_lshl_add_u32 v183, v107, 1, 0
	s_nop 0
	v_readfirstlane_b32 s83, v182
	v_add3_u32 v183, v183, v134, s13
	s_nop 0
	v_readfirstlane_b32 s84, v183
	v_add_u32_e32 v183, 0x400, v182
	s_nop 0
	v_readfirstlane_b32 s85, v183
	v_lshl_add_u32 v183, v109, 1, 0
	v_add3_u32 v183, v183, v134, s13
	s_nop 0
	v_readfirstlane_b32 s86, v183
	v_add_u32_e32 v183, 0x800, v182
	s_nop 0
	v_readfirstlane_b32 s87, v183
	v_lshl_add_u32 v183, v111, 1, 0
	v_add3_u32 v183, v183, v134, s13
	s_nop 0
	v_readfirstlane_b32 s88, v183
	v_add_u32_e32 v182, 0xc00, v182
	s_nop 0
	v_readfirstlane_b32 s89, v182
	v_subrev_u32_e32 v184, s52, v88
	v_subrev_u32_e32 v185, s52, v90
	v_subrev_u32_e32 v186, s52, v92
	v_subrev_u32_e32 v187, s52, v94
	v_subrev_u32_e32 v188, s52, v96
	v_subrev_u32_e32 v189, s52, v98
	v_subrev_u32_e32 v190, s52, v100
	v_subrev_u32_e32 v191, s52, v102
	v_subrev_u32_e32 v187, 0x400, v187
	v_subrev_u32_e32 v186, 0x400, v186
	v_subrev_u32_e32 v189, 0x800, v189
	v_subrev_u32_e32 v188, 0x800, v188
	v_subrev_u32_e32 v191, 0xc00, v191
	v_subrev_u32_e32 v190, 0xc00, v190
	s_and_b32 s24, s22, 0x4000
	s_xor_b32 s23, s24, 0x4000
	s_lshl_b32 s23, s23, 1
	s_add_i32 s23, s23, 32
	s_lshl_b32 s24, s24, 1
	s_add_i32 s24, s24, 32
.LBB0_3472:
	s_xor_b32 s23, s23, 0x8000
	s_xor_b32 s24, s24, 0x8000
	s_add_u32 s90, s52, s8
	s_addc_u32 s91, s53, s9
	s_add_i32 m0, s24, s83
	v_add3_u32 v170, s23, v112, v135
	global_load_lds_dwordx4 v185, s[90:91]
	global_load_lds_dwordx4 v187, s[90:91] offset:1024
	global_load_lds_dwordx4 v189, s[90:91] offset:2048
	global_load_lds_dwordx4 v191, s[90:91] offset:3072
	s_add_i32 m0, s24, s82
	v_add3_u32 v171, s23, v113, v135
	global_load_lds_dwordx4 v184, s[90:91]
	global_load_lds_dwordx4 v186, s[90:91] offset:1024
	global_load_lds_dwordx4 v188, s[90:91] offset:2048
	global_load_lds_dwordx4 v190, s[90:91] offset:3072
	v_add_u32_e32 v158, v170, v136
	v_add_u32_e32 v166, v171, v136
	s_add_u32 s8, s8, 0x80
	s_addc_u32 s9, s9, 0
	ds_read_b128 v[138:141], v158
	ds_read_b128 v[146:149], v166 offset:16384
	ds_read_b128 v[150:153], v166 offset:18432
	ds_read_b128 v[162:165], v166 offset:20480
	ds_read_b128 v[166:169], v166 offset:22528
	ds_read_b128 v[142:145], v158 offset:2048
	ds_read_b128 v[154:157], v158 offset:4096
	ds_read_b128 v[158:161], v158 offset:6144
	v_add_u32_e32 v236, v170, v137
	v_add_u32_e32 v237, v171, v137
	ds_read_b128 v[204:207], v236
	ds_read_b128 v[208:211], v237 offset:16384
	ds_read_b128 v[212:215], v237 offset:18432
	ds_read_b128 v[216:219], v237 offset:20480
	ds_read_b128 v[220:223], v237 offset:22528
	ds_read_b128 v[224:227], v236 offset:2048
	ds_read_b128 v[228:231], v236 offset:4096
	ds_read_b128 v[232:235], v236 offset:6144
	s_setprio 1
	s_waitcnt lgkmcnt(11)
	v_mfma_f32_16x16x32_bf16 v[60:63], v[138:141], v[146:149], v[60:63]
	v_mfma_f32_16x16x32_bf16 v[56:59], v[138:141], v[150:153], v[56:59]
	v_mfma_f32_16x16x32_bf16 v[52:55], v[138:141], v[162:165], v[52:55]
	v_mfma_f32_16x16x32_bf16 v[48:51], v[138:141], v[166:169], v[48:51]
	s_waitcnt lgkmcnt(10)
	v_mfma_f32_16x16x32_bf16 v[44:47], v[142:145], v[146:149], v[44:47]
	v_mfma_f32_16x16x32_bf16 v[40:43], v[142:145], v[150:153], v[40:43]
	v_mfma_f32_16x16x32_bf16 v[36:39], v[142:145], v[162:165], v[36:39]
	v_mfma_f32_16x16x32_bf16 v[32:35], v[142:145], v[166:169], v[32:35]
	s_waitcnt lgkmcnt(9)
	v_mfma_f32_16x16x32_bf16 v[28:31], v[154:157], v[146:149], v[28:31]
	v_mfma_f32_16x16x32_bf16 v[24:27], v[154:157], v[150:153], v[24:27]
	v_mfma_f32_16x16x32_bf16 v[20:23], v[154:157], v[162:165], v[20:23]
	v_mfma_f32_16x16x32_bf16 v[16:19], v[154:157], v[166:169], v[16:19]
	s_waitcnt lgkmcnt(8)
	v_mfma_f32_16x16x32_bf16 v[12:15], v[158:161], v[146:149], v[12:15]
	v_mfma_f32_16x16x32_bf16 v[8:11], v[158:161], v[150:153], v[8:11]
	v_mfma_f32_16x16x32_bf16 v[4:7], v[158:161], v[162:165], v[4:7]
	v_mfma_f32_16x16x32_bf16 v[0:3], v[158:161], v[166:169], v[0:3]
	s_waitcnt lgkmcnt(3)
	v_mfma_f32_16x16x32_bf16 v[60:63], v[204:207], v[208:211], v[60:63]
	v_mfma_f32_16x16x32_bf16 v[56:59], v[204:207], v[212:215], v[56:59]
	v_mfma_f32_16x16x32_bf16 v[52:55], v[204:207], v[216:219], v[52:55]
	v_mfma_f32_16x16x32_bf16 v[48:51], v[204:207], v[220:223], v[48:51]
	s_waitcnt lgkmcnt(2)
	v_mfma_f32_16x16x32_bf16 v[44:47], v[224:227], v[208:211], v[44:47]
	v_mfma_f32_16x16x32_bf16 v[40:43], v[224:227], v[212:215], v[40:43]
	v_mfma_f32_16x16x32_bf16 v[36:39], v[224:227], v[216:219], v[36:39]
	v_mfma_f32_16x16x32_bf16 v[32:35], v[224:227], v[220:223], v[32:35]
	s_waitcnt lgkmcnt(1)
	v_mfma_f32_16x16x32_bf16 v[28:31], v[228:231], v[208:211], v[28:31]
	v_mfma_f32_16x16x32_bf16 v[24:27], v[228:231], v[212:215], v[24:27]
	v_mfma_f32_16x16x32_bf16 v[20:23], v[228:231], v[216:219], v[20:23]
	v_mfma_f32_16x16x32_bf16 v[16:19], v[228:231], v[220:223], v[16:19]
	s_waitcnt lgkmcnt(0)
	v_mfma_f32_16x16x32_bf16 v[12:15], v[232:235], v[208:211], v[12:15]
	v_mfma_f32_16x16x32_bf16 v[8:11], v[232:235], v[212:215], v[8:11]
	v_mfma_f32_16x16x32_bf16 v[4:7], v[232:235], v[216:219], v[4:7]
	v_mfma_f32_16x16x32_bf16 v[0:3], v[232:235], v[220:223], v[0:3]
	s_setprio 0
	s_cmpk_eq_i32 s8, 0x1f80
	s_waitcnt vmcnt(0)
	s_barrier
	s_cbranch_scc0 .LBB0_3472
	ds_read_b128 v[88:91], v116 offset:55296
	ds_read_b128 v[92:95], v116 offset:53248
	ds_read_b128 v[96:99], v117 offset:38912
	ds_read_b128 v[100:103], v117 offset:36864
	ds_read_b128 v[138:141], v116 offset:51200
	ds_read_b128 v[142:145], v116 offset:49152
	ds_read_b128 v[146:149], v117 offset:34816
	ds_read_b128 v[150:153], v117 offset:32768
	ds_read_b128 v[204:207], v118 offset:32768
	ds_read_b128 v[208:211], v118 offset:34816
	ds_read_b128 v[212:215], v119 offset:49152
	ds_read_b128 v[216:219], v119 offset:51200
	ds_read_b128 v[220:223], v118 offset:36864
	ds_read_b128 v[224:227], v118 offset:38912
	ds_read_b128 v[228:231], v119 offset:53248
	ds_read_b128 v[232:235], v119 offset:55296
	s_setprio 1
	s_waitcnt lgkmcnt(13)
	v_mfma_f32_16x16x32_bf16 v[4:7], v[96:99], v[92:95], v[4:7]
	v_mfma_f32_16x16x32_bf16 v[0:3], v[96:99], v[88:91], v[0:3]
	s_waitcnt lgkmcnt(8)
	v_mfma_f32_16x16x32_bf16 v[60:63], v[150:153], v[142:145], v[60:63]
	v_mfma_f32_16x16x32_bf16 v[56:59], v[150:153], v[138:141], v[56:59]
	v_mfma_f32_16x16x32_bf16 v[52:55], v[150:153], v[92:95], v[52:55]
	v_mfma_f32_16x16x32_bf16 v[48:51], v[150:153], v[88:91], v[48:51]
	v_mfma_f32_16x16x32_bf16 v[44:47], v[146:149], v[142:145], v[44:47]
	v_mfma_f32_16x16x32_bf16 v[40:43], v[146:149], v[138:141], v[40:43]
	v_mfma_f32_16x16x32_bf16 v[36:39], v[146:149], v[92:95], v[36:39]
	v_mfma_f32_16x16x32_bf16 v[32:35], v[146:149], v[88:91], v[32:35]
	v_mfma_f32_16x16x32_bf16 v[28:31], v[100:103], v[142:145], v[28:31]
	v_mfma_f32_16x16x32_bf16 v[24:27], v[100:103], v[138:141], v[24:27]
	v_mfma_f32_16x16x32_bf16 v[20:23], v[100:103], v[92:95], v[20:23]
	v_mfma_f32_16x16x32_bf16 v[16:19], v[100:103], v[88:91], v[16:19]
	v_mfma_f32_16x16x32_bf16 v[12:15], v[96:99], v[142:145], v[12:15]
	v_mfma_f32_16x16x32_bf16 v[8:11], v[96:99], v[138:141], v[8:11]
	s_waitcnt lgkmcnt(1)
	v_mfma_f32_16x16x32_bf16 v[4:7], v[224:227], v[228:231], v[4:7]
	s_waitcnt lgkmcnt(0)
	v_mfma_f32_16x16x32_bf16 v[0:3], v[224:227], v[232:235], v[0:3]
	v_mfma_f32_16x16x32_bf16 v[60:63], v[204:207], v[212:215], v[60:63]
	v_mfma_f32_16x16x32_bf16 v[56:59], v[204:207], v[216:219], v[56:59]
	v_mfma_f32_16x16x32_bf16 v[52:55], v[204:207], v[228:231], v[52:55]
	v_mfma_f32_16x16x32_bf16 v[48:51], v[204:207], v[232:235], v[48:51]
	v_mfma_f32_16x16x32_bf16 v[44:47], v[208:211], v[212:215], v[44:47]
	v_mfma_f32_16x16x32_bf16 v[40:43], v[208:211], v[216:219], v[40:43]
	v_mfma_f32_16x16x32_bf16 v[36:39], v[208:211], v[228:231], v[36:39]
	v_mfma_f32_16x16x32_bf16 v[32:35], v[208:211], v[232:235], v[32:35]
	v_mfma_f32_16x16x32_bf16 v[28:31], v[220:223], v[212:215], v[28:31]
	v_mfma_f32_16x16x32_bf16 v[24:27], v[220:223], v[216:219], v[24:27]
	v_mfma_f32_16x16x32_bf16 v[20:23], v[220:223], v[228:231], v[20:23]
	v_mfma_f32_16x16x32_bf16 v[16:19], v[220:223], v[232:235], v[16:19]
	v_mfma_f32_16x16x32_bf16 v[12:15], v[224:227], v[212:215], v[12:15]
	v_mfma_f32_16x16x32_bf16 v[8:11], v[224:227], v[216:219], v[8:11]
	s_setprio 0
	s_barrier
	ds_write2_b32 v114, v60, v56 offset1:16
	ds_write2_b32 v114, v61, v57 offset0:132 offset1:148
	v_add_u32_e32 v56, 0x400, v114
	ds_write2_b32 v56, v62, v58 offset0:8 offset1:24
	ds_write2_b32 v56, v63, v59 offset0:140 offset1:156
	ds_write2_b32 v114, v52, v48 offset0:32 offset1:48
	ds_write2_b32 v114, v53, v49 offset0:164 offset1:180
	ds_write2_b32 v56, v54, v50 offset0:40 offset1:56
	ds_write2_b32 v56, v55, v51 offset0:172 offset1:188
	v_add_u32_e32 v48, 0x2000, v114
	ds_write2_b32 v48, v44, v40 offset0:64 offset1:80
	ds_write2_b32 v48, v45, v41 offset0:196 offset1:212
	v_add_u32_e32 v40, 0x2400, v114
	ds_write2_b32 v40, v46, v42 offset0:72 offset1:88
	ds_write2_b32 v40, v47, v43 offset0:204 offset1:220
	ds_write2_b32 v48, v36, v32 offset0:96 offset1:112
	ds_write2_b32 v48, v37, v33 offset0:228 offset1:244
	ds_write2_b32 v40, v38, v34 offset0:104 offset1:120
	ds_write2_b32 v40, v39, v35 offset0:236 offset1:252
	v_add_u32_e32 v32, 0x4000, v114
	ds_write2_b32 v32, v28, v24 offset0:128 offset1:144
	v_add_u32_e32 v24, 0x4400, v114
	ds_write2_b32 v24, v29, v25 offset0:4 offset1:20
	ds_write2_b32 v24, v30, v26 offset0:136 offset1:152
	v_add_u32_e32 v25, 0x4800, v114
	ds_write2_b32 v25, v31, v27 offset0:12 offset1:28
	ds_write2_b32 v32, v20, v16 offset0:160 offset1:176
	ds_write2_b32 v24, v21, v17 offset0:36 offset1:52
	ds_write2_b32 v24, v22, v18 offset0:168 offset1:184
	ds_write2_b32 v25, v23, v19 offset0:44 offset1:60
	v_add_u32_e32 v16, 0x6000, v114
	ds_write2_b32 v16, v12, v8 offset0:192 offset1:208
	v_add_u32_e32 v8, 0x6400, v114
	ds_write2_b32 v8, v13, v9 offset0:68 offset1:84
	ds_write2_b32 v8, v14, v10 offset0:200 offset1:216
	v_add_u32_e32 v9, 0x6800, v114
	ds_write2_b32 v9, v15, v11 offset0:76 offset1:92
	ds_write2_b32 v16, v4, v0 offset0:224 offset1:240
	ds_write2_b32 v8, v5, v1 offset0:100 offset1:116
	ds_write2_b32 v8, v6, v2 offset0:232 offset1:248
	ds_write2_b32 v9, v7, v3 offset0:108 offset1:124
	v_or_b32_e32 v0, s21, v115
	v_ashrrev_i32_e32 v1, 31, v0
	v_lshlrev_b64 v[2:3], 2, v[0:1]
	v_lshl_add_u64 v[0:1], s[10:11], 0, v[2:3]
	v_lshl_add_u64 v[2:3], s[6:7], 0, v[2:3]
	v_add_u32_e32 v4, s20, v128
	s_mov_b32 s8, 0
	s_waitcnt lgkmcnt(0)
	s_barrier
